# stack2 + halo GEMM prefetch hoist + halo-WG LayerNorm loop fully unrolled with all row loads issued up front (6 register banks)
# speedup vs baseline: 1.0033x; 1.0005x over previous
;     constexpr int NR = 2 * NP;
;     auto rowof = [](int pi) { return SEL == 0 ? 2 * pi : SEL == 1 ? 64 * pi + 62 : 64 * (pi / 31) + 2 * (pi % 31); };
;     auto rowr = [&](int pi, int r) { const int pp = pi + (r >> 1) * pstep; return rowof(pp < p1 ? pp : pi) + (r & 1); };
;     pg8::u32x4 raw[NR][2];
;     if (p0 < p1) {
; #pragma unroll
;         for (int r = 0; r < NR; ++r) { const bf16_t* p = z + (size_t)rowr(p0, r) * DM;
; #pragma unroll
;             for (int j = 0; j < 2; ++j) raw[r][j] = *(const pg8::u32x4*)(p + 8 * lane + 512 * j); } }
;     for (int pi = p0; pi < p1; pi += NP * pstep) {
; __global__ void __launch_bounds__(NWAVES * 64, 2) fwd_mega(Args args) {
;     ...
;         if ((int)blockIdx.x >= 88) {
;             ln_rows_range<1, 2, 2>(ZB, XB, nullptr, STATS, IN(21), IN(22), ((int)blockIdx.x - 88) * NWAVES + wave, (M / 64) * 31, (G - 88) * NWAVES, lane);
;         } else {
;             const int pm_ = (int)blockIdx.x / 11;
;             ln_rows_range<1, 1>(ZB, XB, nullptr, STATS, IN(21), IN(22), 64 * pm_ + wave, 64 * pm_ + 64, NWAVES, lane);
.LBB0_670:
	s_or_b64 exec, exec, s[6:7]
	v_readlane_b32 s0, v253, 2
	v_readlane_b32 s1, v253, 3
	s_add_u32 s58, s0, 0x12800000
	s_addc_u32 s59, s1, 0
	s_waitcnt lgkmcnt(0)
	v_mov_b32_e32 v1, v0
	s_add_u32 s16, s0, 0x1f000000
	s_barrier
	s_addc_u32 s17, s1, 0
	v_readfirstlane_b32 s4, v1
	s_ashr_i32 s38, s4, 6
	v_readlane_b32 s0, v253, 0
	s_cmpk_lt_i32 s0, 0x58
	s_cselect_b64 s[60:61], -1, 0
	v_and_b32_e32 v145, 63, v1
	s_mov_b64 s[6:7], -1
	s_and_b64 vcc, exec, s[60:61]
	s_mul_hi_i32 s54, s0, 0x2e8ba2e9
	v_readlane_b32 s1, v253, 1
	s_cbranch_vccz .LBB0_687
	s_lshr_b32 s0, s54, 31
	s_ashr_i32 s3, s54, 1
	s_add_i32 s3, s3, s0
	s_cmp_gt_i32 s38, 63
	s_cbranch_scc1 .LBB0_680
	s_lshl_b32 s2, s3, 6
	v_readlane_b32 s0, v253, 4
	s_add_i32 s19, s38, s2
	v_readlane_b32 s1, v253, 5
	s_lshl_b32 s5, s19, 6
	s_load_dwordx4 s[8:11], s[0:1], 0xa8
	s_or_b32 s0, s5, 62
	v_readlane_b32 s6, v253, 21
	s_waitcnt vmcnt(5)
	v_lshlrev_b32_e32 v54, 4, v145
	v_mov_b32_e32 v55, 0
	v_readlane_b32 s7, v253, 22
	s_ashr_i32 s1, s0, 31
	s_lshl_b64 s[0:1], s[0:1], 11
	v_lshl_add_u64 v[50:51], s[6:7], 0, v[54:55]
	v_lshl_add_u64 v[2:3], v[50:51], 0, s[0:1]
	s_or_b32 s0, s5, 63
	s_ashr_i32 s1, s0, 31
	s_lshl_b64 s[0:1], s[0:1], 11
	global_load_dwordx4 v[38:41], v[2:3], off
	global_load_dwordx4 v[42:45], v[2:3], off offset:1024
	v_lshl_add_u64 v[2:3], v[50:51], 0, s[0:1]
	v_lshlrev_b32_e32 v52, 5, v145
	global_load_dwordx4 v[34:37], v[2:3], off
	global_load_dwordx4 v[46:49], v[2:3], off offset:1024
	s_waitcnt lgkmcnt(0)
	global_load_dwordx4 v[2:5], v52, s[8:9] offset:16
	global_load_dwordx4 v[6:9], v52, s[10:11] offset:16
	global_load_dwordx4 v[10:13], v52, s[8:9]
	global_load_dwordx4 v[14:17], v52, s[10:11]
	global_load_dwordx4 v[18:21], v52, s[8:9] offset:2064
	global_load_dwordx4 v[22:25], v52, s[10:11] offset:2064
	global_load_dwordx4 v[26:29], v52, s[8:9] offset:2048
	global_load_dwordx4 v[30:33], v52, s[10:11] offset:2048
	s_add_u32 s0, s0, 0x100000
	s_addc_u32 s1, s1, 0
	v_lshl_add_u64 v[156:157], v[50:51], 0, s[0:1]
	global_load_dwordx4 v[160:163], v[156:157], off offset:-2048
	global_load_dwordx4 v[164:167], v[156:157], off offset:-1024
	global_load_dwordx4 v[168:171], v[156:157], off offset:1024
	s_nop 0
	global_load_dwordx4 v[156:159], v[156:157], off
	s_add_u32 s0, s0, 0x100000
	s_addc_u32 s1, s1, 0
	v_lshl_add_u64 v[172:173], v[50:51], 0, s[0:1]
	global_load_dwordx4 v[176:179], v[172:173], off offset:-2048
	global_load_dwordx4 v[180:183], v[172:173], off offset:-1024
	global_load_dwordx4 v[184:187], v[172:173], off offset:1024
	s_nop 0
	global_load_dwordx4 v[172:175], v[172:173], off
	s_add_u32 s0, s0, 0x100000
	s_addc_u32 s1, s1, 0
	v_lshl_add_u64 v[188:189], v[50:51], 0, s[0:1]
	global_load_dwordx4 v[192:195], v[188:189], off offset:-2048
	global_load_dwordx4 v[196:199], v[188:189], off offset:-1024
	global_load_dwordx4 v[200:203], v[188:189], off offset:1024
	s_nop 0
	global_load_dwordx4 v[188:191], v[188:189], off
	s_add_u32 s0, s0, 0x100000
	s_addc_u32 s1, s1, 0
	v_lshl_add_u64 v[204:205], v[50:51], 0, s[0:1]
	global_load_dwordx4 v[208:211], v[204:205], off offset:-2048
	global_load_dwordx4 v[212:215], v[204:205], off offset:-1024
	global_load_dwordx4 v[216:219], v[204:205], off offset:1024
	s_nop 0
	global_load_dwordx4 v[204:207], v[204:205], off
	s_add_u32 s0, s0, 0x100000
	s_addc_u32 s1, s1, 0
	v_lshl_add_u64 v[220:221], v[50:51], 0, s[0:1]
	global_load_dwordx4 v[224:227], v[220:221], off offset:-2048
	global_load_dwordx4 v[228:231], v[220:221], off offset:-1024
	global_load_dwordx4 v[232:235], v[220:221], off offset:1024
	s_nop 0
	global_load_dwordx4 v[220:223], v[220:221], off
	s_add_u32 s0, s0, 0x100000
	s_addc_u32 s1, s1, 0
	v_lshl_add_u64 v[236:237], v[50:51], 0, s[0:1]
	global_load_dwordx4 v[240:243], v[236:237], off offset:-2048
	global_load_dwordx4 v[244:247], v[236:237], off offset:-1024
	global_load_dwordx4 v[248:251], v[236:237], off offset:1024
	s_nop 0
	global_load_dwordx4 v[236:239], v[236:237], off
	v_readlane_b32 s0, v253, 23
	v_readlane_b32 s1, v253, 24
	s_or_b32 s5, s2, 56
	v_mov_b32_e32 v93, 0x3727c5ac
	v_lshl_add_u64 v[52:53], s[0:1], 0, v[54:55]
	v_or_b32_e32 v54, 0x400, v54
	v_lshl_add_u64 v[54:55], s[0:1], 0, v[54:55]
	s_lshl_b32 s0, s3, 12
	s_lshl_b32 s1, s38, 6
	s_add_i32 s0, s0, s1
	s_or_b32 s10, s0, 63
	s_mov_b32 s18, 0xf800000
	v_mov_b32_e32 v95, 0x260
	s_waitcnt vmcnt(24)
; __device__ __forceinline__ float wave_sum_dpp(float x) { x = rowsum16(x); return (rl(x, 0) + rl(x, 16)) + (rl(x, 32) + rl(x, 48)); }
;     ...
; #pragma unroll
;         for (int r = 0; r < NR; ++r) { s[r] = 0.f;
; #pragma unroll
;             for (int j = 0; j < 2; ++j) {
;                 v[r][2 * j][0] = __builtin_bit_cast(float, raw[r][j].x << 16); v[r][2 * j][1] = __builtin_bit_cast(float, raw[r][j].x & 0xffff0000u);
;                 v[r][2 * j][2] = __builtin_bit_cast(float, raw[r][j].y << 16); v[r][2 * j][3] = __builtin_bit_cast(float, raw[r][j].y & 0xffff0000u);
;                 v[r][2 * j + 1][0] = __builtin_bit_cast(float, raw[r][j].z << 16); v[r][2 * j + 1][1] = __builtin_bit_cast(float, raw[r][j].z & 0xffff0000u);
;                 v[r][2 * j + 1][2] = __builtin_bit_cast(float, raw[r][j].w << 16); v[r][2 * j + 1][3] = __builtin_bit_cast(float, raw[r][j].w & 0xffff0000u); } }
;         { const int nxt = pi + NP * pstep, pq = nxt < p1 ? nxt : pi;
; #pragma unroll
;           for (int r = 0; r < NR; ++r) { const bf16_t* pn = z + (size_t)rowr(pq, r) * DM;
; #pragma unroll
;               for (int j = 0; j < 2; ++j) raw[r][j] = *(const pg8::u32x4*)(pn + 8 * lane + 512 * j); } }
; #pragma unroll
;         for (int r = 0; r < NR; ++r)
; #pragma unroll
;             for (int j = 0; j < 4; ++j) s[r] += (v[r][j][0] + v[r][j][1]) + (v[r][j][2] + v[r][j][3]);
;         float mean[NR], q[NR], rstd[NR];
; #pragma unroll
;         for (int r = 0; r < NR; ++r) { mean[r] = wave_sum_dpp(s[r]) * (1.f / DM); q[r] = 0.f;
; #pragma unroll
;             for (int j = 0; j < 4; ++j) { v[r][j] = v[r][j] - mean[r]; q[r] += (v[r][j][0] * v[r][j][0] + v[r][j][1] * v[r][j][1]) + (v[r][j][2] * v[r][j][2] + v[r][j][3] * v[r][j][3]); } }
; #pragma unroll
;         for (int r = 0; r < NR; ++r) rstd[r] = 1.0f / sqrtf(wave_sum_dpp(q[r]) * (1.f / DM) + 1e-5f);
	v_lshlrev_b32_e32 v58, 16, v46
	v_and_b32_e32 v59, 0xffff0000, v46
	v_lshlrev_b32_e32 v62, 16, v47
	v_and_b32_e32 v63, 0xffff0000, v47
	v_lshlrev_b32_e32 v47, 16, v39
	v_lshlrev_b32_e32 v46, 16, v38
	v_and_b32_e32 v39, 0xffff0000, v39
	v_and_b32_e32 v38, 0xffff0000, v38
	v_lshlrev_b32_e32 v68, 16, v42
	v_and_b32_e32 v69, 0xffff0000, v42
	v_lshlrev_b32_e32 v64, 16, v44
	v_and_b32_e32 v82, 0xffff0000, v44
	v_lshlrev_b32_e32 v56, 16, v48
	v_and_b32_e32 v44, 0xffff0000, v48
	v_lshlrev_b32_e32 v60, 16, v49
	v_and_b32_e32 v42, 0xffff0000, v49
	v_pk_add_f32 v[48:49], v[46:47], v[38:39]
	v_lshlrev_b32_e32 v70, 16, v43
	v_and_b32_e32 v71, 0xffff0000, v43
	v_add_f32_e32 v43, v48, v49
	v_lshlrev_b32_e32 v49, 16, v41
	v_lshlrev_b32_e32 v48, 16, v40
	v_and_b32_e32 v41, 0xffff0000, v41
	v_and_b32_e32 v40, 0xffff0000, v40
	v_pk_add_f32 v[72:73], v[48:49], v[40:41]
	v_lshlrev_b32_e32 v66, 16, v45
	v_pk_add_f32 v[72:73], v[72:73], v[72:73] op_sel_hi:[0,1]
	v_and_b32_e32 v84, 0xffff0000, v45
	v_add_f32_e32 v85, 0, v43
	v_add_f32_e32 v65, v68, v69
	v_add_f32_e32 v83, v70, v71
	v_mov_b32_e32 v67, v73
	v_pk_add_f32 v[74:75], v[64:65], v[82:83]
	v_pk_add_f32 v[72:73], v[66:67], v[84:85]
	v_lshlrev_b32_e32 v87, 16, v35
	v_pk_add_f32 v[72:73], v[74:75], v[72:73]
	v_lshlrev_b32_e32 v86, 16, v34
	v_and_b32_e32 v35, 0xffff0000, v35
	v_and_b32_e32 v34, 0xffff0000, v34
	v_add_f32_e32 v65, v72, v73
	v_pk_add_f32 v[72:73], v[86:87], v[34:35]
	v_lshlrev_b32_e32 v97, 16, v37
	v_lshlrev_b32_e32 v96, 16, v36
	v_and_b32_e32 v37, 0xffff0000, v37
	v_and_b32_e32 v36, 0xffff0000, v36
	v_add_f32_e32 v57, v58, v59
	v_add_f32_e32 v45, v62, v63
	v_add_f32_e32 v43, v72, v73
	v_pk_add_f32 v[72:73], v[96:97], v[36:37]
	v_pk_add_f32 v[74:75], v[56:57], v[44:45]
	v_add_f32_dpp v45, v65, v65 row_ror:8 row_mask:0xf bank_mask:0xf bound_ctrl:1
	v_pk_add_f32 v[72:73], v[72:73], v[72:73] op_sel_hi:[0,1]
	v_add_f32_e32 v43, 0, v43
	v_add_f32_dpp v45, v45, v45 row_ror:4 row_mask:0xf bank_mask:0xf bound_ctrl:1
	v_mov_b32_e32 v61, v73
	v_pk_add_f32 v[72:73], v[60:61], v[42:43]
	v_add_f32_dpp v45, v45, v45 row_ror:2 row_mask:0xf bank_mask:0xf bound_ctrl:1
	v_pk_add_f32 v[72:73], v[74:75], v[72:73]
	s_lshl_b32 s12, s19, 6
	v_add_f32_dpp v45, v45, v45 row_ror:1 row_mask:0xf bank_mask:0xf bound_ctrl:1
	v_add_f32_e32 v43, v72, v73
	v_readlane_b32 s0, v45, 16
	v_readlane_b32 s2, v45, 48
	v_readlane_b32 s6, v45, 0
	v_readlane_b32 s7, v45, 32
	v_mov_b32_e32 v72, s0
	v_mov_b32_e32 v73, s2
	v_pk_add_f32 v[72:73], s[6:7], v[72:73]
	s_mov_b32 s1, s19
	v_add_f32_e32 v45, v72, v73
	v_fmac_f32_e32 v39, 0xba800000, v45
	v_fmac_f32_e32 v47, 0xba800000, v45
	v_fmac_f32_e32 v38, 0xba800000, v45
	v_fmac_f32_e32 v46, 0xba800000, v45
	v_mov_b32_e32 v74, v47
	v_mov_b32_e32 v78, v47
	v_mov_b32_e32 v79, v39
	v_mov_b32_e32 v47, v38
	v_mov_b32_e32 v73, v38
	v_mov_b32_e32 v75, v39
	v_pk_mul_f32 v[78:79], v[78:79], v[78:79]
	v_pk_mul_f32 v[38:39], v[46:47], v[46:47]
	v_mov_b32_e32 v72, v46
	v_pk_mov_b32 v[46:47], v[38:39], v[78:79] op_sel:[1,0]
	v_mov_b32_e32 v39, v79
	v_fmac_f32_e32 v41, 0xba800000, v45
	v_fmac_f32_e32 v49, 0xba800000, v45
	v_fmac_f32_e32 v40, 0xba800000, v45
	v_pk_add_f32 v[38:39], v[46:47], v[38:39]
	v_fmac_f32_e32 v48, 0xba800000, v45
	v_mov_b32_e32 v80, v49
	v_mov_b32_e32 v46, v49
	v_mov_b32_e32 v47, v41
	v_mov_b32_e32 v49, v40
	v_pk_add_f32 v[38:39], v[38:39], v[38:39] op_sel_hi:[0,1]
	v_mov_b32_e32 v79, v40
	v_mov_b32_e32 v81, v41
	v_pk_mul_f32 v[46:47], v[46:47], v[46:47]
	v_pk_mul_f32 v[40:41], v[48:49], v[48:49]
	v_fmac_f32_e32 v68, 0xba800000, v45
	v_mov_b32_e32 v78, v48
	v_pk_mov_b32 v[48:49], v[40:41], v[46:47] op_sel:[1,0]
	v_mov_b32_e32 v41, v47
	v_fmac_f32_e32 v70, 0xba800000, v45
	v_fmac_f32_e32 v69, 0xba800000, v45
	v_mul_f32_e32 v38, v68, v68
	v_pk_add_f32 v[40:41], v[48:49], v[40:41]
	v_fmac_f32_e32 v71, 0xba800000, v45
	v_pk_fma_f32 v[46:47], v[68:69], v[68:69], v[38:39] op_sel_hi:[1,1,0]
	v_mul_f32_e32 v38, v70, v70
	v_pk_add_f32 v[40:41], v[40:41], v[40:41] op_sel_hi:[0,1]
	v_pk_fma_f32 v[48:49], v[70:71], v[70:71], v[38:39] op_sel_hi:[1,1,0]
	v_fmac_f32_e32 v84, 0xba800000, v45
	v_fmac_f32_e32 v66, 0xba800000, v45
	v_fmac_f32_e32 v82, 0xba800000, v45
	v_fmac_f32_e32 v64, 0xba800000, v45
	v_mul_f32_e32 v46, v64, v64
	v_mul_f32_e32 v48, v82, v82
	v_mul_f32_e32 v38, v66, v66
	v_mul_f32_e32 v40, v84, v84
	v_pk_add_f32 v[46:47], v[46:47], v[48:49]
	v_pk_add_f32 v[38:39], v[38:39], v[40:41]
	v_mov_b32_e32 v67, v84
	v_pk_add_f32 v[38:39], v[46:47], v[38:39]
	s_or_b32 s15, s12, 62
	v_add_f32_e32 v40, v38, v39
	v_add_f32_dpp v38, v43, v43 row_ror:8 row_mask:0xf bank_mask:0xf bound_ctrl:1
	s_add_i32 s19, s19, 8
	s_cmp_ge_i32 s1, s5
	v_add_f32_dpp v38, v38, v38 row_ror:4 row_mask:0xf bank_mask:0xf bound_ctrl:1
	s_cselect_b64 s[12:13], -1, 0
	s_cmp_lt_i32 s1, s5
	v_add_f32_dpp v38, v38, v38 row_ror:2 row_mask:0xf bank_mask:0xf bound_ctrl:1
	s_cselect_b32 s1, s19, s1
	s_lshl_b32 s1, s1, 6
	v_add_f32_dpp v38, v38, v38 row_ror:1 row_mask:0xf bank_mask:0xf bound_ctrl:1
	s_or_b32 s20, s1, 62
	v_readlane_b32 s0, v38, 16
	v_readlane_b32 s2, v38, 48
	v_readlane_b32 s6, v38, 0
	v_readlane_b32 s7, v38, 32
	v_mov_b32_e32 v38, s0
	v_mov_b32_e32 v39, s2
	v_pk_add_f32 v[38:39], s[6:7], v[38:39]
	s_ashr_i32 s21, s20, 31
	v_add_f32_e32 v38, v38, v39
; __device__ __forceinline__ float wave_sum_dpp(float x) { x = rowsum16(x); return (rl(x, 0) + rl(x, 16)) + (rl(x, 32) + rl(x, 48)); }
;     ...
;             for (int j = 0; j < 4; ++j) s[r] += (v[r][j][0] + v[r][j][1]) + (v[r][j][2] + v[r][j][3]);
;         float mean[NR], q[NR], rstd[NR];
; #pragma unroll
;         for (int r = 0; r < NR; ++r) { mean[r] = wave_sum_dpp(s[r]) * (1.f / DM); q[r] = 0.f;
; #pragma unroll
;             for (int j = 0; j < 4; ++j) { v[r][j] = v[r][j] - mean[r]; q[r] += (v[r][j][0] * v[r][j][0] + v[r][j][1] * v[r][j][1]) + (v[r][j][2] * v[r][j][2] + v[r][j][3] * v[r][j][3]); } }
; #pragma unroll
;         for (int r = 0; r < NR; ++r) rstd[r] = 1.0f / sqrtf(wave_sum_dpp(q[r]) * (1.f / DM) + 1e-5f);
;         if (MODE == 1) {
; #pragma unroll
;             for (int r = 0; r < NR; ++r) if (lane == r) { stats[2 * row[r]] = mean[r]; stats[2 * row[r] + 1] = rstd[r]; } }
	v_fmac_f32_e32 v35, 0xba800000, v38
	v_fmac_f32_e32 v34, 0xba800000, v38
	v_fmac_f32_e32 v87, 0xba800000, v38
	v_fmac_f32_e32 v86, 0xba800000, v38
	v_mov_b32_e32 v83, v34
	v_mov_b32_e32 v85, v35
	v_mul_f32_e32 v34, v34, v34
	v_mul_f32_e32 v35, v35, v35
	v_fmac_f32_e32 v34, v86, v86
	v_fmac_f32_e32 v35, v87, v87
	v_fmac_f32_e32 v37, 0xba800000, v38
	v_fmac_f32_e32 v36, 0xba800000, v38
	v_mov_b32_e32 v84, v87
	v_add_f32_e32 v34, v34, v35
	v_fmac_f32_e32 v97, 0xba800000, v38
	v_fmac_f32_e32 v96, 0xba800000, v38
	v_mov_b32_e32 v87, v36
	v_mul_f32_e32 v35, v36, v36
	v_mul_f32_e32 v36, v37, v37
	v_fmac_f32_e32 v35, v96, v96
	v_fmac_f32_e32 v36, v97, v97
	v_add_f32_e32 v35, v35, v36
	v_fmac_f32_e32 v63, 0xba800000, v38
	v_fmac_f32_e32 v59, 0xba800000, v38
	v_add_f32_e32 v34, v34, v35
	v_fmac_f32_e32 v62, 0xba800000, v38
	v_fmac_f32_e32 v58, 0xba800000, v38
	v_mul_f32_e32 v35, v59, v59
	v_mul_f32_e32 v36, v63, v63
	v_fmac_f32_e32 v35, v58, v58
	v_fmac_f32_e32 v36, v62, v62
	v_add_f32_e32 v35, v35, v36
	v_fmac_f32_e32 v42, 0xba800000, v38
	v_fmac_f32_e32 v44, 0xba800000, v38
	v_add_f32_e32 v34, v35, v34
	v_fmac_f32_e32 v60, 0xba800000, v38
	v_fmac_f32_e32 v56, 0xba800000, v38
	v_mul_f32_e32 v35, v44, v44
	v_mul_f32_e32 v36, v42, v42
	v_fmac_f32_e32 v35, v56, v56
	v_fmac_f32_e32 v36, v60, v60
	v_add_f32_e32 v35, v35, v36
	v_add_f32_e32 v34, v35, v34
	s_lshl_b64 s[20:21], s[20:21], 11
	v_add_f32_dpp v35, v40, v40 row_ror:8 row_mask:0xf bank_mask:0xf bound_ctrl:1
	v_add_f32_dpp v34, v34, v34 row_ror:8 row_mask:0xf bank_mask:0xf bound_ctrl:1
	v_mul_f32_e32 v76, 0x3a800000, v45
	v_add_f32_dpp v35, v35, v35 row_ror:4 row_mask:0xf bank_mask:0xf bound_ctrl:1
	v_add_f32_dpp v34, v34, v34 row_ror:4 row_mask:0xf bank_mask:0xf bound_ctrl:1
	v_mul_f32_e32 v90, 0x3a800000, v38
	v_add_f32_dpp v35, v35, v35 row_ror:2 row_mask:0xf bank_mask:0xf bound_ctrl:1
	v_add_f32_dpp v34, v34, v34 row_ror:2 row_mask:0xf bank_mask:0xf bound_ctrl:1
	v_mov_b32_e32 v89, v37
	v_add_f32_dpp v35, v35, v35 row_ror:1 row_mask:0xf bank_mask:0xf bound_ctrl:1
	v_add_f32_dpp v34, v34, v34 row_ror:1 row_mask:0xf bank_mask:0xf bound_ctrl:1
	v_readlane_b32 s6, v35, 0
	v_readlane_b32 s11, v35, 16
	v_readlane_b32 s7, v35, 32
	v_readlane_b32 s14, v35, 48
	v_readlane_b32 s0, v34, 0
	v_readlane_b32 s8, v34, 16
	v_readlane_b32 s2, v34, 32
	v_readlane_b32 s9, v34, 48
	v_lshl_add_u64 v[34:35], v[50:51], 0, s[20:21]
	s_or_b32 s20, s1, 63
	s_ashr_i32 s21, s20, 31
	s_lshl_b64 s[20:21], s[20:21], 11
	v_lshl_add_u64 v[46:47], v[50:51], 0, s[20:21]
	v_mov_b32_e32 v57, v44
	v_mov_b32_e32 v61, v42
	v_mov_b32_e32 v65, v82
	v_mov_b32_e32 v82, v86
	v_mov_b32_e32 v86, v96
	v_mov_b32_e32 v88, v97
	v_mov_b32_e32 v96, s11
	v_mov_b32_e32 v97, s14
	v_pk_add_f32 v[96:97], s[6:7], v[96:97]
	v_mov_b32_e32 v98, s9
	v_add_f32_e32 v77, v96, v97
	v_fmamk_f32 v77, v77, 0x3a800000, v93
	v_mul_f32_e32 v91, 0x4f800000, v77
	v_cmp_gt_f32_e32 vcc, s18, v77
	v_mov_b32_e32 v97, s8
	v_add_f32_e32 v97, s0, v97
	v_cndmask_b32_e32 v77, v77, v91, vcc
	v_sqrt_f32_e32 v91, v77
	v_add_f32_e32 v98, s2, v98
	v_add_f32_e32 v97, v97, v98
	v_fmamk_f32 v97, v97, 0x3a800000, v93
	v_add_u32_e32 v92, -1, v91
	v_fma_f32 v94, -v92, v91, v77
	v_cmp_ge_f32_e64 s[6:7], 0, v94
	v_add_u32_e32 v94, 1, v91
	v_mul_f32_e32 v98, 0x4f800000, v97
	v_cndmask_b32_e64 v92, v91, v92, s[6:7]
	v_fma_f32 v91, -v94, v91, v77
	v_cmp_lt_f32_e64 s[6:7], 0, v91
	s_nop 1
	v_cndmask_b32_e64 v91, v92, v94, s[6:7]
	v_mul_f32_e32 v92, 0x37800000, v91
	v_cndmask_b32_e32 v91, v91, v92, vcc
	v_cmp_class_f32_e32 vcc, v77, v95
	s_nop 1
	v_cndmask_b32_e32 v77, v91, v77, vcc
	v_div_scale_f32 v91, s[6:7], v77, v77, 1.0
	v_rcp_f32_e32 v92, v91
	v_cmp_gt_f32_e64 s[6:7], s18, v97
	v_fma_f32 v94, -v91, v92, 1.0
	s_nop 0
	v_cndmask_b32_e64 v97, v97, v98, s[6:7]
	v_fmac_f32_e32 v92, v94, v92
	v_div_scale_f32 v94, vcc, 1.0, v77, 1.0
	v_sqrt_f32_e32 v98, v97
	v_mul_f32_e32 v96, v94, v92
	v_fma_f32 v99, -v91, v96, v94
	v_fmac_f32_e32 v96, v99, v92
	v_fma_f32 v91, -v91, v96, v94
	v_add_u32_e32 v94, -1, v98
	v_fma_f32 v99, -v94, v98, v97
	v_cmp_ge_f32_e64 s[8:9], 0, v99
	v_add_u32_e32 v99, 1, v98
	v_div_fmas_f32 v91, v91, v92, v96
	v_cndmask_b32_e64 v94, v98, v94, s[8:9]
	v_fma_f32 v98, -v99, v98, v97
	v_cmp_lt_f32_e64 s[8:9], 0, v98
	s_nop 1
	v_cndmask_b32_e64 v94, v94, v99, s[8:9]
	v_mul_f32_e32 v98, 0x37800000, v94
	v_cndmask_b32_e64 v94, v94, v98, s[6:7]
	v_cmp_class_f32_e64 s[6:7], v97, v95
	s_mov_b64 s[8:9], -1
	s_nop 0
	v_cndmask_b32_e64 v97, v94, v97, s[6:7]
	v_div_scale_f32 v98, s[0:1], v97, v97, 1.0
	v_rcp_f32_e32 v99, v98
	v_div_fixup_f32 v94, v91, v77, 1.0
	v_fma_f32 v77, -v98, v99, 1.0
	v_fmac_f32_e32 v99, v77, v99
	v_div_scale_f32 v77, vcc, 1.0, v97, 1.0
	v_mul_f32_e32 v91, v77, v99
	v_fma_f32 v92, -v98, v91, v77
	v_fmac_f32_e32 v91, v92, v99
	v_fma_f32 v77, -v98, v91, v77
	v_div_fmas_f32 v77, v77, v99, v91
	v_div_fixup_f32 v92, v77, v97, 1.0
	v_mov_b32_e32 v77, v94
	v_cmp_lt_i32_e32 vcc, 0, v145
	v_mov_b32_e32 v91, s15
	s_and_saveexec_b64 s[6:7], vcc
	s_cbranch_execz .Lhln7_m0
	v_cmp_eq_u32_e32 vcc, 1, v145
	s_mov_b64 s[8:9], 0
	s_and_saveexec_b64 s[14:15], vcc
	v_mov_b32_e32 v91, v92
	s_mov_b64 s[8:9], exec
	v_mov_b64_e32 v[76:77], v[90:91]
	s_or_b64 exec, exec, s[14:15]
	v_mov_b32_e32 v91, s10
	s_orn2_b64 s[8:9], s[8:9], exec

; __device__ __forceinline__ unsigned cvtpk(float lo, float hi) { f32x2_t v = {lo, hi}; bf16x2_t b = __builtin_convertvector(v, bf16x2_t); return __builtin_bit_cast(unsigned, b); }
;     ...
; #pragma unroll
;         for (int r = 0; r < NR; ++r) { s[r] = 0.f;
; #pragma unroll
;             for (int j = 0; j < 2; ++j) {
;                 v[r][2 * j][0] = __builtin_bit_cast(float, raw[r][j].x << 16); v[r][2 * j][1] = __builtin_bit_cast(float, raw[r][j].x & 0xffff0000u);
;                 v[r][2 * j][2] = __builtin_bit_cast(float, raw[r][j].y << 16); v[r][2 * j][3] = __builtin_bit_cast(float, raw[r][j].y & 0xffff0000u);
;                 v[r][2 * j + 1][0] = __builtin_bit_cast(float, raw[r][j].z << 16); v[r][2 * j + 1][1] = __builtin_bit_cast(float, raw[r][j].z & 0xffff0000u);
;                 v[r][2 * j + 1][2] = __builtin_bit_cast(float, raw[r][j].w << 16); v[r][2 * j + 1][3] = __builtin_bit_cast(float, raw[r][j].w & 0xffff0000u); } }
;     ...
; #pragma unroll
;         for (int j = 0; j < 2; ++j) {
;             const int c = 8 * lane + 512 * j;
;             const f32x4 g0 = *(const f32x4*)(g + c), g1 = *(const f32x4*)(g + c + 4), b0 = *(const f32x4*)(b + c), b1 = *(const f32x4*)(b + c + 4);
; #pragma unroll
;             for (int r = 0; r < NR; ++r) {
;                 const f32x4 o0 = v[r][2 * j] * rstd[r] * g0 + b0, o1 = v[r][2 * j + 1] * rstd[r] * g1 + b1;
;                 if (MODE == 1) { pg8::u32x4 w; w.x = cvtpk(o0[0], o0[1]); w.y = cvtpk(o0[2], o0[3]); w.z = cvtpk(o1[0], o1[1]); w.w = cvtpk(o1[2], o1[3]); *(pg8::u32x4*)(hb + (size_t)row[r] * DM + c) = w; }
;                 else { *(f32x4*)(outf + (size_t)row[r] * DM + c) = o0; *(f32x4*)(outf + (size_t)row[r] * DM + c + 4) = o1; }
;             }
;         }
.Lhln7_t0:
	s_or_b64 exec, exec, s[6:7]
	s_add_i32 s0, s10, -1
	v_pk_mul_f32 v[74:75], v[74:75], v[94:95] op_sel_hi:[1,0]
	v_pk_mul_f32 v[72:73], v[72:73], v[94:95] op_sel_hi:[1,0]
	v_pk_mul_f32 v[76:77], v[80:81], v[94:95] op_sel_hi:[1,0]
	v_pk_mul_f32 v[78:79], v[78:79], v[94:95] op_sel_hi:[1,0]
	s_ashr_i32 s1, s0, 31
	v_pk_fma_f32 v[74:75], v[12:13], v[74:75], v[16:17]
	v_pk_fma_f32 v[72:73], v[10:11], v[72:73], v[14:15]
	v_pk_fma_f32 v[76:77], v[4:5], v[76:77], v[8:9]
	v_pk_fma_f32 v[78:79], v[2:3], v[78:79], v[6:7]
	s_lshl_b64 s[0:1], s[0:1], 11
	v_cvt_pk_bf16_f32 v72, v72, v73
	v_cvt_pk_bf16_f32 v73, v74, v75
	v_cvt_pk_bf16_f32 v74, v78, v79
	v_cvt_pk_bf16_f32 v75, v76, v77
	v_lshl_add_u64 v[76:77], v[52:53], 0, s[0:1]
	global_store_dwordx4 v[76:77], v[72:75], off
	v_pk_mul_f32 v[78:79], v[86:87], v[92:93] op_sel_hi:[1,0]
	s_ashr_i32 s11, s10, 31
	v_pk_mul_f32 v[72:73], v[84:85], v[92:93] op_sel_hi:[1,0]
	v_pk_mul_f32 v[74:75], v[82:83], v[92:93] op_sel_hi:[1,0]
	v_pk_fma_f32 v[76:77], v[12:13], v[72:73], v[16:17]
	v_pk_fma_f32 v[72:73], v[10:11], v[74:75], v[14:15]
	v_pk_mul_f32 v[74:75], v[88:89], v[92:93] op_sel_hi:[1,0]
	s_lshl_b64 s[6:7], s[10:11], 11
	v_pk_fma_f32 v[80:81], v[4:5], v[74:75], v[8:9]
	v_pk_fma_f32 v[74:75], v[2:3], v[78:79], v[6:7]
	v_cvt_pk_bf16_f32 v72, v72, v73
	v_cvt_pk_bf16_f32 v73, v76, v77
	v_cvt_pk_bf16_f32 v74, v74, v75
	v_cvt_pk_bf16_f32 v75, v80, v81
	v_lshl_add_u64 v[76:77], v[52:53], 0, s[6:7]
	v_pk_mul_f32 v[70:71], v[70:71], v[94:95] op_sel_hi:[1,0]
	v_pk_mul_f32 v[68:69], v[68:69], v[94:95] op_sel_hi:[1,0]
	v_pk_mul_f32 v[66:67], v[66:67], v[94:95] op_sel_hi:[1,0]
	v_pk_mul_f32 v[64:65], v[64:65], v[94:95] op_sel_hi:[1,0]
	global_store_dwordx4 v[76:77], v[72:75], off
	v_pk_fma_f32 v[70:71], v[28:29], v[70:71], v[32:33]
	v_pk_fma_f32 v[68:69], v[26:27], v[68:69], v[30:31]
	v_pk_fma_f32 v[72:73], v[20:21], v[66:67], v[24:25]
	v_pk_fma_f32 v[66:67], v[18:19], v[64:65], v[22:23]
	v_cvt_pk_bf16_f32 v64, v68, v69
	v_cvt_pk_bf16_f32 v65, v70, v71
	v_cvt_pk_bf16_f32 v66, v66, v67
	v_cvt_pk_bf16_f32 v67, v72, v73
	v_lshl_add_u64 v[68:69], v[54:55], 0, s[0:1]
	v_pk_mul_f32 v[62:63], v[62:63], v[92:93] op_sel_hi:[1,0]
	v_pk_mul_f32 v[58:59], v[58:59], v[92:93] op_sel_hi:[1,0]
	v_pk_mul_f32 v[60:61], v[60:61], v[92:93] op_sel_hi:[1,0]
	v_pk_mul_f32 v[56:57], v[56:57], v[92:93] op_sel_hi:[1,0]
	global_store_dwordx4 v[68:69], v[64:67], off
	v_pk_fma_f32 v[62:63], v[28:29], v[62:63], v[32:33]
	v_pk_fma_f32 v[58:59], v[26:27], v[58:59], v[30:31]
	v_pk_fma_f32 v[60:61], v[20:21], v[60:61], v[24:25]
	v_pk_fma_f32 v[64:65], v[18:19], v[56:57], v[22:23]
	v_cvt_pk_bf16_f32 v56, v58, v59
	v_cvt_pk_bf16_f32 v57, v62, v63
	v_cvt_pk_bf16_f32 v58, v64, v65
	v_cvt_pk_bf16_f32 v59, v60, v61
	v_lshl_add_u64 v[60:61], v[54:55], 0, s[6:7]
	s_andn2_b64 vcc, exec, s[12:13]
	s_addk_i32 s10, 0x200
	global_store_dwordx4 v[60:61], v[56:59], off
	s_cbranch_vccz .LBB0_680
	s_waitcnt vmcnt(20)
	v_lshlrev_b32_e32 v58, 16, v168
	v_and_b32_e32 v59, 0xffff0000, v168
	v_lshlrev_b32_e32 v62, 16, v169
	v_and_b32_e32 v63, 0xffff0000, v169
	v_lshlrev_b32_e32 v47, 16, v161
	v_lshlrev_b32_e32 v46, 16, v160
	v_and_b32_e32 v39, 0xffff0000, v161
	v_and_b32_e32 v38, 0xffff0000, v160
	v_lshlrev_b32_e32 v68, 16, v164
	v_and_b32_e32 v69, 0xffff0000, v164
	v_lshlrev_b32_e32 v64, 16, v166
	v_and_b32_e32 v82, 0xffff0000, v166
	v_lshlrev_b32_e32 v56, 16, v170
	v_and_b32_e32 v44, 0xffff0000, v170
	v_lshlrev_b32_e32 v60, 16, v171
	v_and_b32_e32 v42, 0xffff0000, v171
	v_pk_add_f32 v[48:49], v[46:47], v[38:39]
	v_lshlrev_b32_e32 v70, 16, v165
	v_and_b32_e32 v71, 0xffff0000, v165
	v_add_f32_e32 v43, v48, v49
	v_lshlrev_b32_e32 v49, 16, v163
	v_lshlrev_b32_e32 v48, 16, v162
	v_and_b32_e32 v41, 0xffff0000, v163
	v_and_b32_e32 v40, 0xffff0000, v162
	v_pk_add_f32 v[72:73], v[48:49], v[40:41]
	v_lshlrev_b32_e32 v66, 16, v167
	v_pk_add_f32 v[72:73], v[72:73], v[72:73] op_sel_hi:[0,1]
	v_and_b32_e32 v84, 0xffff0000, v167
	v_add_f32_e32 v85, 0, v43
	v_add_f32_e32 v65, v68, v69
	v_add_f32_e32 v83, v70, v71
	v_mov_b32_e32 v67, v73
	v_pk_add_f32 v[74:75], v[64:65], v[82:83]
	v_pk_add_f32 v[72:73], v[66:67], v[84:85]
	v_lshlrev_b32_e32 v87, 16, v157
	v_pk_add_f32 v[72:73], v[74:75], v[72:73]
	v_lshlrev_b32_e32 v86, 16, v156
	v_and_b32_e32 v35, 0xffff0000, v157
	v_and_b32_e32 v34, 0xffff0000, v156
	v_add_f32_e32 v65, v72, v73
	v_pk_add_f32 v[72:73], v[86:87], v[34:35]
	v_lshlrev_b32_e32 v97, 16, v159
	v_lshlrev_b32_e32 v96, 16, v158
	v_and_b32_e32 v37, 0xffff0000, v159
	v_and_b32_e32 v36, 0xffff0000, v158
	v_add_f32_e32 v57, v58, v59
	v_add_f32_e32 v45, v62, v63
	v_add_f32_e32 v43, v72, v73
	v_pk_add_f32 v[72:73], v[96:97], v[36:37]
	v_pk_add_f32 v[74:75], v[56:57], v[44:45]
	v_add_f32_dpp v45, v65, v65 row_ror:8 row_mask:0xf bank_mask:0xf bound_ctrl:1
	v_pk_add_f32 v[72:73], v[72:73], v[72:73] op_sel_hi:[0,1]
	v_add_f32_e32 v43, 0, v43
	v_add_f32_dpp v45, v45, v45 row_ror:4 row_mask:0xf bank_mask:0xf bound_ctrl:1
	v_mov_b32_e32 v61, v73
	v_pk_add_f32 v[72:73], v[60:61], v[42:43]
	v_add_f32_dpp v45, v45, v45 row_ror:2 row_mask:0xf bank_mask:0xf bound_ctrl:1
	v_pk_add_f32 v[72:73], v[74:75], v[72:73]
	s_lshl_b32 s12, s19, 6
	v_add_f32_dpp v45, v45, v45 row_ror:1 row_mask:0xf bank_mask:0xf bound_ctrl:1
	v_add_f32_e32 v43, v72, v73
	v_readlane_b32 s0, v45, 16
	v_readlane_b32 s2, v45, 48
	v_readlane_b32 s6, v45, 0
	v_readlane_b32 s7, v45, 32
	v_mov_b32_e32 v72, s0
	v_mov_b32_e32 v73, s2
	v_pk_add_f32 v[72:73], s[6:7], v[72:73]
	s_mov_b32 s1, s19
	v_add_f32_e32 v45, v72, v73
	v_fmac_f32_e32 v39, 0xba800000, v45
	v_fmac_f32_e32 v47, 0xba800000, v45
	v_fmac_f32_e32 v38, 0xba800000, v45
; __device__ __forceinline__ float wave_sum_dpp(float x) { x = rowsum16(x); return (rl(x, 0) + rl(x, 16)) + (rl(x, 32) + rl(x, 48)); }
;     ...
;             for (int j = 0; j < 4; ++j) s[r] += (v[r][j][0] + v[r][j][1]) + (v[r][j][2] + v[r][j][3]);
;         float mean[NR], q[NR], rstd[NR];
; #pragma unroll
;         for (int r = 0; r < NR; ++r) { mean[r] = wave_sum_dpp(s[r]) * (1.f / DM); q[r] = 0.f;
; #pragma unroll
;             for (int j = 0; j < 4; ++j) { v[r][j] = v[r][j] - mean[r]; q[r] += (v[r][j][0] * v[r][j][0] + v[r][j][1] * v[r][j][1]) + (v[r][j][2] * v[r][j][2] + v[r][j][3] * v[r][j][3]); } }
; #pragma unroll
;         for (int r = 0; r < NR; ++r) rstd[r] = 1.0f / sqrtf(wave_sum_dpp(q[r]) * (1.f / DM) + 1e-5f);
	v_fmac_f32_e32 v46, 0xba800000, v45
	v_mov_b32_e32 v74, v47
	v_mov_b32_e32 v78, v47
	v_mov_b32_e32 v79, v39
	v_mov_b32_e32 v47, v38
	v_mov_b32_e32 v73, v38
	v_mov_b32_e32 v75, v39
	v_pk_mul_f32 v[78:79], v[78:79], v[78:79]
	v_pk_mul_f32 v[38:39], v[46:47], v[46:47]
	v_mov_b32_e32 v72, v46
	v_pk_mov_b32 v[46:47], v[38:39], v[78:79] op_sel:[1,0]
	v_mov_b32_e32 v39, v79
	v_fmac_f32_e32 v41, 0xba800000, v45
	v_fmac_f32_e32 v49, 0xba800000, v45
	v_fmac_f32_e32 v40, 0xba800000, v45
	v_pk_add_f32 v[38:39], v[46:47], v[38:39]
	v_fmac_f32_e32 v48, 0xba800000, v45
	v_mov_b32_e32 v80, v49
	v_mov_b32_e32 v46, v49
	v_mov_b32_e32 v47, v41
	v_mov_b32_e32 v49, v40
	v_pk_add_f32 v[38:39], v[38:39], v[38:39] op_sel_hi:[0,1]
	v_mov_b32_e32 v79, v40
	v_mov_b32_e32 v81, v41
	v_pk_mul_f32 v[46:47], v[46:47], v[46:47]
	v_pk_mul_f32 v[40:41], v[48:49], v[48:49]
	v_fmac_f32_e32 v68, 0xba800000, v45
	v_mov_b32_e32 v78, v48
	v_pk_mov_b32 v[48:49], v[40:41], v[46:47] op_sel:[1,0]
	v_mov_b32_e32 v41, v47
	v_fmac_f32_e32 v70, 0xba800000, v45
	v_fmac_f32_e32 v69, 0xba800000, v45
	v_mul_f32_e32 v38, v68, v68
	v_pk_add_f32 v[40:41], v[48:49], v[40:41]
	v_fmac_f32_e32 v71, 0xba800000, v45
	v_pk_fma_f32 v[46:47], v[68:69], v[68:69], v[38:39] op_sel_hi:[1,1,0]
	v_mul_f32_e32 v38, v70, v70
	v_pk_add_f32 v[40:41], v[40:41], v[40:41] op_sel_hi:[0,1]
	v_pk_fma_f32 v[48:49], v[70:71], v[70:71], v[38:39] op_sel_hi:[1,1,0]
	v_fmac_f32_e32 v84, 0xba800000, v45
	v_fmac_f32_e32 v66, 0xba800000, v45
	v_fmac_f32_e32 v82, 0xba800000, v45
	v_fmac_f32_e32 v64, 0xba800000, v45
	v_mul_f32_e32 v46, v64, v64
	v_mul_f32_e32 v48, v82, v82
	v_mul_f32_e32 v38, v66, v66
	v_mul_f32_e32 v40, v84, v84
	v_pk_add_f32 v[46:47], v[46:47], v[48:49]
	v_pk_add_f32 v[38:39], v[38:39], v[40:41]
	v_mov_b32_e32 v67, v84
	v_pk_add_f32 v[38:39], v[46:47], v[38:39]
	s_or_b32 s15, s12, 62
	v_add_f32_e32 v40, v38, v39
	v_add_f32_dpp v38, v43, v43 row_ror:8 row_mask:0xf bank_mask:0xf bound_ctrl:1
	s_add_i32 s19, s19, 8
	s_cmp_ge_i32 s1, s5
	v_add_f32_dpp v38, v38, v38 row_ror:4 row_mask:0xf bank_mask:0xf bound_ctrl:1
	s_cselect_b64 s[12:13], -1, 0
	s_cmp_lt_i32 s1, s5
	v_add_f32_dpp v38, v38, v38 row_ror:2 row_mask:0xf bank_mask:0xf bound_ctrl:1
	s_cselect_b32 s1, s19, s1
	s_lshl_b32 s1, s1, 6
	v_add_f32_dpp v38, v38, v38 row_ror:1 row_mask:0xf bank_mask:0xf bound_ctrl:1
	s_or_b32 s20, s1, 62
	v_readlane_b32 s0, v38, 16
	v_readlane_b32 s2, v38, 48
	v_readlane_b32 s6, v38, 0
	v_readlane_b32 s7, v38, 32
	v_mov_b32_e32 v38, s0
	v_mov_b32_e32 v39, s2
	v_pk_add_f32 v[38:39], s[6:7], v[38:39]
	s_ashr_i32 s21, s20, 31
	v_add_f32_e32 v38, v38, v39
	v_fmac_f32_e32 v35, 0xba800000, v38
	v_fmac_f32_e32 v34, 0xba800000, v38
	v_fmac_f32_e32 v87, 0xba800000, v38
	v_fmac_f32_e32 v86, 0xba800000, v38
	v_mov_b32_e32 v83, v34
	v_mov_b32_e32 v85, v35
	v_mul_f32_e32 v34, v34, v34
	v_mul_f32_e32 v35, v35, v35
	v_fmac_f32_e32 v34, v86, v86
	v_fmac_f32_e32 v35, v87, v87
	v_fmac_f32_e32 v37, 0xba800000, v38
	v_fmac_f32_e32 v36, 0xba800000, v38
	v_mov_b32_e32 v84, v87
	v_add_f32_e32 v34, v34, v35
	v_fmac_f32_e32 v97, 0xba800000, v38
	v_fmac_f32_e32 v96, 0xba800000, v38
	v_mov_b32_e32 v87, v36
	v_mul_f32_e32 v35, v36, v36
	v_mul_f32_e32 v36, v37, v37
	v_fmac_f32_e32 v35, v96, v96
	v_fmac_f32_e32 v36, v97, v97
	v_add_f32_e32 v35, v35, v36
	v_fmac_f32_e32 v63, 0xba800000, v38
	v_fmac_f32_e32 v59, 0xba800000, v38
	v_add_f32_e32 v34, v34, v35
	v_fmac_f32_e32 v62, 0xba800000, v38
	v_fmac_f32_e32 v58, 0xba800000, v38
	v_mul_f32_e32 v35, v59, v59
	v_mul_f32_e32 v36, v63, v63
	v_fmac_f32_e32 v35, v58, v58
	v_fmac_f32_e32 v36, v62, v62
	v_add_f32_e32 v35, v35, v36
	v_fmac_f32_e32 v42, 0xba800000, v38
	v_fmac_f32_e32 v44, 0xba800000, v38
	v_add_f32_e32 v34, v35, v34
	v_fmac_f32_e32 v60, 0xba800000, v38
	v_fmac_f32_e32 v56, 0xba800000, v38
	v_mul_f32_e32 v35, v44, v44
	v_mul_f32_e32 v36, v42, v42
	v_fmac_f32_e32 v35, v56, v56
	v_fmac_f32_e32 v36, v60, v60
	v_add_f32_e32 v35, v35, v36
	v_add_f32_e32 v34, v35, v34
	s_lshl_b64 s[20:21], s[20:21], 11
	v_add_f32_dpp v35, v40, v40 row_ror:8 row_mask:0xf bank_mask:0xf bound_ctrl:1
; __device__ __forceinline__ float wave_sum_dpp(float x) { x = rowsum16(x); return (rl(x, 0) + rl(x, 16)) + (rl(x, 32) + rl(x, 48)); }
;     ...
;         { const int nxt = pi + NP * pstep, pq = nxt < p1 ? nxt : pi;
; #pragma unroll
;           for (int r = 0; r < NR; ++r) { const bf16_t* pn = z + (size_t)rowr(pq, r) * DM;
; #pragma unroll
;               for (int j = 0; j < 2; ++j) raw[r][j] = *(const pg8::u32x4*)(pn + 8 * lane + 512 * j); } }
; #pragma unroll
;         for (int r = 0; r < NR; ++r)
; #pragma unroll
;             for (int j = 0; j < 4; ++j) s[r] += (v[r][j][0] + v[r][j][1]) + (v[r][j][2] + v[r][j][3]);
;         float mean[NR], q[NR], rstd[NR];
; #pragma unroll
;         for (int r = 0; r < NR; ++r) { mean[r] = wave_sum_dpp(s[r]) * (1.f / DM); q[r] = 0.f;
; #pragma unroll
;             for (int j = 0; j < 4; ++j) { v[r][j] = v[r][j] - mean[r]; q[r] += (v[r][j][0] * v[r][j][0] + v[r][j][1] * v[r][j][1]) + (v[r][j][2] * v[r][j][2] + v[r][j][3] * v[r][j][3]); } }
; #pragma unroll
;         for (int r = 0; r < NR; ++r) rstd[r] = 1.0f / sqrtf(wave_sum_dpp(q[r]) * (1.f / DM) + 1e-5f);
;         if (MODE == 1) {
; #pragma unroll
;             for (int r = 0; r < NR; ++r) if (lane == r) { stats[2 * row[r]] = mean[r]; stats[2 * row[r] + 1] = rstd[r]; } }
	v_add_f32_dpp v34, v34, v34 row_ror:8 row_mask:0xf bank_mask:0xf bound_ctrl:1
	v_mul_f32_e32 v76, 0x3a800000, v45
	v_add_f32_dpp v35, v35, v35 row_ror:4 row_mask:0xf bank_mask:0xf bound_ctrl:1
	v_add_f32_dpp v34, v34, v34 row_ror:4 row_mask:0xf bank_mask:0xf bound_ctrl:1
	v_mul_f32_e32 v90, 0x3a800000, v38
	v_add_f32_dpp v35, v35, v35 row_ror:2 row_mask:0xf bank_mask:0xf bound_ctrl:1
	v_add_f32_dpp v34, v34, v34 row_ror:2 row_mask:0xf bank_mask:0xf bound_ctrl:1
	v_mov_b32_e32 v89, v37
	v_add_f32_dpp v35, v35, v35 row_ror:1 row_mask:0xf bank_mask:0xf bound_ctrl:1
	v_add_f32_dpp v34, v34, v34 row_ror:1 row_mask:0xf bank_mask:0xf bound_ctrl:1
	v_readlane_b32 s6, v35, 0
	v_readlane_b32 s11, v35, 16
	v_readlane_b32 s7, v35, 32
	v_readlane_b32 s14, v35, 48
	v_readlane_b32 s0, v34, 0
	v_readlane_b32 s8, v34, 16
	v_readlane_b32 s2, v34, 32
	v_readlane_b32 s9, v34, 48
	s_add_u32 s20, s20, 0x500000
	s_addc_u32 s21, s21, 0
	v_lshl_add_u64 v[34:35], v[50:51], 0, s[20:21]
	s_or_b32 s20, s1, 63
	s_ashr_i32 s21, s20, 31
	s_lshl_b64 s[20:21], s[20:21], 11
	s_add_u32 s20, s20, 0x500000
	s_addc_u32 s21, s21, 0
	v_lshl_add_u64 v[46:47], v[50:51], 0, s[20:21]
	v_mov_b32_e32 v57, v44
	v_mov_b32_e32 v61, v42
	global_load_dwordx4 v[160:163], v[34:35], off
	s_nop 0
	global_load_dwordx4 v[164:167], v[34:35], off offset:1024
	s_nop 0
	global_load_dwordx4 v[156:159], v[46:47], off
	s_nop 0
	global_load_dwordx4 v[168:171], v[46:47], off offset:1024
	s_nop 0
	v_mov_b32_e32 v65, v82
	v_mov_b32_e32 v82, v86
	v_mov_b32_e32 v86, v96
	v_mov_b32_e32 v88, v97
	v_mov_b32_e32 v96, s11
	v_mov_b32_e32 v97, s14
	v_pk_add_f32 v[96:97], s[6:7], v[96:97]
	v_mov_b32_e32 v98, s9
	v_add_f32_e32 v77, v96, v97
	v_fmamk_f32 v77, v77, 0x3a800000, v93
	v_mul_f32_e32 v91, 0x4f800000, v77
	v_cmp_gt_f32_e32 vcc, s18, v77
	v_mov_b32_e32 v97, s8
	v_add_f32_e32 v97, s0, v97
	v_cndmask_b32_e32 v77, v77, v91, vcc
	v_sqrt_f32_e32 v91, v77
	v_add_f32_e32 v98, s2, v98
	v_add_f32_e32 v97, v97, v98
	v_fmamk_f32 v97, v97, 0x3a800000, v93
	v_add_u32_e32 v92, -1, v91
	v_fma_f32 v94, -v92, v91, v77
	v_cmp_ge_f32_e64 s[6:7], 0, v94
	v_add_u32_e32 v94, 1, v91
	v_mul_f32_e32 v98, 0x4f800000, v97
	v_cndmask_b32_e64 v92, v91, v92, s[6:7]
	v_fma_f32 v91, -v94, v91, v77
	v_cmp_lt_f32_e64 s[6:7], 0, v91
	s_nop 1
	v_cndmask_b32_e64 v91, v92, v94, s[6:7]
	v_mul_f32_e32 v92, 0x37800000, v91
	v_cndmask_b32_e32 v91, v91, v92, vcc
	v_cmp_class_f32_e32 vcc, v77, v95
	s_nop 1
	v_cndmask_b32_e32 v77, v91, v77, vcc
	v_div_scale_f32 v91, s[6:7], v77, v77, 1.0
	v_rcp_f32_e32 v92, v91
	v_cmp_gt_f32_e64 s[6:7], s18, v97
	v_fma_f32 v94, -v91, v92, 1.0
	s_nop 0
	v_cndmask_b32_e64 v97, v97, v98, s[6:7]
	v_fmac_f32_e32 v92, v94, v92
	v_div_scale_f32 v94, vcc, 1.0, v77, 1.0
	v_sqrt_f32_e32 v98, v97
	v_mul_f32_e32 v96, v94, v92
	v_fma_f32 v99, -v91, v96, v94
	v_fmac_f32_e32 v96, v99, v92
	v_fma_f32 v91, -v91, v96, v94
	v_add_u32_e32 v94, -1, v98
	v_fma_f32 v99, -v94, v98, v97
	v_cmp_ge_f32_e64 s[8:9], 0, v99
	v_add_u32_e32 v99, 1, v98
	v_div_fmas_f32 v91, v91, v92, v96
	v_cndmask_b32_e64 v94, v98, v94, s[8:9]
	v_fma_f32 v98, -v99, v98, v97
	v_cmp_lt_f32_e64 s[8:9], 0, v98
	s_nop 1
	v_cndmask_b32_e64 v94, v94, v99, s[8:9]
	v_mul_f32_e32 v98, 0x37800000, v94
	v_cndmask_b32_e64 v94, v94, v98, s[6:7]
	v_cmp_class_f32_e64 s[6:7], v97, v95
	s_mov_b64 s[8:9], -1
	s_nop 0
	v_cndmask_b32_e64 v97, v94, v97, s[6:7]
	v_div_scale_f32 v98, s[0:1], v97, v97, 1.0
	v_rcp_f32_e32 v99, v98
	v_div_fixup_f32 v94, v91, v77, 1.0
	v_fma_f32 v77, -v98, v99, 1.0
	v_fmac_f32_e32 v99, v77, v99
	v_div_scale_f32 v77, vcc, 1.0, v97, 1.0
	v_mul_f32_e32 v91, v77, v99
	v_fma_f32 v92, -v98, v91, v77
	v_fmac_f32_e32 v91, v92, v99
	v_fma_f32 v77, -v98, v91, v77
	v_div_fmas_f32 v77, v77, v99, v91
	v_div_fixup_f32 v92, v77, v97, 1.0
	v_mov_b32_e32 v77, v94
	v_cmp_lt_i32_e32 vcc, 0, v145
	v_mov_b32_e32 v91, s15
	s_and_saveexec_b64 s[6:7], vcc
	s_cbranch_execz .Lhln7_m1
	v_cmp_eq_u32_e32 vcc, 1, v145
	s_mov_b64 s[8:9], 0
	s_and_saveexec_b64 s[14:15], vcc
	v_mov_b32_e32 v91, v92
	s_mov_b64 s[8:9], exec
	v_mov_b64_e32 v[76:77], v[90:91]
	s_or_b64 exec, exec, s[14:15]
	v_mov_b32_e32 v91, s10
	s_orn2_b64 s[8:9], s[8:9], exec

; __device__ __forceinline__ unsigned cvtpk(float lo, float hi) { f32x2_t v = {lo, hi}; bf16x2_t b = __builtin_convertvector(v, bf16x2_t); return __builtin_bit_cast(unsigned, b); }
;     ...
; #pragma unroll
;         for (int r = 0; r < NR; ++r) { s[r] = 0.f;
; #pragma unroll
;             for (int j = 0; j < 2; ++j) {
;                 v[r][2 * j][0] = __builtin_bit_cast(float, raw[r][j].x << 16); v[r][2 * j][1] = __builtin_bit_cast(float, raw[r][j].x & 0xffff0000u);
;                 v[r][2 * j][2] = __builtin_bit_cast(float, raw[r][j].y << 16); v[r][2 * j][3] = __builtin_bit_cast(float, raw[r][j].y & 0xffff0000u);
;                 v[r][2 * j + 1][0] = __builtin_bit_cast(float, raw[r][j].z << 16); v[r][2 * j + 1][1] = __builtin_bit_cast(float, raw[r][j].z & 0xffff0000u);
;                 v[r][2 * j + 1][2] = __builtin_bit_cast(float, raw[r][j].w << 16); v[r][2 * j + 1][3] = __builtin_bit_cast(float, raw[r][j].w & 0xffff0000u); } }
;     ...
; #pragma unroll
;         for (int j = 0; j < 2; ++j) {
;             const int c = 8 * lane + 512 * j;
;             const f32x4 g0 = *(const f32x4*)(g + c), g1 = *(const f32x4*)(g + c + 4), b0 = *(const f32x4*)(b + c), b1 = *(const f32x4*)(b + c + 4);
; #pragma unroll
;             for (int r = 0; r < NR; ++r) {
;                 const f32x4 o0 = v[r][2 * j] * rstd[r] * g0 + b0, o1 = v[r][2 * j + 1] * rstd[r] * g1 + b1;
;                 if (MODE == 1) { pg8::u32x4 w; w.x = cvtpk(o0[0], o0[1]); w.y = cvtpk(o0[2], o0[3]); w.z = cvtpk(o1[0], o1[1]); w.w = cvtpk(o1[2], o1[3]); *(pg8::u32x4*)(hb + (size_t)row[r] * DM + c) = w; }
;                 else { *(f32x4*)(outf + (size_t)row[r] * DM + c) = o0; *(f32x4*)(outf + (size_t)row[r] * DM + c + 4) = o1; }
;             }
;         }
.Lhln7_t1:
	s_or_b64 exec, exec, s[6:7]
	s_add_i32 s0, s10, -1
	v_pk_mul_f32 v[74:75], v[74:75], v[94:95] op_sel_hi:[1,0]
	v_pk_mul_f32 v[72:73], v[72:73], v[94:95] op_sel_hi:[1,0]
	v_pk_mul_f32 v[76:77], v[80:81], v[94:95] op_sel_hi:[1,0]
	v_pk_mul_f32 v[78:79], v[78:79], v[94:95] op_sel_hi:[1,0]
	s_ashr_i32 s1, s0, 31
	v_pk_fma_f32 v[74:75], v[12:13], v[74:75], v[16:17]
	v_pk_fma_f32 v[72:73], v[10:11], v[72:73], v[14:15]
	v_pk_fma_f32 v[76:77], v[4:5], v[76:77], v[8:9]
	v_pk_fma_f32 v[78:79], v[2:3], v[78:79], v[6:7]
	s_lshl_b64 s[0:1], s[0:1], 11
	v_cvt_pk_bf16_f32 v72, v72, v73
	v_cvt_pk_bf16_f32 v73, v74, v75
	v_cvt_pk_bf16_f32 v74, v78, v79
	v_cvt_pk_bf16_f32 v75, v76, v77
	v_lshl_add_u64 v[76:77], v[52:53], 0, s[0:1]
	global_store_dwordx4 v[76:77], v[72:75], off
	v_pk_mul_f32 v[78:79], v[86:87], v[92:93] op_sel_hi:[1,0]
	s_ashr_i32 s11, s10, 31
	v_pk_mul_f32 v[72:73], v[84:85], v[92:93] op_sel_hi:[1,0]
	v_pk_mul_f32 v[74:75], v[82:83], v[92:93] op_sel_hi:[1,0]
	v_pk_fma_f32 v[76:77], v[12:13], v[72:73], v[16:17]
	v_pk_fma_f32 v[72:73], v[10:11], v[74:75], v[14:15]
	v_pk_mul_f32 v[74:75], v[88:89], v[92:93] op_sel_hi:[1,0]
	s_lshl_b64 s[6:7], s[10:11], 11
	v_pk_fma_f32 v[80:81], v[4:5], v[74:75], v[8:9]
	v_pk_fma_f32 v[74:75], v[2:3], v[78:79], v[6:7]
	v_cvt_pk_bf16_f32 v72, v72, v73
	v_cvt_pk_bf16_f32 v73, v76, v77
	v_cvt_pk_bf16_f32 v74, v74, v75
	v_cvt_pk_bf16_f32 v75, v80, v81
	v_lshl_add_u64 v[76:77], v[52:53], 0, s[6:7]
	v_pk_mul_f32 v[70:71], v[70:71], v[94:95] op_sel_hi:[1,0]
	v_pk_mul_f32 v[68:69], v[68:69], v[94:95] op_sel_hi:[1,0]
	v_pk_mul_f32 v[66:67], v[66:67], v[94:95] op_sel_hi:[1,0]
	v_pk_mul_f32 v[64:65], v[64:65], v[94:95] op_sel_hi:[1,0]
	global_store_dwordx4 v[76:77], v[72:75], off
	v_pk_fma_f32 v[70:71], v[28:29], v[70:71], v[32:33]
	v_pk_fma_f32 v[68:69], v[26:27], v[68:69], v[30:31]
	v_pk_fma_f32 v[72:73], v[20:21], v[66:67], v[24:25]
	v_pk_fma_f32 v[66:67], v[18:19], v[64:65], v[22:23]
	v_cvt_pk_bf16_f32 v64, v68, v69
	v_cvt_pk_bf16_f32 v65, v70, v71
	v_cvt_pk_bf16_f32 v66, v66, v67
	v_cvt_pk_bf16_f32 v67, v72, v73
	v_lshl_add_u64 v[68:69], v[54:55], 0, s[0:1]
	v_pk_mul_f32 v[62:63], v[62:63], v[92:93] op_sel_hi:[1,0]
	v_pk_mul_f32 v[58:59], v[58:59], v[92:93] op_sel_hi:[1,0]
	v_pk_mul_f32 v[60:61], v[60:61], v[92:93] op_sel_hi:[1,0]
	v_pk_mul_f32 v[56:57], v[56:57], v[92:93] op_sel_hi:[1,0]
	global_store_dwordx4 v[68:69], v[64:67], off
	v_pk_fma_f32 v[62:63], v[28:29], v[62:63], v[32:33]
	v_pk_fma_f32 v[58:59], v[26:27], v[58:59], v[30:31]
	v_pk_fma_f32 v[60:61], v[20:21], v[60:61], v[24:25]
	v_pk_fma_f32 v[64:65], v[18:19], v[56:57], v[22:23]
	v_cvt_pk_bf16_f32 v56, v58, v59
	v_cvt_pk_bf16_f32 v57, v62, v63
	v_cvt_pk_bf16_f32 v58, v64, v65
	v_cvt_pk_bf16_f32 v59, v60, v61
	v_lshl_add_u64 v[60:61], v[54:55], 0, s[6:7]
	s_andn2_b64 vcc, exec, s[12:13]
	s_addk_i32 s10, 0x200
	global_store_dwordx4 v[60:61], v[56:59], off
	s_cbranch_vccz .LBB0_680
	s_waitcnt vmcnt(20)
	v_lshlrev_b32_e32 v58, 16, v184
	v_and_b32_e32 v59, 0xffff0000, v184
	v_lshlrev_b32_e32 v62, 16, v185
	v_and_b32_e32 v63, 0xffff0000, v185
	v_lshlrev_b32_e32 v47, 16, v177
	v_lshlrev_b32_e32 v46, 16, v176
	v_and_b32_e32 v39, 0xffff0000, v177
	v_and_b32_e32 v38, 0xffff0000, v176
	v_lshlrev_b32_e32 v68, 16, v180
	v_and_b32_e32 v69, 0xffff0000, v180
	v_lshlrev_b32_e32 v64, 16, v182
	v_and_b32_e32 v82, 0xffff0000, v182
	v_lshlrev_b32_e32 v56, 16, v186
	v_and_b32_e32 v44, 0xffff0000, v186
	v_lshlrev_b32_e32 v60, 16, v187
	v_and_b32_e32 v42, 0xffff0000, v187
	v_pk_add_f32 v[48:49], v[46:47], v[38:39]
	v_lshlrev_b32_e32 v70, 16, v181
	v_and_b32_e32 v71, 0xffff0000, v181
	v_add_f32_e32 v43, v48, v49
	v_lshlrev_b32_e32 v49, 16, v179
	v_lshlrev_b32_e32 v48, 16, v178
	v_and_b32_e32 v41, 0xffff0000, v179
	v_and_b32_e32 v40, 0xffff0000, v178
	v_pk_add_f32 v[72:73], v[48:49], v[40:41]
	v_lshlrev_b32_e32 v66, 16, v183
	v_pk_add_f32 v[72:73], v[72:73], v[72:73] op_sel_hi:[0,1]
	v_and_b32_e32 v84, 0xffff0000, v183
	v_add_f32_e32 v85, 0, v43
	v_add_f32_e32 v65, v68, v69
	v_add_f32_e32 v83, v70, v71
	v_mov_b32_e32 v67, v73
	v_pk_add_f32 v[74:75], v[64:65], v[82:83]
	v_pk_add_f32 v[72:73], v[66:67], v[84:85]
	v_lshlrev_b32_e32 v87, 16, v173
	v_pk_add_f32 v[72:73], v[74:75], v[72:73]
	v_lshlrev_b32_e32 v86, 16, v172
	v_and_b32_e32 v35, 0xffff0000, v173
	v_and_b32_e32 v34, 0xffff0000, v172
	v_add_f32_e32 v65, v72, v73
	v_pk_add_f32 v[72:73], v[86:87], v[34:35]
	v_lshlrev_b32_e32 v97, 16, v175
	v_lshlrev_b32_e32 v96, 16, v174
	v_and_b32_e32 v37, 0xffff0000, v175
	v_and_b32_e32 v36, 0xffff0000, v174
	v_add_f32_e32 v57, v58, v59
	v_add_f32_e32 v45, v62, v63
	v_add_f32_e32 v43, v72, v73
	v_pk_add_f32 v[72:73], v[96:97], v[36:37]
	v_pk_add_f32 v[74:75], v[56:57], v[44:45]
	v_add_f32_dpp v45, v65, v65 row_ror:8 row_mask:0xf bank_mask:0xf bound_ctrl:1
	v_pk_add_f32 v[72:73], v[72:73], v[72:73] op_sel_hi:[0,1]
	v_add_f32_e32 v43, 0, v43
	v_add_f32_dpp v45, v45, v45 row_ror:4 row_mask:0xf bank_mask:0xf bound_ctrl:1
	v_mov_b32_e32 v61, v73
	v_pk_add_f32 v[72:73], v[60:61], v[42:43]
	v_add_f32_dpp v45, v45, v45 row_ror:2 row_mask:0xf bank_mask:0xf bound_ctrl:1
	v_pk_add_f32 v[72:73], v[74:75], v[72:73]
	s_lshl_b32 s12, s19, 6
	v_add_f32_dpp v45, v45, v45 row_ror:1 row_mask:0xf bank_mask:0xf bound_ctrl:1
	v_add_f32_e32 v43, v72, v73
	v_readlane_b32 s0, v45, 16
	v_readlane_b32 s2, v45, 48
	v_readlane_b32 s6, v45, 0
	v_readlane_b32 s7, v45, 32
	v_mov_b32_e32 v72, s0
	v_mov_b32_e32 v73, s2
	v_pk_add_f32 v[72:73], s[6:7], v[72:73]
	s_mov_b32 s1, s19
	v_add_f32_e32 v45, v72, v73
	v_fmac_f32_e32 v39, 0xba800000, v45
	v_fmac_f32_e32 v47, 0xba800000, v45
	v_fmac_f32_e32 v38, 0xba800000, v45
; __device__ __forceinline__ float wave_sum_dpp(float x) { x = rowsum16(x); return (rl(x, 0) + rl(x, 16)) + (rl(x, 32) + rl(x, 48)); }
;     ...
;             for (int j = 0; j < 4; ++j) s[r] += (v[r][j][0] + v[r][j][1]) + (v[r][j][2] + v[r][j][3]);
;         float mean[NR], q[NR], rstd[NR];
; #pragma unroll
;         for (int r = 0; r < NR; ++r) { mean[r] = wave_sum_dpp(s[r]) * (1.f / DM); q[r] = 0.f;
; #pragma unroll
;             for (int j = 0; j < 4; ++j) { v[r][j] = v[r][j] - mean[r]; q[r] += (v[r][j][0] * v[r][j][0] + v[r][j][1] * v[r][j][1]) + (v[r][j][2] * v[r][j][2] + v[r][j][3] * v[r][j][3]); } }
; #pragma unroll
;         for (int r = 0; r < NR; ++r) rstd[r] = 1.0f / sqrtf(wave_sum_dpp(q[r]) * (1.f / DM) + 1e-5f);
	v_fmac_f32_e32 v46, 0xba800000, v45
	v_mov_b32_e32 v74, v47
	v_mov_b32_e32 v78, v47
	v_mov_b32_e32 v79, v39
	v_mov_b32_e32 v47, v38
	v_mov_b32_e32 v73, v38
	v_mov_b32_e32 v75, v39
	v_pk_mul_f32 v[78:79], v[78:79], v[78:79]
	v_pk_mul_f32 v[38:39], v[46:47], v[46:47]
	v_mov_b32_e32 v72, v46
	v_pk_mov_b32 v[46:47], v[38:39], v[78:79] op_sel:[1,0]
	v_mov_b32_e32 v39, v79
	v_fmac_f32_e32 v41, 0xba800000, v45
	v_fmac_f32_e32 v49, 0xba800000, v45
	v_fmac_f32_e32 v40, 0xba800000, v45
	v_pk_add_f32 v[38:39], v[46:47], v[38:39]
	v_fmac_f32_e32 v48, 0xba800000, v45
	v_mov_b32_e32 v80, v49
	v_mov_b32_e32 v46, v49
	v_mov_b32_e32 v47, v41
	v_mov_b32_e32 v49, v40
	v_pk_add_f32 v[38:39], v[38:39], v[38:39] op_sel_hi:[0,1]
	v_mov_b32_e32 v79, v40
	v_mov_b32_e32 v81, v41
	v_pk_mul_f32 v[46:47], v[46:47], v[46:47]
	v_pk_mul_f32 v[40:41], v[48:49], v[48:49]
	v_fmac_f32_e32 v68, 0xba800000, v45
	v_mov_b32_e32 v78, v48
	v_pk_mov_b32 v[48:49], v[40:41], v[46:47] op_sel:[1,0]
	v_mov_b32_e32 v41, v47
	v_fmac_f32_e32 v70, 0xba800000, v45
	v_fmac_f32_e32 v69, 0xba800000, v45
	v_mul_f32_e32 v38, v68, v68
	v_pk_add_f32 v[40:41], v[48:49], v[40:41]
	v_fmac_f32_e32 v71, 0xba800000, v45
	v_pk_fma_f32 v[46:47], v[68:69], v[68:69], v[38:39] op_sel_hi:[1,1,0]
	v_mul_f32_e32 v38, v70, v70
	v_pk_add_f32 v[40:41], v[40:41], v[40:41] op_sel_hi:[0,1]
	v_pk_fma_f32 v[48:49], v[70:71], v[70:71], v[38:39] op_sel_hi:[1,1,0]
	v_fmac_f32_e32 v84, 0xba800000, v45
	v_fmac_f32_e32 v66, 0xba800000, v45
	v_fmac_f32_e32 v82, 0xba800000, v45
	v_fmac_f32_e32 v64, 0xba800000, v45
	v_mul_f32_e32 v46, v64, v64
	v_mul_f32_e32 v48, v82, v82
	v_mul_f32_e32 v38, v66, v66
	v_mul_f32_e32 v40, v84, v84
	v_pk_add_f32 v[46:47], v[46:47], v[48:49]
	v_pk_add_f32 v[38:39], v[38:39], v[40:41]
	v_mov_b32_e32 v67, v84
	v_pk_add_f32 v[38:39], v[46:47], v[38:39]
	s_or_b32 s15, s12, 62
	v_add_f32_e32 v40, v38, v39
	v_add_f32_dpp v38, v43, v43 row_ror:8 row_mask:0xf bank_mask:0xf bound_ctrl:1
	s_add_i32 s19, s19, 8
	s_cmp_ge_i32 s1, s5
	v_add_f32_dpp v38, v38, v38 row_ror:4 row_mask:0xf bank_mask:0xf bound_ctrl:1
	s_cselect_b64 s[12:13], -1, 0
	s_cmp_lt_i32 s1, s5
	v_add_f32_dpp v38, v38, v38 row_ror:2 row_mask:0xf bank_mask:0xf bound_ctrl:1
	s_cselect_b32 s1, s19, s1
	s_lshl_b32 s1, s1, 6
	v_add_f32_dpp v38, v38, v38 row_ror:1 row_mask:0xf bank_mask:0xf bound_ctrl:1
	s_or_b32 s20, s1, 62
	v_readlane_b32 s0, v38, 16
	v_readlane_b32 s2, v38, 48
	v_readlane_b32 s6, v38, 0
	v_readlane_b32 s7, v38, 32
	v_mov_b32_e32 v38, s0
	v_mov_b32_e32 v39, s2
	v_pk_add_f32 v[38:39], s[6:7], v[38:39]
	s_ashr_i32 s21, s20, 31
	v_add_f32_e32 v38, v38, v39
	v_fmac_f32_e32 v35, 0xba800000, v38
	v_fmac_f32_e32 v34, 0xba800000, v38
	v_fmac_f32_e32 v87, 0xba800000, v38
	v_fmac_f32_e32 v86, 0xba800000, v38
	v_mov_b32_e32 v83, v34
	v_mov_b32_e32 v85, v35
	v_mul_f32_e32 v34, v34, v34
	v_mul_f32_e32 v35, v35, v35
	v_fmac_f32_e32 v34, v86, v86
	v_fmac_f32_e32 v35, v87, v87
	v_fmac_f32_e32 v37, 0xba800000, v38
	v_fmac_f32_e32 v36, 0xba800000, v38
	v_mov_b32_e32 v84, v87
	v_add_f32_e32 v34, v34, v35
	v_fmac_f32_e32 v97, 0xba800000, v38
	v_fmac_f32_e32 v96, 0xba800000, v38
	v_mov_b32_e32 v87, v36
	v_mul_f32_e32 v35, v36, v36
	v_mul_f32_e32 v36, v37, v37
	v_fmac_f32_e32 v35, v96, v96
	v_fmac_f32_e32 v36, v97, v97
	v_add_f32_e32 v35, v35, v36
	v_fmac_f32_e32 v63, 0xba800000, v38
	v_fmac_f32_e32 v59, 0xba800000, v38
	v_add_f32_e32 v34, v34, v35
	v_fmac_f32_e32 v62, 0xba800000, v38
	v_fmac_f32_e32 v58, 0xba800000, v38
	v_mul_f32_e32 v35, v59, v59
	v_mul_f32_e32 v36, v63, v63
	v_fmac_f32_e32 v35, v58, v58
	v_fmac_f32_e32 v36, v62, v62
	v_add_f32_e32 v35, v35, v36
	v_fmac_f32_e32 v42, 0xba800000, v38
	v_fmac_f32_e32 v44, 0xba800000, v38
	v_add_f32_e32 v34, v35, v34
	v_fmac_f32_e32 v60, 0xba800000, v38
	v_fmac_f32_e32 v56, 0xba800000, v38
	v_mul_f32_e32 v35, v44, v44
	v_mul_f32_e32 v36, v42, v42
	v_fmac_f32_e32 v35, v56, v56
	v_fmac_f32_e32 v36, v60, v60
	v_add_f32_e32 v35, v35, v36
; __device__ __forceinline__ float wave_sum_dpp(float x) { x = rowsum16(x); return (rl(x, 0) + rl(x, 16)) + (rl(x, 32) + rl(x, 48)); }
;     ...
;             for (int j = 0; j < 4; ++j) s[r] += (v[r][j][0] + v[r][j][1]) + (v[r][j][2] + v[r][j][3]);
;         float mean[NR], q[NR], rstd[NR];
; #pragma unroll
;         for (int r = 0; r < NR; ++r) { mean[r] = wave_sum_dpp(s[r]) * (1.f / DM); q[r] = 0.f;
; #pragma unroll
;             for (int j = 0; j < 4; ++j) { v[r][j] = v[r][j] - mean[r]; q[r] += (v[r][j][0] * v[r][j][0] + v[r][j][1] * v[r][j][1]) + (v[r][j][2] * v[r][j][2] + v[r][j][3] * v[r][j][3]); } }
; #pragma unroll
;         for (int r = 0; r < NR; ++r) rstd[r] = 1.0f / sqrtf(wave_sum_dpp(q[r]) * (1.f / DM) + 1e-5f);
;         if (MODE == 1) {
; #pragma unroll
;             for (int r = 0; r < NR; ++r) if (lane == r) { stats[2 * row[r]] = mean[r]; stats[2 * row[r] + 1] = rstd[r]; } }
	v_add_f32_e32 v34, v35, v34
	s_lshl_b64 s[20:21], s[20:21], 11
	v_add_f32_dpp v35, v40, v40 row_ror:8 row_mask:0xf bank_mask:0xf bound_ctrl:1
	v_add_f32_dpp v34, v34, v34 row_ror:8 row_mask:0xf bank_mask:0xf bound_ctrl:1
	v_mul_f32_e32 v76, 0x3a800000, v45
	v_add_f32_dpp v35, v35, v35 row_ror:4 row_mask:0xf bank_mask:0xf bound_ctrl:1
	v_add_f32_dpp v34, v34, v34 row_ror:4 row_mask:0xf bank_mask:0xf bound_ctrl:1
	v_mul_f32_e32 v90, 0x3a800000, v38
	v_add_f32_dpp v35, v35, v35 row_ror:2 row_mask:0xf bank_mask:0xf bound_ctrl:1
	v_add_f32_dpp v34, v34, v34 row_ror:2 row_mask:0xf bank_mask:0xf bound_ctrl:1
	v_mov_b32_e32 v89, v37
	v_add_f32_dpp v35, v35, v35 row_ror:1 row_mask:0xf bank_mask:0xf bound_ctrl:1
	v_add_f32_dpp v34, v34, v34 row_ror:1 row_mask:0xf bank_mask:0xf bound_ctrl:1
	v_readlane_b32 s6, v35, 0
	v_readlane_b32 s11, v35, 16
	v_readlane_b32 s7, v35, 32
	v_readlane_b32 s14, v35, 48
	v_readlane_b32 s0, v34, 0
	v_readlane_b32 s8, v34, 16
	v_readlane_b32 s2, v34, 32
	v_readlane_b32 s9, v34, 48
	v_lshl_add_u64 v[34:35], v[50:51], 0, s[20:21]
	s_or_b32 s20, s1, 63
	s_ashr_i32 s21, s20, 31
	s_lshl_b64 s[20:21], s[20:21], 11
	v_lshl_add_u64 v[46:47], v[50:51], 0, s[20:21]
	v_mov_b32_e32 v57, v44
	v_mov_b32_e32 v61, v42
	v_mov_b32_e32 v65, v82
	v_mov_b32_e32 v82, v86
	v_mov_b32_e32 v86, v96
	v_mov_b32_e32 v88, v97
	v_mov_b32_e32 v96, s11
	v_mov_b32_e32 v97, s14
	v_pk_add_f32 v[96:97], s[6:7], v[96:97]
	v_mov_b32_e32 v98, s9
	v_add_f32_e32 v77, v96, v97
	v_fmamk_f32 v77, v77, 0x3a800000, v93
	v_mul_f32_e32 v91, 0x4f800000, v77
	v_cmp_gt_f32_e32 vcc, s18, v77
	v_mov_b32_e32 v97, s8
	v_add_f32_e32 v97, s0, v97
	v_cndmask_b32_e32 v77, v77, v91, vcc
	v_sqrt_f32_e32 v91, v77
	v_add_f32_e32 v98, s2, v98
	v_add_f32_e32 v97, v97, v98
	v_fmamk_f32 v97, v97, 0x3a800000, v93
	v_add_u32_e32 v92, -1, v91
	v_fma_f32 v94, -v92, v91, v77
	v_cmp_ge_f32_e64 s[6:7], 0, v94
	v_add_u32_e32 v94, 1, v91
	v_mul_f32_e32 v98, 0x4f800000, v97
	v_cndmask_b32_e64 v92, v91, v92, s[6:7]
	v_fma_f32 v91, -v94, v91, v77
	v_cmp_lt_f32_e64 s[6:7], 0, v91
	s_nop 1
	v_cndmask_b32_e64 v91, v92, v94, s[6:7]
	v_mul_f32_e32 v92, 0x37800000, v91
	v_cndmask_b32_e32 v91, v91, v92, vcc
	v_cmp_class_f32_e32 vcc, v77, v95
	s_nop 1
	v_cndmask_b32_e32 v77, v91, v77, vcc
	v_div_scale_f32 v91, s[6:7], v77, v77, 1.0
	v_rcp_f32_e32 v92, v91
	v_cmp_gt_f32_e64 s[6:7], s18, v97
	v_fma_f32 v94, -v91, v92, 1.0
	s_nop 0
	v_cndmask_b32_e64 v97, v97, v98, s[6:7]
	v_fmac_f32_e32 v92, v94, v92
	v_div_scale_f32 v94, vcc, 1.0, v77, 1.0
	v_sqrt_f32_e32 v98, v97
	v_mul_f32_e32 v96, v94, v92
	v_fma_f32 v99, -v91, v96, v94
	v_fmac_f32_e32 v96, v99, v92
	v_fma_f32 v91, -v91, v96, v94
	v_add_u32_e32 v94, -1, v98
	v_fma_f32 v99, -v94, v98, v97
	v_cmp_ge_f32_e64 s[8:9], 0, v99
	v_add_u32_e32 v99, 1, v98
	v_div_fmas_f32 v91, v91, v92, v96
	v_cndmask_b32_e64 v94, v98, v94, s[8:9]
	v_fma_f32 v98, -v99, v98, v97
	v_cmp_lt_f32_e64 s[8:9], 0, v98
	s_nop 1
	v_cndmask_b32_e64 v94, v94, v99, s[8:9]
	v_mul_f32_e32 v98, 0x37800000, v94
	v_cndmask_b32_e64 v94, v94, v98, s[6:7]
	v_cmp_class_f32_e64 s[6:7], v97, v95
	s_mov_b64 s[8:9], -1
	s_nop 0
	v_cndmask_b32_e64 v97, v94, v97, s[6:7]
	v_div_scale_f32 v98, s[0:1], v97, v97, 1.0
	v_rcp_f32_e32 v99, v98
	v_div_fixup_f32 v94, v91, v77, 1.0
	v_fma_f32 v77, -v98, v99, 1.0
	v_fmac_f32_e32 v99, v77, v99
	v_div_scale_f32 v77, vcc, 1.0, v97, 1.0
	v_mul_f32_e32 v91, v77, v99
	v_fma_f32 v92, -v98, v91, v77
	v_fmac_f32_e32 v91, v92, v99
	v_fma_f32 v77, -v98, v91, v77
	v_div_fmas_f32 v77, v77, v99, v91
	v_div_fixup_f32 v92, v77, v97, 1.0
	v_mov_b32_e32 v77, v94
	v_cmp_lt_i32_e32 vcc, 0, v145
	v_mov_b32_e32 v91, s15
	s_and_saveexec_b64 s[6:7], vcc
	s_cbranch_execz .Lhln7_m2
	v_cmp_eq_u32_e32 vcc, 1, v145
	s_mov_b64 s[8:9], 0
	s_and_saveexec_b64 s[14:15], vcc
	v_mov_b32_e32 v91, v92
	s_mov_b64 s[8:9], exec
	v_mov_b64_e32 v[76:77], v[90:91]
	s_or_b64 exec, exec, s[14:15]
	v_mov_b32_e32 v91, s10
	s_orn2_b64 s[8:9], s[8:9], exec

; __device__ __forceinline__ unsigned cvtpk(float lo, float hi) { f32x2_t v = {lo, hi}; bf16x2_t b = __builtin_convertvector(v, bf16x2_t); return __builtin_bit_cast(unsigned, b); }
;     ...
; #pragma unroll
;         for (int r = 0; r < NR; ++r) { s[r] = 0.f;
; #pragma unroll
;             for (int j = 0; j < 2; ++j) {
;                 v[r][2 * j][0] = __builtin_bit_cast(float, raw[r][j].x << 16); v[r][2 * j][1] = __builtin_bit_cast(float, raw[r][j].x & 0xffff0000u);
;                 v[r][2 * j][2] = __builtin_bit_cast(float, raw[r][j].y << 16); v[r][2 * j][3] = __builtin_bit_cast(float, raw[r][j].y & 0xffff0000u);
;                 v[r][2 * j + 1][0] = __builtin_bit_cast(float, raw[r][j].z << 16); v[r][2 * j + 1][1] = __builtin_bit_cast(float, raw[r][j].z & 0xffff0000u);
;                 v[r][2 * j + 1][2] = __builtin_bit_cast(float, raw[r][j].w << 16); v[r][2 * j + 1][3] = __builtin_bit_cast(float, raw[r][j].w & 0xffff0000u); } }
;     ...
; #pragma unroll
;         for (int j = 0; j < 2; ++j) {
;             const int c = 8 * lane + 512 * j;
;             const f32x4 g0 = *(const f32x4*)(g + c), g1 = *(const f32x4*)(g + c + 4), b0 = *(const f32x4*)(b + c), b1 = *(const f32x4*)(b + c + 4);
; #pragma unroll
;             for (int r = 0; r < NR; ++r) {
;                 const f32x4 o0 = v[r][2 * j] * rstd[r] * g0 + b0, o1 = v[r][2 * j + 1] * rstd[r] * g1 + b1;
;                 if (MODE == 1) { pg8::u32x4 w; w.x = cvtpk(o0[0], o0[1]); w.y = cvtpk(o0[2], o0[3]); w.z = cvtpk(o1[0], o1[1]); w.w = cvtpk(o1[2], o1[3]); *(pg8::u32x4*)(hb + (size_t)row[r] * DM + c) = w; }
;                 else { *(f32x4*)(outf + (size_t)row[r] * DM + c) = o0; *(f32x4*)(outf + (size_t)row[r] * DM + c + 4) = o1; }
;             }
;         }
.Lhln7_t2:
	s_or_b64 exec, exec, s[6:7]
	s_add_i32 s0, s10, -1
	v_pk_mul_f32 v[74:75], v[74:75], v[94:95] op_sel_hi:[1,0]
	v_pk_mul_f32 v[72:73], v[72:73], v[94:95] op_sel_hi:[1,0]
	v_pk_mul_f32 v[76:77], v[80:81], v[94:95] op_sel_hi:[1,0]
	v_pk_mul_f32 v[78:79], v[78:79], v[94:95] op_sel_hi:[1,0]
	s_ashr_i32 s1, s0, 31
	v_pk_fma_f32 v[74:75], v[12:13], v[74:75], v[16:17]
	v_pk_fma_f32 v[72:73], v[10:11], v[72:73], v[14:15]
	v_pk_fma_f32 v[76:77], v[4:5], v[76:77], v[8:9]
	v_pk_fma_f32 v[78:79], v[2:3], v[78:79], v[6:7]
	s_lshl_b64 s[0:1], s[0:1], 11
	v_cvt_pk_bf16_f32 v72, v72, v73
	v_cvt_pk_bf16_f32 v73, v74, v75
	v_cvt_pk_bf16_f32 v74, v78, v79
	v_cvt_pk_bf16_f32 v75, v76, v77
	v_lshl_add_u64 v[76:77], v[52:53], 0, s[0:1]
	global_store_dwordx4 v[76:77], v[72:75], off
	v_pk_mul_f32 v[78:79], v[86:87], v[92:93] op_sel_hi:[1,0]
	s_ashr_i32 s11, s10, 31
	v_pk_mul_f32 v[72:73], v[84:85], v[92:93] op_sel_hi:[1,0]
	v_pk_mul_f32 v[74:75], v[82:83], v[92:93] op_sel_hi:[1,0]
	v_pk_fma_f32 v[76:77], v[12:13], v[72:73], v[16:17]
	v_pk_fma_f32 v[72:73], v[10:11], v[74:75], v[14:15]
	v_pk_mul_f32 v[74:75], v[88:89], v[92:93] op_sel_hi:[1,0]
	s_lshl_b64 s[6:7], s[10:11], 11
	v_pk_fma_f32 v[80:81], v[4:5], v[74:75], v[8:9]
	v_pk_fma_f32 v[74:75], v[2:3], v[78:79], v[6:7]
	v_cvt_pk_bf16_f32 v72, v72, v73
	v_cvt_pk_bf16_f32 v73, v76, v77
	v_cvt_pk_bf16_f32 v74, v74, v75
	v_cvt_pk_bf16_f32 v75, v80, v81
	v_lshl_add_u64 v[76:77], v[52:53], 0, s[6:7]
	v_pk_mul_f32 v[70:71], v[70:71], v[94:95] op_sel_hi:[1,0]
	v_pk_mul_f32 v[68:69], v[68:69], v[94:95] op_sel_hi:[1,0]
	v_pk_mul_f32 v[66:67], v[66:67], v[94:95] op_sel_hi:[1,0]
	v_pk_mul_f32 v[64:65], v[64:65], v[94:95] op_sel_hi:[1,0]
	global_store_dwordx4 v[76:77], v[72:75], off
	v_pk_fma_f32 v[70:71], v[28:29], v[70:71], v[32:33]
	v_pk_fma_f32 v[68:69], v[26:27], v[68:69], v[30:31]
	v_pk_fma_f32 v[72:73], v[20:21], v[66:67], v[24:25]
	v_pk_fma_f32 v[66:67], v[18:19], v[64:65], v[22:23]
	v_cvt_pk_bf16_f32 v64, v68, v69
	v_cvt_pk_bf16_f32 v65, v70, v71
	v_cvt_pk_bf16_f32 v66, v66, v67
	v_cvt_pk_bf16_f32 v67, v72, v73
	v_lshl_add_u64 v[68:69], v[54:55], 0, s[0:1]
	v_pk_mul_f32 v[62:63], v[62:63], v[92:93] op_sel_hi:[1,0]
	v_pk_mul_f32 v[58:59], v[58:59], v[92:93] op_sel_hi:[1,0]
	v_pk_mul_f32 v[60:61], v[60:61], v[92:93] op_sel_hi:[1,0]
	v_pk_mul_f32 v[56:57], v[56:57], v[92:93] op_sel_hi:[1,0]
	global_store_dwordx4 v[68:69], v[64:67], off
	v_pk_fma_f32 v[62:63], v[28:29], v[62:63], v[32:33]
	v_pk_fma_f32 v[58:59], v[26:27], v[58:59], v[30:31]
	v_pk_fma_f32 v[60:61], v[20:21], v[60:61], v[24:25]
	v_pk_fma_f32 v[64:65], v[18:19], v[56:57], v[22:23]
	v_cvt_pk_bf16_f32 v56, v58, v59
	v_cvt_pk_bf16_f32 v57, v62, v63
	v_cvt_pk_bf16_f32 v58, v64, v65
	v_cvt_pk_bf16_f32 v59, v60, v61
	v_lshl_add_u64 v[60:61], v[54:55], 0, s[6:7]
	s_andn2_b64 vcc, exec, s[12:13]
	s_addk_i32 s10, 0x200
	global_store_dwordx4 v[60:61], v[56:59], off
	s_cbranch_vccz .LBB0_680
	s_waitcnt vmcnt(20)
	v_lshlrev_b32_e32 v58, 16, v200
	v_and_b32_e32 v59, 0xffff0000, v200
	v_lshlrev_b32_e32 v62, 16, v201
	v_and_b32_e32 v63, 0xffff0000, v201
	v_lshlrev_b32_e32 v47, 16, v193
	v_lshlrev_b32_e32 v46, 16, v192
	v_and_b32_e32 v39, 0xffff0000, v193
	v_and_b32_e32 v38, 0xffff0000, v192
	v_lshlrev_b32_e32 v68, 16, v196
	v_and_b32_e32 v69, 0xffff0000, v196
	v_lshlrev_b32_e32 v64, 16, v198
	v_and_b32_e32 v82, 0xffff0000, v198
	v_lshlrev_b32_e32 v56, 16, v202
	v_and_b32_e32 v44, 0xffff0000, v202
	v_lshlrev_b32_e32 v60, 16, v203
	v_and_b32_e32 v42, 0xffff0000, v203
	v_pk_add_f32 v[48:49], v[46:47], v[38:39]
	v_lshlrev_b32_e32 v70, 16, v197
	v_and_b32_e32 v71, 0xffff0000, v197
	v_add_f32_e32 v43, v48, v49
	v_lshlrev_b32_e32 v49, 16, v195
	v_lshlrev_b32_e32 v48, 16, v194
	v_and_b32_e32 v41, 0xffff0000, v195
	v_and_b32_e32 v40, 0xffff0000, v194
	v_pk_add_f32 v[72:73], v[48:49], v[40:41]
	v_lshlrev_b32_e32 v66, 16, v199
	v_pk_add_f32 v[72:73], v[72:73], v[72:73] op_sel_hi:[0,1]
	v_and_b32_e32 v84, 0xffff0000, v199
	v_add_f32_e32 v85, 0, v43
	v_add_f32_e32 v65, v68, v69
	v_add_f32_e32 v83, v70, v71
	v_mov_b32_e32 v67, v73
	v_pk_add_f32 v[74:75], v[64:65], v[82:83]
	v_pk_add_f32 v[72:73], v[66:67], v[84:85]
	v_lshlrev_b32_e32 v87, 16, v189
	v_pk_add_f32 v[72:73], v[74:75], v[72:73]
	v_lshlrev_b32_e32 v86, 16, v188
	v_and_b32_e32 v35, 0xffff0000, v189
	v_and_b32_e32 v34, 0xffff0000, v188
	v_add_f32_e32 v65, v72, v73
	v_pk_add_f32 v[72:73], v[86:87], v[34:35]
	v_lshlrev_b32_e32 v97, 16, v191
	v_lshlrev_b32_e32 v96, 16, v190
	v_and_b32_e32 v37, 0xffff0000, v191
	v_and_b32_e32 v36, 0xffff0000, v190
	v_add_f32_e32 v57, v58, v59
	v_add_f32_e32 v45, v62, v63
	v_add_f32_e32 v43, v72, v73
	v_pk_add_f32 v[72:73], v[96:97], v[36:37]
	v_pk_add_f32 v[74:75], v[56:57], v[44:45]
	v_add_f32_dpp v45, v65, v65 row_ror:8 row_mask:0xf bank_mask:0xf bound_ctrl:1
	v_pk_add_f32 v[72:73], v[72:73], v[72:73] op_sel_hi:[0,1]
	v_add_f32_e32 v43, 0, v43
	v_add_f32_dpp v45, v45, v45 row_ror:4 row_mask:0xf bank_mask:0xf bound_ctrl:1
	v_mov_b32_e32 v61, v73
	v_pk_add_f32 v[72:73], v[60:61], v[42:43]
	v_add_f32_dpp v45, v45, v45 row_ror:2 row_mask:0xf bank_mask:0xf bound_ctrl:1
	v_pk_add_f32 v[72:73], v[74:75], v[72:73]
	s_lshl_b32 s12, s19, 6
	v_add_f32_dpp v45, v45, v45 row_ror:1 row_mask:0xf bank_mask:0xf bound_ctrl:1
	v_add_f32_e32 v43, v72, v73
	v_readlane_b32 s0, v45, 16
	v_readlane_b32 s2, v45, 48
	v_readlane_b32 s6, v45, 0
	v_readlane_b32 s7, v45, 32
	v_mov_b32_e32 v72, s0
	v_mov_b32_e32 v73, s2
	v_pk_add_f32 v[72:73], s[6:7], v[72:73]
	s_mov_b32 s1, s19
	v_add_f32_e32 v45, v72, v73
	v_fmac_f32_e32 v39, 0xba800000, v45
	v_fmac_f32_e32 v47, 0xba800000, v45
	v_fmac_f32_e32 v38, 0xba800000, v45
; __device__ __forceinline__ float wave_sum_dpp(float x) { x = rowsum16(x); return (rl(x, 0) + rl(x, 16)) + (rl(x, 32) + rl(x, 48)); }
;     ...
;         float mean[NR], q[NR], rstd[NR];
; #pragma unroll
;         for (int r = 0; r < NR; ++r) { mean[r] = wave_sum_dpp(s[r]) * (1.f / DM); q[r] = 0.f;
; #pragma unroll
;             for (int j = 0; j < 4; ++j) { v[r][j] = v[r][j] - mean[r]; q[r] += (v[r][j][0] * v[r][j][0] + v[r][j][1] * v[r][j][1]) + (v[r][j][2] * v[r][j][2] + v[r][j][3] * v[r][j][3]); } }
; #pragma unroll
;         for (int r = 0; r < NR; ++r) rstd[r] = 1.0f / sqrtf(wave_sum_dpp(q[r]) * (1.f / DM) + 1e-5f);
	v_fmac_f32_e32 v46, 0xba800000, v45
	v_mov_b32_e32 v74, v47
	v_mov_b32_e32 v78, v47
	v_mov_b32_e32 v79, v39
	v_mov_b32_e32 v47, v38
	v_mov_b32_e32 v73, v38
	v_mov_b32_e32 v75, v39
	v_pk_mul_f32 v[78:79], v[78:79], v[78:79]
	v_pk_mul_f32 v[38:39], v[46:47], v[46:47]
	v_mov_b32_e32 v72, v46
	v_pk_mov_b32 v[46:47], v[38:39], v[78:79] op_sel:[1,0]
	v_mov_b32_e32 v39, v79
	v_fmac_f32_e32 v41, 0xba800000, v45
	v_fmac_f32_e32 v49, 0xba800000, v45
	v_fmac_f32_e32 v40, 0xba800000, v45
	v_pk_add_f32 v[38:39], v[46:47], v[38:39]
	v_fmac_f32_e32 v48, 0xba800000, v45
	v_mov_b32_e32 v80, v49
	v_mov_b32_e32 v46, v49
	v_mov_b32_e32 v47, v41
	v_mov_b32_e32 v49, v40
	v_pk_add_f32 v[38:39], v[38:39], v[38:39] op_sel_hi:[0,1]
	v_mov_b32_e32 v79, v40
	v_mov_b32_e32 v81, v41
	v_pk_mul_f32 v[46:47], v[46:47], v[46:47]
	v_pk_mul_f32 v[40:41], v[48:49], v[48:49]
	v_fmac_f32_e32 v68, 0xba800000, v45
	v_mov_b32_e32 v78, v48
	v_pk_mov_b32 v[48:49], v[40:41], v[46:47] op_sel:[1,0]
	v_mov_b32_e32 v41, v47
	v_fmac_f32_e32 v70, 0xba800000, v45
	v_fmac_f32_e32 v69, 0xba800000, v45
	v_mul_f32_e32 v38, v68, v68
	v_pk_add_f32 v[40:41], v[48:49], v[40:41]
	v_fmac_f32_e32 v71, 0xba800000, v45
	v_pk_fma_f32 v[46:47], v[68:69], v[68:69], v[38:39] op_sel_hi:[1,1,0]
	v_mul_f32_e32 v38, v70, v70
	v_pk_add_f32 v[40:41], v[40:41], v[40:41] op_sel_hi:[0,1]
	v_pk_fma_f32 v[48:49], v[70:71], v[70:71], v[38:39] op_sel_hi:[1,1,0]
	v_fmac_f32_e32 v84, 0xba800000, v45
	v_fmac_f32_e32 v66, 0xba800000, v45
	v_fmac_f32_e32 v82, 0xba800000, v45
	v_fmac_f32_e32 v64, 0xba800000, v45
	v_mul_f32_e32 v46, v64, v64
	v_mul_f32_e32 v48, v82, v82
	v_mul_f32_e32 v38, v66, v66
	v_mul_f32_e32 v40, v84, v84
	v_pk_add_f32 v[46:47], v[46:47], v[48:49]
	v_pk_add_f32 v[38:39], v[38:39], v[40:41]
	v_mov_b32_e32 v67, v84
	v_pk_add_f32 v[38:39], v[46:47], v[38:39]
	s_or_b32 s15, s12, 62
	v_add_f32_e32 v40, v38, v39
	v_add_f32_dpp v38, v43, v43 row_ror:8 row_mask:0xf bank_mask:0xf bound_ctrl:1
	s_add_i32 s19, s19, 8
	s_cmp_ge_i32 s1, s5
	v_add_f32_dpp v38, v38, v38 row_ror:4 row_mask:0xf bank_mask:0xf bound_ctrl:1
	s_cselect_b64 s[12:13], -1, 0
	s_cmp_lt_i32 s1, s5
	v_add_f32_dpp v38, v38, v38 row_ror:2 row_mask:0xf bank_mask:0xf bound_ctrl:1
	s_cselect_b32 s1, s19, s1
	s_lshl_b32 s1, s1, 6
	v_add_f32_dpp v38, v38, v38 row_ror:1 row_mask:0xf bank_mask:0xf bound_ctrl:1
	s_or_b32 s20, s1, 62
	v_readlane_b32 s0, v38, 16
	v_readlane_b32 s2, v38, 48
	v_readlane_b32 s6, v38, 0
	v_readlane_b32 s7, v38, 32
	v_mov_b32_e32 v38, s0
	v_mov_b32_e32 v39, s2
	v_pk_add_f32 v[38:39], s[6:7], v[38:39]
	s_ashr_i32 s21, s20, 31
	v_add_f32_e32 v38, v38, v39
	v_fmac_f32_e32 v35, 0xba800000, v38
	v_fmac_f32_e32 v34, 0xba800000, v38
	v_fmac_f32_e32 v87, 0xba800000, v38
	v_fmac_f32_e32 v86, 0xba800000, v38
	v_mov_b32_e32 v83, v34
	v_mov_b32_e32 v85, v35
	v_mul_f32_e32 v34, v34, v34
	v_mul_f32_e32 v35, v35, v35
	v_fmac_f32_e32 v34, v86, v86
	v_fmac_f32_e32 v35, v87, v87
	v_fmac_f32_e32 v37, 0xba800000, v38
	v_fmac_f32_e32 v36, 0xba800000, v38
	v_mov_b32_e32 v84, v87
	v_add_f32_e32 v34, v34, v35
	v_fmac_f32_e32 v97, 0xba800000, v38
	v_fmac_f32_e32 v96, 0xba800000, v38
	v_mov_b32_e32 v87, v36
	v_mul_f32_e32 v35, v36, v36
	v_mul_f32_e32 v36, v37, v37
	v_fmac_f32_e32 v35, v96, v96
	v_fmac_f32_e32 v36, v97, v97
	v_add_f32_e32 v35, v35, v36
	v_fmac_f32_e32 v63, 0xba800000, v38
	v_fmac_f32_e32 v59, 0xba800000, v38
	v_add_f32_e32 v34, v34, v35
	v_fmac_f32_e32 v62, 0xba800000, v38
	v_fmac_f32_e32 v58, 0xba800000, v38
	v_mul_f32_e32 v35, v59, v59
	v_mul_f32_e32 v36, v63, v63
	v_fmac_f32_e32 v35, v58, v58
	v_fmac_f32_e32 v36, v62, v62
	v_add_f32_e32 v35, v35, v36
	v_fmac_f32_e32 v42, 0xba800000, v38
	v_fmac_f32_e32 v44, 0xba800000, v38
	v_add_f32_e32 v34, v35, v34
	v_fmac_f32_e32 v60, 0xba800000, v38
	v_fmac_f32_e32 v56, 0xba800000, v38
	v_mul_f32_e32 v35, v44, v44
	v_mul_f32_e32 v36, v42, v42
	v_fmac_f32_e32 v35, v56, v56
	v_fmac_f32_e32 v36, v60, v60
	v_add_f32_e32 v35, v35, v36
; __device__ __forceinline__ float wave_sum_dpp(float x) { x = rowsum16(x); return (rl(x, 0) + rl(x, 16)) + (rl(x, 32) + rl(x, 48)); }
;     ...
;         for (int r = 0; r < NR; ++r) { mean[r] = wave_sum_dpp(s[r]) * (1.f / DM); q[r] = 0.f;
; #pragma unroll
;             for (int j = 0; j < 4; ++j) { v[r][j] = v[r][j] - mean[r]; q[r] += (v[r][j][0] * v[r][j][0] + v[r][j][1] * v[r][j][1]) + (v[r][j][2] * v[r][j][2] + v[r][j][3] * v[r][j][3]); } }
; #pragma unroll
;         for (int r = 0; r < NR; ++r) rstd[r] = 1.0f / sqrtf(wave_sum_dpp(q[r]) * (1.f / DM) + 1e-5f);
;         if (MODE == 1) {
; #pragma unroll
;             for (int r = 0; r < NR; ++r) if (lane == r) { stats[2 * row[r]] = mean[r]; stats[2 * row[r] + 1] = rstd[r]; } }
	v_add_f32_e32 v34, v35, v34
	s_lshl_b64 s[20:21], s[20:21], 11
	v_add_f32_dpp v35, v40, v40 row_ror:8 row_mask:0xf bank_mask:0xf bound_ctrl:1
	v_add_f32_dpp v34, v34, v34 row_ror:8 row_mask:0xf bank_mask:0xf bound_ctrl:1
	v_mul_f32_e32 v76, 0x3a800000, v45
	v_add_f32_dpp v35, v35, v35 row_ror:4 row_mask:0xf bank_mask:0xf bound_ctrl:1
	v_add_f32_dpp v34, v34, v34 row_ror:4 row_mask:0xf bank_mask:0xf bound_ctrl:1
	v_mul_f32_e32 v90, 0x3a800000, v38
	v_add_f32_dpp v35, v35, v35 row_ror:2 row_mask:0xf bank_mask:0xf bound_ctrl:1
	v_add_f32_dpp v34, v34, v34 row_ror:2 row_mask:0xf bank_mask:0xf bound_ctrl:1
	v_mov_b32_e32 v89, v37
	v_add_f32_dpp v35, v35, v35 row_ror:1 row_mask:0xf bank_mask:0xf bound_ctrl:1
	v_add_f32_dpp v34, v34, v34 row_ror:1 row_mask:0xf bank_mask:0xf bound_ctrl:1
	v_readlane_b32 s6, v35, 0
	v_readlane_b32 s11, v35, 16
	v_readlane_b32 s7, v35, 32
	v_readlane_b32 s14, v35, 48
	v_readlane_b32 s0, v34, 0
	v_readlane_b32 s8, v34, 16
	v_readlane_b32 s2, v34, 32
	v_readlane_b32 s9, v34, 48
	v_lshl_add_u64 v[34:35], v[50:51], 0, s[20:21]
	s_or_b32 s20, s1, 63
	s_ashr_i32 s21, s20, 31
	s_lshl_b64 s[20:21], s[20:21], 11
	v_lshl_add_u64 v[46:47], v[50:51], 0, s[20:21]
	v_mov_b32_e32 v57, v44
	v_mov_b32_e32 v61, v42
	v_mov_b32_e32 v65, v82
	v_mov_b32_e32 v82, v86
	v_mov_b32_e32 v86, v96
	v_mov_b32_e32 v88, v97
	v_mov_b32_e32 v96, s11
	v_mov_b32_e32 v97, s14
	v_pk_add_f32 v[96:97], s[6:7], v[96:97]
	v_mov_b32_e32 v98, s9
	v_add_f32_e32 v77, v96, v97
	v_fmamk_f32 v77, v77, 0x3a800000, v93
	v_mul_f32_e32 v91, 0x4f800000, v77
	v_cmp_gt_f32_e32 vcc, s18, v77
	v_mov_b32_e32 v97, s8
	v_add_f32_e32 v97, s0, v97
	v_cndmask_b32_e32 v77, v77, v91, vcc
	v_sqrt_f32_e32 v91, v77
	v_add_f32_e32 v98, s2, v98
	v_add_f32_e32 v97, v97, v98
	v_fmamk_f32 v97, v97, 0x3a800000, v93
	v_add_u32_e32 v92, -1, v91
	v_fma_f32 v94, -v92, v91, v77
	v_cmp_ge_f32_e64 s[6:7], 0, v94
	v_add_u32_e32 v94, 1, v91
	v_mul_f32_e32 v98, 0x4f800000, v97
	v_cndmask_b32_e64 v92, v91, v92, s[6:7]
	v_fma_f32 v91, -v94, v91, v77
	v_cmp_lt_f32_e64 s[6:7], 0, v91
	s_nop 1
	v_cndmask_b32_e64 v91, v92, v94, s[6:7]
	v_mul_f32_e32 v92, 0x37800000, v91
	v_cndmask_b32_e32 v91, v91, v92, vcc
	v_cmp_class_f32_e32 vcc, v77, v95
	s_nop 1
	v_cndmask_b32_e32 v77, v91, v77, vcc
	v_div_scale_f32 v91, s[6:7], v77, v77, 1.0
	v_rcp_f32_e32 v92, v91
	v_cmp_gt_f32_e64 s[6:7], s18, v97
	v_fma_f32 v94, -v91, v92, 1.0
	s_nop 0
	v_cndmask_b32_e64 v97, v97, v98, s[6:7]
	v_fmac_f32_e32 v92, v94, v92
	v_div_scale_f32 v94, vcc, 1.0, v77, 1.0
	v_sqrt_f32_e32 v98, v97
	v_mul_f32_e32 v96, v94, v92
	v_fma_f32 v99, -v91, v96, v94
	v_fmac_f32_e32 v96, v99, v92
	v_fma_f32 v91, -v91, v96, v94
	v_add_u32_e32 v94, -1, v98
	v_fma_f32 v99, -v94, v98, v97
	v_cmp_ge_f32_e64 s[8:9], 0, v99
	v_add_u32_e32 v99, 1, v98
	v_div_fmas_f32 v91, v91, v92, v96
	v_cndmask_b32_e64 v94, v98, v94, s[8:9]
	v_fma_f32 v98, -v99, v98, v97
	v_cmp_lt_f32_e64 s[8:9], 0, v98
	s_nop 1
	v_cndmask_b32_e64 v94, v94, v99, s[8:9]
	v_mul_f32_e32 v98, 0x37800000, v94
	v_cndmask_b32_e64 v94, v94, v98, s[6:7]
	v_cmp_class_f32_e64 s[6:7], v97, v95
	s_mov_b64 s[8:9], -1
	s_nop 0
	v_cndmask_b32_e64 v97, v94, v97, s[6:7]
	v_div_scale_f32 v98, s[0:1], v97, v97, 1.0
	v_rcp_f32_e32 v99, v98
	v_div_fixup_f32 v94, v91, v77, 1.0
	v_fma_f32 v77, -v98, v99, 1.0
	v_fmac_f32_e32 v99, v77, v99
	v_div_scale_f32 v77, vcc, 1.0, v97, 1.0
	v_mul_f32_e32 v91, v77, v99
	v_fma_f32 v92, -v98, v91, v77
	v_fmac_f32_e32 v91, v92, v99
	v_fma_f32 v77, -v98, v91, v77
	v_div_fmas_f32 v77, v77, v99, v91
	v_div_fixup_f32 v92, v77, v97, 1.0
	v_mov_b32_e32 v77, v94
	v_cmp_lt_i32_e32 vcc, 0, v145
	v_mov_b32_e32 v91, s15
	s_and_saveexec_b64 s[6:7], vcc
	s_cbranch_execz .Lhln7_m3
	v_cmp_eq_u32_e32 vcc, 1, v145
	s_mov_b64 s[8:9], 0
	s_and_saveexec_b64 s[14:15], vcc
	v_mov_b32_e32 v91, v92
	s_mov_b64 s[8:9], exec
	v_mov_b64_e32 v[76:77], v[90:91]
	s_or_b64 exec, exec, s[14:15]
	v_mov_b32_e32 v91, s10
	s_orn2_b64 s[8:9], s[8:9], exec

; __device__ __forceinline__ unsigned cvtpk(float lo, float hi) { f32x2_t v = {lo, hi}; bf16x2_t b = __builtin_convertvector(v, bf16x2_t); return __builtin_bit_cast(unsigned, b); }
;     ...
;         f32x4 v[NR][4]; float s[NR];
; #pragma unroll
;         for (int r = 0; r < NR; ++r) { s[r] = 0.f;
; #pragma unroll
;             for (int j = 0; j < 2; ++j) {
;                 v[r][2 * j][0] = __builtin_bit_cast(float, raw[r][j].x << 16); v[r][2 * j][1] = __builtin_bit_cast(float, raw[r][j].x & 0xffff0000u);
;                 v[r][2 * j][2] = __builtin_bit_cast(float, raw[r][j].y << 16); v[r][2 * j][3] = __builtin_bit_cast(float, raw[r][j].y & 0xffff0000u);
;                 v[r][2 * j + 1][0] = __builtin_bit_cast(float, raw[r][j].z << 16); v[r][2 * j + 1][1] = __builtin_bit_cast(float, raw[r][j].z & 0xffff0000u);
;                 v[r][2 * j + 1][2] = __builtin_bit_cast(float, raw[r][j].w << 16); v[r][2 * j + 1][3] = __builtin_bit_cast(float, raw[r][j].w & 0xffff0000u); } }
;         { const int nxt = pi + NP * pstep, pq = nxt < p1 ? nxt : pi;
; #pragma unroll
;           for (int r = 0; r < NR; ++r) { const bf16_t* pn = z + (size_t)rowr(pq, r) * DM;
; #pragma unroll
;               for (int j = 0; j < 2; ++j) raw[r][j] = *(const pg8::u32x4*)(pn + 8 * lane + 512 * j); } }
; #pragma unroll
;         for (int r = 0; r < NR; ++r)
; #pragma unroll
;             for (int j = 0; j < 4; ++j) s[r] += (v[r][j][0] + v[r][j][1]) + (v[r][j][2] + v[r][j][3]);
;         float mean[NR], q[NR], rstd[NR];
; #pragma unroll
;         for (int r = 0; r < NR; ++r) { mean[r] = wave_sum_dpp(s[r]) * (1.f / DM); q[r] = 0.f;
;     ...
;         for (int j = 0; j < 2; ++j) {
;             const int c = 8 * lane + 512 * j;
;             const f32x4 g0 = *(const f32x4*)(g + c), g1 = *(const f32x4*)(g + c + 4), b0 = *(const f32x4*)(b + c), b1 = *(const f32x4*)(b + c + 4);
; #pragma unroll
;             for (int r = 0; r < NR; ++r) {
;                 const f32x4 o0 = v[r][2 * j] * rstd[r] * g0 + b0, o1 = v[r][2 * j + 1] * rstd[r] * g1 + b1;
;                 if (MODE == 1) { pg8::u32x4 w; w.x = cvtpk(o0[0], o0[1]); w.y = cvtpk(o0[2], o0[3]); w.z = cvtpk(o1[0], o1[1]); w.w = cvtpk(o1[2], o1[3]); *(pg8::u32x4*)(hb + (size_t)row[r] * DM + c) = w; }
;                 else { *(f32x4*)(outf + (size_t)row[r] * DM + c) = o0; *(f32x4*)(outf + (size_t)row[r] * DM + c + 4) = o1; }
;             }
;         }
.Lhln7_t3:
	s_or_b64 exec, exec, s[6:7]
	s_add_i32 s0, s10, -1
	v_pk_mul_f32 v[74:75], v[74:75], v[94:95] op_sel_hi:[1,0]
	v_pk_mul_f32 v[72:73], v[72:73], v[94:95] op_sel_hi:[1,0]
	v_pk_mul_f32 v[76:77], v[80:81], v[94:95] op_sel_hi:[1,0]
	v_pk_mul_f32 v[78:79], v[78:79], v[94:95] op_sel_hi:[1,0]
	s_ashr_i32 s1, s0, 31
	v_pk_fma_f32 v[74:75], v[12:13], v[74:75], v[16:17]
	v_pk_fma_f32 v[72:73], v[10:11], v[72:73], v[14:15]
	v_pk_fma_f32 v[76:77], v[4:5], v[76:77], v[8:9]
	v_pk_fma_f32 v[78:79], v[2:3], v[78:79], v[6:7]
	s_lshl_b64 s[0:1], s[0:1], 11
	v_cvt_pk_bf16_f32 v72, v72, v73
	v_cvt_pk_bf16_f32 v73, v74, v75
	v_cvt_pk_bf16_f32 v74, v78, v79
	v_cvt_pk_bf16_f32 v75, v76, v77
	v_lshl_add_u64 v[76:77], v[52:53], 0, s[0:1]
	global_store_dwordx4 v[76:77], v[72:75], off
	v_pk_mul_f32 v[78:79], v[86:87], v[92:93] op_sel_hi:[1,0]
	s_ashr_i32 s11, s10, 31
	v_pk_mul_f32 v[72:73], v[84:85], v[92:93] op_sel_hi:[1,0]
	v_pk_mul_f32 v[74:75], v[82:83], v[92:93] op_sel_hi:[1,0]
	v_pk_fma_f32 v[76:77], v[12:13], v[72:73], v[16:17]
	v_pk_fma_f32 v[72:73], v[10:11], v[74:75], v[14:15]
	v_pk_mul_f32 v[74:75], v[88:89], v[92:93] op_sel_hi:[1,0]
	s_lshl_b64 s[6:7], s[10:11], 11
	v_pk_fma_f32 v[80:81], v[4:5], v[74:75], v[8:9]
	v_pk_fma_f32 v[74:75], v[2:3], v[78:79], v[6:7]
	v_cvt_pk_bf16_f32 v72, v72, v73
	v_cvt_pk_bf16_f32 v73, v76, v77
	v_cvt_pk_bf16_f32 v74, v74, v75
	v_cvt_pk_bf16_f32 v75, v80, v81
	v_lshl_add_u64 v[76:77], v[52:53], 0, s[6:7]
	v_pk_mul_f32 v[70:71], v[70:71], v[94:95] op_sel_hi:[1,0]
	v_pk_mul_f32 v[68:69], v[68:69], v[94:95] op_sel_hi:[1,0]
	v_pk_mul_f32 v[66:67], v[66:67], v[94:95] op_sel_hi:[1,0]
	v_pk_mul_f32 v[64:65], v[64:65], v[94:95] op_sel_hi:[1,0]
	global_store_dwordx4 v[76:77], v[72:75], off
	v_pk_fma_f32 v[70:71], v[28:29], v[70:71], v[32:33]
	v_pk_fma_f32 v[68:69], v[26:27], v[68:69], v[30:31]
	v_pk_fma_f32 v[72:73], v[20:21], v[66:67], v[24:25]
	v_pk_fma_f32 v[66:67], v[18:19], v[64:65], v[22:23]
	v_cvt_pk_bf16_f32 v64, v68, v69
	v_cvt_pk_bf16_f32 v65, v70, v71
	v_cvt_pk_bf16_f32 v66, v66, v67
	v_cvt_pk_bf16_f32 v67, v72, v73
	v_lshl_add_u64 v[68:69], v[54:55], 0, s[0:1]
	v_pk_mul_f32 v[62:63], v[62:63], v[92:93] op_sel_hi:[1,0]
	v_pk_mul_f32 v[58:59], v[58:59], v[92:93] op_sel_hi:[1,0]
	v_pk_mul_f32 v[60:61], v[60:61], v[92:93] op_sel_hi:[1,0]
	v_pk_mul_f32 v[56:57], v[56:57], v[92:93] op_sel_hi:[1,0]
	global_store_dwordx4 v[68:69], v[64:67], off
	v_pk_fma_f32 v[62:63], v[28:29], v[62:63], v[32:33]
	v_pk_fma_f32 v[58:59], v[26:27], v[58:59], v[30:31]
	v_pk_fma_f32 v[60:61], v[20:21], v[60:61], v[24:25]
	v_pk_fma_f32 v[64:65], v[18:19], v[56:57], v[22:23]
	v_cvt_pk_bf16_f32 v56, v58, v59
	v_cvt_pk_bf16_f32 v57, v62, v63
	v_cvt_pk_bf16_f32 v58, v64, v65
	v_cvt_pk_bf16_f32 v59, v60, v61
	v_lshl_add_u64 v[60:61], v[54:55], 0, s[6:7]
	s_andn2_b64 vcc, exec, s[12:13]
	s_addk_i32 s10, 0x200
	global_store_dwordx4 v[60:61], v[56:59], off
	s_cbranch_vccz .LBB0_680
	s_waitcnt vmcnt(20)
	v_lshlrev_b32_e32 v58, 16, v216
	v_and_b32_e32 v59, 0xffff0000, v216
	v_lshlrev_b32_e32 v62, 16, v217
	v_and_b32_e32 v63, 0xffff0000, v217
	v_lshlrev_b32_e32 v47, 16, v209
	v_lshlrev_b32_e32 v46, 16, v208
	v_and_b32_e32 v39, 0xffff0000, v209
	v_and_b32_e32 v38, 0xffff0000, v208
	v_lshlrev_b32_e32 v68, 16, v212
	v_and_b32_e32 v69, 0xffff0000, v212
	v_lshlrev_b32_e32 v64, 16, v214
	v_and_b32_e32 v82, 0xffff0000, v214
	v_lshlrev_b32_e32 v56, 16, v218
	v_and_b32_e32 v44, 0xffff0000, v218
	v_lshlrev_b32_e32 v60, 16, v219
	v_and_b32_e32 v42, 0xffff0000, v219
	v_pk_add_f32 v[48:49], v[46:47], v[38:39]
	v_lshlrev_b32_e32 v70, 16, v213
	v_and_b32_e32 v71, 0xffff0000, v213
	v_add_f32_e32 v43, v48, v49
	v_lshlrev_b32_e32 v49, 16, v211
	v_lshlrev_b32_e32 v48, 16, v210
	v_and_b32_e32 v41, 0xffff0000, v211
	v_and_b32_e32 v40, 0xffff0000, v210
	v_pk_add_f32 v[72:73], v[48:49], v[40:41]
	v_lshlrev_b32_e32 v66, 16, v215
	v_pk_add_f32 v[72:73], v[72:73], v[72:73] op_sel_hi:[0,1]
	v_and_b32_e32 v84, 0xffff0000, v215
	v_add_f32_e32 v85, 0, v43
	v_add_f32_e32 v65, v68, v69
	v_add_f32_e32 v83, v70, v71
	v_mov_b32_e32 v67, v73
	v_pk_add_f32 v[74:75], v[64:65], v[82:83]
	v_pk_add_f32 v[72:73], v[66:67], v[84:85]
	v_lshlrev_b32_e32 v87, 16, v205
	v_pk_add_f32 v[72:73], v[74:75], v[72:73]
	v_lshlrev_b32_e32 v86, 16, v204
	v_and_b32_e32 v35, 0xffff0000, v205
	v_and_b32_e32 v34, 0xffff0000, v204
	v_add_f32_e32 v65, v72, v73
	v_pk_add_f32 v[72:73], v[86:87], v[34:35]
	v_lshlrev_b32_e32 v97, 16, v207
	v_lshlrev_b32_e32 v96, 16, v206
	v_and_b32_e32 v37, 0xffff0000, v207
	v_and_b32_e32 v36, 0xffff0000, v206
	v_add_f32_e32 v57, v58, v59
	v_add_f32_e32 v45, v62, v63
	v_add_f32_e32 v43, v72, v73
	v_pk_add_f32 v[72:73], v[96:97], v[36:37]
	v_pk_add_f32 v[74:75], v[56:57], v[44:45]
	v_add_f32_dpp v45, v65, v65 row_ror:8 row_mask:0xf bank_mask:0xf bound_ctrl:1
	v_pk_add_f32 v[72:73], v[72:73], v[72:73] op_sel_hi:[0,1]
	v_add_f32_e32 v43, 0, v43
	v_add_f32_dpp v45, v45, v45 row_ror:4 row_mask:0xf bank_mask:0xf bound_ctrl:1
	v_mov_b32_e32 v61, v73
	v_pk_add_f32 v[72:73], v[60:61], v[42:43]
	v_add_f32_dpp v45, v45, v45 row_ror:2 row_mask:0xf bank_mask:0xf bound_ctrl:1
	v_pk_add_f32 v[72:73], v[74:75], v[72:73]
	s_lshl_b32 s12, s19, 6
	v_add_f32_dpp v45, v45, v45 row_ror:1 row_mask:0xf bank_mask:0xf bound_ctrl:1
	v_add_f32_e32 v43, v72, v73
	v_readlane_b32 s0, v45, 16
	v_readlane_b32 s2, v45, 48
	v_readlane_b32 s6, v45, 0
	v_readlane_b32 s7, v45, 32
	v_mov_b32_e32 v72, s0
	v_mov_b32_e32 v73, s2
	v_pk_add_f32 v[72:73], s[6:7], v[72:73]
	s_mov_b32 s1, s19
	v_add_f32_e32 v45, v72, v73
	v_fmac_f32_e32 v39, 0xba800000, v45
	v_fmac_f32_e32 v47, 0xba800000, v45
	v_fmac_f32_e32 v38, 0xba800000, v45
; __device__ __forceinline__ float wave_sum_dpp(float x) { x = rowsum16(x); return (rl(x, 0) + rl(x, 16)) + (rl(x, 32) + rl(x, 48)); }
;     ...
;         float mean[NR], q[NR], rstd[NR];
; #pragma unroll
;         for (int r = 0; r < NR; ++r) { mean[r] = wave_sum_dpp(s[r]) * (1.f / DM); q[r] = 0.f;
; #pragma unroll
;             for (int j = 0; j < 4; ++j) { v[r][j] = v[r][j] - mean[r]; q[r] += (v[r][j][0] * v[r][j][0] + v[r][j][1] * v[r][j][1]) + (v[r][j][2] * v[r][j][2] + v[r][j][3] * v[r][j][3]); } }
; #pragma unroll
;         for (int r = 0; r < NR; ++r) rstd[r] = 1.0f / sqrtf(wave_sum_dpp(q[r]) * (1.f / DM) + 1e-5f);
	v_fmac_f32_e32 v46, 0xba800000, v45
	v_mov_b32_e32 v74, v47
	v_mov_b32_e32 v78, v47
	v_mov_b32_e32 v79, v39
	v_mov_b32_e32 v47, v38
	v_mov_b32_e32 v73, v38
	v_mov_b32_e32 v75, v39
	v_pk_mul_f32 v[78:79], v[78:79], v[78:79]
	v_pk_mul_f32 v[38:39], v[46:47], v[46:47]
	v_mov_b32_e32 v72, v46
	v_pk_mov_b32 v[46:47], v[38:39], v[78:79] op_sel:[1,0]
	v_mov_b32_e32 v39, v79
	v_fmac_f32_e32 v41, 0xba800000, v45
	v_fmac_f32_e32 v49, 0xba800000, v45
	v_fmac_f32_e32 v40, 0xba800000, v45
	v_pk_add_f32 v[38:39], v[46:47], v[38:39]
	v_fmac_f32_e32 v48, 0xba800000, v45
	v_mov_b32_e32 v80, v49
	v_mov_b32_e32 v46, v49
	v_mov_b32_e32 v47, v41
	v_mov_b32_e32 v49, v40
	v_pk_add_f32 v[38:39], v[38:39], v[38:39] op_sel_hi:[0,1]
	v_mov_b32_e32 v79, v40
	v_mov_b32_e32 v81, v41
	v_pk_mul_f32 v[46:47], v[46:47], v[46:47]
	v_pk_mul_f32 v[40:41], v[48:49], v[48:49]
	v_fmac_f32_e32 v68, 0xba800000, v45
	v_mov_b32_e32 v78, v48
	v_pk_mov_b32 v[48:49], v[40:41], v[46:47] op_sel:[1,0]
	v_mov_b32_e32 v41, v47
	v_fmac_f32_e32 v70, 0xba800000, v45
	v_fmac_f32_e32 v69, 0xba800000, v45
	v_mul_f32_e32 v38, v68, v68
	v_pk_add_f32 v[40:41], v[48:49], v[40:41]
	v_fmac_f32_e32 v71, 0xba800000, v45
	v_pk_fma_f32 v[46:47], v[68:69], v[68:69], v[38:39] op_sel_hi:[1,1,0]
	v_mul_f32_e32 v38, v70, v70
	v_pk_add_f32 v[40:41], v[40:41], v[40:41] op_sel_hi:[0,1]
	v_pk_fma_f32 v[48:49], v[70:71], v[70:71], v[38:39] op_sel_hi:[1,1,0]
	v_fmac_f32_e32 v84, 0xba800000, v45
	v_fmac_f32_e32 v66, 0xba800000, v45
	v_fmac_f32_e32 v82, 0xba800000, v45
	v_fmac_f32_e32 v64, 0xba800000, v45
	v_mul_f32_e32 v46, v64, v64
	v_mul_f32_e32 v48, v82, v82
	v_mul_f32_e32 v38, v66, v66
	v_mul_f32_e32 v40, v84, v84
	v_pk_add_f32 v[46:47], v[46:47], v[48:49]
	v_pk_add_f32 v[38:39], v[38:39], v[40:41]
	v_mov_b32_e32 v67, v84
	v_pk_add_f32 v[38:39], v[46:47], v[38:39]
	s_or_b32 s15, s12, 62
	v_add_f32_e32 v40, v38, v39
	v_add_f32_dpp v38, v43, v43 row_ror:8 row_mask:0xf bank_mask:0xf bound_ctrl:1
	s_add_i32 s19, s19, 8
	s_cmp_ge_i32 s1, s5
	v_add_f32_dpp v38, v38, v38 row_ror:4 row_mask:0xf bank_mask:0xf bound_ctrl:1
	s_cselect_b64 s[12:13], -1, 0
	s_cmp_lt_i32 s1, s5
	v_add_f32_dpp v38, v38, v38 row_ror:2 row_mask:0xf bank_mask:0xf bound_ctrl:1
	s_cselect_b32 s1, s19, s1
	s_lshl_b32 s1, s1, 6
	v_add_f32_dpp v38, v38, v38 row_ror:1 row_mask:0xf bank_mask:0xf bound_ctrl:1
	s_or_b32 s20, s1, 62
	v_readlane_b32 s0, v38, 16
	v_readlane_b32 s2, v38, 48
	v_readlane_b32 s6, v38, 0
	v_readlane_b32 s7, v38, 32
	v_mov_b32_e32 v38, s0
	v_mov_b32_e32 v39, s2
	v_pk_add_f32 v[38:39], s[6:7], v[38:39]
	s_ashr_i32 s21, s20, 31
	v_add_f32_e32 v38, v38, v39
	v_fmac_f32_e32 v35, 0xba800000, v38
	v_fmac_f32_e32 v34, 0xba800000, v38
	v_fmac_f32_e32 v87, 0xba800000, v38
	v_fmac_f32_e32 v86, 0xba800000, v38
	v_mov_b32_e32 v83, v34
	v_mov_b32_e32 v85, v35
	v_mul_f32_e32 v34, v34, v34
	v_mul_f32_e32 v35, v35, v35
	v_fmac_f32_e32 v34, v86, v86
	v_fmac_f32_e32 v35, v87, v87
	v_fmac_f32_e32 v37, 0xba800000, v38
	v_fmac_f32_e32 v36, 0xba800000, v38
	v_mov_b32_e32 v84, v87
	v_add_f32_e32 v34, v34, v35
	v_fmac_f32_e32 v97, 0xba800000, v38
	v_fmac_f32_e32 v96, 0xba800000, v38
	v_mov_b32_e32 v87, v36
	v_mul_f32_e32 v35, v36, v36
	v_mul_f32_e32 v36, v37, v37
	v_fmac_f32_e32 v35, v96, v96
	v_fmac_f32_e32 v36, v97, v97
	v_add_f32_e32 v35, v35, v36
	v_fmac_f32_e32 v63, 0xba800000, v38
	v_fmac_f32_e32 v59, 0xba800000, v38
	v_add_f32_e32 v34, v34, v35
	v_fmac_f32_e32 v62, 0xba800000, v38
	v_fmac_f32_e32 v58, 0xba800000, v38
	v_mul_f32_e32 v35, v59, v59
	v_mul_f32_e32 v36, v63, v63
	v_fmac_f32_e32 v35, v58, v58
	v_fmac_f32_e32 v36, v62, v62
	v_add_f32_e32 v35, v35, v36
	v_fmac_f32_e32 v42, 0xba800000, v38
	v_fmac_f32_e32 v44, 0xba800000, v38
	v_add_f32_e32 v34, v35, v34
	v_fmac_f32_e32 v60, 0xba800000, v38
	v_fmac_f32_e32 v56, 0xba800000, v38
	v_mul_f32_e32 v35, v44, v44
	v_mul_f32_e32 v36, v42, v42
	v_fmac_f32_e32 v35, v56, v56
	v_fmac_f32_e32 v36, v60, v60
	v_add_f32_e32 v35, v35, v36
; __device__ __forceinline__ float wave_sum_dpp(float x) { x = rowsum16(x); return (rl(x, 0) + rl(x, 16)) + (rl(x, 32) + rl(x, 48)); }
;     ...
;         for (int r = 0; r < NR; ++r) { mean[r] = wave_sum_dpp(s[r]) * (1.f / DM); q[r] = 0.f;
; #pragma unroll
;             for (int j = 0; j < 4; ++j) { v[r][j] = v[r][j] - mean[r]; q[r] += (v[r][j][0] * v[r][j][0] + v[r][j][1] * v[r][j][1]) + (v[r][j][2] * v[r][j][2] + v[r][j][3] * v[r][j][3]); } }
; #pragma unroll
;         for (int r = 0; r < NR; ++r) rstd[r] = 1.0f / sqrtf(wave_sum_dpp(q[r]) * (1.f / DM) + 1e-5f);
;         if (MODE == 1) {
; #pragma unroll
;             for (int r = 0; r < NR; ++r) if (lane == r) { stats[2 * row[r]] = mean[r]; stats[2 * row[r] + 1] = rstd[r]; } }
	v_add_f32_e32 v34, v35, v34
	s_lshl_b64 s[20:21], s[20:21], 11
	v_add_f32_dpp v35, v40, v40 row_ror:8 row_mask:0xf bank_mask:0xf bound_ctrl:1
	v_add_f32_dpp v34, v34, v34 row_ror:8 row_mask:0xf bank_mask:0xf bound_ctrl:1
	v_mul_f32_e32 v76, 0x3a800000, v45
	v_add_f32_dpp v35, v35, v35 row_ror:4 row_mask:0xf bank_mask:0xf bound_ctrl:1
	v_add_f32_dpp v34, v34, v34 row_ror:4 row_mask:0xf bank_mask:0xf bound_ctrl:1
	v_mul_f32_e32 v90, 0x3a800000, v38
	v_add_f32_dpp v35, v35, v35 row_ror:2 row_mask:0xf bank_mask:0xf bound_ctrl:1
	v_add_f32_dpp v34, v34, v34 row_ror:2 row_mask:0xf bank_mask:0xf bound_ctrl:1
	v_mov_b32_e32 v89, v37
	v_add_f32_dpp v35, v35, v35 row_ror:1 row_mask:0xf bank_mask:0xf bound_ctrl:1
	v_add_f32_dpp v34, v34, v34 row_ror:1 row_mask:0xf bank_mask:0xf bound_ctrl:1
	v_readlane_b32 s6, v35, 0
	v_readlane_b32 s11, v35, 16
	v_readlane_b32 s7, v35, 32
	v_readlane_b32 s14, v35, 48
	v_readlane_b32 s0, v34, 0
	v_readlane_b32 s8, v34, 16
	v_readlane_b32 s2, v34, 32
	v_readlane_b32 s9, v34, 48
	v_lshl_add_u64 v[34:35], v[50:51], 0, s[20:21]
	s_or_b32 s20, s1, 63
	s_ashr_i32 s21, s20, 31
	s_lshl_b64 s[20:21], s[20:21], 11
	v_lshl_add_u64 v[46:47], v[50:51], 0, s[20:21]
	v_mov_b32_e32 v57, v44
	v_mov_b32_e32 v61, v42
	v_mov_b32_e32 v65, v82
	v_mov_b32_e32 v82, v86
	v_mov_b32_e32 v86, v96
	v_mov_b32_e32 v88, v97
	v_mov_b32_e32 v96, s11
	v_mov_b32_e32 v97, s14
	v_pk_add_f32 v[96:97], s[6:7], v[96:97]
	v_mov_b32_e32 v98, s9
	v_add_f32_e32 v77, v96, v97
	v_fmamk_f32 v77, v77, 0x3a800000, v93
	v_mul_f32_e32 v91, 0x4f800000, v77
	v_cmp_gt_f32_e32 vcc, s18, v77
	v_mov_b32_e32 v97, s8
	v_add_f32_e32 v97, s0, v97
	v_cndmask_b32_e32 v77, v77, v91, vcc
	v_sqrt_f32_e32 v91, v77
	v_add_f32_e32 v98, s2, v98
	v_add_f32_e32 v97, v97, v98
	v_fmamk_f32 v97, v97, 0x3a800000, v93
	v_add_u32_e32 v92, -1, v91
	v_fma_f32 v94, -v92, v91, v77
	v_cmp_ge_f32_e64 s[6:7], 0, v94
	v_add_u32_e32 v94, 1, v91
	v_mul_f32_e32 v98, 0x4f800000, v97
	v_cndmask_b32_e64 v92, v91, v92, s[6:7]
	v_fma_f32 v91, -v94, v91, v77
	v_cmp_lt_f32_e64 s[6:7], 0, v91
	s_nop 1
	v_cndmask_b32_e64 v91, v92, v94, s[6:7]
	v_mul_f32_e32 v92, 0x37800000, v91
	v_cndmask_b32_e32 v91, v91, v92, vcc
	v_cmp_class_f32_e32 vcc, v77, v95
	s_nop 1
	v_cndmask_b32_e32 v77, v91, v77, vcc
	v_div_scale_f32 v91, s[6:7], v77, v77, 1.0
	v_rcp_f32_e32 v92, v91
	v_cmp_gt_f32_e64 s[6:7], s18, v97
	v_fma_f32 v94, -v91, v92, 1.0
	s_nop 0
	v_cndmask_b32_e64 v97, v97, v98, s[6:7]
	v_fmac_f32_e32 v92, v94, v92
	v_div_scale_f32 v94, vcc, 1.0, v77, 1.0
	v_sqrt_f32_e32 v98, v97
	v_mul_f32_e32 v96, v94, v92
	v_fma_f32 v99, -v91, v96, v94
	v_fmac_f32_e32 v96, v99, v92
	v_fma_f32 v91, -v91, v96, v94
	v_add_u32_e32 v94, -1, v98
	v_fma_f32 v99, -v94, v98, v97
	v_cmp_ge_f32_e64 s[8:9], 0, v99
	v_add_u32_e32 v99, 1, v98
	v_div_fmas_f32 v91, v91, v92, v96
	v_cndmask_b32_e64 v94, v98, v94, s[8:9]
	v_fma_f32 v98, -v99, v98, v97
	v_cmp_lt_f32_e64 s[8:9], 0, v98
	s_nop 1
	v_cndmask_b32_e64 v94, v94, v99, s[8:9]
	v_mul_f32_e32 v98, 0x37800000, v94
	v_cndmask_b32_e64 v94, v94, v98, s[6:7]
	v_cmp_class_f32_e64 s[6:7], v97, v95
	s_mov_b64 s[8:9], -1
	s_nop 0
	v_cndmask_b32_e64 v97, v94, v97, s[6:7]
	v_div_scale_f32 v98, s[0:1], v97, v97, 1.0
	v_rcp_f32_e32 v99, v98
	v_div_fixup_f32 v94, v91, v77, 1.0
	v_fma_f32 v77, -v98, v99, 1.0
	v_fmac_f32_e32 v99, v77, v99
	v_div_scale_f32 v77, vcc, 1.0, v97, 1.0
	v_mul_f32_e32 v91, v77, v99
	v_fma_f32 v92, -v98, v91, v77
	v_fmac_f32_e32 v91, v92, v99
	v_fma_f32 v77, -v98, v91, v77
	v_div_fmas_f32 v77, v77, v99, v91
	v_div_fixup_f32 v92, v77, v97, 1.0
	v_mov_b32_e32 v77, v94
	v_cmp_lt_i32_e32 vcc, 0, v145
	v_mov_b32_e32 v91, s15
	s_and_saveexec_b64 s[6:7], vcc
	s_cbranch_execz .Lhln7_m4
	v_cmp_eq_u32_e32 vcc, 1, v145
	s_mov_b64 s[8:9], 0
	s_and_saveexec_b64 s[14:15], vcc
	v_mov_b32_e32 v91, v92
	s_mov_b64 s[8:9], exec
	v_mov_b64_e32 v[76:77], v[90:91]
	s_or_b64 exec, exec, s[14:15]
	v_mov_b32_e32 v91, s10
	s_orn2_b64 s[8:9], s[8:9], exec

; __device__ __forceinline__ unsigned cvtpk(float lo, float hi) { f32x2_t v = {lo, hi}; bf16x2_t b = __builtin_convertvector(v, bf16x2_t); return __builtin_bit_cast(unsigned, b); }
;     ...
;         f32x4 v[NR][4]; float s[NR];
; #pragma unroll
;         for (int r = 0; r < NR; ++r) { s[r] = 0.f;
; #pragma unroll
;             for (int j = 0; j < 2; ++j) {
;                 v[r][2 * j][0] = __builtin_bit_cast(float, raw[r][j].x << 16); v[r][2 * j][1] = __builtin_bit_cast(float, raw[r][j].x & 0xffff0000u);
;                 v[r][2 * j][2] = __builtin_bit_cast(float, raw[r][j].y << 16); v[r][2 * j][3] = __builtin_bit_cast(float, raw[r][j].y & 0xffff0000u);
;                 v[r][2 * j + 1][0] = __builtin_bit_cast(float, raw[r][j].z << 16); v[r][2 * j + 1][1] = __builtin_bit_cast(float, raw[r][j].z & 0xffff0000u);
;                 v[r][2 * j + 1][2] = __builtin_bit_cast(float, raw[r][j].w << 16); v[r][2 * j + 1][3] = __builtin_bit_cast(float, raw[r][j].w & 0xffff0000u); } }
;         { const int nxt = pi + NP * pstep, pq = nxt < p1 ? nxt : pi;
; #pragma unroll
;           for (int r = 0; r < NR; ++r) { const bf16_t* pn = z + (size_t)rowr(pq, r) * DM;
; #pragma unroll
;               for (int j = 0; j < 2; ++j) raw[r][j] = *(const pg8::u32x4*)(pn + 8 * lane + 512 * j); } }
; #pragma unroll
;         for (int r = 0; r < NR; ++r)
; #pragma unroll
;             for (int j = 0; j < 4; ++j) s[r] += (v[r][j][0] + v[r][j][1]) + (v[r][j][2] + v[r][j][3]);
;         float mean[NR], q[NR], rstd[NR];
; #pragma unroll
;         for (int r = 0; r < NR; ++r) { mean[r] = wave_sum_dpp(s[r]) * (1.f / DM); q[r] = 0.f;
;     ...
;         for (int j = 0; j < 2; ++j) {
;             const int c = 8 * lane + 512 * j;
;             const f32x4 g0 = *(const f32x4*)(g + c), g1 = *(const f32x4*)(g + c + 4), b0 = *(const f32x4*)(b + c), b1 = *(const f32x4*)(b + c + 4);
; #pragma unroll
;             for (int r = 0; r < NR; ++r) {
;                 const f32x4 o0 = v[r][2 * j] * rstd[r] * g0 + b0, o1 = v[r][2 * j + 1] * rstd[r] * g1 + b1;
;                 if (MODE == 1) { pg8::u32x4 w; w.x = cvtpk(o0[0], o0[1]); w.y = cvtpk(o0[2], o0[3]); w.z = cvtpk(o1[0], o1[1]); w.w = cvtpk(o1[2], o1[3]); *(pg8::u32x4*)(hb + (size_t)row[r] * DM + c) = w; }
;                 else { *(f32x4*)(outf + (size_t)row[r] * DM + c) = o0; *(f32x4*)(outf + (size_t)row[r] * DM + c + 4) = o1; }
;             }
;         }
.Lhln7_t4:
	s_or_b64 exec, exec, s[6:7]
	s_add_i32 s0, s10, -1
	v_pk_mul_f32 v[74:75], v[74:75], v[94:95] op_sel_hi:[1,0]
	v_pk_mul_f32 v[72:73], v[72:73], v[94:95] op_sel_hi:[1,0]
	v_pk_mul_f32 v[76:77], v[80:81], v[94:95] op_sel_hi:[1,0]
	v_pk_mul_f32 v[78:79], v[78:79], v[94:95] op_sel_hi:[1,0]
	s_ashr_i32 s1, s0, 31
	v_pk_fma_f32 v[74:75], v[12:13], v[74:75], v[16:17]
	v_pk_fma_f32 v[72:73], v[10:11], v[72:73], v[14:15]
	v_pk_fma_f32 v[76:77], v[4:5], v[76:77], v[8:9]
	v_pk_fma_f32 v[78:79], v[2:3], v[78:79], v[6:7]
	s_lshl_b64 s[0:1], s[0:1], 11
	v_cvt_pk_bf16_f32 v72, v72, v73
	v_cvt_pk_bf16_f32 v73, v74, v75
	v_cvt_pk_bf16_f32 v74, v78, v79
	v_cvt_pk_bf16_f32 v75, v76, v77
	v_lshl_add_u64 v[76:77], v[52:53], 0, s[0:1]
	global_store_dwordx4 v[76:77], v[72:75], off
	v_pk_mul_f32 v[78:79], v[86:87], v[92:93] op_sel_hi:[1,0]
	s_ashr_i32 s11, s10, 31
	v_pk_mul_f32 v[72:73], v[84:85], v[92:93] op_sel_hi:[1,0]
	v_pk_mul_f32 v[74:75], v[82:83], v[92:93] op_sel_hi:[1,0]
	v_pk_fma_f32 v[76:77], v[12:13], v[72:73], v[16:17]
	v_pk_fma_f32 v[72:73], v[10:11], v[74:75], v[14:15]
	v_pk_mul_f32 v[74:75], v[88:89], v[92:93] op_sel_hi:[1,0]
	s_lshl_b64 s[6:7], s[10:11], 11
	v_pk_fma_f32 v[80:81], v[4:5], v[74:75], v[8:9]
	v_pk_fma_f32 v[74:75], v[2:3], v[78:79], v[6:7]
	v_cvt_pk_bf16_f32 v72, v72, v73
	v_cvt_pk_bf16_f32 v73, v76, v77
	v_cvt_pk_bf16_f32 v74, v74, v75
	v_cvt_pk_bf16_f32 v75, v80, v81
	v_lshl_add_u64 v[76:77], v[52:53], 0, s[6:7]
	v_pk_mul_f32 v[70:71], v[70:71], v[94:95] op_sel_hi:[1,0]
	v_pk_mul_f32 v[68:69], v[68:69], v[94:95] op_sel_hi:[1,0]
	v_pk_mul_f32 v[66:67], v[66:67], v[94:95] op_sel_hi:[1,0]
	v_pk_mul_f32 v[64:65], v[64:65], v[94:95] op_sel_hi:[1,0]
	global_store_dwordx4 v[76:77], v[72:75], off
	v_pk_fma_f32 v[70:71], v[28:29], v[70:71], v[32:33]
	v_pk_fma_f32 v[68:69], v[26:27], v[68:69], v[30:31]
	v_pk_fma_f32 v[72:73], v[20:21], v[66:67], v[24:25]
	v_pk_fma_f32 v[66:67], v[18:19], v[64:65], v[22:23]
	v_cvt_pk_bf16_f32 v64, v68, v69
	v_cvt_pk_bf16_f32 v65, v70, v71
	v_cvt_pk_bf16_f32 v66, v66, v67
	v_cvt_pk_bf16_f32 v67, v72, v73
	v_lshl_add_u64 v[68:69], v[54:55], 0, s[0:1]
	v_pk_mul_f32 v[62:63], v[62:63], v[92:93] op_sel_hi:[1,0]
	v_pk_mul_f32 v[58:59], v[58:59], v[92:93] op_sel_hi:[1,0]
	v_pk_mul_f32 v[60:61], v[60:61], v[92:93] op_sel_hi:[1,0]
	v_pk_mul_f32 v[56:57], v[56:57], v[92:93] op_sel_hi:[1,0]
	global_store_dwordx4 v[68:69], v[64:67], off
	v_pk_fma_f32 v[62:63], v[28:29], v[62:63], v[32:33]
	v_pk_fma_f32 v[58:59], v[26:27], v[58:59], v[30:31]
	v_pk_fma_f32 v[60:61], v[20:21], v[60:61], v[24:25]
	v_pk_fma_f32 v[64:65], v[18:19], v[56:57], v[22:23]
	v_cvt_pk_bf16_f32 v56, v58, v59
	v_cvt_pk_bf16_f32 v57, v62, v63
	v_cvt_pk_bf16_f32 v58, v64, v65
	v_cvt_pk_bf16_f32 v59, v60, v61
	v_lshl_add_u64 v[60:61], v[54:55], 0, s[6:7]
	s_andn2_b64 vcc, exec, s[12:13]
	s_addk_i32 s10, 0x200
	global_store_dwordx4 v[60:61], v[56:59], off
	s_cbranch_vccz .LBB0_680
	s_waitcnt vmcnt(20)
	v_lshlrev_b32_e32 v58, 16, v232
	v_and_b32_e32 v59, 0xffff0000, v232
	v_lshlrev_b32_e32 v62, 16, v233
	v_and_b32_e32 v63, 0xffff0000, v233
	v_lshlrev_b32_e32 v47, 16, v225
	v_lshlrev_b32_e32 v46, 16, v224
	v_and_b32_e32 v39, 0xffff0000, v225
	v_and_b32_e32 v38, 0xffff0000, v224
	v_lshlrev_b32_e32 v68, 16, v228
	v_and_b32_e32 v69, 0xffff0000, v228
	v_lshlrev_b32_e32 v64, 16, v230
	v_and_b32_e32 v82, 0xffff0000, v230
	v_lshlrev_b32_e32 v56, 16, v234
	v_and_b32_e32 v44, 0xffff0000, v234
	v_lshlrev_b32_e32 v60, 16, v235
	v_and_b32_e32 v42, 0xffff0000, v235
	v_pk_add_f32 v[48:49], v[46:47], v[38:39]
	v_lshlrev_b32_e32 v70, 16, v229
	v_and_b32_e32 v71, 0xffff0000, v229
	v_add_f32_e32 v43, v48, v49
	v_lshlrev_b32_e32 v49, 16, v227
	v_lshlrev_b32_e32 v48, 16, v226
	v_and_b32_e32 v41, 0xffff0000, v227
	v_and_b32_e32 v40, 0xffff0000, v226
	v_pk_add_f32 v[72:73], v[48:49], v[40:41]
	v_lshlrev_b32_e32 v66, 16, v231
	v_pk_add_f32 v[72:73], v[72:73], v[72:73] op_sel_hi:[0,1]
	v_and_b32_e32 v84, 0xffff0000, v231
	v_add_f32_e32 v85, 0, v43
	v_add_f32_e32 v65, v68, v69
	v_add_f32_e32 v83, v70, v71
	v_mov_b32_e32 v67, v73
	v_pk_add_f32 v[74:75], v[64:65], v[82:83]
	v_pk_add_f32 v[72:73], v[66:67], v[84:85]
	v_lshlrev_b32_e32 v87, 16, v221
	v_pk_add_f32 v[72:73], v[74:75], v[72:73]
	v_lshlrev_b32_e32 v86, 16, v220
	v_and_b32_e32 v35, 0xffff0000, v221
	v_and_b32_e32 v34, 0xffff0000, v220
	v_add_f32_e32 v65, v72, v73
	v_pk_add_f32 v[72:73], v[86:87], v[34:35]
	v_lshlrev_b32_e32 v97, 16, v223
	v_lshlrev_b32_e32 v96, 16, v222
	v_and_b32_e32 v37, 0xffff0000, v223
	v_and_b32_e32 v36, 0xffff0000, v222
	v_add_f32_e32 v57, v58, v59
	v_add_f32_e32 v45, v62, v63
	v_add_f32_e32 v43, v72, v73
	v_pk_add_f32 v[72:73], v[96:97], v[36:37]
	v_pk_add_f32 v[74:75], v[56:57], v[44:45]
	v_add_f32_dpp v45, v65, v65 row_ror:8 row_mask:0xf bank_mask:0xf bound_ctrl:1
	v_pk_add_f32 v[72:73], v[72:73], v[72:73] op_sel_hi:[0,1]
	v_add_f32_e32 v43, 0, v43
	v_add_f32_dpp v45, v45, v45 row_ror:4 row_mask:0xf bank_mask:0xf bound_ctrl:1
	v_mov_b32_e32 v61, v73
	v_pk_add_f32 v[72:73], v[60:61], v[42:43]
	v_add_f32_dpp v45, v45, v45 row_ror:2 row_mask:0xf bank_mask:0xf bound_ctrl:1
	v_pk_add_f32 v[72:73], v[74:75], v[72:73]
	s_lshl_b32 s12, s19, 6
	v_add_f32_dpp v45, v45, v45 row_ror:1 row_mask:0xf bank_mask:0xf bound_ctrl:1
	v_add_f32_e32 v43, v72, v73
	v_readlane_b32 s0, v45, 16
	v_readlane_b32 s2, v45, 48
	v_readlane_b32 s6, v45, 0
	v_readlane_b32 s7, v45, 32
	v_mov_b32_e32 v72, s0
	v_mov_b32_e32 v73, s2
	v_pk_add_f32 v[72:73], s[6:7], v[72:73]
	s_mov_b32 s1, s19
	v_add_f32_e32 v45, v72, v73
	v_fmac_f32_e32 v39, 0xba800000, v45
	v_fmac_f32_e32 v47, 0xba800000, v45
	v_fmac_f32_e32 v38, 0xba800000, v45
; __device__ __forceinline__ float wave_sum_dpp(float x) { x = rowsum16(x); return (rl(x, 0) + rl(x, 16)) + (rl(x, 32) + rl(x, 48)); }
;     ...
;         float mean[NR], q[NR], rstd[NR];
; #pragma unroll
;         for (int r = 0; r < NR; ++r) { mean[r] = wave_sum_dpp(s[r]) * (1.f / DM); q[r] = 0.f;
; #pragma unroll
;             for (int j = 0; j < 4; ++j) { v[r][j] = v[r][j] - mean[r]; q[r] += (v[r][j][0] * v[r][j][0] + v[r][j][1] * v[r][j][1]) + (v[r][j][2] * v[r][j][2] + v[r][j][3] * v[r][j][3]); } }
; #pragma unroll
;         for (int r = 0; r < NR; ++r) rstd[r] = 1.0f / sqrtf(wave_sum_dpp(q[r]) * (1.f / DM) + 1e-5f);
	v_fmac_f32_e32 v46, 0xba800000, v45
	v_mov_b32_e32 v74, v47
	v_mov_b32_e32 v78, v47
	v_mov_b32_e32 v79, v39
	v_mov_b32_e32 v47, v38
	v_mov_b32_e32 v73, v38
	v_mov_b32_e32 v75, v39
	v_pk_mul_f32 v[78:79], v[78:79], v[78:79]
	v_pk_mul_f32 v[38:39], v[46:47], v[46:47]
	v_mov_b32_e32 v72, v46
	v_pk_mov_b32 v[46:47], v[38:39], v[78:79] op_sel:[1,0]
	v_mov_b32_e32 v39, v79
	v_fmac_f32_e32 v41, 0xba800000, v45
	v_fmac_f32_e32 v49, 0xba800000, v45
	v_fmac_f32_e32 v40, 0xba800000, v45
	v_pk_add_f32 v[38:39], v[46:47], v[38:39]
	v_fmac_f32_e32 v48, 0xba800000, v45
	v_mov_b32_e32 v80, v49
	v_mov_b32_e32 v46, v49
	v_mov_b32_e32 v47, v41
	v_mov_b32_e32 v49, v40
	v_pk_add_f32 v[38:39], v[38:39], v[38:39] op_sel_hi:[0,1]
	v_mov_b32_e32 v79, v40
	v_mov_b32_e32 v81, v41
	v_pk_mul_f32 v[46:47], v[46:47], v[46:47]
	v_pk_mul_f32 v[40:41], v[48:49], v[48:49]
	v_fmac_f32_e32 v68, 0xba800000, v45
	v_mov_b32_e32 v78, v48
	v_pk_mov_b32 v[48:49], v[40:41], v[46:47] op_sel:[1,0]
	v_mov_b32_e32 v41, v47
	v_fmac_f32_e32 v70, 0xba800000, v45
	v_fmac_f32_e32 v69, 0xba800000, v45
	v_mul_f32_e32 v38, v68, v68
	v_pk_add_f32 v[40:41], v[48:49], v[40:41]
	v_fmac_f32_e32 v71, 0xba800000, v45
	v_pk_fma_f32 v[46:47], v[68:69], v[68:69], v[38:39] op_sel_hi:[1,1,0]
	v_mul_f32_e32 v38, v70, v70
	v_pk_add_f32 v[40:41], v[40:41], v[40:41] op_sel_hi:[0,1]
	v_pk_fma_f32 v[48:49], v[70:71], v[70:71], v[38:39] op_sel_hi:[1,1,0]
	v_fmac_f32_e32 v84, 0xba800000, v45
	v_fmac_f32_e32 v66, 0xba800000, v45
	v_fmac_f32_e32 v82, 0xba800000, v45
	v_fmac_f32_e32 v64, 0xba800000, v45
	v_mul_f32_e32 v46, v64, v64
	v_mul_f32_e32 v48, v82, v82
	v_mul_f32_e32 v38, v66, v66
	v_mul_f32_e32 v40, v84, v84
	v_pk_add_f32 v[46:47], v[46:47], v[48:49]
	v_pk_add_f32 v[38:39], v[38:39], v[40:41]
	v_mov_b32_e32 v67, v84
	v_pk_add_f32 v[38:39], v[46:47], v[38:39]
	s_or_b32 s15, s12, 62
	v_add_f32_e32 v40, v38, v39
	v_add_f32_dpp v38, v43, v43 row_ror:8 row_mask:0xf bank_mask:0xf bound_ctrl:1
	s_add_i32 s19, s19, 8
	s_cmp_ge_i32 s1, s5
	v_add_f32_dpp v38, v38, v38 row_ror:4 row_mask:0xf bank_mask:0xf bound_ctrl:1
	s_cselect_b64 s[12:13], -1, 0
	s_cmp_lt_i32 s1, s5
	v_add_f32_dpp v38, v38, v38 row_ror:2 row_mask:0xf bank_mask:0xf bound_ctrl:1
	s_cselect_b32 s1, s19, s1
	s_lshl_b32 s1, s1, 6
	v_add_f32_dpp v38, v38, v38 row_ror:1 row_mask:0xf bank_mask:0xf bound_ctrl:1
	s_or_b32 s20, s1, 62
	v_readlane_b32 s0, v38, 16
	v_readlane_b32 s2, v38, 48
	v_readlane_b32 s6, v38, 0
	v_readlane_b32 s7, v38, 32
	v_mov_b32_e32 v38, s0
	v_mov_b32_e32 v39, s2
	v_pk_add_f32 v[38:39], s[6:7], v[38:39]
	s_ashr_i32 s21, s20, 31
	v_add_f32_e32 v38, v38, v39
	v_fmac_f32_e32 v35, 0xba800000, v38
	v_fmac_f32_e32 v34, 0xba800000, v38
	v_fmac_f32_e32 v87, 0xba800000, v38
	v_fmac_f32_e32 v86, 0xba800000, v38
	v_mov_b32_e32 v83, v34
	v_mov_b32_e32 v85, v35
	v_mul_f32_e32 v34, v34, v34
	v_mul_f32_e32 v35, v35, v35
	v_fmac_f32_e32 v34, v86, v86
	v_fmac_f32_e32 v35, v87, v87
	v_fmac_f32_e32 v37, 0xba800000, v38
	v_fmac_f32_e32 v36, 0xba800000, v38
	v_mov_b32_e32 v84, v87
	v_add_f32_e32 v34, v34, v35
	v_fmac_f32_e32 v97, 0xba800000, v38
	v_fmac_f32_e32 v96, 0xba800000, v38
	v_mov_b32_e32 v87, v36
	v_mul_f32_e32 v35, v36, v36
	v_mul_f32_e32 v36, v37, v37
	v_fmac_f32_e32 v35, v96, v96
	v_fmac_f32_e32 v36, v97, v97
	v_add_f32_e32 v35, v35, v36
	v_fmac_f32_e32 v63, 0xba800000, v38
	v_fmac_f32_e32 v59, 0xba800000, v38
	v_add_f32_e32 v34, v34, v35
	v_fmac_f32_e32 v62, 0xba800000, v38
	v_fmac_f32_e32 v58, 0xba800000, v38
	v_mul_f32_e32 v35, v59, v59
	v_mul_f32_e32 v36, v63, v63
	v_fmac_f32_e32 v35, v58, v58
	v_fmac_f32_e32 v36, v62, v62
	v_add_f32_e32 v35, v35, v36
	v_fmac_f32_e32 v42, 0xba800000, v38
	v_fmac_f32_e32 v44, 0xba800000, v38
	v_add_f32_e32 v34, v35, v34
	v_fmac_f32_e32 v60, 0xba800000, v38
	v_fmac_f32_e32 v56, 0xba800000, v38
	v_mul_f32_e32 v35, v44, v44
	v_mul_f32_e32 v36, v42, v42
	v_fmac_f32_e32 v35, v56, v56
	v_fmac_f32_e32 v36, v60, v60
	v_add_f32_e32 v35, v35, v36
; __device__ __forceinline__ float wave_sum_dpp(float x) { x = rowsum16(x); return (rl(x, 0) + rl(x, 16)) + (rl(x, 32) + rl(x, 48)); }
;     ...
;         for (int r = 0; r < NR; ++r) { mean[r] = wave_sum_dpp(s[r]) * (1.f / DM); q[r] = 0.f;
; #pragma unroll
;             for (int j = 0; j < 4; ++j) { v[r][j] = v[r][j] - mean[r]; q[r] += (v[r][j][0] * v[r][j][0] + v[r][j][1] * v[r][j][1]) + (v[r][j][2] * v[r][j][2] + v[r][j][3] * v[r][j][3]); } }
; #pragma unroll
;         for (int r = 0; r < NR; ++r) rstd[r] = 1.0f / sqrtf(wave_sum_dpp(q[r]) * (1.f / DM) + 1e-5f);
;         if (MODE == 1) {
; #pragma unroll
;             for (int r = 0; r < NR; ++r) if (lane == r) { stats[2 * row[r]] = mean[r]; stats[2 * row[r] + 1] = rstd[r]; } }
	v_add_f32_e32 v34, v35, v34
	s_lshl_b64 s[20:21], s[20:21], 11
	v_add_f32_dpp v35, v40, v40 row_ror:8 row_mask:0xf bank_mask:0xf bound_ctrl:1
	v_add_f32_dpp v34, v34, v34 row_ror:8 row_mask:0xf bank_mask:0xf bound_ctrl:1
	v_mul_f32_e32 v76, 0x3a800000, v45
	v_add_f32_dpp v35, v35, v35 row_ror:4 row_mask:0xf bank_mask:0xf bound_ctrl:1
	v_add_f32_dpp v34, v34, v34 row_ror:4 row_mask:0xf bank_mask:0xf bound_ctrl:1
	v_mul_f32_e32 v90, 0x3a800000, v38
	v_add_f32_dpp v35, v35, v35 row_ror:2 row_mask:0xf bank_mask:0xf bound_ctrl:1
	v_add_f32_dpp v34, v34, v34 row_ror:2 row_mask:0xf bank_mask:0xf bound_ctrl:1
	v_mov_b32_e32 v89, v37
	v_add_f32_dpp v35, v35, v35 row_ror:1 row_mask:0xf bank_mask:0xf bound_ctrl:1
	v_add_f32_dpp v34, v34, v34 row_ror:1 row_mask:0xf bank_mask:0xf bound_ctrl:1
	v_readlane_b32 s6, v35, 0
	v_readlane_b32 s11, v35, 16
	v_readlane_b32 s7, v35, 32
	v_readlane_b32 s14, v35, 48
	v_readlane_b32 s0, v34, 0
	v_readlane_b32 s8, v34, 16
	v_readlane_b32 s2, v34, 32
	v_readlane_b32 s9, v34, 48
	v_lshl_add_u64 v[34:35], v[50:51], 0, s[20:21]
	s_or_b32 s20, s1, 63
	s_ashr_i32 s21, s20, 31
	s_lshl_b64 s[20:21], s[20:21], 11
	v_lshl_add_u64 v[46:47], v[50:51], 0, s[20:21]
	v_mov_b32_e32 v57, v44
	v_mov_b32_e32 v61, v42
	v_mov_b32_e32 v65, v82
	v_mov_b32_e32 v82, v86
	v_mov_b32_e32 v86, v96
	v_mov_b32_e32 v88, v97
	v_mov_b32_e32 v96, s11
	v_mov_b32_e32 v97, s14
	v_pk_add_f32 v[96:97], s[6:7], v[96:97]
	v_mov_b32_e32 v98, s9
	v_add_f32_e32 v77, v96, v97
	v_fmamk_f32 v77, v77, 0x3a800000, v93
	v_mul_f32_e32 v91, 0x4f800000, v77
	v_cmp_gt_f32_e32 vcc, s18, v77
	v_mov_b32_e32 v97, s8
	v_add_f32_e32 v97, s0, v97
	v_cndmask_b32_e32 v77, v77, v91, vcc
	v_sqrt_f32_e32 v91, v77
	v_add_f32_e32 v98, s2, v98
	v_add_f32_e32 v97, v97, v98
	v_fmamk_f32 v97, v97, 0x3a800000, v93
	v_add_u32_e32 v92, -1, v91
	v_fma_f32 v94, -v92, v91, v77
	v_cmp_ge_f32_e64 s[6:7], 0, v94
	v_add_u32_e32 v94, 1, v91
	v_mul_f32_e32 v98, 0x4f800000, v97
	v_cndmask_b32_e64 v92, v91, v92, s[6:7]
	v_fma_f32 v91, -v94, v91, v77
	v_cmp_lt_f32_e64 s[6:7], 0, v91
	s_nop 1
	v_cndmask_b32_e64 v91, v92, v94, s[6:7]
	v_mul_f32_e32 v92, 0x37800000, v91
	v_cndmask_b32_e32 v91, v91, v92, vcc
	v_cmp_class_f32_e32 vcc, v77, v95
	s_nop 1
	v_cndmask_b32_e32 v77, v91, v77, vcc
	v_div_scale_f32 v91, s[6:7], v77, v77, 1.0
	v_rcp_f32_e32 v92, v91
	v_cmp_gt_f32_e64 s[6:7], s18, v97
	v_fma_f32 v94, -v91, v92, 1.0
	s_nop 0
	v_cndmask_b32_e64 v97, v97, v98, s[6:7]
	v_fmac_f32_e32 v92, v94, v92
	v_div_scale_f32 v94, vcc, 1.0, v77, 1.0
	v_sqrt_f32_e32 v98, v97
	v_mul_f32_e32 v96, v94, v92
	v_fma_f32 v99, -v91, v96, v94
	v_fmac_f32_e32 v96, v99, v92
	v_fma_f32 v91, -v91, v96, v94
	v_add_u32_e32 v94, -1, v98
	v_fma_f32 v99, -v94, v98, v97
	v_cmp_ge_f32_e64 s[8:9], 0, v99
	v_add_u32_e32 v99, 1, v98
	v_div_fmas_f32 v91, v91, v92, v96
	v_cndmask_b32_e64 v94, v98, v94, s[8:9]
	v_fma_f32 v98, -v99, v98, v97
	v_cmp_lt_f32_e64 s[8:9], 0, v98
	s_nop 1
	v_cndmask_b32_e64 v94, v94, v99, s[8:9]
	v_mul_f32_e32 v98, 0x37800000, v94
	v_cndmask_b32_e64 v94, v94, v98, s[6:7]
	v_cmp_class_f32_e64 s[6:7], v97, v95
	s_mov_b64 s[8:9], -1
	s_nop 0
	v_cndmask_b32_e64 v97, v94, v97, s[6:7]
	v_div_scale_f32 v98, s[0:1], v97, v97, 1.0
	v_rcp_f32_e32 v99, v98
	v_div_fixup_f32 v94, v91, v77, 1.0
	v_fma_f32 v77, -v98, v99, 1.0
	v_fmac_f32_e32 v99, v77, v99
	v_div_scale_f32 v77, vcc, 1.0, v97, 1.0
	v_mul_f32_e32 v91, v77, v99
	v_fma_f32 v92, -v98, v91, v77
	v_fmac_f32_e32 v91, v92, v99
	v_fma_f32 v77, -v98, v91, v77
	v_div_fmas_f32 v77, v77, v99, v91
	v_div_fixup_f32 v92, v77, v97, 1.0
	v_mov_b32_e32 v77, v94
	v_cmp_lt_i32_e32 vcc, 0, v145
	v_mov_b32_e32 v91, s15
	s_and_saveexec_b64 s[6:7], vcc
	s_cbranch_execz .Lhln7_m5
	v_cmp_eq_u32_e32 vcc, 1, v145
	s_mov_b64 s[8:9], 0
	s_and_saveexec_b64 s[14:15], vcc
	v_mov_b32_e32 v91, v92
	s_mov_b64 s[8:9], exec
	v_mov_b64_e32 v[76:77], v[90:91]
	s_or_b64 exec, exec, s[14:15]
	v_mov_b32_e32 v91, s10
	s_orn2_b64 s[8:9], s[8:9], exec

; __device__ __forceinline__ unsigned cvtpk(float lo, float hi) { f32x2_t v = {lo, hi}; bf16x2_t b = __builtin_convertvector(v, bf16x2_t); return __builtin_bit_cast(unsigned, b); }
;     ...
;         f32x4 v[NR][4]; float s[NR];
; #pragma unroll
;         for (int r = 0; r < NR; ++r) { s[r] = 0.f;
; #pragma unroll
;             for (int j = 0; j < 2; ++j) {
;                 v[r][2 * j][0] = __builtin_bit_cast(float, raw[r][j].x << 16); v[r][2 * j][1] = __builtin_bit_cast(float, raw[r][j].x & 0xffff0000u);
;                 v[r][2 * j][2] = __builtin_bit_cast(float, raw[r][j].y << 16); v[r][2 * j][3] = __builtin_bit_cast(float, raw[r][j].y & 0xffff0000u);
;                 v[r][2 * j + 1][0] = __builtin_bit_cast(float, raw[r][j].z << 16); v[r][2 * j + 1][1] = __builtin_bit_cast(float, raw[r][j].z & 0xffff0000u);
;                 v[r][2 * j + 1][2] = __builtin_bit_cast(float, raw[r][j].w << 16); v[r][2 * j + 1][3] = __builtin_bit_cast(float, raw[r][j].w & 0xffff0000u); } }
;         { const int nxt = pi + NP * pstep, pq = nxt < p1 ? nxt : pi;
; #pragma unroll
;           for (int r = 0; r < NR; ++r) { const bf16_t* pn = z + (size_t)rowr(pq, r) * DM;
; #pragma unroll
;               for (int j = 0; j < 2; ++j) raw[r][j] = *(const pg8::u32x4*)(pn + 8 * lane + 512 * j); } }
; #pragma unroll
;         for (int r = 0; r < NR; ++r)
; #pragma unroll
;             for (int j = 0; j < 4; ++j) s[r] += (v[r][j][0] + v[r][j][1]) + (v[r][j][2] + v[r][j][3]);
;         float mean[NR], q[NR], rstd[NR];
; #pragma unroll
;         for (int r = 0; r < NR; ++r) { mean[r] = wave_sum_dpp(s[r]) * (1.f / DM); q[r] = 0.f;
;     ...
;         for (int j = 0; j < 2; ++j) {
;             const int c = 8 * lane + 512 * j;
;             const f32x4 g0 = *(const f32x4*)(g + c), g1 = *(const f32x4*)(g + c + 4), b0 = *(const f32x4*)(b + c), b1 = *(const f32x4*)(b + c + 4);
; #pragma unroll
;             for (int r = 0; r < NR; ++r) {
;                 const f32x4 o0 = v[r][2 * j] * rstd[r] * g0 + b0, o1 = v[r][2 * j + 1] * rstd[r] * g1 + b1;
;                 if (MODE == 1) { pg8::u32x4 w; w.x = cvtpk(o0[0], o0[1]); w.y = cvtpk(o0[2], o0[3]); w.z = cvtpk(o1[0], o1[1]); w.w = cvtpk(o1[2], o1[3]); *(pg8::u32x4*)(hb + (size_t)row[r] * DM + c) = w; }
;                 else { *(f32x4*)(outf + (size_t)row[r] * DM + c) = o0; *(f32x4*)(outf + (size_t)row[r] * DM + c + 4) = o1; }
;             }
;         }
.Lhln7_t5:
	s_or_b64 exec, exec, s[6:7]
	s_add_i32 s0, s10, -1
	v_pk_mul_f32 v[74:75], v[74:75], v[94:95] op_sel_hi:[1,0]
	v_pk_mul_f32 v[72:73], v[72:73], v[94:95] op_sel_hi:[1,0]
	v_pk_mul_f32 v[76:77], v[80:81], v[94:95] op_sel_hi:[1,0]
	v_pk_mul_f32 v[78:79], v[78:79], v[94:95] op_sel_hi:[1,0]
	s_ashr_i32 s1, s0, 31
	v_pk_fma_f32 v[74:75], v[12:13], v[74:75], v[16:17]
	v_pk_fma_f32 v[72:73], v[10:11], v[72:73], v[14:15]
	v_pk_fma_f32 v[76:77], v[4:5], v[76:77], v[8:9]
	v_pk_fma_f32 v[78:79], v[2:3], v[78:79], v[6:7]
	s_lshl_b64 s[0:1], s[0:1], 11
	v_cvt_pk_bf16_f32 v72, v72, v73
	v_cvt_pk_bf16_f32 v73, v74, v75
	v_cvt_pk_bf16_f32 v74, v78, v79
	v_cvt_pk_bf16_f32 v75, v76, v77
	v_lshl_add_u64 v[76:77], v[52:53], 0, s[0:1]
	global_store_dwordx4 v[76:77], v[72:75], off
	v_pk_mul_f32 v[78:79], v[86:87], v[92:93] op_sel_hi:[1,0]
	s_ashr_i32 s11, s10, 31
	v_pk_mul_f32 v[72:73], v[84:85], v[92:93] op_sel_hi:[1,0]
	v_pk_mul_f32 v[74:75], v[82:83], v[92:93] op_sel_hi:[1,0]
	v_pk_fma_f32 v[76:77], v[12:13], v[72:73], v[16:17]
	v_pk_fma_f32 v[72:73], v[10:11], v[74:75], v[14:15]
	v_pk_mul_f32 v[74:75], v[88:89], v[92:93] op_sel_hi:[1,0]
	s_lshl_b64 s[6:7], s[10:11], 11
	v_pk_fma_f32 v[80:81], v[4:5], v[74:75], v[8:9]
	v_pk_fma_f32 v[74:75], v[2:3], v[78:79], v[6:7]
	v_cvt_pk_bf16_f32 v72, v72, v73
	v_cvt_pk_bf16_f32 v73, v76, v77
	v_cvt_pk_bf16_f32 v74, v74, v75
	v_cvt_pk_bf16_f32 v75, v80, v81
	v_lshl_add_u64 v[76:77], v[52:53], 0, s[6:7]
	v_pk_mul_f32 v[70:71], v[70:71], v[94:95] op_sel_hi:[1,0]
	v_pk_mul_f32 v[68:69], v[68:69], v[94:95] op_sel_hi:[1,0]
	v_pk_mul_f32 v[66:67], v[66:67], v[94:95] op_sel_hi:[1,0]
	v_pk_mul_f32 v[64:65], v[64:65], v[94:95] op_sel_hi:[1,0]
	global_store_dwordx4 v[76:77], v[72:75], off
	v_pk_fma_f32 v[70:71], v[28:29], v[70:71], v[32:33]
	v_pk_fma_f32 v[68:69], v[26:27], v[68:69], v[30:31]
	v_pk_fma_f32 v[72:73], v[20:21], v[66:67], v[24:25]
	v_pk_fma_f32 v[66:67], v[18:19], v[64:65], v[22:23]
	v_cvt_pk_bf16_f32 v64, v68, v69
	v_cvt_pk_bf16_f32 v65, v70, v71
	v_cvt_pk_bf16_f32 v66, v66, v67
	v_cvt_pk_bf16_f32 v67, v72, v73
	v_lshl_add_u64 v[68:69], v[54:55], 0, s[0:1]
	v_pk_mul_f32 v[62:63], v[62:63], v[92:93] op_sel_hi:[1,0]
	v_pk_mul_f32 v[58:59], v[58:59], v[92:93] op_sel_hi:[1,0]
	v_pk_mul_f32 v[60:61], v[60:61], v[92:93] op_sel_hi:[1,0]
	v_pk_mul_f32 v[56:57], v[56:57], v[92:93] op_sel_hi:[1,0]
	global_store_dwordx4 v[68:69], v[64:67], off
	v_pk_fma_f32 v[62:63], v[28:29], v[62:63], v[32:33]
	v_pk_fma_f32 v[58:59], v[26:27], v[58:59], v[30:31]
	v_pk_fma_f32 v[60:61], v[20:21], v[60:61], v[24:25]
	v_pk_fma_f32 v[64:65], v[18:19], v[56:57], v[22:23]
	v_cvt_pk_bf16_f32 v56, v58, v59
	v_cvt_pk_bf16_f32 v57, v62, v63
	v_cvt_pk_bf16_f32 v58, v64, v65
	v_cvt_pk_bf16_f32 v59, v60, v61
	v_lshl_add_u64 v[60:61], v[54:55], 0, s[6:7]
	s_andn2_b64 vcc, exec, s[12:13]
	s_addk_i32 s10, 0x200
	global_store_dwordx4 v[60:61], v[56:59], off
	s_cbranch_vccz .LBB0_680
	s_waitcnt vmcnt(20)
	v_lshlrev_b32_e32 v58, 16, v248
	v_and_b32_e32 v59, 0xffff0000, v248
	v_lshlrev_b32_e32 v62, 16, v249
	v_and_b32_e32 v63, 0xffff0000, v249
	v_lshlrev_b32_e32 v47, 16, v241
	v_lshlrev_b32_e32 v46, 16, v240
	v_and_b32_e32 v39, 0xffff0000, v241
	v_and_b32_e32 v38, 0xffff0000, v240
	v_lshlrev_b32_e32 v68, 16, v244
	v_and_b32_e32 v69, 0xffff0000, v244
	v_lshlrev_b32_e32 v64, 16, v246
	v_and_b32_e32 v82, 0xffff0000, v246
	v_lshlrev_b32_e32 v56, 16, v250
	v_and_b32_e32 v44, 0xffff0000, v250
	v_lshlrev_b32_e32 v60, 16, v251
	v_and_b32_e32 v42, 0xffff0000, v251
	v_pk_add_f32 v[48:49], v[46:47], v[38:39]
	v_lshlrev_b32_e32 v70, 16, v245
	v_and_b32_e32 v71, 0xffff0000, v245
	v_add_f32_e32 v43, v48, v49
	v_lshlrev_b32_e32 v49, 16, v243
	v_lshlrev_b32_e32 v48, 16, v242
	v_and_b32_e32 v41, 0xffff0000, v243
	v_and_b32_e32 v40, 0xffff0000, v242
	v_pk_add_f32 v[72:73], v[48:49], v[40:41]
	v_lshlrev_b32_e32 v66, 16, v247
	v_pk_add_f32 v[72:73], v[72:73], v[72:73] op_sel_hi:[0,1]
	v_and_b32_e32 v84, 0xffff0000, v247
	v_add_f32_e32 v85, 0, v43
	v_add_f32_e32 v65, v68, v69
	v_add_f32_e32 v83, v70, v71
	v_mov_b32_e32 v67, v73
	v_pk_add_f32 v[74:75], v[64:65], v[82:83]
	v_pk_add_f32 v[72:73], v[66:67], v[84:85]
	v_lshlrev_b32_e32 v87, 16, v237
	v_pk_add_f32 v[72:73], v[74:75], v[72:73]
	v_lshlrev_b32_e32 v86, 16, v236
	v_and_b32_e32 v35, 0xffff0000, v237
	v_and_b32_e32 v34, 0xffff0000, v236
	v_add_f32_e32 v65, v72, v73
	v_pk_add_f32 v[72:73], v[86:87], v[34:35]
	v_lshlrev_b32_e32 v97, 16, v239
	v_lshlrev_b32_e32 v96, 16, v238
	v_and_b32_e32 v37, 0xffff0000, v239
	v_and_b32_e32 v36, 0xffff0000, v238
	v_add_f32_e32 v57, v58, v59
	v_add_f32_e32 v45, v62, v63
	v_add_f32_e32 v43, v72, v73
	v_pk_add_f32 v[72:73], v[96:97], v[36:37]
	v_pk_add_f32 v[74:75], v[56:57], v[44:45]
	v_add_f32_dpp v45, v65, v65 row_ror:8 row_mask:0xf bank_mask:0xf bound_ctrl:1
	v_pk_add_f32 v[72:73], v[72:73], v[72:73] op_sel_hi:[0,1]
	v_add_f32_e32 v43, 0, v43
	v_add_f32_dpp v45, v45, v45 row_ror:4 row_mask:0xf bank_mask:0xf bound_ctrl:1
	v_mov_b32_e32 v61, v73
	v_pk_add_f32 v[72:73], v[60:61], v[42:43]
	v_add_f32_dpp v45, v45, v45 row_ror:2 row_mask:0xf bank_mask:0xf bound_ctrl:1
	v_pk_add_f32 v[72:73], v[74:75], v[72:73]
	s_lshl_b32 s12, s19, 6
	v_add_f32_dpp v45, v45, v45 row_ror:1 row_mask:0xf bank_mask:0xf bound_ctrl:1
	v_add_f32_e32 v43, v72, v73
	v_readlane_b32 s0, v45, 16
	v_readlane_b32 s2, v45, 48
	v_readlane_b32 s6, v45, 0
	v_readlane_b32 s7, v45, 32
	v_mov_b32_e32 v72, s0
	v_mov_b32_e32 v73, s2
	v_pk_add_f32 v[72:73], s[6:7], v[72:73]
	s_mov_b32 s1, s19
	v_add_f32_e32 v45, v72, v73
	v_fmac_f32_e32 v39, 0xba800000, v45
	v_fmac_f32_e32 v47, 0xba800000, v45
	v_fmac_f32_e32 v38, 0xba800000, v45
; __device__ __forceinline__ float wave_sum_dpp(float x) { x = rowsum16(x); return (rl(x, 0) + rl(x, 16)) + (rl(x, 32) + rl(x, 48)); }
;     ...
;         float mean[NR], q[NR], rstd[NR];
; #pragma unroll
;         for (int r = 0; r < NR; ++r) { mean[r] = wave_sum_dpp(s[r]) * (1.f / DM); q[r] = 0.f;
; #pragma unroll
;             for (int j = 0; j < 4; ++j) { v[r][j] = v[r][j] - mean[r]; q[r] += (v[r][j][0] * v[r][j][0] + v[r][j][1] * v[r][j][1]) + (v[r][j][2] * v[r][j][2] + v[r][j][3] * v[r][j][3]); } }
; #pragma unroll
;         for (int r = 0; r < NR; ++r) rstd[r] = 1.0f / sqrtf(wave_sum_dpp(q[r]) * (1.f / DM) + 1e-5f);
	v_fmac_f32_e32 v46, 0xba800000, v45
	v_mov_b32_e32 v74, v47
	v_mov_b32_e32 v78, v47
	v_mov_b32_e32 v79, v39
	v_mov_b32_e32 v47, v38
	v_mov_b32_e32 v73, v38
	v_mov_b32_e32 v75, v39
	v_pk_mul_f32 v[78:79], v[78:79], v[78:79]
	v_pk_mul_f32 v[38:39], v[46:47], v[46:47]
	v_mov_b32_e32 v72, v46
	v_pk_mov_b32 v[46:47], v[38:39], v[78:79] op_sel:[1,0]
	v_mov_b32_e32 v39, v79
	v_fmac_f32_e32 v41, 0xba800000, v45
	v_fmac_f32_e32 v49, 0xba800000, v45
	v_fmac_f32_e32 v40, 0xba800000, v45
	v_pk_add_f32 v[38:39], v[46:47], v[38:39]
	v_fmac_f32_e32 v48, 0xba800000, v45
	v_mov_b32_e32 v80, v49
	v_mov_b32_e32 v46, v49
	v_mov_b32_e32 v47, v41
	v_mov_b32_e32 v49, v40
	v_pk_add_f32 v[38:39], v[38:39], v[38:39] op_sel_hi:[0,1]
	v_mov_b32_e32 v79, v40
	v_mov_b32_e32 v81, v41
	v_pk_mul_f32 v[46:47], v[46:47], v[46:47]
	v_pk_mul_f32 v[40:41], v[48:49], v[48:49]
	v_fmac_f32_e32 v68, 0xba800000, v45
	v_mov_b32_e32 v78, v48
	v_pk_mov_b32 v[48:49], v[40:41], v[46:47] op_sel:[1,0]
	v_mov_b32_e32 v41, v47
	v_fmac_f32_e32 v70, 0xba800000, v45
	v_fmac_f32_e32 v69, 0xba800000, v45
	v_mul_f32_e32 v38, v68, v68
	v_pk_add_f32 v[40:41], v[48:49], v[40:41]
	v_fmac_f32_e32 v71, 0xba800000, v45
	v_pk_fma_f32 v[46:47], v[68:69], v[68:69], v[38:39] op_sel_hi:[1,1,0]
	v_mul_f32_e32 v38, v70, v70
	v_pk_add_f32 v[40:41], v[40:41], v[40:41] op_sel_hi:[0,1]
	v_pk_fma_f32 v[48:49], v[70:71], v[70:71], v[38:39] op_sel_hi:[1,1,0]
	v_fmac_f32_e32 v84, 0xba800000, v45
	v_fmac_f32_e32 v66, 0xba800000, v45
	v_fmac_f32_e32 v82, 0xba800000, v45
	v_fmac_f32_e32 v64, 0xba800000, v45
	v_mul_f32_e32 v46, v64, v64
	v_mul_f32_e32 v48, v82, v82
	v_mul_f32_e32 v38, v66, v66
	v_mul_f32_e32 v40, v84, v84
	v_pk_add_f32 v[46:47], v[46:47], v[48:49]
	v_pk_add_f32 v[38:39], v[38:39], v[40:41]
	v_mov_b32_e32 v67, v84
	v_pk_add_f32 v[38:39], v[46:47], v[38:39]
	s_or_b32 s15, s12, 62
	v_add_f32_e32 v40, v38, v39
	v_add_f32_dpp v38, v43, v43 row_ror:8 row_mask:0xf bank_mask:0xf bound_ctrl:1
	s_add_i32 s19, s19, 8
	s_cmp_ge_i32 s1, s5
	v_add_f32_dpp v38, v38, v38 row_ror:4 row_mask:0xf bank_mask:0xf bound_ctrl:1
	s_cselect_b64 s[12:13], -1, 0
	s_cmp_lt_i32 s1, s5
	v_add_f32_dpp v38, v38, v38 row_ror:2 row_mask:0xf bank_mask:0xf bound_ctrl:1
	s_cselect_b32 s1, s19, s1
	s_lshl_b32 s1, s1, 6
	v_add_f32_dpp v38, v38, v38 row_ror:1 row_mask:0xf bank_mask:0xf bound_ctrl:1
	s_or_b32 s20, s1, 62
	v_readlane_b32 s0, v38, 16
	v_readlane_b32 s2, v38, 48
	v_readlane_b32 s6, v38, 0
	v_readlane_b32 s7, v38, 32
	v_mov_b32_e32 v38, s0
	v_mov_b32_e32 v39, s2
	v_pk_add_f32 v[38:39], s[6:7], v[38:39]
	s_ashr_i32 s21, s20, 31
	v_add_f32_e32 v38, v38, v39
	v_fmac_f32_e32 v35, 0xba800000, v38
	v_fmac_f32_e32 v34, 0xba800000, v38
	v_fmac_f32_e32 v87, 0xba800000, v38
	v_fmac_f32_e32 v86, 0xba800000, v38
	v_mov_b32_e32 v83, v34
	v_mov_b32_e32 v85, v35
	v_mul_f32_e32 v34, v34, v34
	v_mul_f32_e32 v35, v35, v35
	v_fmac_f32_e32 v34, v86, v86
	v_fmac_f32_e32 v35, v87, v87
	v_fmac_f32_e32 v37, 0xba800000, v38
	v_fmac_f32_e32 v36, 0xba800000, v38
	v_mov_b32_e32 v84, v87
	v_add_f32_e32 v34, v34, v35
	v_fmac_f32_e32 v97, 0xba800000, v38
	v_fmac_f32_e32 v96, 0xba800000, v38
	v_mov_b32_e32 v87, v36
	v_mul_f32_e32 v35, v36, v36
	v_mul_f32_e32 v36, v37, v37
	v_fmac_f32_e32 v35, v96, v96
	v_fmac_f32_e32 v36, v97, v97
	v_add_f32_e32 v35, v35, v36
	v_fmac_f32_e32 v63, 0xba800000, v38
	v_fmac_f32_e32 v59, 0xba800000, v38
	v_add_f32_e32 v34, v34, v35
	v_fmac_f32_e32 v62, 0xba800000, v38
	v_fmac_f32_e32 v58, 0xba800000, v38
	v_mul_f32_e32 v35, v59, v59
	v_mul_f32_e32 v36, v63, v63
	v_fmac_f32_e32 v35, v58, v58
	v_fmac_f32_e32 v36, v62, v62
	v_add_f32_e32 v35, v35, v36
	v_fmac_f32_e32 v42, 0xba800000, v38
	v_fmac_f32_e32 v44, 0xba800000, v38
	v_add_f32_e32 v34, v35, v34
	v_fmac_f32_e32 v60, 0xba800000, v38
	v_fmac_f32_e32 v56, 0xba800000, v38
	v_mul_f32_e32 v35, v44, v44
	v_mul_f32_e32 v36, v42, v42
	v_fmac_f32_e32 v35, v56, v56
	v_fmac_f32_e32 v36, v60, v60
	v_add_f32_e32 v35, v35, v36
; __device__ __forceinline__ float wave_sum_dpp(float x) { x = rowsum16(x); return (rl(x, 0) + rl(x, 16)) + (rl(x, 32) + rl(x, 48)); }
;     ...
;         for (int r = 0; r < NR; ++r) { mean[r] = wave_sum_dpp(s[r]) * (1.f / DM); q[r] = 0.f;
; #pragma unroll
;             for (int j = 0; j < 4; ++j) { v[r][j] = v[r][j] - mean[r]; q[r] += (v[r][j][0] * v[r][j][0] + v[r][j][1] * v[r][j][1]) + (v[r][j][2] * v[r][j][2] + v[r][j][3] * v[r][j][3]); } }
; #pragma unroll
;         for (int r = 0; r < NR; ++r) rstd[r] = 1.0f / sqrtf(wave_sum_dpp(q[r]) * (1.f / DM) + 1e-5f);
;         if (MODE == 1) {
; #pragma unroll
;             for (int r = 0; r < NR; ++r) if (lane == r) { stats[2 * row[r]] = mean[r]; stats[2 * row[r] + 1] = rstd[r]; } }
	v_add_f32_e32 v34, v35, v34
	s_lshl_b64 s[20:21], s[20:21], 11
	v_add_f32_dpp v35, v40, v40 row_ror:8 row_mask:0xf bank_mask:0xf bound_ctrl:1
	v_add_f32_dpp v34, v34, v34 row_ror:8 row_mask:0xf bank_mask:0xf bound_ctrl:1
	v_mul_f32_e32 v76, 0x3a800000, v45
	v_add_f32_dpp v35, v35, v35 row_ror:4 row_mask:0xf bank_mask:0xf bound_ctrl:1
	v_add_f32_dpp v34, v34, v34 row_ror:4 row_mask:0xf bank_mask:0xf bound_ctrl:1
	v_mul_f32_e32 v90, 0x3a800000, v38
	v_add_f32_dpp v35, v35, v35 row_ror:2 row_mask:0xf bank_mask:0xf bound_ctrl:1
	v_add_f32_dpp v34, v34, v34 row_ror:2 row_mask:0xf bank_mask:0xf bound_ctrl:1
	v_mov_b32_e32 v89, v37
	v_add_f32_dpp v35, v35, v35 row_ror:1 row_mask:0xf bank_mask:0xf bound_ctrl:1
	v_add_f32_dpp v34, v34, v34 row_ror:1 row_mask:0xf bank_mask:0xf bound_ctrl:1
	v_readlane_b32 s6, v35, 0
	v_readlane_b32 s11, v35, 16
	v_readlane_b32 s7, v35, 32
	v_readlane_b32 s14, v35, 48
	v_readlane_b32 s0, v34, 0
	v_readlane_b32 s8, v34, 16
	v_readlane_b32 s2, v34, 32
	v_readlane_b32 s9, v34, 48
	v_lshl_add_u64 v[34:35], v[50:51], 0, s[20:21]
	s_or_b32 s20, s1, 63
	s_ashr_i32 s21, s20, 31
	s_lshl_b64 s[20:21], s[20:21], 11
	v_lshl_add_u64 v[46:47], v[50:51], 0, s[20:21]
	v_mov_b32_e32 v57, v44
	v_mov_b32_e32 v61, v42
	v_mov_b32_e32 v65, v82
	v_mov_b32_e32 v82, v86
	v_mov_b32_e32 v86, v96
	v_mov_b32_e32 v88, v97
	v_mov_b32_e32 v96, s11
	v_mov_b32_e32 v97, s14
	v_pk_add_f32 v[96:97], s[6:7], v[96:97]
	v_mov_b32_e32 v98, s9
	v_add_f32_e32 v77, v96, v97
	v_fmamk_f32 v77, v77, 0x3a800000, v93
	v_mul_f32_e32 v91, 0x4f800000, v77
	v_cmp_gt_f32_e32 vcc, s18, v77
	v_mov_b32_e32 v97, s8
	v_add_f32_e32 v97, s0, v97
	v_cndmask_b32_e32 v77, v77, v91, vcc
	v_sqrt_f32_e32 v91, v77
	v_add_f32_e32 v98, s2, v98
	v_add_f32_e32 v97, v97, v98
	v_fmamk_f32 v97, v97, 0x3a800000, v93
	v_add_u32_e32 v92, -1, v91
	v_fma_f32 v94, -v92, v91, v77
	v_cmp_ge_f32_e64 s[6:7], 0, v94
	v_add_u32_e32 v94, 1, v91
	v_mul_f32_e32 v98, 0x4f800000, v97
	v_cndmask_b32_e64 v92, v91, v92, s[6:7]
	v_fma_f32 v91, -v94, v91, v77
	v_cmp_lt_f32_e64 s[6:7], 0, v91
	s_nop 1
	v_cndmask_b32_e64 v91, v92, v94, s[6:7]
	v_mul_f32_e32 v92, 0x37800000, v91
	v_cndmask_b32_e32 v91, v91, v92, vcc
	v_cmp_class_f32_e32 vcc, v77, v95
	s_nop 1
	v_cndmask_b32_e32 v77, v91, v77, vcc
	v_div_scale_f32 v91, s[6:7], v77, v77, 1.0
	v_rcp_f32_e32 v92, v91
	v_cmp_gt_f32_e64 s[6:7], s18, v97
	v_fma_f32 v94, -v91, v92, 1.0
	s_nop 0
	v_cndmask_b32_e64 v97, v97, v98, s[6:7]
	v_fmac_f32_e32 v92, v94, v92
	v_div_scale_f32 v94, vcc, 1.0, v77, 1.0
	v_sqrt_f32_e32 v98, v97
	v_mul_f32_e32 v96, v94, v92
	v_fma_f32 v99, -v91, v96, v94
	v_fmac_f32_e32 v96, v99, v92
	v_fma_f32 v91, -v91, v96, v94
	v_add_u32_e32 v94, -1, v98
	v_fma_f32 v99, -v94, v98, v97
	v_cmp_ge_f32_e64 s[8:9], 0, v99
	v_add_u32_e32 v99, 1, v98
	v_div_fmas_f32 v91, v91, v92, v96
	v_cndmask_b32_e64 v94, v98, v94, s[8:9]
	v_fma_f32 v98, -v99, v98, v97
	v_cmp_lt_f32_e64 s[8:9], 0, v98
	s_nop 1
	v_cndmask_b32_e64 v94, v94, v99, s[8:9]
	v_mul_f32_e32 v98, 0x37800000, v94
	v_cndmask_b32_e64 v94, v94, v98, s[6:7]
	v_cmp_class_f32_e64 s[6:7], v97, v95
	s_mov_b64 s[8:9], -1
	s_nop 0
	v_cndmask_b32_e64 v97, v94, v97, s[6:7]
	v_div_scale_f32 v98, s[0:1], v97, v97, 1.0
	v_rcp_f32_e32 v99, v98
	v_div_fixup_f32 v94, v91, v77, 1.0
	v_fma_f32 v77, -v98, v99, 1.0
	v_fmac_f32_e32 v99, v77, v99
	v_div_scale_f32 v77, vcc, 1.0, v97, 1.0
	v_mul_f32_e32 v91, v77, v99
	v_fma_f32 v92, -v98, v91, v77
	v_fmac_f32_e32 v91, v92, v99
	v_fma_f32 v77, -v98, v91, v77
	v_div_fmas_f32 v77, v77, v99, v91
	v_div_fixup_f32 v92, v77, v97, 1.0
	v_mov_b32_e32 v77, v94
	v_cmp_lt_i32_e32 vcc, 0, v145
	v_mov_b32_e32 v91, s15
	s_and_saveexec_b64 s[6:7], vcc
	s_cbranch_execz .Lhln7_m6
	v_cmp_eq_u32_e32 vcc, 1, v145
	s_mov_b64 s[8:9], 0
	s_and_saveexec_b64 s[14:15], vcc
	v_mov_b32_e32 v91, v92
	s_mov_b64 s[8:9], exec
	v_mov_b64_e32 v[76:77], v[90:91]
	s_or_b64 exec, exec, s[14:15]
	v_mov_b32_e32 v91, s10
	s_orn2_b64 s[8:9], s[8:9], exec

; __device__ __forceinline__ unsigned cvtpk(float lo, float hi) { f32x2_t v = {lo, hi}; bf16x2_t b = __builtin_convertvector(v, bf16x2_t); return __builtin_bit_cast(unsigned, b); }
;     ...
;         f32x4 v[NR][4]; float s[NR];
; #pragma unroll
;         for (int r = 0; r < NR; ++r) { s[r] = 0.f;
; #pragma unroll
;             for (int j = 0; j < 2; ++j) {
;                 v[r][2 * j][0] = __builtin_bit_cast(float, raw[r][j].x << 16); v[r][2 * j][1] = __builtin_bit_cast(float, raw[r][j].x & 0xffff0000u);
;                 v[r][2 * j][2] = __builtin_bit_cast(float, raw[r][j].y << 16); v[r][2 * j][3] = __builtin_bit_cast(float, raw[r][j].y & 0xffff0000u);
;                 v[r][2 * j + 1][0] = __builtin_bit_cast(float, raw[r][j].z << 16); v[r][2 * j + 1][1] = __builtin_bit_cast(float, raw[r][j].z & 0xffff0000u);
;                 v[r][2 * j + 1][2] = __builtin_bit_cast(float, raw[r][j].w << 16); v[r][2 * j + 1][3] = __builtin_bit_cast(float, raw[r][j].w & 0xffff0000u); } }
;         { const int nxt = pi + NP * pstep, pq = nxt < p1 ? nxt : pi;
; #pragma unroll
;           for (int r = 0; r < NR; ++r) { const bf16_t* pn = z + (size_t)rowr(pq, r) * DM;
; #pragma unroll
;               for (int j = 0; j < 2; ++j) raw[r][j] = *(const pg8::u32x4*)(pn + 8 * lane + 512 * j); } }
; #pragma unroll
;         for (int r = 0; r < NR; ++r)
; #pragma unroll
;             for (int j = 0; j < 4; ++j) s[r] += (v[r][j][0] + v[r][j][1]) + (v[r][j][2] + v[r][j][3]);
;         float mean[NR], q[NR], rstd[NR];
; #pragma unroll
;         for (int r = 0; r < NR; ++r) { mean[r] = wave_sum_dpp(s[r]) * (1.f / DM); q[r] = 0.f;
;     ...
;         for (int j = 0; j < 2; ++j) {
;             const int c = 8 * lane + 512 * j;
;             const f32x4 g0 = *(const f32x4*)(g + c), g1 = *(const f32x4*)(g + c + 4), b0 = *(const f32x4*)(b + c), b1 = *(const f32x4*)(b + c + 4);
; #pragma unroll
;             for (int r = 0; r < NR; ++r) {
;                 const f32x4 o0 = v[r][2 * j] * rstd[r] * g0 + b0, o1 = v[r][2 * j + 1] * rstd[r] * g1 + b1;
;                 if (MODE == 1) { pg8::u32x4 w; w.x = cvtpk(o0[0], o0[1]); w.y = cvtpk(o0[2], o0[3]); w.z = cvtpk(o1[0], o1[1]); w.w = cvtpk(o1[2], o1[3]); *(pg8::u32x4*)(hb + (size_t)row[r] * DM + c) = w; }
;                 else { *(f32x4*)(outf + (size_t)row[r] * DM + c) = o0; *(f32x4*)(outf + (size_t)row[r] * DM + c + 4) = o1; }
;             }
;         }
.Lhln7_t6:
	s_or_b64 exec, exec, s[6:7]
	s_add_i32 s0, s10, -1
	v_pk_mul_f32 v[74:75], v[74:75], v[94:95] op_sel_hi:[1,0]
	v_pk_mul_f32 v[72:73], v[72:73], v[94:95] op_sel_hi:[1,0]
	v_pk_mul_f32 v[76:77], v[80:81], v[94:95] op_sel_hi:[1,0]
	v_pk_mul_f32 v[78:79], v[78:79], v[94:95] op_sel_hi:[1,0]
	s_ashr_i32 s1, s0, 31
	v_pk_fma_f32 v[74:75], v[12:13], v[74:75], v[16:17]
	v_pk_fma_f32 v[72:73], v[10:11], v[72:73], v[14:15]
	v_pk_fma_f32 v[76:77], v[4:5], v[76:77], v[8:9]
	v_pk_fma_f32 v[78:79], v[2:3], v[78:79], v[6:7]
	s_lshl_b64 s[0:1], s[0:1], 11
	v_cvt_pk_bf16_f32 v72, v72, v73
	v_cvt_pk_bf16_f32 v73, v74, v75
	v_cvt_pk_bf16_f32 v74, v78, v79
	v_cvt_pk_bf16_f32 v75, v76, v77
	v_lshl_add_u64 v[76:77], v[52:53], 0, s[0:1]
	global_store_dwordx4 v[76:77], v[72:75], off
	v_pk_mul_f32 v[78:79], v[86:87], v[92:93] op_sel_hi:[1,0]
	s_ashr_i32 s11, s10, 31
	v_pk_mul_f32 v[72:73], v[84:85], v[92:93] op_sel_hi:[1,0]
	v_pk_mul_f32 v[74:75], v[82:83], v[92:93] op_sel_hi:[1,0]
	v_pk_fma_f32 v[76:77], v[12:13], v[72:73], v[16:17]
	v_pk_fma_f32 v[72:73], v[10:11], v[74:75], v[14:15]
	v_pk_mul_f32 v[74:75], v[88:89], v[92:93] op_sel_hi:[1,0]
	s_lshl_b64 s[6:7], s[10:11], 11
	v_pk_fma_f32 v[80:81], v[4:5], v[74:75], v[8:9]
	v_pk_fma_f32 v[74:75], v[2:3], v[78:79], v[6:7]
	v_cvt_pk_bf16_f32 v72, v72, v73
	v_cvt_pk_bf16_f32 v73, v76, v77
	v_cvt_pk_bf16_f32 v74, v74, v75
	v_cvt_pk_bf16_f32 v75, v80, v81
	v_lshl_add_u64 v[76:77], v[52:53], 0, s[6:7]
	v_pk_mul_f32 v[70:71], v[70:71], v[94:95] op_sel_hi:[1,0]
	v_pk_mul_f32 v[68:69], v[68:69], v[94:95] op_sel_hi:[1,0]
	v_pk_mul_f32 v[66:67], v[66:67], v[94:95] op_sel_hi:[1,0]
	v_pk_mul_f32 v[64:65], v[64:65], v[94:95] op_sel_hi:[1,0]
	global_store_dwordx4 v[76:77], v[72:75], off
	v_pk_fma_f32 v[70:71], v[28:29], v[70:71], v[32:33]
	v_pk_fma_f32 v[68:69], v[26:27], v[68:69], v[30:31]
	v_pk_fma_f32 v[72:73], v[20:21], v[66:67], v[24:25]
	v_pk_fma_f32 v[66:67], v[18:19], v[64:65], v[22:23]
	v_cvt_pk_bf16_f32 v64, v68, v69
	v_cvt_pk_bf16_f32 v65, v70, v71
	v_cvt_pk_bf16_f32 v66, v66, v67
	v_cvt_pk_bf16_f32 v67, v72, v73
	v_lshl_add_u64 v[68:69], v[54:55], 0, s[0:1]
	v_pk_mul_f32 v[62:63], v[62:63], v[92:93] op_sel_hi:[1,0]
	v_pk_mul_f32 v[58:59], v[58:59], v[92:93] op_sel_hi:[1,0]
	v_pk_mul_f32 v[60:61], v[60:61], v[92:93] op_sel_hi:[1,0]
	v_pk_mul_f32 v[56:57], v[56:57], v[92:93] op_sel_hi:[1,0]
	global_store_dwordx4 v[68:69], v[64:67], off
	v_pk_fma_f32 v[62:63], v[28:29], v[62:63], v[32:33]
	v_pk_fma_f32 v[58:59], v[26:27], v[58:59], v[30:31]
	v_pk_fma_f32 v[60:61], v[20:21], v[60:61], v[24:25]
	v_pk_fma_f32 v[64:65], v[18:19], v[56:57], v[22:23]
	v_cvt_pk_bf16_f32 v56, v58, v59
	v_cvt_pk_bf16_f32 v57, v62, v63
	v_cvt_pk_bf16_f32 v58, v64, v65
	v_cvt_pk_bf16_f32 v59, v60, v61
	v_lshl_add_u64 v[60:61], v[54:55], 0, s[6:7]
	s_andn2_b64 vcc, exec, s[12:13]
	s_addk_i32 s10, 0x200
	global_store_dwordx4 v[60:61], v[56:59], off
	s_cbranch_vccz .LBB0_680
	s_waitcnt vmcnt(20)
	v_lshlrev_b32_e32 v58, 16, v168
	v_and_b32_e32 v59, 0xffff0000, v168
	v_lshlrev_b32_e32 v62, 16, v169
	v_and_b32_e32 v63, 0xffff0000, v169
	v_lshlrev_b32_e32 v47, 16, v161
	v_lshlrev_b32_e32 v46, 16, v160
	v_and_b32_e32 v39, 0xffff0000, v161
	v_and_b32_e32 v38, 0xffff0000, v160
	v_lshlrev_b32_e32 v68, 16, v164
	v_and_b32_e32 v69, 0xffff0000, v164
	v_lshlrev_b32_e32 v64, 16, v166
	v_and_b32_e32 v82, 0xffff0000, v166
	v_lshlrev_b32_e32 v56, 16, v170
	v_and_b32_e32 v44, 0xffff0000, v170
	v_lshlrev_b32_e32 v60, 16, v171
	v_and_b32_e32 v42, 0xffff0000, v171
	v_pk_add_f32 v[48:49], v[46:47], v[38:39]
	v_lshlrev_b32_e32 v70, 16, v165
	v_and_b32_e32 v71, 0xffff0000, v165
	v_add_f32_e32 v43, v48, v49
	v_lshlrev_b32_e32 v49, 16, v163
	v_lshlrev_b32_e32 v48, 16, v162
	v_and_b32_e32 v41, 0xffff0000, v163
	v_and_b32_e32 v40, 0xffff0000, v162
	v_pk_add_f32 v[72:73], v[48:49], v[40:41]
	v_lshlrev_b32_e32 v66, 16, v167
	v_pk_add_f32 v[72:73], v[72:73], v[72:73] op_sel_hi:[0,1]
	v_and_b32_e32 v84, 0xffff0000, v167
	v_add_f32_e32 v85, 0, v43
	v_add_f32_e32 v65, v68, v69
	v_add_f32_e32 v83, v70, v71
	v_mov_b32_e32 v67, v73
	v_pk_add_f32 v[74:75], v[64:65], v[82:83]
	v_pk_add_f32 v[72:73], v[66:67], v[84:85]
	v_lshlrev_b32_e32 v87, 16, v157
	v_pk_add_f32 v[72:73], v[74:75], v[72:73]
	v_lshlrev_b32_e32 v86, 16, v156
	v_and_b32_e32 v35, 0xffff0000, v157
	v_and_b32_e32 v34, 0xffff0000, v156
	v_add_f32_e32 v65, v72, v73
	v_pk_add_f32 v[72:73], v[86:87], v[34:35]
	v_lshlrev_b32_e32 v97, 16, v159
	v_lshlrev_b32_e32 v96, 16, v158
	v_and_b32_e32 v37, 0xffff0000, v159
	v_and_b32_e32 v36, 0xffff0000, v158
	v_add_f32_e32 v57, v58, v59
	v_add_f32_e32 v45, v62, v63
	v_add_f32_e32 v43, v72, v73
	v_pk_add_f32 v[72:73], v[96:97], v[36:37]
	v_pk_add_f32 v[74:75], v[56:57], v[44:45]
	v_add_f32_dpp v45, v65, v65 row_ror:8 row_mask:0xf bank_mask:0xf bound_ctrl:1
	v_pk_add_f32 v[72:73], v[72:73], v[72:73] op_sel_hi:[0,1]
	v_add_f32_e32 v43, 0, v43
	v_add_f32_dpp v45, v45, v45 row_ror:4 row_mask:0xf bank_mask:0xf bound_ctrl:1
	v_mov_b32_e32 v61, v73
	v_pk_add_f32 v[72:73], v[60:61], v[42:43]
	v_add_f32_dpp v45, v45, v45 row_ror:2 row_mask:0xf bank_mask:0xf bound_ctrl:1
	v_pk_add_f32 v[72:73], v[74:75], v[72:73]
	s_lshl_b32 s12, s19, 6
	v_add_f32_dpp v45, v45, v45 row_ror:1 row_mask:0xf bank_mask:0xf bound_ctrl:1
	v_add_f32_e32 v43, v72, v73
	v_readlane_b32 s0, v45, 16
	v_readlane_b32 s2, v45, 48
	v_readlane_b32 s6, v45, 0
	v_readlane_b32 s7, v45, 32
	v_mov_b32_e32 v72, s0
	v_mov_b32_e32 v73, s2
	v_pk_add_f32 v[72:73], s[6:7], v[72:73]
	s_mov_b32 s1, s19
	v_add_f32_e32 v45, v72, v73
	v_fmac_f32_e32 v39, 0xba800000, v45
	v_fmac_f32_e32 v47, 0xba800000, v45
	v_fmac_f32_e32 v38, 0xba800000, v45
; __device__ __forceinline__ float wave_sum_dpp(float x) { x = rowsum16(x); return (rl(x, 0) + rl(x, 16)) + (rl(x, 32) + rl(x, 48)); }
;     ...
;         float mean[NR], q[NR], rstd[NR];
; #pragma unroll
;         for (int r = 0; r < NR; ++r) { mean[r] = wave_sum_dpp(s[r]) * (1.f / DM); q[r] = 0.f;
; #pragma unroll
;             for (int j = 0; j < 4; ++j) { v[r][j] = v[r][j] - mean[r]; q[r] += (v[r][j][0] * v[r][j][0] + v[r][j][1] * v[r][j][1]) + (v[r][j][2] * v[r][j][2] + v[r][j][3] * v[r][j][3]); } }
; #pragma unroll
;         for (int r = 0; r < NR; ++r) rstd[r] = 1.0f / sqrtf(wave_sum_dpp(q[r]) * (1.f / DM) + 1e-5f);
	v_fmac_f32_e32 v46, 0xba800000, v45
	v_mov_b32_e32 v74, v47
	v_mov_b32_e32 v78, v47
	v_mov_b32_e32 v79, v39
	v_mov_b32_e32 v47, v38
	v_mov_b32_e32 v73, v38
	v_mov_b32_e32 v75, v39
	v_pk_mul_f32 v[78:79], v[78:79], v[78:79]
	v_pk_mul_f32 v[38:39], v[46:47], v[46:47]
	v_mov_b32_e32 v72, v46
	v_pk_mov_b32 v[46:47], v[38:39], v[78:79] op_sel:[1,0]
	v_mov_b32_e32 v39, v79
	v_fmac_f32_e32 v41, 0xba800000, v45
	v_fmac_f32_e32 v49, 0xba800000, v45
	v_fmac_f32_e32 v40, 0xba800000, v45
	v_pk_add_f32 v[38:39], v[46:47], v[38:39]
	v_fmac_f32_e32 v48, 0xba800000, v45
	v_mov_b32_e32 v80, v49
	v_mov_b32_e32 v46, v49
	v_mov_b32_e32 v47, v41
	v_mov_b32_e32 v49, v40
	v_pk_add_f32 v[38:39], v[38:39], v[38:39] op_sel_hi:[0,1]
	v_mov_b32_e32 v79, v40
	v_mov_b32_e32 v81, v41
	v_pk_mul_f32 v[46:47], v[46:47], v[46:47]
	v_pk_mul_f32 v[40:41], v[48:49], v[48:49]
	v_fmac_f32_e32 v68, 0xba800000, v45
	v_mov_b32_e32 v78, v48
	v_pk_mov_b32 v[48:49], v[40:41], v[46:47] op_sel:[1,0]
	v_mov_b32_e32 v41, v47
	v_fmac_f32_e32 v70, 0xba800000, v45
	v_fmac_f32_e32 v69, 0xba800000, v45
	v_mul_f32_e32 v38, v68, v68
	v_pk_add_f32 v[40:41], v[48:49], v[40:41]
	v_fmac_f32_e32 v71, 0xba800000, v45
	v_pk_fma_f32 v[46:47], v[68:69], v[68:69], v[38:39] op_sel_hi:[1,1,0]
	v_mul_f32_e32 v38, v70, v70
	v_pk_add_f32 v[40:41], v[40:41], v[40:41] op_sel_hi:[0,1]
	v_pk_fma_f32 v[48:49], v[70:71], v[70:71], v[38:39] op_sel_hi:[1,1,0]
	v_fmac_f32_e32 v84, 0xba800000, v45
	v_fmac_f32_e32 v66, 0xba800000, v45
	v_fmac_f32_e32 v82, 0xba800000, v45
	v_fmac_f32_e32 v64, 0xba800000, v45
	v_mul_f32_e32 v46, v64, v64
	v_mul_f32_e32 v48, v82, v82
	v_mul_f32_e32 v38, v66, v66
	v_mul_f32_e32 v40, v84, v84
	v_pk_add_f32 v[46:47], v[46:47], v[48:49]
	v_pk_add_f32 v[38:39], v[38:39], v[40:41]
	v_mov_b32_e32 v67, v84
	v_pk_add_f32 v[38:39], v[46:47], v[38:39]
	s_or_b32 s15, s12, 62
	v_add_f32_e32 v40, v38, v39
	v_add_f32_dpp v38, v43, v43 row_ror:8 row_mask:0xf bank_mask:0xf bound_ctrl:1
	s_add_i32 s19, s19, 8
	s_cmp_ge_i32 s1, s5
	v_add_f32_dpp v38, v38, v38 row_ror:4 row_mask:0xf bank_mask:0xf bound_ctrl:1
	s_cselect_b64 s[12:13], -1, 0
	s_cmp_lt_i32 s1, s5
	v_add_f32_dpp v38, v38, v38 row_ror:2 row_mask:0xf bank_mask:0xf bound_ctrl:1
	s_cselect_b32 s1, s19, s1
	s_lshl_b32 s1, s1, 6
	v_add_f32_dpp v38, v38, v38 row_ror:1 row_mask:0xf bank_mask:0xf bound_ctrl:1
	s_or_b32 s20, s1, 62
	v_readlane_b32 s0, v38, 16
	v_readlane_b32 s2, v38, 48
	v_readlane_b32 s6, v38, 0
	v_readlane_b32 s7, v38, 32
	v_mov_b32_e32 v38, s0
	v_mov_b32_e32 v39, s2
	v_pk_add_f32 v[38:39], s[6:7], v[38:39]
	s_ashr_i32 s21, s20, 31
	v_add_f32_e32 v38, v38, v39
	v_fmac_f32_e32 v35, 0xba800000, v38
	v_fmac_f32_e32 v34, 0xba800000, v38
	v_fmac_f32_e32 v87, 0xba800000, v38
	v_fmac_f32_e32 v86, 0xba800000, v38
	v_mov_b32_e32 v83, v34
	v_mov_b32_e32 v85, v35
	v_mul_f32_e32 v34, v34, v34
	v_mul_f32_e32 v35, v35, v35
	v_fmac_f32_e32 v34, v86, v86
	v_fmac_f32_e32 v35, v87, v87
	v_fmac_f32_e32 v37, 0xba800000, v38
	v_fmac_f32_e32 v36, 0xba800000, v38
	v_mov_b32_e32 v84, v87
	v_add_f32_e32 v34, v34, v35
	v_fmac_f32_e32 v97, 0xba800000, v38
	v_fmac_f32_e32 v96, 0xba800000, v38
	v_mov_b32_e32 v87, v36
	v_mul_f32_e32 v35, v36, v36
	v_mul_f32_e32 v36, v37, v37
	v_fmac_f32_e32 v35, v96, v96
	v_fmac_f32_e32 v36, v97, v97
	v_add_f32_e32 v35, v35, v36
	v_fmac_f32_e32 v63, 0xba800000, v38
	v_fmac_f32_e32 v59, 0xba800000, v38
	v_add_f32_e32 v34, v34, v35
	v_fmac_f32_e32 v62, 0xba800000, v38
	v_fmac_f32_e32 v58, 0xba800000, v38
	v_mul_f32_e32 v35, v59, v59
	v_mul_f32_e32 v36, v63, v63
	v_fmac_f32_e32 v35, v58, v58
	v_fmac_f32_e32 v36, v62, v62
	v_add_f32_e32 v35, v35, v36
	v_fmac_f32_e32 v42, 0xba800000, v38
	v_fmac_f32_e32 v44, 0xba800000, v38
	v_add_f32_e32 v34, v35, v34
	v_fmac_f32_e32 v60, 0xba800000, v38
	v_fmac_f32_e32 v56, 0xba800000, v38
	v_mul_f32_e32 v35, v44, v44
	v_mul_f32_e32 v36, v42, v42
	v_fmac_f32_e32 v35, v56, v56
	v_fmac_f32_e32 v36, v60, v60
	v_add_f32_e32 v35, v35, v36
; __device__ __forceinline__ float wave_sum_dpp(float x) { x = rowsum16(x); return (rl(x, 0) + rl(x, 16)) + (rl(x, 32) + rl(x, 48)); }
;     ...
;         for (int r = 0; r < NR; ++r) { mean[r] = wave_sum_dpp(s[r]) * (1.f / DM); q[r] = 0.f;
; #pragma unroll
;             for (int j = 0; j < 4; ++j) { v[r][j] = v[r][j] - mean[r]; q[r] += (v[r][j][0] * v[r][j][0] + v[r][j][1] * v[r][j][1]) + (v[r][j][2] * v[r][j][2] + v[r][j][3] * v[r][j][3]); } }
; #pragma unroll
;         for (int r = 0; r < NR; ++r) rstd[r] = 1.0f / sqrtf(wave_sum_dpp(q[r]) * (1.f / DM) + 1e-5f);
;         if (MODE == 1) {
; #pragma unroll
;             for (int r = 0; r < NR; ++r) if (lane == r) { stats[2 * row[r]] = mean[r]; stats[2 * row[r] + 1] = rstd[r]; } }
	v_add_f32_e32 v34, v35, v34
	s_lshl_b64 s[20:21], s[20:21], 11
	v_add_f32_dpp v35, v40, v40 row_ror:8 row_mask:0xf bank_mask:0xf bound_ctrl:1
	v_add_f32_dpp v34, v34, v34 row_ror:8 row_mask:0xf bank_mask:0xf bound_ctrl:1
	v_mul_f32_e32 v76, 0x3a800000, v45
	v_add_f32_dpp v35, v35, v35 row_ror:4 row_mask:0xf bank_mask:0xf bound_ctrl:1
	v_add_f32_dpp v34, v34, v34 row_ror:4 row_mask:0xf bank_mask:0xf bound_ctrl:1
	v_mul_f32_e32 v90, 0x3a800000, v38
	v_add_f32_dpp v35, v35, v35 row_ror:2 row_mask:0xf bank_mask:0xf bound_ctrl:1
	v_add_f32_dpp v34, v34, v34 row_ror:2 row_mask:0xf bank_mask:0xf bound_ctrl:1
	v_mov_b32_e32 v89, v37
	v_add_f32_dpp v35, v35, v35 row_ror:1 row_mask:0xf bank_mask:0xf bound_ctrl:1
	v_add_f32_dpp v34, v34, v34 row_ror:1 row_mask:0xf bank_mask:0xf bound_ctrl:1
	v_readlane_b32 s6, v35, 0
	v_readlane_b32 s11, v35, 16
	v_readlane_b32 s7, v35, 32
	v_readlane_b32 s14, v35, 48
	v_readlane_b32 s0, v34, 0
	v_readlane_b32 s8, v34, 16
	v_readlane_b32 s2, v34, 32
	v_readlane_b32 s9, v34, 48
	v_lshl_add_u64 v[34:35], v[50:51], 0, s[20:21]
	s_or_b32 s20, s1, 63
	s_ashr_i32 s21, s20, 31
	s_lshl_b64 s[20:21], s[20:21], 11
	v_lshl_add_u64 v[46:47], v[50:51], 0, s[20:21]
	v_mov_b32_e32 v57, v44
	v_mov_b32_e32 v61, v42
	v_mov_b32_e32 v65, v82
	v_mov_b32_e32 v82, v86
	v_mov_b32_e32 v86, v96
	v_mov_b32_e32 v88, v97
	v_mov_b32_e32 v96, s11
	v_mov_b32_e32 v97, s14
	v_pk_add_f32 v[96:97], s[6:7], v[96:97]
	v_mov_b32_e32 v98, s9
	v_add_f32_e32 v77, v96, v97
	v_fmamk_f32 v77, v77, 0x3a800000, v93
	v_mul_f32_e32 v91, 0x4f800000, v77
	v_cmp_gt_f32_e32 vcc, s18, v77
	v_mov_b32_e32 v97, s8
	v_add_f32_e32 v97, s0, v97
	v_cndmask_b32_e32 v77, v77, v91, vcc
	v_sqrt_f32_e32 v91, v77
	v_add_f32_e32 v98, s2, v98
	v_add_f32_e32 v97, v97, v98
	v_fmamk_f32 v97, v97, 0x3a800000, v93
	v_add_u32_e32 v92, -1, v91
	v_fma_f32 v94, -v92, v91, v77
	v_cmp_ge_f32_e64 s[6:7], 0, v94
	v_add_u32_e32 v94, 1, v91
	v_mul_f32_e32 v98, 0x4f800000, v97
	v_cndmask_b32_e64 v92, v91, v92, s[6:7]
	v_fma_f32 v91, -v94, v91, v77
	v_cmp_lt_f32_e64 s[6:7], 0, v91
	s_nop 1
	v_cndmask_b32_e64 v91, v92, v94, s[6:7]
	v_mul_f32_e32 v92, 0x37800000, v91
	v_cndmask_b32_e32 v91, v91, v92, vcc
	v_cmp_class_f32_e32 vcc, v77, v95
	s_nop 1
	v_cndmask_b32_e32 v77, v91, v77, vcc
	v_div_scale_f32 v91, s[6:7], v77, v77, 1.0
	v_rcp_f32_e32 v92, v91
	v_cmp_gt_f32_e64 s[6:7], s18, v97
	v_fma_f32 v94, -v91, v92, 1.0
	s_nop 0
	v_cndmask_b32_e64 v97, v97, v98, s[6:7]
	v_fmac_f32_e32 v92, v94, v92
	v_div_scale_f32 v94, vcc, 1.0, v77, 1.0
	v_sqrt_f32_e32 v98, v97
	v_mul_f32_e32 v96, v94, v92
	v_fma_f32 v99, -v91, v96, v94
	v_fmac_f32_e32 v96, v99, v92
	v_fma_f32 v91, -v91, v96, v94
	v_add_u32_e32 v94, -1, v98
	v_fma_f32 v99, -v94, v98, v97
	v_cmp_ge_f32_e64 s[8:9], 0, v99
	v_add_u32_e32 v99, 1, v98
	v_div_fmas_f32 v91, v91, v92, v96
	v_cndmask_b32_e64 v94, v98, v94, s[8:9]
	v_fma_f32 v98, -v99, v98, v97
	v_cmp_lt_f32_e64 s[8:9], 0, v98
	s_nop 1
	v_cndmask_b32_e64 v94, v94, v99, s[8:9]
	v_mul_f32_e32 v98, 0x37800000, v94
	v_cndmask_b32_e64 v94, v94, v98, s[6:7]
	v_cmp_class_f32_e64 s[6:7], v97, v95
	s_mov_b64 s[8:9], -1
	s_nop 0
	v_cndmask_b32_e64 v97, v94, v97, s[6:7]
	v_div_scale_f32 v98, s[0:1], v97, v97, 1.0
	v_rcp_f32_e32 v99, v98
	v_div_fixup_f32 v94, v91, v77, 1.0
	v_fma_f32 v77, -v98, v99, 1.0
	v_fmac_f32_e32 v99, v77, v99
	v_div_scale_f32 v77, vcc, 1.0, v97, 1.0
	v_mul_f32_e32 v91, v77, v99
	v_fma_f32 v92, -v98, v91, v77
	v_fmac_f32_e32 v91, v92, v99
	v_fma_f32 v77, -v98, v91, v77
	v_div_fmas_f32 v77, v77, v99, v91
	v_div_fixup_f32 v92, v77, v97, 1.0
	v_mov_b32_e32 v77, v94
	v_cmp_lt_i32_e32 vcc, 0, v145
	v_mov_b32_e32 v91, s15
	s_and_saveexec_b64 s[6:7], vcc
	s_cbranch_execz .Lhln7_m7
	v_cmp_eq_u32_e32 vcc, 1, v145
	s_mov_b64 s[8:9], 0
	s_and_saveexec_b64 s[14:15], vcc
	v_mov_b32_e32 v91, v92
	s_mov_b64 s[8:9], exec
	v_mov_b64_e32 v[76:77], v[90:91]
	s_or_b64 exec, exec, s[14:15]
	v_mov_b32_e32 v91, s10
	s_orn2_b64 s[8:9], s[8:9], exec

; __device__ __forceinline__ unsigned cvtpk(float lo, float hi) { f32x2_t v = {lo, hi}; bf16x2_t b = __builtin_convertvector(v, bf16x2_t); return __builtin_bit_cast(unsigned, b); }
;     ...
;         for (int j = 0; j < 2; ++j) {
;             const int c = 8 * lane + 512 * j;
;             const f32x4 g0 = *(const f32x4*)(g + c), g1 = *(const f32x4*)(g + c + 4), b0 = *(const f32x4*)(b + c), b1 = *(const f32x4*)(b + c + 4);
; #pragma unroll
;             for (int r = 0; r < NR; ++r) {
;                 const f32x4 o0 = v[r][2 * j] * rstd[r] * g0 + b0, o1 = v[r][2 * j + 1] * rstd[r] * g1 + b1;
;                 if (MODE == 1) { pg8::u32x4 w; w.x = cvtpk(o0[0], o0[1]); w.y = cvtpk(o0[2], o0[3]); w.z = cvtpk(o1[0], o1[1]); w.w = cvtpk(o1[2], o1[3]); *(pg8::u32x4*)(hb + (size_t)row[r] * DM + c) = w; }
;                 else { *(f32x4*)(outf + (size_t)row[r] * DM + c) = o0; *(f32x4*)(outf + (size_t)row[r] * DM + c + 4) = o1; }
;             }
;         }
.Lhln7_t7:
	s_or_b64 exec, exec, s[6:7]
	s_add_i32 s0, s10, -1
	v_pk_mul_f32 v[74:75], v[74:75], v[94:95] op_sel_hi:[1,0]
	v_pk_mul_f32 v[72:73], v[72:73], v[94:95] op_sel_hi:[1,0]
	v_pk_mul_f32 v[76:77], v[80:81], v[94:95] op_sel_hi:[1,0]
	v_pk_mul_f32 v[78:79], v[78:79], v[94:95] op_sel_hi:[1,0]
	s_ashr_i32 s1, s0, 31
	v_pk_fma_f32 v[74:75], v[12:13], v[74:75], v[16:17]
	v_pk_fma_f32 v[72:73], v[10:11], v[72:73], v[14:15]
	v_pk_fma_f32 v[76:77], v[4:5], v[76:77], v[8:9]
	v_pk_fma_f32 v[78:79], v[2:3], v[78:79], v[6:7]
	s_lshl_b64 s[0:1], s[0:1], 11
	v_cvt_pk_bf16_f32 v72, v72, v73
	v_cvt_pk_bf16_f32 v73, v74, v75
	v_cvt_pk_bf16_f32 v74, v78, v79
	v_cvt_pk_bf16_f32 v75, v76, v77
	v_lshl_add_u64 v[76:77], v[52:53], 0, s[0:1]
	global_store_dwordx4 v[76:77], v[72:75], off
	v_pk_mul_f32 v[78:79], v[86:87], v[92:93] op_sel_hi:[1,0]
	s_ashr_i32 s11, s10, 31
	v_pk_mul_f32 v[72:73], v[84:85], v[92:93] op_sel_hi:[1,0]
	v_pk_mul_f32 v[74:75], v[82:83], v[92:93] op_sel_hi:[1,0]
	v_pk_fma_f32 v[76:77], v[12:13], v[72:73], v[16:17]
	v_pk_fma_f32 v[72:73], v[10:11], v[74:75], v[14:15]
	v_pk_mul_f32 v[74:75], v[88:89], v[92:93] op_sel_hi:[1,0]
	s_lshl_b64 s[6:7], s[10:11], 11
	v_pk_fma_f32 v[80:81], v[4:5], v[74:75], v[8:9]
	v_pk_fma_f32 v[74:75], v[2:3], v[78:79], v[6:7]
	v_cvt_pk_bf16_f32 v72, v72, v73
	v_cvt_pk_bf16_f32 v73, v76, v77
	v_cvt_pk_bf16_f32 v74, v74, v75
	v_cvt_pk_bf16_f32 v75, v80, v81
	v_lshl_add_u64 v[76:77], v[52:53], 0, s[6:7]
	v_pk_mul_f32 v[70:71], v[70:71], v[94:95] op_sel_hi:[1,0]
	v_pk_mul_f32 v[68:69], v[68:69], v[94:95] op_sel_hi:[1,0]
	v_pk_mul_f32 v[66:67], v[66:67], v[94:95] op_sel_hi:[1,0]
	v_pk_mul_f32 v[64:65], v[64:65], v[94:95] op_sel_hi:[1,0]
	global_store_dwordx4 v[76:77], v[72:75], off
	v_pk_fma_f32 v[70:71], v[28:29], v[70:71], v[32:33]
	v_pk_fma_f32 v[68:69], v[26:27], v[68:69], v[30:31]
	v_pk_fma_f32 v[72:73], v[20:21], v[66:67], v[24:25]
	v_pk_fma_f32 v[66:67], v[18:19], v[64:65], v[22:23]
	v_cvt_pk_bf16_f32 v64, v68, v69
	v_cvt_pk_bf16_f32 v65, v70, v71
	v_cvt_pk_bf16_f32 v66, v66, v67
	v_cvt_pk_bf16_f32 v67, v72, v73
	v_lshl_add_u64 v[68:69], v[54:55], 0, s[0:1]
	v_pk_mul_f32 v[62:63], v[62:63], v[92:93] op_sel_hi:[1,0]
	v_pk_mul_f32 v[58:59], v[58:59], v[92:93] op_sel_hi:[1,0]
	v_pk_mul_f32 v[60:61], v[60:61], v[92:93] op_sel_hi:[1,0]
	v_pk_mul_f32 v[56:57], v[56:57], v[92:93] op_sel_hi:[1,0]
	global_store_dwordx4 v[68:69], v[64:67], off
	v_pk_fma_f32 v[62:63], v[28:29], v[62:63], v[32:33]
	v_pk_fma_f32 v[58:59], v[26:27], v[58:59], v[30:31]
	v_pk_fma_f32 v[60:61], v[20:21], v[60:61], v[24:25]
	v_pk_fma_f32 v[64:65], v[18:19], v[56:57], v[22:23]
	v_cvt_pk_bf16_f32 v56, v58, v59
	v_cvt_pk_bf16_f32 v57, v62, v63
	v_cvt_pk_bf16_f32 v58, v64, v65
	v_cvt_pk_bf16_f32 v59, v60, v61
	v_lshl_add_u64 v[60:61], v[54:55], 0, s[6:7]
	s_andn2_b64 vcc, exec, s[12:13]
	s_addk_i32 s10, 0x200
	global_store_dwordx4 v[60:61], v[56:59], off
	s_cbranch_vccz .LBB0_680
	s_branch .LBB0_680

;     ...
;     if (p0 < p1) {
; #pragma unroll
;         for (int r = 0; r < NR; ++r) { const bf16_t* p = z + (size_t)rowr(p0, r) * DM;
; #pragma unroll
;             for (int j = 0; j < 2; ++j) raw[r][j] = *(const pg8::u32x4*)(p + 8 * lane + 512 * j); } }
;     ...
;         for (int j = 0; j < 2; ++j) {
;             const int c = 8 * lane + 512 * j;
;             const f32x4 g0 = *(const f32x4*)(g + c), g1 = *(const f32x4*)(g + c + 4), b0 = *(const f32x4*)(b + c), b1 = *(const f32x4*)(b + c + 4);
.LBB0_1742:
	s_or_b64 exec, exec, s[8:9]
	v_mov_b32_e32 v93, v0
	s_waitcnt lgkmcnt(0)
	s_barrier
	s_mov_b64 s[8:9], -1
	v_readfirstlane_b32 s4, v93
	v_and_b32_e32 v1, 63, v93
	s_ashr_i32 s6, s4, 6
	s_and_b64 vcc, exec, s[60:61]
	s_cbranch_vccz .LBB0_1759
	s_lshr_b32 s0, s54, 31
	s_ashr_i32 s7, s54, 1
	s_add_i32 s7, s7, s0
	s_cmp_gt_i32 s6, 63
	s_cbranch_scc1 .LBB0_1752
	s_lshl_b32 s2, s7, 6
	v_readlane_b32 s0, v253, 4
	s_add_i32 s15, s6, s2
	v_readlane_b32 s1, v253, 5
	s_lshl_b32 s3, s15, 6
	s_load_dwordx4 s[8:11], s[0:1], 0x118
	s_or_b32 s0, s3, 62
	v_readlane_b32 s12, v253, 21
	v_lshlrev_b32_e32 v54, 4, v1
	v_mov_b32_e32 v55, 0
	v_readlane_b32 s13, v253, 22
	s_ashr_i32 s1, s0, 31
	s_lshl_b64 s[0:1], s[0:1], 11
	v_lshl_add_u64 v[50:51], s[12:13], 0, v[54:55]
	v_lshl_add_u64 v[2:3], v[50:51], 0, s[0:1]
	s_or_b32 s0, s3, 63
	s_ashr_i32 s1, s0, 31
	s_lshl_b64 s[0:1], s[0:1], 11
	global_load_dwordx4 v[38:41], v[2:3], off
	global_load_dwordx4 v[42:45], v[2:3], off offset:1024
	v_lshl_add_u64 v[2:3], v[50:51], 0, s[0:1]
	v_lshlrev_b32_e32 v52, 5, v1
	global_load_dwordx4 v[34:37], v[2:3], off
	global_load_dwordx4 v[46:49], v[2:3], off offset:1024
	s_waitcnt lgkmcnt(0)
	global_load_dwordx4 v[2:5], v52, s[8:9] offset:16
	global_load_dwordx4 v[6:9], v52, s[10:11] offset:16
	global_load_dwordx4 v[10:13], v52, s[8:9]
	global_load_dwordx4 v[14:17], v52, s[10:11]
	global_load_dwordx4 v[18:21], v52, s[8:9] offset:2064
	global_load_dwordx4 v[22:25], v52, s[10:11] offset:2064
	global_load_dwordx4 v[26:29], v52, s[8:9] offset:2048
	global_load_dwordx4 v[30:33], v52, s[10:11] offset:2048
	s_add_u32 s0, s0, 0x100000
	s_addc_u32 s1, s1, 0
	v_lshl_add_u64 v[156:157], v[50:51], 0, s[0:1]
	global_load_dwordx4 v[160:163], v[156:157], off offset:-2048
	global_load_dwordx4 v[164:167], v[156:157], off offset:-1024
	global_load_dwordx4 v[168:171], v[156:157], off offset:1024
	s_nop 0
	global_load_dwordx4 v[156:159], v[156:157], off
	s_add_u32 s0, s0, 0x100000
	s_addc_u32 s1, s1, 0
	v_lshl_add_u64 v[172:173], v[50:51], 0, s[0:1]
	global_load_dwordx4 v[176:179], v[172:173], off offset:-2048
	global_load_dwordx4 v[180:183], v[172:173], off offset:-1024
	global_load_dwordx4 v[184:187], v[172:173], off offset:1024
	s_nop 0
	global_load_dwordx4 v[172:175], v[172:173], off
	s_add_u32 s0, s0, 0x100000
	s_addc_u32 s1, s1, 0
	v_lshl_add_u64 v[188:189], v[50:51], 0, s[0:1]
	global_load_dwordx4 v[192:195], v[188:189], off offset:-2048
	global_load_dwordx4 v[196:199], v[188:189], off offset:-1024
	global_load_dwordx4 v[200:203], v[188:189], off offset:1024
	s_nop 0
	global_load_dwordx4 v[188:191], v[188:189], off
	s_add_u32 s0, s0, 0x100000
	s_addc_u32 s1, s1, 0
	v_lshl_add_u64 v[204:205], v[50:51], 0, s[0:1]
	global_load_dwordx4 v[208:211], v[204:205], off offset:-2048
	global_load_dwordx4 v[212:215], v[204:205], off offset:-1024
	global_load_dwordx4 v[216:219], v[204:205], off offset:1024
	s_nop 0
	global_load_dwordx4 v[204:207], v[204:205], off
	s_add_u32 s0, s0, 0x100000
	s_addc_u32 s1, s1, 0
	v_lshl_add_u64 v[220:221], v[50:51], 0, s[0:1]
	global_load_dwordx4 v[224:227], v[220:221], off offset:-2048
	global_load_dwordx4 v[228:231], v[220:221], off offset:-1024
	global_load_dwordx4 v[232:235], v[220:221], off offset:1024
	s_nop 0
	global_load_dwordx4 v[220:223], v[220:221], off
	s_add_u32 s0, s0, 0x100000
	s_addc_u32 s1, s1, 0
	v_lshl_add_u64 v[236:237], v[50:51], 0, s[0:1]
	global_load_dwordx4 v[240:243], v[236:237], off offset:-2048
	global_load_dwordx4 v[244:247], v[236:237], off offset:-1024
	global_load_dwordx4 v[248:251], v[236:237], off offset:1024
	s_nop 0
	global_load_dwordx4 v[236:239], v[236:237], off
	v_readlane_b32 s0, v253, 23
	v_readlane_b32 s1, v253, 24
	s_or_b32 s5, s2, 56
	v_mov_b32_e32 v95, 0x3727c5ac
	v_lshl_add_u64 v[52:53], s[0:1], 0, v[54:55]
	v_or_b32_e32 v54, 0x400, v54
	v_lshl_add_u64 v[54:55], s[0:1], 0, v[54:55]
	s_lshl_b32 s0, s7, 12
	s_lshl_b32 s1, s6, 6
	s_add_i32 s0, s0, s1
	s_or_b32 s12, s0, 63
	s_mov_b32 s14, 0xf800000
	v_mov_b32_e32 v96, 0x260
	s_waitcnt vmcnt(24)
	v_lshlrev_b32_e32 v58, 16, v46
	v_and_b32_e32 v59, 0xffff0000, v46
	v_lshlrev_b32_e32 v62, 16, v47
	v_and_b32_e32 v63, 0xffff0000, v47
	v_lshlrev_b32_e32 v47, 16, v39
	v_lshlrev_b32_e32 v46, 16, v38
	v_and_b32_e32 v39, 0xffff0000, v39
	v_and_b32_e32 v38, 0xffff0000, v38
	v_lshlrev_b32_e32 v68, 16, v42
	v_and_b32_e32 v69, 0xffff0000, v42
	v_lshlrev_b32_e32 v64, 16, v44
	v_and_b32_e32 v82, 0xffff0000, v44
	v_lshlrev_b32_e32 v56, 16, v48
	v_and_b32_e32 v44, 0xffff0000, v48
	v_lshlrev_b32_e32 v60, 16, v49
	v_and_b32_e32 v42, 0xffff0000, v49
	v_pk_add_f32 v[48:49], v[46:47], v[38:39]
	v_lshlrev_b32_e32 v70, 16, v43
	v_and_b32_e32 v71, 0xffff0000, v43
	v_add_f32_e32 v43, v48, v49
	v_lshlrev_b32_e32 v49, 16, v41
	v_lshlrev_b32_e32 v48, 16, v40
	v_and_b32_e32 v41, 0xffff0000, v41
	v_and_b32_e32 v40, 0xffff0000, v40
	v_pk_add_f32 v[72:73], v[48:49], v[40:41]
	v_lshlrev_b32_e32 v66, 16, v45
	v_pk_add_f32 v[72:73], v[72:73], v[72:73] op_sel_hi:[0,1]
	v_and_b32_e32 v84, 0xffff0000, v45
	v_add_f32_e32 v85, 0, v43
	v_add_f32_e32 v65, v68, v69
	v_add_f32_e32 v83, v70, v71
	v_mov_b32_e32 v67, v73
	v_pk_add_f32 v[74:75], v[64:65], v[82:83]
	v_pk_add_f32 v[72:73], v[66:67], v[84:85]
	v_lshlrev_b32_e32 v87, 16, v35
	v_pk_add_f32 v[72:73], v[74:75], v[72:73]
	v_lshlrev_b32_e32 v86, 16, v34
	v_and_b32_e32 v35, 0xffff0000, v35
	v_and_b32_e32 v34, 0xffff0000, v34
	v_add_f32_e32 v65, v72, v73
	v_pk_add_f32 v[72:73], v[86:87], v[34:35]
	v_lshlrev_b32_e32 v99, 16, v37
	v_lshlrev_b32_e32 v98, 16, v36
	v_and_b32_e32 v37, 0xffff0000, v37
	v_and_b32_e32 v36, 0xffff0000, v36
	v_add_f32_e32 v57, v58, v59
; __device__ __forceinline__ float wave_sum_dpp(float x) { x = rowsum16(x); return (rl(x, 0) + rl(x, 16)) + (rl(x, 32) + rl(x, 48)); }
;     ...
; #pragma unroll
;         for (int r = 0; r < NR; ++r)
; #pragma unroll
;             for (int j = 0; j < 4; ++j) s[r] += (v[r][j][0] + v[r][j][1]) + (v[r][j][2] + v[r][j][3]);
;         float mean[NR], q[NR], rstd[NR];
; #pragma unroll
;         for (int r = 0; r < NR; ++r) { mean[r] = wave_sum_dpp(s[r]) * (1.f / DM); q[r] = 0.f;
; #pragma unroll
;             for (int j = 0; j < 4; ++j) { v[r][j] = v[r][j] - mean[r]; q[r] += (v[r][j][0] * v[r][j][0] + v[r][j][1] * v[r][j][1]) + (v[r][j][2] * v[r][j][2] + v[r][j][3] * v[r][j][3]); } }
; #pragma unroll
;         for (int r = 0; r < NR; ++r) rstd[r] = 1.0f / sqrtf(wave_sum_dpp(q[r]) * (1.f / DM) + 1e-5f);
	v_add_f32_e32 v45, v62, v63
	v_add_f32_e32 v43, v72, v73
	v_pk_add_f32 v[72:73], v[98:99], v[36:37]
	v_pk_add_f32 v[74:75], v[56:57], v[44:45]
	v_add_f32_dpp v45, v65, v65 row_ror:8 row_mask:0xf bank_mask:0xf bound_ctrl:1
	v_pk_add_f32 v[72:73], v[72:73], v[72:73] op_sel_hi:[0,1]
	v_add_f32_e32 v43, 0, v43
	v_add_f32_dpp v45, v45, v45 row_ror:4 row_mask:0xf bank_mask:0xf bound_ctrl:1
	v_mov_b32_e32 v61, v73
	v_pk_add_f32 v[72:73], v[60:61], v[42:43]
	v_add_f32_dpp v45, v45, v45 row_ror:2 row_mask:0xf bank_mask:0xf bound_ctrl:1
	v_pk_add_f32 v[72:73], v[74:75], v[72:73]
	s_mov_b32 s1, s15
	v_add_f32_dpp v45, v45, v45 row_ror:1 row_mask:0xf bank_mask:0xf bound_ctrl:1
	v_add_f32_e32 v43, v72, v73
	v_readlane_b32 s0, v45, 16
	v_readlane_b32 s8, v45, 48
	v_readlane_b32 s2, v45, 0
	v_readlane_b32 s3, v45, 32
	v_mov_b32_e32 v72, s0
	v_mov_b32_e32 v73, s8
	v_pk_add_f32 v[72:73], s[2:3], v[72:73]
	s_lshl_b32 s15, s15, 6
	v_add_f32_e32 v45, v72, v73
	v_fmac_f32_e32 v39, 0xba800000, v45
	v_fmac_f32_e32 v47, 0xba800000, v45
	v_fmac_f32_e32 v38, 0xba800000, v45
	v_fmac_f32_e32 v46, 0xba800000, v45
	v_mov_b32_e32 v74, v47
	v_mov_b32_e32 v78, v47
	v_mov_b32_e32 v79, v39
	v_mov_b32_e32 v47, v38
	v_mov_b32_e32 v73, v38
	v_mov_b32_e32 v75, v39
	v_pk_mul_f32 v[78:79], v[78:79], v[78:79]
	v_pk_mul_f32 v[38:39], v[46:47], v[46:47]
	v_mov_b32_e32 v72, v46
	v_pk_mov_b32 v[46:47], v[38:39], v[78:79] op_sel:[1,0]
	v_mov_b32_e32 v39, v79
	v_fmac_f32_e32 v41, 0xba800000, v45
	v_fmac_f32_e32 v49, 0xba800000, v45
	v_fmac_f32_e32 v40, 0xba800000, v45
	v_pk_add_f32 v[38:39], v[46:47], v[38:39]
	v_fmac_f32_e32 v48, 0xba800000, v45
	v_mov_b32_e32 v80, v49
	v_mov_b32_e32 v46, v49
	v_mov_b32_e32 v47, v41
	v_mov_b32_e32 v49, v40
	v_pk_add_f32 v[38:39], v[38:39], v[38:39] op_sel_hi:[0,1]
	v_mov_b32_e32 v79, v40
	v_mov_b32_e32 v81, v41
	v_pk_mul_f32 v[46:47], v[46:47], v[46:47]
	v_pk_mul_f32 v[40:41], v[48:49], v[48:49]
	v_fmac_f32_e32 v68, 0xba800000, v45
	v_mov_b32_e32 v78, v48
	v_pk_mov_b32 v[48:49], v[40:41], v[46:47] op_sel:[1,0]
	v_mov_b32_e32 v41, v47
	v_fmac_f32_e32 v70, 0xba800000, v45
	v_fmac_f32_e32 v69, 0xba800000, v45
	v_mul_f32_e32 v38, v68, v68
	v_pk_add_f32 v[40:41], v[48:49], v[40:41]
	v_fmac_f32_e32 v71, 0xba800000, v45
	v_pk_fma_f32 v[46:47], v[68:69], v[68:69], v[38:39] op_sel_hi:[1,1,0]
	v_mul_f32_e32 v38, v70, v70
	v_pk_add_f32 v[40:41], v[40:41], v[40:41] op_sel_hi:[0,1]
	v_pk_fma_f32 v[48:49], v[70:71], v[70:71], v[38:39] op_sel_hi:[1,1,0]
	v_fmac_f32_e32 v84, 0xba800000, v45
	v_fmac_f32_e32 v66, 0xba800000, v45
	v_fmac_f32_e32 v82, 0xba800000, v45
	v_fmac_f32_e32 v64, 0xba800000, v45
	v_mul_f32_e32 v46, v64, v64
	v_mul_f32_e32 v48, v82, v82
	v_mul_f32_e32 v38, v66, v66
	v_mul_f32_e32 v40, v84, v84
	v_pk_add_f32 v[46:47], v[46:47], v[48:49]
	v_pk_add_f32 v[38:39], v[38:39], v[40:41]
	v_mov_b32_e32 v67, v84
	v_pk_add_f32 v[38:39], v[46:47], v[38:39]
	s_or_b32 s22, s15, 62
	v_add_f32_e32 v40, v38, v39
	v_add_f32_dpp v38, v43, v43 row_ror:8 row_mask:0xf bank_mask:0xf bound_ctrl:1
	s_add_i32 s15, s1, 8
	s_cmp_ge_i32 s1, s5
	v_add_f32_dpp v38, v38, v38 row_ror:4 row_mask:0xf bank_mask:0xf bound_ctrl:1
	s_cselect_b64 s[20:21], -1, 0
	s_cmp_lt_i32 s1, s5
	v_add_f32_dpp v38, v38, v38 row_ror:2 row_mask:0xf bank_mask:0xf bound_ctrl:1
	s_cselect_b32 s1, s15, s1
	s_lshl_b32 s1, s1, 6
	v_add_f32_dpp v38, v38, v38 row_ror:1 row_mask:0xf bank_mask:0xf bound_ctrl:1
	s_or_b32 s18, s1, 62
	v_readlane_b32 s0, v38, 16
	v_readlane_b32 s8, v38, 48
	v_readlane_b32 s2, v38, 0
	v_readlane_b32 s3, v38, 32
	v_mov_b32_e32 v38, s0
	v_mov_b32_e32 v39, s8
	v_pk_add_f32 v[38:39], s[2:3], v[38:39]
	s_ashr_i32 s19, s18, 31
	v_add_f32_e32 v38, v38, v39
	v_fmac_f32_e32 v35, 0xba800000, v38
	v_fmac_f32_e32 v34, 0xba800000, v38
	v_fmac_f32_e32 v87, 0xba800000, v38
	v_fmac_f32_e32 v86, 0xba800000, v38
	v_mov_b32_e32 v83, v34
	v_mov_b32_e32 v85, v35
	v_mul_f32_e32 v34, v34, v34
	v_mul_f32_e32 v35, v35, v35
	v_fmac_f32_e32 v34, v86, v86
	v_fmac_f32_e32 v35, v87, v87
	v_fmac_f32_e32 v37, 0xba800000, v38
	v_fmac_f32_e32 v36, 0xba800000, v38
	v_mov_b32_e32 v84, v87
	v_add_f32_e32 v34, v34, v35
	v_fmac_f32_e32 v99, 0xba800000, v38
	v_fmac_f32_e32 v98, 0xba800000, v38
	v_mov_b32_e32 v87, v36
	v_mul_f32_e32 v35, v36, v36
	v_mul_f32_e32 v36, v37, v37
	v_fmac_f32_e32 v35, v98, v98
	v_fmac_f32_e32 v36, v99, v99
	v_add_f32_e32 v35, v35, v36
	v_fmac_f32_e32 v63, 0xba800000, v38
	v_fmac_f32_e32 v59, 0xba800000, v38
	v_add_f32_e32 v34, v34, v35
	v_fmac_f32_e32 v62, 0xba800000, v38
; __device__ __forceinline__ float wave_sum_dpp(float x) { x = rowsum16(x); return (rl(x, 0) + rl(x, 16)) + (rl(x, 32) + rl(x, 48)); }
;     ...
;         { const int nxt = pi + NP * pstep, pq = nxt < p1 ? nxt : pi;
; #pragma unroll
;           for (int r = 0; r < NR; ++r) { const bf16_t* pn = z + (size_t)rowr(pq, r) * DM;
; #pragma unroll
;               for (int j = 0; j < 2; ++j) raw[r][j] = *(const pg8::u32x4*)(pn + 8 * lane + 512 * j); } }
;     ...
;         for (int r = 0; r < NR; ++r) { mean[r] = wave_sum_dpp(s[r]) * (1.f / DM); q[r] = 0.f;
; #pragma unroll
;             for (int j = 0; j < 4; ++j) { v[r][j] = v[r][j] - mean[r]; q[r] += (v[r][j][0] * v[r][j][0] + v[r][j][1] * v[r][j][1]) + (v[r][j][2] * v[r][j][2] + v[r][j][3] * v[r][j][3]); } }
; #pragma unroll
;         for (int r = 0; r < NR; ++r) rstd[r] = 1.0f / sqrtf(wave_sum_dpp(q[r]) * (1.f / DM) + 1e-5f);
;         if (MODE == 1) {
; #pragma unroll
;             for (int r = 0; r < NR; ++r) if (lane == r) { stats[2 * row[r]] = mean[r]; stats[2 * row[r] + 1] = rstd[r]; } }
	v_fmac_f32_e32 v58, 0xba800000, v38
	v_mul_f32_e32 v35, v59, v59
	v_mul_f32_e32 v36, v63, v63
	v_fmac_f32_e32 v35, v58, v58
	v_fmac_f32_e32 v36, v62, v62
	v_add_f32_e32 v35, v35, v36
	v_fmac_f32_e32 v42, 0xba800000, v38
	v_fmac_f32_e32 v44, 0xba800000, v38
	v_add_f32_e32 v34, v35, v34
	v_fmac_f32_e32 v60, 0xba800000, v38
	v_fmac_f32_e32 v56, 0xba800000, v38
	v_mul_f32_e32 v35, v44, v44
	v_mul_f32_e32 v36, v42, v42
	v_fmac_f32_e32 v35, v56, v56
	v_fmac_f32_e32 v36, v60, v60
	v_add_f32_e32 v35, v35, v36
	v_add_f32_e32 v34, v35, v34
	s_lshl_b64 s[18:19], s[18:19], 11
	v_add_f32_dpp v35, v40, v40 row_ror:8 row_mask:0xf bank_mask:0xf bound_ctrl:1
	v_add_f32_dpp v34, v34, v34 row_ror:8 row_mask:0xf bank_mask:0xf bound_ctrl:1
	v_mul_f32_e32 v76, 0x3a800000, v45
	v_add_f32_dpp v35, v35, v35 row_ror:4 row_mask:0xf bank_mask:0xf bound_ctrl:1
	v_add_f32_dpp v34, v34, v34 row_ror:4 row_mask:0xf bank_mask:0xf bound_ctrl:1
	v_mul_f32_e32 v90, 0x3a800000, v38
	v_add_f32_dpp v35, v35, v35 row_ror:2 row_mask:0xf bank_mask:0xf bound_ctrl:1
	v_add_f32_dpp v34, v34, v34 row_ror:2 row_mask:0xf bank_mask:0xf bound_ctrl:1
	v_mov_b32_e32 v89, v37
	v_add_f32_dpp v35, v35, v35 row_ror:1 row_mask:0xf bank_mask:0xf bound_ctrl:1
	v_add_f32_dpp v34, v34, v34 row_ror:1 row_mask:0xf bank_mask:0xf bound_ctrl:1
	v_readlane_b32 s8, v35, 0
	v_readlane_b32 s11, v35, 16
	v_readlane_b32 s9, v35, 32
	v_readlane_b32 s13, v35, 48
	v_readlane_b32 s0, v34, 0
	v_readlane_b32 s3, v34, 16
	v_readlane_b32 s2, v34, 32
	v_readlane_b32 s10, v34, 48
	v_lshl_add_u64 v[34:35], v[50:51], 0, s[18:19]
	s_or_b32 s18, s1, 63
	s_ashr_i32 s19, s18, 31
	s_lshl_b64 s[18:19], s[18:19], 11
	v_lshl_add_u64 v[46:47], v[50:51], 0, s[18:19]
	v_mov_b32_e32 v57, v44
	v_mov_b32_e32 v61, v42
	v_mov_b32_e32 v65, v82
	v_mov_b32_e32 v82, v86
	v_mov_b32_e32 v86, v98
	v_mov_b32_e32 v88, v99
	v_mov_b32_e32 v98, s11
	v_mov_b32_e32 v99, s13
	v_pk_add_f32 v[98:99], s[8:9], v[98:99]
	s_nop 0
	v_add_f32_e32 v77, v98, v99
	v_fmamk_f32 v77, v77, 0x3a800000, v95
	v_mul_f32_e32 v91, 0x4f800000, v77
	v_cmp_gt_f32_e32 vcc, s14, v77
	v_mov_b32_e32 v98, s3
	v_mov_b32_e32 v99, s10
	v_cndmask_b32_e32 v77, v77, v91, vcc
	v_sqrt_f32_e32 v91, v77
	v_add_f32_e32 v98, s0, v98
	v_add_f32_e32 v99, s2, v99
	v_add_f32_e32 v98, v98, v99
	v_add_u32_e32 v92, -1, v91
	v_fma_f32 v94, -v92, v91, v77
	v_cmp_ge_f32_e64 s[8:9], 0, v94
	v_add_u32_e32 v94, 1, v91
	v_fmamk_f32 v98, v98, 0x3a800000, v95
	v_cndmask_b32_e64 v92, v91, v92, s[8:9]
	v_fma_f32 v91, -v94, v91, v77
	v_cmp_lt_f32_e64 s[8:9], 0, v91
	v_mul_f32_e32 v99, 0x4f800000, v98
	s_nop 0
	v_cndmask_b32_e64 v91, v92, v94, s[8:9]
	v_mul_f32_e32 v92, 0x37800000, v91
	v_cndmask_b32_e32 v91, v91, v92, vcc
	v_cmp_class_f32_e32 vcc, v77, v96
	s_nop 1
	v_cndmask_b32_e32 v77, v91, v77, vcc
	v_div_scale_f32 v91, s[8:9], v77, v77, 1.0
	v_rcp_f32_e32 v92, v91
	v_cmp_gt_f32_e64 s[8:9], s14, v98
	v_fma_f32 v94, -v91, v92, 1.0
	s_nop 0
	v_cndmask_b32_e64 v98, v98, v99, s[8:9]
	v_fmac_f32_e32 v92, v94, v92
	v_div_scale_f32 v94, vcc, 1.0, v77, 1.0
	v_sqrt_f32_e32 v99, v98
	v_mul_f32_e32 v97, v94, v92
	v_fma_f32 v100, -v91, v97, v94
	v_fmac_f32_e32 v97, v100, v92
	v_fma_f32 v91, -v91, v97, v94
	v_add_u32_e32 v94, -1, v99
	v_fma_f32 v100, -v94, v99, v98
	v_cmp_ge_f32_e64 s[10:11], 0, v100
	v_add_u32_e32 v100, 1, v99
	v_div_fmas_f32 v91, v91, v92, v97
	v_cndmask_b32_e64 v94, v99, v94, s[10:11]
	v_fma_f32 v99, -v100, v99, v98
	v_cmp_lt_f32_e64 s[10:11], 0, v99
	s_nop 1
	v_cndmask_b32_e64 v94, v94, v100, s[10:11]
	v_mul_f32_e32 v99, 0x37800000, v94
	v_cndmask_b32_e64 v94, v94, v99, s[8:9]
	v_cmp_class_f32_e64 s[8:9], v98, v96
	s_mov_b64 s[10:11], -1
	s_nop 0
	v_cndmask_b32_e64 v98, v94, v98, s[8:9]
	v_div_scale_f32 v99, s[0:1], v98, v98, 1.0
	v_rcp_f32_e32 v100, v99
	v_div_fixup_f32 v94, v91, v77, 1.0
	v_fma_f32 v77, -v99, v100, 1.0
	v_fmac_f32_e32 v100, v77, v100
	v_div_scale_f32 v77, vcc, 1.0, v98, 1.0
	v_mul_f32_e32 v91, v77, v100
	v_fma_f32 v92, -v99, v91, v77
	v_fmac_f32_e32 v91, v92, v100
	v_fma_f32 v77, -v99, v91, v77
	v_div_fmas_f32 v77, v77, v100, v91
	v_div_fixup_f32 v92, v77, v98, 1.0
	v_mov_b32_e32 v77, v94
	v_cmp_lt_i32_e32 vcc, 0, v1
	v_mov_b32_e32 v91, s22
	s_and_saveexec_b64 s[8:9], vcc
	s_cbranch_execz .Lhln15_m0
	v_cmp_eq_u32_e32 vcc, 1, v1
	s_mov_b64 s[10:11], 0
	s_and_saveexec_b64 s[26:27], vcc
	v_mov_b32_e32 v91, v92
	s_mov_b64 s[10:11], exec
	v_mov_b64_e32 v[76:77], v[90:91]
	s_or_b64 exec, exec, s[26:27]
	v_mov_b32_e32 v91, s12
	s_orn2_b64 s[10:11], s[10:11], exec

; __device__ __forceinline__ unsigned cvtpk(float lo, float hi) { f32x2_t v = {lo, hi}; bf16x2_t b = __builtin_convertvector(v, bf16x2_t); return __builtin_bit_cast(unsigned, b); }
;     ...
;         f32x4 v[NR][4]; float s[NR];
; #pragma unroll
;         for (int r = 0; r < NR; ++r) { s[r] = 0.f;
; #pragma unroll
;             for (int j = 0; j < 2; ++j) {
;                 v[r][2 * j][0] = __builtin_bit_cast(float, raw[r][j].x << 16); v[r][2 * j][1] = __builtin_bit_cast(float, raw[r][j].x & 0xffff0000u);
;                 v[r][2 * j][2] = __builtin_bit_cast(float, raw[r][j].y << 16); v[r][2 * j][3] = __builtin_bit_cast(float, raw[r][j].y & 0xffff0000u);
;                 v[r][2 * j + 1][0] = __builtin_bit_cast(float, raw[r][j].z << 16); v[r][2 * j + 1][1] = __builtin_bit_cast(float, raw[r][j].z & 0xffff0000u);
;                 v[r][2 * j + 1][2] = __builtin_bit_cast(float, raw[r][j].w << 16); v[r][2 * j + 1][3] = __builtin_bit_cast(float, raw[r][j].w & 0xffff0000u); } }
;         { const int nxt = pi + NP * pstep, pq = nxt < p1 ? nxt : pi;
; #pragma unroll
;           for (int r = 0; r < NR; ++r) { const bf16_t* pn = z + (size_t)rowr(pq, r) * DM;
; #pragma unroll
;               for (int j = 0; j < 2; ++j) raw[r][j] = *(const pg8::u32x4*)(pn + 8 * lane + 512 * j); } }
; #pragma unroll
;         for (int r = 0; r < NR; ++r)
; #pragma unroll
;             for (int j = 0; j < 4; ++j) s[r] += (v[r][j][0] + v[r][j][1]) + (v[r][j][2] + v[r][j][3]);
;         float mean[NR], q[NR], rstd[NR];
; #pragma unroll
;         for (int r = 0; r < NR; ++r) { mean[r] = wave_sum_dpp(s[r]) * (1.f / DM); q[r] = 0.f;
;     ...
;         for (int j = 0; j < 2; ++j) {
;             const int c = 8 * lane + 512 * j;
;             const f32x4 g0 = *(const f32x4*)(g + c), g1 = *(const f32x4*)(g + c + 4), b0 = *(const f32x4*)(b + c), b1 = *(const f32x4*)(b + c + 4);
; #pragma unroll
;             for (int r = 0; r < NR; ++r) {
;                 const f32x4 o0 = v[r][2 * j] * rstd[r] * g0 + b0, o1 = v[r][2 * j + 1] * rstd[r] * g1 + b1;
;                 if (MODE == 1) { pg8::u32x4 w; w.x = cvtpk(o0[0], o0[1]); w.y = cvtpk(o0[2], o0[3]); w.z = cvtpk(o1[0], o1[1]); w.w = cvtpk(o1[2], o1[3]); *(pg8::u32x4*)(hb + (size_t)row[r] * DM + c) = w; }
;                 else { *(f32x4*)(outf + (size_t)row[r] * DM + c) = o0; *(f32x4*)(outf + (size_t)row[r] * DM + c + 4) = o1; }
;             }
;         }
.Lhln15_t0:
	s_or_b64 exec, exec, s[8:9]
	s_add_i32 s0, s12, -1
	v_pk_mul_f32 v[74:75], v[74:75], v[94:95] op_sel_hi:[1,0]
	v_pk_mul_f32 v[72:73], v[72:73], v[94:95] op_sel_hi:[1,0]
	v_pk_mul_f32 v[76:77], v[80:81], v[94:95] op_sel_hi:[1,0]
	v_pk_mul_f32 v[78:79], v[78:79], v[94:95] op_sel_hi:[1,0]
	s_ashr_i32 s1, s0, 31
	v_pk_fma_f32 v[74:75], v[12:13], v[74:75], v[16:17]
	v_pk_fma_f32 v[72:73], v[10:11], v[72:73], v[14:15]
	v_pk_fma_f32 v[76:77], v[4:5], v[76:77], v[8:9]
	v_pk_fma_f32 v[78:79], v[2:3], v[78:79], v[6:7]
	s_lshl_b64 s[0:1], s[0:1], 11
	v_cvt_pk_bf16_f32 v72, v72, v73
	v_cvt_pk_bf16_f32 v73, v74, v75
	v_cvt_pk_bf16_f32 v74, v78, v79
	v_cvt_pk_bf16_f32 v75, v76, v77
	v_lshl_add_u64 v[76:77], v[52:53], 0, s[0:1]
	global_store_dwordx4 v[76:77], v[72:75], off
	v_pk_mul_f32 v[78:79], v[86:87], v[92:93] op_sel_hi:[1,0]
	s_ashr_i32 s13, s12, 31
	v_pk_mul_f32 v[72:73], v[84:85], v[92:93] op_sel_hi:[1,0]
	v_pk_mul_f32 v[74:75], v[82:83], v[92:93] op_sel_hi:[1,0]
	v_pk_fma_f32 v[76:77], v[12:13], v[72:73], v[16:17]
	v_pk_fma_f32 v[72:73], v[10:11], v[74:75], v[14:15]
	v_pk_mul_f32 v[74:75], v[88:89], v[92:93] op_sel_hi:[1,0]
	s_lshl_b64 s[2:3], s[12:13], 11
	v_pk_fma_f32 v[80:81], v[4:5], v[74:75], v[8:9]
	v_pk_fma_f32 v[74:75], v[2:3], v[78:79], v[6:7]
	v_cvt_pk_bf16_f32 v72, v72, v73
	v_cvt_pk_bf16_f32 v73, v76, v77
	v_cvt_pk_bf16_f32 v74, v74, v75
	v_cvt_pk_bf16_f32 v75, v80, v81
	v_lshl_add_u64 v[76:77], v[52:53], 0, s[2:3]
	v_pk_mul_f32 v[70:71], v[70:71], v[94:95] op_sel_hi:[1,0]
	v_pk_mul_f32 v[68:69], v[68:69], v[94:95] op_sel_hi:[1,0]
	v_pk_mul_f32 v[66:67], v[66:67], v[94:95] op_sel_hi:[1,0]
	v_pk_mul_f32 v[64:65], v[64:65], v[94:95] op_sel_hi:[1,0]
	global_store_dwordx4 v[76:77], v[72:75], off
	v_pk_fma_f32 v[70:71], v[28:29], v[70:71], v[32:33]
	v_pk_fma_f32 v[68:69], v[26:27], v[68:69], v[30:31]
	v_pk_fma_f32 v[72:73], v[20:21], v[66:67], v[24:25]
	v_pk_fma_f32 v[66:67], v[18:19], v[64:65], v[22:23]
	v_cvt_pk_bf16_f32 v64, v68, v69
	v_cvt_pk_bf16_f32 v65, v70, v71
	v_cvt_pk_bf16_f32 v66, v66, v67
	v_cvt_pk_bf16_f32 v67, v72, v73
	v_lshl_add_u64 v[68:69], v[54:55], 0, s[0:1]
	v_pk_mul_f32 v[62:63], v[62:63], v[92:93] op_sel_hi:[1,0]
	v_pk_mul_f32 v[58:59], v[58:59], v[92:93] op_sel_hi:[1,0]
	v_pk_mul_f32 v[60:61], v[60:61], v[92:93] op_sel_hi:[1,0]
	v_pk_mul_f32 v[56:57], v[56:57], v[92:93] op_sel_hi:[1,0]
	global_store_dwordx4 v[68:69], v[64:67], off
	v_pk_fma_f32 v[62:63], v[28:29], v[62:63], v[32:33]
	v_pk_fma_f32 v[58:59], v[26:27], v[58:59], v[30:31]
	v_pk_fma_f32 v[60:61], v[20:21], v[60:61], v[24:25]
	v_pk_fma_f32 v[64:65], v[18:19], v[56:57], v[22:23]
	v_cvt_pk_bf16_f32 v56, v58, v59
	v_cvt_pk_bf16_f32 v57, v62, v63
	v_cvt_pk_bf16_f32 v58, v64, v65
	v_cvt_pk_bf16_f32 v59, v60, v61
	v_lshl_add_u64 v[60:61], v[54:55], 0, s[2:3]
	s_andn2_b64 vcc, exec, s[20:21]
	s_addk_i32 s12, 0x200
	global_store_dwordx4 v[60:61], v[56:59], off
	s_cbranch_vccz .LBB0_1752
	s_waitcnt vmcnt(20)
	v_lshlrev_b32_e32 v58, 16, v168
	v_and_b32_e32 v59, 0xffff0000, v168
	v_lshlrev_b32_e32 v62, 16, v169
	v_and_b32_e32 v63, 0xffff0000, v169
	v_lshlrev_b32_e32 v47, 16, v161
	v_lshlrev_b32_e32 v46, 16, v160
	v_and_b32_e32 v39, 0xffff0000, v161
	v_and_b32_e32 v38, 0xffff0000, v160
	v_lshlrev_b32_e32 v68, 16, v164
	v_and_b32_e32 v69, 0xffff0000, v164
	v_lshlrev_b32_e32 v64, 16, v166
	v_and_b32_e32 v82, 0xffff0000, v166
	v_lshlrev_b32_e32 v56, 16, v170
	v_and_b32_e32 v44, 0xffff0000, v170
	v_lshlrev_b32_e32 v60, 16, v171
	v_and_b32_e32 v42, 0xffff0000, v171
	v_pk_add_f32 v[48:49], v[46:47], v[38:39]
	v_lshlrev_b32_e32 v70, 16, v165
	v_and_b32_e32 v71, 0xffff0000, v165
	v_add_f32_e32 v43, v48, v49
	v_lshlrev_b32_e32 v49, 16, v163
	v_lshlrev_b32_e32 v48, 16, v162
	v_and_b32_e32 v41, 0xffff0000, v163
	v_and_b32_e32 v40, 0xffff0000, v162
	v_pk_add_f32 v[72:73], v[48:49], v[40:41]
	v_lshlrev_b32_e32 v66, 16, v167
	v_pk_add_f32 v[72:73], v[72:73], v[72:73] op_sel_hi:[0,1]
	v_and_b32_e32 v84, 0xffff0000, v167
	v_add_f32_e32 v85, 0, v43
	v_add_f32_e32 v65, v68, v69
	v_add_f32_e32 v83, v70, v71
	v_mov_b32_e32 v67, v73
	v_pk_add_f32 v[74:75], v[64:65], v[82:83]
	v_pk_add_f32 v[72:73], v[66:67], v[84:85]
	v_lshlrev_b32_e32 v87, 16, v157
	v_pk_add_f32 v[72:73], v[74:75], v[72:73]
	v_lshlrev_b32_e32 v86, 16, v156
	v_and_b32_e32 v35, 0xffff0000, v157
	v_and_b32_e32 v34, 0xffff0000, v156
	v_add_f32_e32 v65, v72, v73
	v_pk_add_f32 v[72:73], v[86:87], v[34:35]
	v_lshlrev_b32_e32 v99, 16, v159
	v_lshlrev_b32_e32 v98, 16, v158
	v_and_b32_e32 v37, 0xffff0000, v159
	v_and_b32_e32 v36, 0xffff0000, v158
	v_add_f32_e32 v57, v58, v59
	v_add_f32_e32 v45, v62, v63
	v_add_f32_e32 v43, v72, v73
	v_pk_add_f32 v[72:73], v[98:99], v[36:37]
	v_pk_add_f32 v[74:75], v[56:57], v[44:45]
	v_add_f32_dpp v45, v65, v65 row_ror:8 row_mask:0xf bank_mask:0xf bound_ctrl:1
	v_pk_add_f32 v[72:73], v[72:73], v[72:73] op_sel_hi:[0,1]
	v_add_f32_e32 v43, 0, v43
	v_add_f32_dpp v45, v45, v45 row_ror:4 row_mask:0xf bank_mask:0xf bound_ctrl:1
	v_mov_b32_e32 v61, v73
	v_pk_add_f32 v[72:73], v[60:61], v[42:43]
	v_add_f32_dpp v45, v45, v45 row_ror:2 row_mask:0xf bank_mask:0xf bound_ctrl:1
	v_pk_add_f32 v[72:73], v[74:75], v[72:73]
	s_mov_b32 s1, s15
	v_add_f32_dpp v45, v45, v45 row_ror:1 row_mask:0xf bank_mask:0xf bound_ctrl:1
	v_add_f32_e32 v43, v72, v73
	v_readlane_b32 s0, v45, 16
	v_readlane_b32 s8, v45, 48
	v_readlane_b32 s2, v45, 0
	v_readlane_b32 s3, v45, 32
	v_mov_b32_e32 v72, s0
	v_mov_b32_e32 v73, s8
	v_pk_add_f32 v[72:73], s[2:3], v[72:73]
	s_lshl_b32 s15, s15, 6
	v_add_f32_e32 v45, v72, v73
	v_fmac_f32_e32 v39, 0xba800000, v45
	v_fmac_f32_e32 v47, 0xba800000, v45
	v_fmac_f32_e32 v38, 0xba800000, v45
; __device__ __forceinline__ float wave_sum_dpp(float x) { x = rowsum16(x); return (rl(x, 0) + rl(x, 16)) + (rl(x, 32) + rl(x, 48)); }
;     ...
;         float mean[NR], q[NR], rstd[NR];
; #pragma unroll
;         for (int r = 0; r < NR; ++r) { mean[r] = wave_sum_dpp(s[r]) * (1.f / DM); q[r] = 0.f;
; #pragma unroll
;             for (int j = 0; j < 4; ++j) { v[r][j] = v[r][j] - mean[r]; q[r] += (v[r][j][0] * v[r][j][0] + v[r][j][1] * v[r][j][1]) + (v[r][j][2] * v[r][j][2] + v[r][j][3] * v[r][j][3]); } }
; #pragma unroll
;         for (int r = 0; r < NR; ++r) rstd[r] = 1.0f / sqrtf(wave_sum_dpp(q[r]) * (1.f / DM) + 1e-5f);
	v_fmac_f32_e32 v46, 0xba800000, v45
	v_mov_b32_e32 v74, v47
	v_mov_b32_e32 v78, v47
	v_mov_b32_e32 v79, v39
	v_mov_b32_e32 v47, v38
	v_mov_b32_e32 v73, v38
	v_mov_b32_e32 v75, v39
	v_pk_mul_f32 v[78:79], v[78:79], v[78:79]
	v_pk_mul_f32 v[38:39], v[46:47], v[46:47]
	v_mov_b32_e32 v72, v46
	v_pk_mov_b32 v[46:47], v[38:39], v[78:79] op_sel:[1,0]
	v_mov_b32_e32 v39, v79
	v_fmac_f32_e32 v41, 0xba800000, v45
	v_fmac_f32_e32 v49, 0xba800000, v45
	v_fmac_f32_e32 v40, 0xba800000, v45
	v_pk_add_f32 v[38:39], v[46:47], v[38:39]
	v_fmac_f32_e32 v48, 0xba800000, v45
	v_mov_b32_e32 v80, v49
	v_mov_b32_e32 v46, v49
	v_mov_b32_e32 v47, v41
	v_mov_b32_e32 v49, v40
	v_pk_add_f32 v[38:39], v[38:39], v[38:39] op_sel_hi:[0,1]
	v_mov_b32_e32 v79, v40
	v_mov_b32_e32 v81, v41
	v_pk_mul_f32 v[46:47], v[46:47], v[46:47]
	v_pk_mul_f32 v[40:41], v[48:49], v[48:49]
	v_fmac_f32_e32 v68, 0xba800000, v45
	v_mov_b32_e32 v78, v48
	v_pk_mov_b32 v[48:49], v[40:41], v[46:47] op_sel:[1,0]
	v_mov_b32_e32 v41, v47
	v_fmac_f32_e32 v70, 0xba800000, v45
	v_fmac_f32_e32 v69, 0xba800000, v45
	v_mul_f32_e32 v38, v68, v68
	v_pk_add_f32 v[40:41], v[48:49], v[40:41]
	v_fmac_f32_e32 v71, 0xba800000, v45
	v_pk_fma_f32 v[46:47], v[68:69], v[68:69], v[38:39] op_sel_hi:[1,1,0]
	v_mul_f32_e32 v38, v70, v70
	v_pk_add_f32 v[40:41], v[40:41], v[40:41] op_sel_hi:[0,1]
	v_pk_fma_f32 v[48:49], v[70:71], v[70:71], v[38:39] op_sel_hi:[1,1,0]
	v_fmac_f32_e32 v84, 0xba800000, v45
	v_fmac_f32_e32 v66, 0xba800000, v45
	v_fmac_f32_e32 v82, 0xba800000, v45
	v_fmac_f32_e32 v64, 0xba800000, v45
	v_mul_f32_e32 v46, v64, v64
	v_mul_f32_e32 v48, v82, v82
	v_mul_f32_e32 v38, v66, v66
	v_mul_f32_e32 v40, v84, v84
	v_pk_add_f32 v[46:47], v[46:47], v[48:49]
	v_pk_add_f32 v[38:39], v[38:39], v[40:41]
	v_mov_b32_e32 v67, v84
	v_pk_add_f32 v[38:39], v[46:47], v[38:39]
	s_or_b32 s22, s15, 62
	v_add_f32_e32 v40, v38, v39
	v_add_f32_dpp v38, v43, v43 row_ror:8 row_mask:0xf bank_mask:0xf bound_ctrl:1
	s_add_i32 s15, s1, 8
	s_cmp_ge_i32 s1, s5
	v_add_f32_dpp v38, v38, v38 row_ror:4 row_mask:0xf bank_mask:0xf bound_ctrl:1
	s_cselect_b64 s[20:21], -1, 0
	s_cmp_lt_i32 s1, s5
	v_add_f32_dpp v38, v38, v38 row_ror:2 row_mask:0xf bank_mask:0xf bound_ctrl:1
	s_cselect_b32 s1, s15, s1
	s_lshl_b32 s1, s1, 6
	v_add_f32_dpp v38, v38, v38 row_ror:1 row_mask:0xf bank_mask:0xf bound_ctrl:1
	s_or_b32 s18, s1, 62
	v_readlane_b32 s0, v38, 16
	v_readlane_b32 s8, v38, 48
	v_readlane_b32 s2, v38, 0
	v_readlane_b32 s3, v38, 32
	v_mov_b32_e32 v38, s0
	v_mov_b32_e32 v39, s8
	v_pk_add_f32 v[38:39], s[2:3], v[38:39]
	s_ashr_i32 s19, s18, 31
	v_add_f32_e32 v38, v38, v39
	v_fmac_f32_e32 v35, 0xba800000, v38
	v_fmac_f32_e32 v34, 0xba800000, v38
	v_fmac_f32_e32 v87, 0xba800000, v38
	v_fmac_f32_e32 v86, 0xba800000, v38
	v_mov_b32_e32 v83, v34
	v_mov_b32_e32 v85, v35
	v_mul_f32_e32 v34, v34, v34
	v_mul_f32_e32 v35, v35, v35
	v_fmac_f32_e32 v34, v86, v86
	v_fmac_f32_e32 v35, v87, v87
	v_fmac_f32_e32 v37, 0xba800000, v38
	v_fmac_f32_e32 v36, 0xba800000, v38
	v_mov_b32_e32 v84, v87
	v_add_f32_e32 v34, v34, v35
	v_fmac_f32_e32 v99, 0xba800000, v38
	v_fmac_f32_e32 v98, 0xba800000, v38
	v_mov_b32_e32 v87, v36
	v_mul_f32_e32 v35, v36, v36
	v_mul_f32_e32 v36, v37, v37
	v_fmac_f32_e32 v35, v98, v98
	v_fmac_f32_e32 v36, v99, v99
	v_add_f32_e32 v35, v35, v36
	v_fmac_f32_e32 v63, 0xba800000, v38
	v_fmac_f32_e32 v59, 0xba800000, v38
	v_add_f32_e32 v34, v34, v35
	v_fmac_f32_e32 v62, 0xba800000, v38
	v_fmac_f32_e32 v58, 0xba800000, v38
	v_mul_f32_e32 v35, v59, v59
	v_mul_f32_e32 v36, v63, v63
	v_fmac_f32_e32 v35, v58, v58
	v_fmac_f32_e32 v36, v62, v62
	v_add_f32_e32 v35, v35, v36
	v_fmac_f32_e32 v42, 0xba800000, v38
	v_fmac_f32_e32 v44, 0xba800000, v38
	v_add_f32_e32 v34, v35, v34
	v_fmac_f32_e32 v60, 0xba800000, v38
	v_fmac_f32_e32 v56, 0xba800000, v38
	v_mul_f32_e32 v35, v44, v44
	v_mul_f32_e32 v36, v42, v42
	v_fmac_f32_e32 v35, v56, v56
	v_fmac_f32_e32 v36, v60, v60
	v_add_f32_e32 v35, v35, v36
	v_add_f32_e32 v34, v35, v34
	s_lshl_b64 s[18:19], s[18:19], 11
	v_add_f32_dpp v35, v40, v40 row_ror:8 row_mask:0xf bank_mask:0xf bound_ctrl:1
	v_add_f32_dpp v34, v34, v34 row_ror:8 row_mask:0xf bank_mask:0xf bound_ctrl:1
; __device__ __forceinline__ float wave_sum_dpp(float x) { x = rowsum16(x); return (rl(x, 0) + rl(x, 16)) + (rl(x, 32) + rl(x, 48)); }
;     ...
;         { const int nxt = pi + NP * pstep, pq = nxt < p1 ? nxt : pi;
; #pragma unroll
;           for (int r = 0; r < NR; ++r) { const bf16_t* pn = z + (size_t)rowr(pq, r) * DM;
; #pragma unroll
;               for (int j = 0; j < 2; ++j) raw[r][j] = *(const pg8::u32x4*)(pn + 8 * lane + 512 * j); } }
;     ...
;         for (int r = 0; r < NR; ++r) { mean[r] = wave_sum_dpp(s[r]) * (1.f / DM); q[r] = 0.f;
; #pragma unroll
;             for (int j = 0; j < 4; ++j) { v[r][j] = v[r][j] - mean[r]; q[r] += (v[r][j][0] * v[r][j][0] + v[r][j][1] * v[r][j][1]) + (v[r][j][2] * v[r][j][2] + v[r][j][3] * v[r][j][3]); } }
; #pragma unroll
;         for (int r = 0; r < NR; ++r) rstd[r] = 1.0f / sqrtf(wave_sum_dpp(q[r]) * (1.f / DM) + 1e-5f);
;         if (MODE == 1) {
; #pragma unroll
;             for (int r = 0; r < NR; ++r) if (lane == r) { stats[2 * row[r]] = mean[r]; stats[2 * row[r] + 1] = rstd[r]; } }
	v_mul_f32_e32 v76, 0x3a800000, v45
	v_add_f32_dpp v35, v35, v35 row_ror:4 row_mask:0xf bank_mask:0xf bound_ctrl:1
	v_add_f32_dpp v34, v34, v34 row_ror:4 row_mask:0xf bank_mask:0xf bound_ctrl:1
	v_mul_f32_e32 v90, 0x3a800000, v38
	v_add_f32_dpp v35, v35, v35 row_ror:2 row_mask:0xf bank_mask:0xf bound_ctrl:1
	v_add_f32_dpp v34, v34, v34 row_ror:2 row_mask:0xf bank_mask:0xf bound_ctrl:1
	v_mov_b32_e32 v89, v37
	v_add_f32_dpp v35, v35, v35 row_ror:1 row_mask:0xf bank_mask:0xf bound_ctrl:1
	v_add_f32_dpp v34, v34, v34 row_ror:1 row_mask:0xf bank_mask:0xf bound_ctrl:1
	v_readlane_b32 s8, v35, 0
	v_readlane_b32 s11, v35, 16
	v_readlane_b32 s9, v35, 32
	v_readlane_b32 s13, v35, 48
	v_readlane_b32 s0, v34, 0
	v_readlane_b32 s3, v34, 16
	v_readlane_b32 s2, v34, 32
	v_readlane_b32 s10, v34, 48
	s_add_u32 s18, s18, 0x500000
	s_addc_u32 s19, s19, 0
	v_lshl_add_u64 v[34:35], v[50:51], 0, s[18:19]
	s_or_b32 s18, s1, 63
	s_ashr_i32 s19, s18, 31
	s_lshl_b64 s[18:19], s[18:19], 11
	s_add_u32 s18, s18, 0x500000
	s_addc_u32 s19, s19, 0
	v_lshl_add_u64 v[46:47], v[50:51], 0, s[18:19]
	v_mov_b32_e32 v57, v44
	v_mov_b32_e32 v61, v42
	global_load_dwordx4 v[160:163], v[34:35], off
	s_nop 0
	global_load_dwordx4 v[164:167], v[34:35], off offset:1024
	s_nop 0
	global_load_dwordx4 v[156:159], v[46:47], off
	s_nop 0
	global_load_dwordx4 v[168:171], v[46:47], off offset:1024
	s_nop 0
	v_mov_b32_e32 v65, v82
	v_mov_b32_e32 v82, v86
	v_mov_b32_e32 v86, v98
	v_mov_b32_e32 v88, v99
	v_mov_b32_e32 v98, s11
	v_mov_b32_e32 v99, s13
	v_pk_add_f32 v[98:99], s[8:9], v[98:99]
	s_nop 0
	v_add_f32_e32 v77, v98, v99
	v_fmamk_f32 v77, v77, 0x3a800000, v95
	v_mul_f32_e32 v91, 0x4f800000, v77
	v_cmp_gt_f32_e32 vcc, s14, v77
	v_mov_b32_e32 v98, s3
	v_mov_b32_e32 v99, s10
	v_cndmask_b32_e32 v77, v77, v91, vcc
	v_sqrt_f32_e32 v91, v77
	v_add_f32_e32 v98, s0, v98
	v_add_f32_e32 v99, s2, v99
	v_add_f32_e32 v98, v98, v99
	v_add_u32_e32 v92, -1, v91
	v_fma_f32 v94, -v92, v91, v77
	v_cmp_ge_f32_e64 s[8:9], 0, v94
	v_add_u32_e32 v94, 1, v91
	v_fmamk_f32 v98, v98, 0x3a800000, v95
	v_cndmask_b32_e64 v92, v91, v92, s[8:9]
	v_fma_f32 v91, -v94, v91, v77
	v_cmp_lt_f32_e64 s[8:9], 0, v91
	v_mul_f32_e32 v99, 0x4f800000, v98
	s_nop 0
	v_cndmask_b32_e64 v91, v92, v94, s[8:9]
	v_mul_f32_e32 v92, 0x37800000, v91
	v_cndmask_b32_e32 v91, v91, v92, vcc
	v_cmp_class_f32_e32 vcc, v77, v96
	s_nop 1
	v_cndmask_b32_e32 v77, v91, v77, vcc
	v_div_scale_f32 v91, s[8:9], v77, v77, 1.0
	v_rcp_f32_e32 v92, v91
	v_cmp_gt_f32_e64 s[8:9], s14, v98
	v_fma_f32 v94, -v91, v92, 1.0
	s_nop 0
	v_cndmask_b32_e64 v98, v98, v99, s[8:9]
	v_fmac_f32_e32 v92, v94, v92
	v_div_scale_f32 v94, vcc, 1.0, v77, 1.0
	v_sqrt_f32_e32 v99, v98
	v_mul_f32_e32 v97, v94, v92
	v_fma_f32 v100, -v91, v97, v94
	v_fmac_f32_e32 v97, v100, v92
	v_fma_f32 v91, -v91, v97, v94
	v_add_u32_e32 v94, -1, v99
	v_fma_f32 v100, -v94, v99, v98
	v_cmp_ge_f32_e64 s[10:11], 0, v100
	v_add_u32_e32 v100, 1, v99
	v_div_fmas_f32 v91, v91, v92, v97
	v_cndmask_b32_e64 v94, v99, v94, s[10:11]
	v_fma_f32 v99, -v100, v99, v98
	v_cmp_lt_f32_e64 s[10:11], 0, v99
	s_nop 1
	v_cndmask_b32_e64 v94, v94, v100, s[10:11]
	v_mul_f32_e32 v99, 0x37800000, v94
	v_cndmask_b32_e64 v94, v94, v99, s[8:9]
	v_cmp_class_f32_e64 s[8:9], v98, v96
	s_mov_b64 s[10:11], -1
	s_nop 0
	v_cndmask_b32_e64 v98, v94, v98, s[8:9]
	v_div_scale_f32 v99, s[0:1], v98, v98, 1.0
	v_rcp_f32_e32 v100, v99
	v_div_fixup_f32 v94, v91, v77, 1.0
	v_fma_f32 v77, -v99, v100, 1.0
	v_fmac_f32_e32 v100, v77, v100
	v_div_scale_f32 v77, vcc, 1.0, v98, 1.0
	v_mul_f32_e32 v91, v77, v100
	v_fma_f32 v92, -v99, v91, v77
	v_fmac_f32_e32 v91, v92, v100
	v_fma_f32 v77, -v99, v91, v77
	v_div_fmas_f32 v77, v77, v100, v91
	v_div_fixup_f32 v92, v77, v98, 1.0
	v_mov_b32_e32 v77, v94
	v_cmp_lt_i32_e32 vcc, 0, v1
	v_mov_b32_e32 v91, s22
	s_and_saveexec_b64 s[8:9], vcc
	s_cbranch_execz .Lhln15_m1
	v_cmp_eq_u32_e32 vcc, 1, v1
	s_mov_b64 s[10:11], 0
	s_and_saveexec_b64 s[26:27], vcc
	v_mov_b32_e32 v91, v92
	s_mov_b64 s[10:11], exec
	v_mov_b64_e32 v[76:77], v[90:91]
	s_or_b64 exec, exec, s[26:27]
	v_mov_b32_e32 v91, s12
	s_orn2_b64 s[10:11], s[10:11], exec

; __device__ __forceinline__ unsigned cvtpk(float lo, float hi) { f32x2_t v = {lo, hi}; bf16x2_t b = __builtin_convertvector(v, bf16x2_t); return __builtin_bit_cast(unsigned, b); }
;     ...
;         f32x4 v[NR][4]; float s[NR];
; #pragma unroll
;         for (int r = 0; r < NR; ++r) { s[r] = 0.f;
; #pragma unroll
;             for (int j = 0; j < 2; ++j) {
;                 v[r][2 * j][0] = __builtin_bit_cast(float, raw[r][j].x << 16); v[r][2 * j][1] = __builtin_bit_cast(float, raw[r][j].x & 0xffff0000u);
;                 v[r][2 * j][2] = __builtin_bit_cast(float, raw[r][j].y << 16); v[r][2 * j][3] = __builtin_bit_cast(float, raw[r][j].y & 0xffff0000u);
;                 v[r][2 * j + 1][0] = __builtin_bit_cast(float, raw[r][j].z << 16); v[r][2 * j + 1][1] = __builtin_bit_cast(float, raw[r][j].z & 0xffff0000u);
;                 v[r][2 * j + 1][2] = __builtin_bit_cast(float, raw[r][j].w << 16); v[r][2 * j + 1][3] = __builtin_bit_cast(float, raw[r][j].w & 0xffff0000u); } }
;         { const int nxt = pi + NP * pstep, pq = nxt < p1 ? nxt : pi;
; #pragma unroll
;           for (int r = 0; r < NR; ++r) { const bf16_t* pn = z + (size_t)rowr(pq, r) * DM;
; #pragma unroll
;               for (int j = 0; j < 2; ++j) raw[r][j] = *(const pg8::u32x4*)(pn + 8 * lane + 512 * j); } }
; #pragma unroll
;         for (int r = 0; r < NR; ++r)
; #pragma unroll
;             for (int j = 0; j < 4; ++j) s[r] += (v[r][j][0] + v[r][j][1]) + (v[r][j][2] + v[r][j][3]);
;         float mean[NR], q[NR], rstd[NR];
; #pragma unroll
;         for (int r = 0; r < NR; ++r) { mean[r] = wave_sum_dpp(s[r]) * (1.f / DM); q[r] = 0.f;
;     ...
;         for (int j = 0; j < 2; ++j) {
;             const int c = 8 * lane + 512 * j;
;             const f32x4 g0 = *(const f32x4*)(g + c), g1 = *(const f32x4*)(g + c + 4), b0 = *(const f32x4*)(b + c), b1 = *(const f32x4*)(b + c + 4);
; #pragma unroll
;             for (int r = 0; r < NR; ++r) {
;                 const f32x4 o0 = v[r][2 * j] * rstd[r] * g0 + b0, o1 = v[r][2 * j + 1] * rstd[r] * g1 + b1;
;                 if (MODE == 1) { pg8::u32x4 w; w.x = cvtpk(o0[0], o0[1]); w.y = cvtpk(o0[2], o0[3]); w.z = cvtpk(o1[0], o1[1]); w.w = cvtpk(o1[2], o1[3]); *(pg8::u32x4*)(hb + (size_t)row[r] * DM + c) = w; }
;                 else { *(f32x4*)(outf + (size_t)row[r] * DM + c) = o0; *(f32x4*)(outf + (size_t)row[r] * DM + c + 4) = o1; }
;             }
;         }
.Lhln15_t1:
	s_or_b64 exec, exec, s[8:9]
	s_add_i32 s0, s12, -1
	v_pk_mul_f32 v[74:75], v[74:75], v[94:95] op_sel_hi:[1,0]
	v_pk_mul_f32 v[72:73], v[72:73], v[94:95] op_sel_hi:[1,0]
	v_pk_mul_f32 v[76:77], v[80:81], v[94:95] op_sel_hi:[1,0]
	v_pk_mul_f32 v[78:79], v[78:79], v[94:95] op_sel_hi:[1,0]
	s_ashr_i32 s1, s0, 31
	v_pk_fma_f32 v[74:75], v[12:13], v[74:75], v[16:17]
	v_pk_fma_f32 v[72:73], v[10:11], v[72:73], v[14:15]
	v_pk_fma_f32 v[76:77], v[4:5], v[76:77], v[8:9]
	v_pk_fma_f32 v[78:79], v[2:3], v[78:79], v[6:7]
	s_lshl_b64 s[0:1], s[0:1], 11
	v_cvt_pk_bf16_f32 v72, v72, v73
	v_cvt_pk_bf16_f32 v73, v74, v75
	v_cvt_pk_bf16_f32 v74, v78, v79
	v_cvt_pk_bf16_f32 v75, v76, v77
	v_lshl_add_u64 v[76:77], v[52:53], 0, s[0:1]
	global_store_dwordx4 v[76:77], v[72:75], off
	v_pk_mul_f32 v[78:79], v[86:87], v[92:93] op_sel_hi:[1,0]
	s_ashr_i32 s13, s12, 31
	v_pk_mul_f32 v[72:73], v[84:85], v[92:93] op_sel_hi:[1,0]
	v_pk_mul_f32 v[74:75], v[82:83], v[92:93] op_sel_hi:[1,0]
	v_pk_fma_f32 v[76:77], v[12:13], v[72:73], v[16:17]
	v_pk_fma_f32 v[72:73], v[10:11], v[74:75], v[14:15]
	v_pk_mul_f32 v[74:75], v[88:89], v[92:93] op_sel_hi:[1,0]
	s_lshl_b64 s[2:3], s[12:13], 11
	v_pk_fma_f32 v[80:81], v[4:5], v[74:75], v[8:9]
	v_pk_fma_f32 v[74:75], v[2:3], v[78:79], v[6:7]
	v_cvt_pk_bf16_f32 v72, v72, v73
	v_cvt_pk_bf16_f32 v73, v76, v77
	v_cvt_pk_bf16_f32 v74, v74, v75
	v_cvt_pk_bf16_f32 v75, v80, v81
	v_lshl_add_u64 v[76:77], v[52:53], 0, s[2:3]
	v_pk_mul_f32 v[70:71], v[70:71], v[94:95] op_sel_hi:[1,0]
	v_pk_mul_f32 v[68:69], v[68:69], v[94:95] op_sel_hi:[1,0]
	v_pk_mul_f32 v[66:67], v[66:67], v[94:95] op_sel_hi:[1,0]
	v_pk_mul_f32 v[64:65], v[64:65], v[94:95] op_sel_hi:[1,0]
	global_store_dwordx4 v[76:77], v[72:75], off
	v_pk_fma_f32 v[70:71], v[28:29], v[70:71], v[32:33]
	v_pk_fma_f32 v[68:69], v[26:27], v[68:69], v[30:31]
	v_pk_fma_f32 v[72:73], v[20:21], v[66:67], v[24:25]
	v_pk_fma_f32 v[66:67], v[18:19], v[64:65], v[22:23]
	v_cvt_pk_bf16_f32 v64, v68, v69
	v_cvt_pk_bf16_f32 v65, v70, v71
	v_cvt_pk_bf16_f32 v66, v66, v67
	v_cvt_pk_bf16_f32 v67, v72, v73
	v_lshl_add_u64 v[68:69], v[54:55], 0, s[0:1]
	v_pk_mul_f32 v[62:63], v[62:63], v[92:93] op_sel_hi:[1,0]
	v_pk_mul_f32 v[58:59], v[58:59], v[92:93] op_sel_hi:[1,0]
	v_pk_mul_f32 v[60:61], v[60:61], v[92:93] op_sel_hi:[1,0]
	v_pk_mul_f32 v[56:57], v[56:57], v[92:93] op_sel_hi:[1,0]
	global_store_dwordx4 v[68:69], v[64:67], off
	v_pk_fma_f32 v[62:63], v[28:29], v[62:63], v[32:33]
	v_pk_fma_f32 v[58:59], v[26:27], v[58:59], v[30:31]
	v_pk_fma_f32 v[60:61], v[20:21], v[60:61], v[24:25]
	v_pk_fma_f32 v[64:65], v[18:19], v[56:57], v[22:23]
	v_cvt_pk_bf16_f32 v56, v58, v59
	v_cvt_pk_bf16_f32 v57, v62, v63
	v_cvt_pk_bf16_f32 v58, v64, v65
	v_cvt_pk_bf16_f32 v59, v60, v61
	v_lshl_add_u64 v[60:61], v[54:55], 0, s[2:3]
	s_andn2_b64 vcc, exec, s[20:21]
	s_addk_i32 s12, 0x200
	global_store_dwordx4 v[60:61], v[56:59], off
	s_cbranch_vccz .LBB0_1752
	s_waitcnt vmcnt(20)
	v_lshlrev_b32_e32 v58, 16, v184
	v_and_b32_e32 v59, 0xffff0000, v184
	v_lshlrev_b32_e32 v62, 16, v185
	v_and_b32_e32 v63, 0xffff0000, v185
	v_lshlrev_b32_e32 v47, 16, v177
	v_lshlrev_b32_e32 v46, 16, v176
	v_and_b32_e32 v39, 0xffff0000, v177
	v_and_b32_e32 v38, 0xffff0000, v176
	v_lshlrev_b32_e32 v68, 16, v180
	v_and_b32_e32 v69, 0xffff0000, v180
	v_lshlrev_b32_e32 v64, 16, v182
	v_and_b32_e32 v82, 0xffff0000, v182
	v_lshlrev_b32_e32 v56, 16, v186
	v_and_b32_e32 v44, 0xffff0000, v186
	v_lshlrev_b32_e32 v60, 16, v187
	v_and_b32_e32 v42, 0xffff0000, v187
	v_pk_add_f32 v[48:49], v[46:47], v[38:39]
	v_lshlrev_b32_e32 v70, 16, v181
	v_and_b32_e32 v71, 0xffff0000, v181
	v_add_f32_e32 v43, v48, v49
	v_lshlrev_b32_e32 v49, 16, v179
	v_lshlrev_b32_e32 v48, 16, v178
	v_and_b32_e32 v41, 0xffff0000, v179
	v_and_b32_e32 v40, 0xffff0000, v178
	v_pk_add_f32 v[72:73], v[48:49], v[40:41]
	v_lshlrev_b32_e32 v66, 16, v183
	v_pk_add_f32 v[72:73], v[72:73], v[72:73] op_sel_hi:[0,1]
	v_and_b32_e32 v84, 0xffff0000, v183
	v_add_f32_e32 v85, 0, v43
	v_add_f32_e32 v65, v68, v69
	v_add_f32_e32 v83, v70, v71
	v_mov_b32_e32 v67, v73
	v_pk_add_f32 v[74:75], v[64:65], v[82:83]
	v_pk_add_f32 v[72:73], v[66:67], v[84:85]
	v_lshlrev_b32_e32 v87, 16, v173
	v_pk_add_f32 v[72:73], v[74:75], v[72:73]
	v_lshlrev_b32_e32 v86, 16, v172
	v_and_b32_e32 v35, 0xffff0000, v173
	v_and_b32_e32 v34, 0xffff0000, v172
	v_add_f32_e32 v65, v72, v73
	v_pk_add_f32 v[72:73], v[86:87], v[34:35]
	v_lshlrev_b32_e32 v99, 16, v175
	v_lshlrev_b32_e32 v98, 16, v174
	v_and_b32_e32 v37, 0xffff0000, v175
	v_and_b32_e32 v36, 0xffff0000, v174
	v_add_f32_e32 v57, v58, v59
	v_add_f32_e32 v45, v62, v63
	v_add_f32_e32 v43, v72, v73
	v_pk_add_f32 v[72:73], v[98:99], v[36:37]
	v_pk_add_f32 v[74:75], v[56:57], v[44:45]
	v_add_f32_dpp v45, v65, v65 row_ror:8 row_mask:0xf bank_mask:0xf bound_ctrl:1
	v_pk_add_f32 v[72:73], v[72:73], v[72:73] op_sel_hi:[0,1]
	v_add_f32_e32 v43, 0, v43
	v_add_f32_dpp v45, v45, v45 row_ror:4 row_mask:0xf bank_mask:0xf bound_ctrl:1
	v_mov_b32_e32 v61, v73
	v_pk_add_f32 v[72:73], v[60:61], v[42:43]
	v_add_f32_dpp v45, v45, v45 row_ror:2 row_mask:0xf bank_mask:0xf bound_ctrl:1
	v_pk_add_f32 v[72:73], v[74:75], v[72:73]
	s_mov_b32 s1, s15
	v_add_f32_dpp v45, v45, v45 row_ror:1 row_mask:0xf bank_mask:0xf bound_ctrl:1
	v_add_f32_e32 v43, v72, v73
	v_readlane_b32 s0, v45, 16
	v_readlane_b32 s8, v45, 48
	v_readlane_b32 s2, v45, 0
	v_readlane_b32 s3, v45, 32
	v_mov_b32_e32 v72, s0
	v_mov_b32_e32 v73, s8
	v_pk_add_f32 v[72:73], s[2:3], v[72:73]
	s_lshl_b32 s15, s15, 6
	v_add_f32_e32 v45, v72, v73
	v_fmac_f32_e32 v39, 0xba800000, v45
	v_fmac_f32_e32 v47, 0xba800000, v45
	v_fmac_f32_e32 v38, 0xba800000, v45
; __device__ __forceinline__ float wave_sum_dpp(float x) { x = rowsum16(x); return (rl(x, 0) + rl(x, 16)) + (rl(x, 32) + rl(x, 48)); }
;     ...
;         float mean[NR], q[NR], rstd[NR];
; #pragma unroll
;         for (int r = 0; r < NR; ++r) { mean[r] = wave_sum_dpp(s[r]) * (1.f / DM); q[r] = 0.f;
; #pragma unroll
;             for (int j = 0; j < 4; ++j) { v[r][j] = v[r][j] - mean[r]; q[r] += (v[r][j][0] * v[r][j][0] + v[r][j][1] * v[r][j][1]) + (v[r][j][2] * v[r][j][2] + v[r][j][3] * v[r][j][3]); } }
; #pragma unroll
;         for (int r = 0; r < NR; ++r) rstd[r] = 1.0f / sqrtf(wave_sum_dpp(q[r]) * (1.f / DM) + 1e-5f);
	v_fmac_f32_e32 v46, 0xba800000, v45
	v_mov_b32_e32 v74, v47
	v_mov_b32_e32 v78, v47
	v_mov_b32_e32 v79, v39
	v_mov_b32_e32 v47, v38
	v_mov_b32_e32 v73, v38
	v_mov_b32_e32 v75, v39
	v_pk_mul_f32 v[78:79], v[78:79], v[78:79]
	v_pk_mul_f32 v[38:39], v[46:47], v[46:47]
	v_mov_b32_e32 v72, v46
	v_pk_mov_b32 v[46:47], v[38:39], v[78:79] op_sel:[1,0]
	v_mov_b32_e32 v39, v79
	v_fmac_f32_e32 v41, 0xba800000, v45
	v_fmac_f32_e32 v49, 0xba800000, v45
	v_fmac_f32_e32 v40, 0xba800000, v45
	v_pk_add_f32 v[38:39], v[46:47], v[38:39]
	v_fmac_f32_e32 v48, 0xba800000, v45
	v_mov_b32_e32 v80, v49
	v_mov_b32_e32 v46, v49
	v_mov_b32_e32 v47, v41
	v_mov_b32_e32 v49, v40
	v_pk_add_f32 v[38:39], v[38:39], v[38:39] op_sel_hi:[0,1]
	v_mov_b32_e32 v79, v40
	v_mov_b32_e32 v81, v41
	v_pk_mul_f32 v[46:47], v[46:47], v[46:47]
	v_pk_mul_f32 v[40:41], v[48:49], v[48:49]
	v_fmac_f32_e32 v68, 0xba800000, v45
	v_mov_b32_e32 v78, v48
	v_pk_mov_b32 v[48:49], v[40:41], v[46:47] op_sel:[1,0]
	v_mov_b32_e32 v41, v47
	v_fmac_f32_e32 v70, 0xba800000, v45
	v_fmac_f32_e32 v69, 0xba800000, v45
	v_mul_f32_e32 v38, v68, v68
	v_pk_add_f32 v[40:41], v[48:49], v[40:41]
	v_fmac_f32_e32 v71, 0xba800000, v45
	v_pk_fma_f32 v[46:47], v[68:69], v[68:69], v[38:39] op_sel_hi:[1,1,0]
	v_mul_f32_e32 v38, v70, v70
	v_pk_add_f32 v[40:41], v[40:41], v[40:41] op_sel_hi:[0,1]
	v_pk_fma_f32 v[48:49], v[70:71], v[70:71], v[38:39] op_sel_hi:[1,1,0]
	v_fmac_f32_e32 v84, 0xba800000, v45
	v_fmac_f32_e32 v66, 0xba800000, v45
	v_fmac_f32_e32 v82, 0xba800000, v45
	v_fmac_f32_e32 v64, 0xba800000, v45
	v_mul_f32_e32 v46, v64, v64
	v_mul_f32_e32 v48, v82, v82
	v_mul_f32_e32 v38, v66, v66
	v_mul_f32_e32 v40, v84, v84
	v_pk_add_f32 v[46:47], v[46:47], v[48:49]
	v_pk_add_f32 v[38:39], v[38:39], v[40:41]
	v_mov_b32_e32 v67, v84
	v_pk_add_f32 v[38:39], v[46:47], v[38:39]
	s_or_b32 s22, s15, 62
	v_add_f32_e32 v40, v38, v39
	v_add_f32_dpp v38, v43, v43 row_ror:8 row_mask:0xf bank_mask:0xf bound_ctrl:1
	s_add_i32 s15, s1, 8
	s_cmp_ge_i32 s1, s5
	v_add_f32_dpp v38, v38, v38 row_ror:4 row_mask:0xf bank_mask:0xf bound_ctrl:1
	s_cselect_b64 s[20:21], -1, 0
	s_cmp_lt_i32 s1, s5
	v_add_f32_dpp v38, v38, v38 row_ror:2 row_mask:0xf bank_mask:0xf bound_ctrl:1
	s_cselect_b32 s1, s15, s1
	s_lshl_b32 s1, s1, 6
	v_add_f32_dpp v38, v38, v38 row_ror:1 row_mask:0xf bank_mask:0xf bound_ctrl:1
	s_or_b32 s18, s1, 62
	v_readlane_b32 s0, v38, 16
	v_readlane_b32 s8, v38, 48
	v_readlane_b32 s2, v38, 0
	v_readlane_b32 s3, v38, 32
	v_mov_b32_e32 v38, s0
	v_mov_b32_e32 v39, s8
	v_pk_add_f32 v[38:39], s[2:3], v[38:39]
	s_ashr_i32 s19, s18, 31
	v_add_f32_e32 v38, v38, v39
	v_fmac_f32_e32 v35, 0xba800000, v38
	v_fmac_f32_e32 v34, 0xba800000, v38
	v_fmac_f32_e32 v87, 0xba800000, v38
	v_fmac_f32_e32 v86, 0xba800000, v38
	v_mov_b32_e32 v83, v34
	v_mov_b32_e32 v85, v35
	v_mul_f32_e32 v34, v34, v34
	v_mul_f32_e32 v35, v35, v35
	v_fmac_f32_e32 v34, v86, v86
	v_fmac_f32_e32 v35, v87, v87
	v_fmac_f32_e32 v37, 0xba800000, v38
	v_fmac_f32_e32 v36, 0xba800000, v38
	v_mov_b32_e32 v84, v87
	v_add_f32_e32 v34, v34, v35
	v_fmac_f32_e32 v99, 0xba800000, v38
	v_fmac_f32_e32 v98, 0xba800000, v38
	v_mov_b32_e32 v87, v36
	v_mul_f32_e32 v35, v36, v36
	v_mul_f32_e32 v36, v37, v37
	v_fmac_f32_e32 v35, v98, v98
	v_fmac_f32_e32 v36, v99, v99
	v_add_f32_e32 v35, v35, v36
	v_fmac_f32_e32 v63, 0xba800000, v38
	v_fmac_f32_e32 v59, 0xba800000, v38
	v_add_f32_e32 v34, v34, v35
	v_fmac_f32_e32 v62, 0xba800000, v38
	v_fmac_f32_e32 v58, 0xba800000, v38
	v_mul_f32_e32 v35, v59, v59
	v_mul_f32_e32 v36, v63, v63
	v_fmac_f32_e32 v35, v58, v58
	v_fmac_f32_e32 v36, v62, v62
	v_add_f32_e32 v35, v35, v36
	v_fmac_f32_e32 v42, 0xba800000, v38
	v_fmac_f32_e32 v44, 0xba800000, v38
	v_add_f32_e32 v34, v35, v34
	v_fmac_f32_e32 v60, 0xba800000, v38
	v_fmac_f32_e32 v56, 0xba800000, v38
	v_mul_f32_e32 v35, v44, v44
	v_mul_f32_e32 v36, v42, v42
	v_fmac_f32_e32 v35, v56, v56
	v_fmac_f32_e32 v36, v60, v60
	v_add_f32_e32 v35, v35, v36
	v_add_f32_e32 v34, v35, v34
; __device__ __forceinline__ float wave_sum_dpp(float x) { x = rowsum16(x); return (rl(x, 0) + rl(x, 16)) + (rl(x, 32) + rl(x, 48)); }
;     ...
;         for (int r = 0; r < NR; ++r) { mean[r] = wave_sum_dpp(s[r]) * (1.f / DM); q[r] = 0.f;
; #pragma unroll
;             for (int j = 0; j < 4; ++j) { v[r][j] = v[r][j] - mean[r]; q[r] += (v[r][j][0] * v[r][j][0] + v[r][j][1] * v[r][j][1]) + (v[r][j][2] * v[r][j][2] + v[r][j][3] * v[r][j][3]); } }
; #pragma unroll
;         for (int r = 0; r < NR; ++r) rstd[r] = 1.0f / sqrtf(wave_sum_dpp(q[r]) * (1.f / DM) + 1e-5f);
;         if (MODE == 1) {
; #pragma unroll
;             for (int r = 0; r < NR; ++r) if (lane == r) { stats[2 * row[r]] = mean[r]; stats[2 * row[r] + 1] = rstd[r]; } }
	s_lshl_b64 s[18:19], s[18:19], 11
	v_add_f32_dpp v35, v40, v40 row_ror:8 row_mask:0xf bank_mask:0xf bound_ctrl:1
	v_add_f32_dpp v34, v34, v34 row_ror:8 row_mask:0xf bank_mask:0xf bound_ctrl:1
	v_mul_f32_e32 v76, 0x3a800000, v45
	v_add_f32_dpp v35, v35, v35 row_ror:4 row_mask:0xf bank_mask:0xf bound_ctrl:1
	v_add_f32_dpp v34, v34, v34 row_ror:4 row_mask:0xf bank_mask:0xf bound_ctrl:1
	v_mul_f32_e32 v90, 0x3a800000, v38
	v_add_f32_dpp v35, v35, v35 row_ror:2 row_mask:0xf bank_mask:0xf bound_ctrl:1
	v_add_f32_dpp v34, v34, v34 row_ror:2 row_mask:0xf bank_mask:0xf bound_ctrl:1
	v_mov_b32_e32 v89, v37
	v_add_f32_dpp v35, v35, v35 row_ror:1 row_mask:0xf bank_mask:0xf bound_ctrl:1
	v_add_f32_dpp v34, v34, v34 row_ror:1 row_mask:0xf bank_mask:0xf bound_ctrl:1
	v_readlane_b32 s8, v35, 0
	v_readlane_b32 s11, v35, 16
	v_readlane_b32 s9, v35, 32
	v_readlane_b32 s13, v35, 48
	v_readlane_b32 s0, v34, 0
	v_readlane_b32 s3, v34, 16
	v_readlane_b32 s2, v34, 32
	v_readlane_b32 s10, v34, 48
	v_lshl_add_u64 v[34:35], v[50:51], 0, s[18:19]
	s_or_b32 s18, s1, 63
	s_ashr_i32 s19, s18, 31
	s_lshl_b64 s[18:19], s[18:19], 11
	v_lshl_add_u64 v[46:47], v[50:51], 0, s[18:19]
	v_mov_b32_e32 v57, v44
	v_mov_b32_e32 v61, v42
	v_mov_b32_e32 v65, v82
	v_mov_b32_e32 v82, v86
	v_mov_b32_e32 v86, v98
	v_mov_b32_e32 v88, v99
	v_mov_b32_e32 v98, s11
	v_mov_b32_e32 v99, s13
	v_pk_add_f32 v[98:99], s[8:9], v[98:99]
	s_nop 0
	v_add_f32_e32 v77, v98, v99
	v_fmamk_f32 v77, v77, 0x3a800000, v95
	v_mul_f32_e32 v91, 0x4f800000, v77
	v_cmp_gt_f32_e32 vcc, s14, v77
	v_mov_b32_e32 v98, s3
	v_mov_b32_e32 v99, s10
	v_cndmask_b32_e32 v77, v77, v91, vcc
	v_sqrt_f32_e32 v91, v77
	v_add_f32_e32 v98, s0, v98
	v_add_f32_e32 v99, s2, v99
	v_add_f32_e32 v98, v98, v99
	v_add_u32_e32 v92, -1, v91
	v_fma_f32 v94, -v92, v91, v77
	v_cmp_ge_f32_e64 s[8:9], 0, v94
	v_add_u32_e32 v94, 1, v91
	v_fmamk_f32 v98, v98, 0x3a800000, v95
	v_cndmask_b32_e64 v92, v91, v92, s[8:9]
	v_fma_f32 v91, -v94, v91, v77
	v_cmp_lt_f32_e64 s[8:9], 0, v91
	v_mul_f32_e32 v99, 0x4f800000, v98
	s_nop 0
	v_cndmask_b32_e64 v91, v92, v94, s[8:9]
	v_mul_f32_e32 v92, 0x37800000, v91
	v_cndmask_b32_e32 v91, v91, v92, vcc
	v_cmp_class_f32_e32 vcc, v77, v96
	s_nop 1
	v_cndmask_b32_e32 v77, v91, v77, vcc
	v_div_scale_f32 v91, s[8:9], v77, v77, 1.0
	v_rcp_f32_e32 v92, v91
	v_cmp_gt_f32_e64 s[8:9], s14, v98
	v_fma_f32 v94, -v91, v92, 1.0
	s_nop 0
	v_cndmask_b32_e64 v98, v98, v99, s[8:9]
	v_fmac_f32_e32 v92, v94, v92
	v_div_scale_f32 v94, vcc, 1.0, v77, 1.0
	v_sqrt_f32_e32 v99, v98
	v_mul_f32_e32 v97, v94, v92
	v_fma_f32 v100, -v91, v97, v94
	v_fmac_f32_e32 v97, v100, v92
	v_fma_f32 v91, -v91, v97, v94
	v_add_u32_e32 v94, -1, v99
	v_fma_f32 v100, -v94, v99, v98
	v_cmp_ge_f32_e64 s[10:11], 0, v100
	v_add_u32_e32 v100, 1, v99
	v_div_fmas_f32 v91, v91, v92, v97
	v_cndmask_b32_e64 v94, v99, v94, s[10:11]
	v_fma_f32 v99, -v100, v99, v98
	v_cmp_lt_f32_e64 s[10:11], 0, v99
	s_nop 1
	v_cndmask_b32_e64 v94, v94, v100, s[10:11]
	v_mul_f32_e32 v99, 0x37800000, v94
	v_cndmask_b32_e64 v94, v94, v99, s[8:9]
	v_cmp_class_f32_e64 s[8:9], v98, v96
	s_mov_b64 s[10:11], -1
	s_nop 0
	v_cndmask_b32_e64 v98, v94, v98, s[8:9]
	v_div_scale_f32 v99, s[0:1], v98, v98, 1.0
	v_rcp_f32_e32 v100, v99
	v_div_fixup_f32 v94, v91, v77, 1.0
	v_fma_f32 v77, -v99, v100, 1.0
	v_fmac_f32_e32 v100, v77, v100
	v_div_scale_f32 v77, vcc, 1.0, v98, 1.0
	v_mul_f32_e32 v91, v77, v100
	v_fma_f32 v92, -v99, v91, v77
	v_fmac_f32_e32 v91, v92, v100
	v_fma_f32 v77, -v99, v91, v77
	v_div_fmas_f32 v77, v77, v100, v91
	v_div_fixup_f32 v92, v77, v98, 1.0
	v_mov_b32_e32 v77, v94
	v_cmp_lt_i32_e32 vcc, 0, v1
	v_mov_b32_e32 v91, s22
	s_and_saveexec_b64 s[8:9], vcc
	s_cbranch_execz .Lhln15_m2
	v_cmp_eq_u32_e32 vcc, 1, v1
	s_mov_b64 s[10:11], 0
	s_and_saveexec_b64 s[26:27], vcc
	v_mov_b32_e32 v91, v92
	s_mov_b64 s[10:11], exec
	v_mov_b64_e32 v[76:77], v[90:91]
	s_or_b64 exec, exec, s[26:27]
	v_mov_b32_e32 v91, s12
	s_orn2_b64 s[10:11], s[10:11], exec

; __device__ __forceinline__ unsigned cvtpk(float lo, float hi) { f32x2_t v = {lo, hi}; bf16x2_t b = __builtin_convertvector(v, bf16x2_t); return __builtin_bit_cast(unsigned, b); }
;     ...
;         f32x4 v[NR][4]; float s[NR];
; #pragma unroll
;         for (int r = 0; r < NR; ++r) { s[r] = 0.f;
; #pragma unroll
;             for (int j = 0; j < 2; ++j) {
;                 v[r][2 * j][0] = __builtin_bit_cast(float, raw[r][j].x << 16); v[r][2 * j][1] = __builtin_bit_cast(float, raw[r][j].x & 0xffff0000u);
;                 v[r][2 * j][2] = __builtin_bit_cast(float, raw[r][j].y << 16); v[r][2 * j][3] = __builtin_bit_cast(float, raw[r][j].y & 0xffff0000u);
;                 v[r][2 * j + 1][0] = __builtin_bit_cast(float, raw[r][j].z << 16); v[r][2 * j + 1][1] = __builtin_bit_cast(float, raw[r][j].z & 0xffff0000u);
;                 v[r][2 * j + 1][2] = __builtin_bit_cast(float, raw[r][j].w << 16); v[r][2 * j + 1][3] = __builtin_bit_cast(float, raw[r][j].w & 0xffff0000u); } }
;         { const int nxt = pi + NP * pstep, pq = nxt < p1 ? nxt : pi;
; #pragma unroll
;           for (int r = 0; r < NR; ++r) { const bf16_t* pn = z + (size_t)rowr(pq, r) * DM;
; #pragma unroll
;               for (int j = 0; j < 2; ++j) raw[r][j] = *(const pg8::u32x4*)(pn + 8 * lane + 512 * j); } }
; #pragma unroll
;         for (int r = 0; r < NR; ++r)
; #pragma unroll
;             for (int j = 0; j < 4; ++j) s[r] += (v[r][j][0] + v[r][j][1]) + (v[r][j][2] + v[r][j][3]);
;         float mean[NR], q[NR], rstd[NR];
; #pragma unroll
;         for (int r = 0; r < NR; ++r) { mean[r] = wave_sum_dpp(s[r]) * (1.f / DM); q[r] = 0.f;
;     ...
;         for (int j = 0; j < 2; ++j) {
;             const int c = 8 * lane + 512 * j;
;             const f32x4 g0 = *(const f32x4*)(g + c), g1 = *(const f32x4*)(g + c + 4), b0 = *(const f32x4*)(b + c), b1 = *(const f32x4*)(b + c + 4);
; #pragma unroll
;             for (int r = 0; r < NR; ++r) {
;                 const f32x4 o0 = v[r][2 * j] * rstd[r] * g0 + b0, o1 = v[r][2 * j + 1] * rstd[r] * g1 + b1;
;                 if (MODE == 1) { pg8::u32x4 w; w.x = cvtpk(o0[0], o0[1]); w.y = cvtpk(o0[2], o0[3]); w.z = cvtpk(o1[0], o1[1]); w.w = cvtpk(o1[2], o1[3]); *(pg8::u32x4*)(hb + (size_t)row[r] * DM + c) = w; }
;                 else { *(f32x4*)(outf + (size_t)row[r] * DM + c) = o0; *(f32x4*)(outf + (size_t)row[r] * DM + c + 4) = o1; }
;             }
;         }
.Lhln15_t2:
	s_or_b64 exec, exec, s[8:9]
	s_add_i32 s0, s12, -1
	v_pk_mul_f32 v[74:75], v[74:75], v[94:95] op_sel_hi:[1,0]
	v_pk_mul_f32 v[72:73], v[72:73], v[94:95] op_sel_hi:[1,0]
	v_pk_mul_f32 v[76:77], v[80:81], v[94:95] op_sel_hi:[1,0]
	v_pk_mul_f32 v[78:79], v[78:79], v[94:95] op_sel_hi:[1,0]
	s_ashr_i32 s1, s0, 31
	v_pk_fma_f32 v[74:75], v[12:13], v[74:75], v[16:17]
	v_pk_fma_f32 v[72:73], v[10:11], v[72:73], v[14:15]
	v_pk_fma_f32 v[76:77], v[4:5], v[76:77], v[8:9]
	v_pk_fma_f32 v[78:79], v[2:3], v[78:79], v[6:7]
	s_lshl_b64 s[0:1], s[0:1], 11
	v_cvt_pk_bf16_f32 v72, v72, v73
	v_cvt_pk_bf16_f32 v73, v74, v75
	v_cvt_pk_bf16_f32 v74, v78, v79
	v_cvt_pk_bf16_f32 v75, v76, v77
	v_lshl_add_u64 v[76:77], v[52:53], 0, s[0:1]
	global_store_dwordx4 v[76:77], v[72:75], off
	v_pk_mul_f32 v[78:79], v[86:87], v[92:93] op_sel_hi:[1,0]
	s_ashr_i32 s13, s12, 31
	v_pk_mul_f32 v[72:73], v[84:85], v[92:93] op_sel_hi:[1,0]
	v_pk_mul_f32 v[74:75], v[82:83], v[92:93] op_sel_hi:[1,0]
	v_pk_fma_f32 v[76:77], v[12:13], v[72:73], v[16:17]
	v_pk_fma_f32 v[72:73], v[10:11], v[74:75], v[14:15]
	v_pk_mul_f32 v[74:75], v[88:89], v[92:93] op_sel_hi:[1,0]
	s_lshl_b64 s[2:3], s[12:13], 11
	v_pk_fma_f32 v[80:81], v[4:5], v[74:75], v[8:9]
	v_pk_fma_f32 v[74:75], v[2:3], v[78:79], v[6:7]
	v_cvt_pk_bf16_f32 v72, v72, v73
	v_cvt_pk_bf16_f32 v73, v76, v77
	v_cvt_pk_bf16_f32 v74, v74, v75
	v_cvt_pk_bf16_f32 v75, v80, v81
	v_lshl_add_u64 v[76:77], v[52:53], 0, s[2:3]
	v_pk_mul_f32 v[70:71], v[70:71], v[94:95] op_sel_hi:[1,0]
	v_pk_mul_f32 v[68:69], v[68:69], v[94:95] op_sel_hi:[1,0]
	v_pk_mul_f32 v[66:67], v[66:67], v[94:95] op_sel_hi:[1,0]
	v_pk_mul_f32 v[64:65], v[64:65], v[94:95] op_sel_hi:[1,0]
	global_store_dwordx4 v[76:77], v[72:75], off
	v_pk_fma_f32 v[70:71], v[28:29], v[70:71], v[32:33]
	v_pk_fma_f32 v[68:69], v[26:27], v[68:69], v[30:31]
	v_pk_fma_f32 v[72:73], v[20:21], v[66:67], v[24:25]
	v_pk_fma_f32 v[66:67], v[18:19], v[64:65], v[22:23]
	v_cvt_pk_bf16_f32 v64, v68, v69
	v_cvt_pk_bf16_f32 v65, v70, v71
	v_cvt_pk_bf16_f32 v66, v66, v67
	v_cvt_pk_bf16_f32 v67, v72, v73
	v_lshl_add_u64 v[68:69], v[54:55], 0, s[0:1]
	v_pk_mul_f32 v[62:63], v[62:63], v[92:93] op_sel_hi:[1,0]
	v_pk_mul_f32 v[58:59], v[58:59], v[92:93] op_sel_hi:[1,0]
	v_pk_mul_f32 v[60:61], v[60:61], v[92:93] op_sel_hi:[1,0]
	v_pk_mul_f32 v[56:57], v[56:57], v[92:93] op_sel_hi:[1,0]
	global_store_dwordx4 v[68:69], v[64:67], off
	v_pk_fma_f32 v[62:63], v[28:29], v[62:63], v[32:33]
	v_pk_fma_f32 v[58:59], v[26:27], v[58:59], v[30:31]
	v_pk_fma_f32 v[60:61], v[20:21], v[60:61], v[24:25]
	v_pk_fma_f32 v[64:65], v[18:19], v[56:57], v[22:23]
	v_cvt_pk_bf16_f32 v56, v58, v59
	v_cvt_pk_bf16_f32 v57, v62, v63
	v_cvt_pk_bf16_f32 v58, v64, v65
	v_cvt_pk_bf16_f32 v59, v60, v61
	v_lshl_add_u64 v[60:61], v[54:55], 0, s[2:3]
	s_andn2_b64 vcc, exec, s[20:21]
	s_addk_i32 s12, 0x200
	global_store_dwordx4 v[60:61], v[56:59], off
	s_cbranch_vccz .LBB0_1752
	s_waitcnt vmcnt(20)
	v_lshlrev_b32_e32 v58, 16, v200
	v_and_b32_e32 v59, 0xffff0000, v200
	v_lshlrev_b32_e32 v62, 16, v201
	v_and_b32_e32 v63, 0xffff0000, v201
	v_lshlrev_b32_e32 v47, 16, v193
	v_lshlrev_b32_e32 v46, 16, v192
	v_and_b32_e32 v39, 0xffff0000, v193
	v_and_b32_e32 v38, 0xffff0000, v192
	v_lshlrev_b32_e32 v68, 16, v196
	v_and_b32_e32 v69, 0xffff0000, v196
	v_lshlrev_b32_e32 v64, 16, v198
	v_and_b32_e32 v82, 0xffff0000, v198
	v_lshlrev_b32_e32 v56, 16, v202
	v_and_b32_e32 v44, 0xffff0000, v202
	v_lshlrev_b32_e32 v60, 16, v203
	v_and_b32_e32 v42, 0xffff0000, v203
	v_pk_add_f32 v[48:49], v[46:47], v[38:39]
	v_lshlrev_b32_e32 v70, 16, v197
	v_and_b32_e32 v71, 0xffff0000, v197
	v_add_f32_e32 v43, v48, v49
	v_lshlrev_b32_e32 v49, 16, v195
	v_lshlrev_b32_e32 v48, 16, v194
	v_and_b32_e32 v41, 0xffff0000, v195
	v_and_b32_e32 v40, 0xffff0000, v194
	v_pk_add_f32 v[72:73], v[48:49], v[40:41]
	v_lshlrev_b32_e32 v66, 16, v199
	v_pk_add_f32 v[72:73], v[72:73], v[72:73] op_sel_hi:[0,1]
	v_and_b32_e32 v84, 0xffff0000, v199
	v_add_f32_e32 v85, 0, v43
	v_add_f32_e32 v65, v68, v69
	v_add_f32_e32 v83, v70, v71
	v_mov_b32_e32 v67, v73
	v_pk_add_f32 v[74:75], v[64:65], v[82:83]
	v_pk_add_f32 v[72:73], v[66:67], v[84:85]
	v_lshlrev_b32_e32 v87, 16, v189
	v_pk_add_f32 v[72:73], v[74:75], v[72:73]
	v_lshlrev_b32_e32 v86, 16, v188
	v_and_b32_e32 v35, 0xffff0000, v189
	v_and_b32_e32 v34, 0xffff0000, v188
	v_add_f32_e32 v65, v72, v73
	v_pk_add_f32 v[72:73], v[86:87], v[34:35]
	v_lshlrev_b32_e32 v99, 16, v191
	v_lshlrev_b32_e32 v98, 16, v190
	v_and_b32_e32 v37, 0xffff0000, v191
	v_and_b32_e32 v36, 0xffff0000, v190
	v_add_f32_e32 v57, v58, v59
	v_add_f32_e32 v45, v62, v63
	v_add_f32_e32 v43, v72, v73
	v_pk_add_f32 v[72:73], v[98:99], v[36:37]
	v_pk_add_f32 v[74:75], v[56:57], v[44:45]
	v_add_f32_dpp v45, v65, v65 row_ror:8 row_mask:0xf bank_mask:0xf bound_ctrl:1
	v_pk_add_f32 v[72:73], v[72:73], v[72:73] op_sel_hi:[0,1]
	v_add_f32_e32 v43, 0, v43
	v_add_f32_dpp v45, v45, v45 row_ror:4 row_mask:0xf bank_mask:0xf bound_ctrl:1
	v_mov_b32_e32 v61, v73
	v_pk_add_f32 v[72:73], v[60:61], v[42:43]
	v_add_f32_dpp v45, v45, v45 row_ror:2 row_mask:0xf bank_mask:0xf bound_ctrl:1
	v_pk_add_f32 v[72:73], v[74:75], v[72:73]
	s_mov_b32 s1, s15
	v_add_f32_dpp v45, v45, v45 row_ror:1 row_mask:0xf bank_mask:0xf bound_ctrl:1
	v_add_f32_e32 v43, v72, v73
	v_readlane_b32 s0, v45, 16
	v_readlane_b32 s8, v45, 48
	v_readlane_b32 s2, v45, 0
	v_readlane_b32 s3, v45, 32
	v_mov_b32_e32 v72, s0
	v_mov_b32_e32 v73, s8
	v_pk_add_f32 v[72:73], s[2:3], v[72:73]
	s_lshl_b32 s15, s15, 6
	v_add_f32_e32 v45, v72, v73
	v_fmac_f32_e32 v39, 0xba800000, v45
	v_fmac_f32_e32 v47, 0xba800000, v45
	v_fmac_f32_e32 v38, 0xba800000, v45
; __device__ __forceinline__ float wave_sum_dpp(float x) { x = rowsum16(x); return (rl(x, 0) + rl(x, 16)) + (rl(x, 32) + rl(x, 48)); }
;     ...
;         float mean[NR], q[NR], rstd[NR];
; #pragma unroll
;         for (int r = 0; r < NR; ++r) { mean[r] = wave_sum_dpp(s[r]) * (1.f / DM); q[r] = 0.f;
; #pragma unroll
;             for (int j = 0; j < 4; ++j) { v[r][j] = v[r][j] - mean[r]; q[r] += (v[r][j][0] * v[r][j][0] + v[r][j][1] * v[r][j][1]) + (v[r][j][2] * v[r][j][2] + v[r][j][3] * v[r][j][3]); } }
; #pragma unroll
;         for (int r = 0; r < NR; ++r) rstd[r] = 1.0f / sqrtf(wave_sum_dpp(q[r]) * (1.f / DM) + 1e-5f);
	v_fmac_f32_e32 v46, 0xba800000, v45
	v_mov_b32_e32 v74, v47
	v_mov_b32_e32 v78, v47
	v_mov_b32_e32 v79, v39
	v_mov_b32_e32 v47, v38
	v_mov_b32_e32 v73, v38
	v_mov_b32_e32 v75, v39
	v_pk_mul_f32 v[78:79], v[78:79], v[78:79]
	v_pk_mul_f32 v[38:39], v[46:47], v[46:47]
	v_mov_b32_e32 v72, v46
	v_pk_mov_b32 v[46:47], v[38:39], v[78:79] op_sel:[1,0]
	v_mov_b32_e32 v39, v79
	v_fmac_f32_e32 v41, 0xba800000, v45
	v_fmac_f32_e32 v49, 0xba800000, v45
	v_fmac_f32_e32 v40, 0xba800000, v45
	v_pk_add_f32 v[38:39], v[46:47], v[38:39]
	v_fmac_f32_e32 v48, 0xba800000, v45
	v_mov_b32_e32 v80, v49
	v_mov_b32_e32 v46, v49
	v_mov_b32_e32 v47, v41
	v_mov_b32_e32 v49, v40
	v_pk_add_f32 v[38:39], v[38:39], v[38:39] op_sel_hi:[0,1]
	v_mov_b32_e32 v79, v40
	v_mov_b32_e32 v81, v41
	v_pk_mul_f32 v[46:47], v[46:47], v[46:47]
	v_pk_mul_f32 v[40:41], v[48:49], v[48:49]
	v_fmac_f32_e32 v68, 0xba800000, v45
	v_mov_b32_e32 v78, v48
	v_pk_mov_b32 v[48:49], v[40:41], v[46:47] op_sel:[1,0]
	v_mov_b32_e32 v41, v47
	v_fmac_f32_e32 v70, 0xba800000, v45
	v_fmac_f32_e32 v69, 0xba800000, v45
	v_mul_f32_e32 v38, v68, v68
	v_pk_add_f32 v[40:41], v[48:49], v[40:41]
	v_fmac_f32_e32 v71, 0xba800000, v45
	v_pk_fma_f32 v[46:47], v[68:69], v[68:69], v[38:39] op_sel_hi:[1,1,0]
	v_mul_f32_e32 v38, v70, v70
	v_pk_add_f32 v[40:41], v[40:41], v[40:41] op_sel_hi:[0,1]
	v_pk_fma_f32 v[48:49], v[70:71], v[70:71], v[38:39] op_sel_hi:[1,1,0]
	v_fmac_f32_e32 v84, 0xba800000, v45
	v_fmac_f32_e32 v66, 0xba800000, v45
	v_fmac_f32_e32 v82, 0xba800000, v45
	v_fmac_f32_e32 v64, 0xba800000, v45
	v_mul_f32_e32 v46, v64, v64
	v_mul_f32_e32 v48, v82, v82
	v_mul_f32_e32 v38, v66, v66
	v_mul_f32_e32 v40, v84, v84
	v_pk_add_f32 v[46:47], v[46:47], v[48:49]
	v_pk_add_f32 v[38:39], v[38:39], v[40:41]
	v_mov_b32_e32 v67, v84
	v_pk_add_f32 v[38:39], v[46:47], v[38:39]
	s_or_b32 s22, s15, 62
	v_add_f32_e32 v40, v38, v39
	v_add_f32_dpp v38, v43, v43 row_ror:8 row_mask:0xf bank_mask:0xf bound_ctrl:1
	s_add_i32 s15, s1, 8
	s_cmp_ge_i32 s1, s5
	v_add_f32_dpp v38, v38, v38 row_ror:4 row_mask:0xf bank_mask:0xf bound_ctrl:1
	s_cselect_b64 s[20:21], -1, 0
	s_cmp_lt_i32 s1, s5
	v_add_f32_dpp v38, v38, v38 row_ror:2 row_mask:0xf bank_mask:0xf bound_ctrl:1
	s_cselect_b32 s1, s15, s1
	s_lshl_b32 s1, s1, 6
	v_add_f32_dpp v38, v38, v38 row_ror:1 row_mask:0xf bank_mask:0xf bound_ctrl:1
	s_or_b32 s18, s1, 62
	v_readlane_b32 s0, v38, 16
	v_readlane_b32 s8, v38, 48
	v_readlane_b32 s2, v38, 0
	v_readlane_b32 s3, v38, 32
	v_mov_b32_e32 v38, s0
	v_mov_b32_e32 v39, s8
	v_pk_add_f32 v[38:39], s[2:3], v[38:39]
	s_ashr_i32 s19, s18, 31
	v_add_f32_e32 v38, v38, v39
	v_fmac_f32_e32 v35, 0xba800000, v38
	v_fmac_f32_e32 v34, 0xba800000, v38
	v_fmac_f32_e32 v87, 0xba800000, v38
	v_fmac_f32_e32 v86, 0xba800000, v38
	v_mov_b32_e32 v83, v34
	v_mov_b32_e32 v85, v35
	v_mul_f32_e32 v34, v34, v34
	v_mul_f32_e32 v35, v35, v35
	v_fmac_f32_e32 v34, v86, v86
	v_fmac_f32_e32 v35, v87, v87
	v_fmac_f32_e32 v37, 0xba800000, v38
	v_fmac_f32_e32 v36, 0xba800000, v38
	v_mov_b32_e32 v84, v87
	v_add_f32_e32 v34, v34, v35
	v_fmac_f32_e32 v99, 0xba800000, v38
	v_fmac_f32_e32 v98, 0xba800000, v38
	v_mov_b32_e32 v87, v36
	v_mul_f32_e32 v35, v36, v36
	v_mul_f32_e32 v36, v37, v37
	v_fmac_f32_e32 v35, v98, v98
	v_fmac_f32_e32 v36, v99, v99
	v_add_f32_e32 v35, v35, v36
	v_fmac_f32_e32 v63, 0xba800000, v38
	v_fmac_f32_e32 v59, 0xba800000, v38
	v_add_f32_e32 v34, v34, v35
	v_fmac_f32_e32 v62, 0xba800000, v38
	v_fmac_f32_e32 v58, 0xba800000, v38
	v_mul_f32_e32 v35, v59, v59
	v_mul_f32_e32 v36, v63, v63
	v_fmac_f32_e32 v35, v58, v58
	v_fmac_f32_e32 v36, v62, v62
	v_add_f32_e32 v35, v35, v36
	v_fmac_f32_e32 v42, 0xba800000, v38
	v_fmac_f32_e32 v44, 0xba800000, v38
	v_add_f32_e32 v34, v35, v34
	v_fmac_f32_e32 v60, 0xba800000, v38
	v_fmac_f32_e32 v56, 0xba800000, v38
	v_mul_f32_e32 v35, v44, v44
	v_mul_f32_e32 v36, v42, v42
	v_fmac_f32_e32 v35, v56, v56
	v_fmac_f32_e32 v36, v60, v60
	v_add_f32_e32 v35, v35, v36
	v_add_f32_e32 v34, v35, v34
; __device__ __forceinline__ float wave_sum_dpp(float x) { x = rowsum16(x); return (rl(x, 0) + rl(x, 16)) + (rl(x, 32) + rl(x, 48)); }
;     ...
;         for (int r = 0; r < NR; ++r) { mean[r] = wave_sum_dpp(s[r]) * (1.f / DM); q[r] = 0.f;
; #pragma unroll
;             for (int j = 0; j < 4; ++j) { v[r][j] = v[r][j] - mean[r]; q[r] += (v[r][j][0] * v[r][j][0] + v[r][j][1] * v[r][j][1]) + (v[r][j][2] * v[r][j][2] + v[r][j][3] * v[r][j][3]); } }
; #pragma unroll
;         for (int r = 0; r < NR; ++r) rstd[r] = 1.0f / sqrtf(wave_sum_dpp(q[r]) * (1.f / DM) + 1e-5f);
;         if (MODE == 1) {
; #pragma unroll
;             for (int r = 0; r < NR; ++r) if (lane == r) { stats[2 * row[r]] = mean[r]; stats[2 * row[r] + 1] = rstd[r]; } }
	s_lshl_b64 s[18:19], s[18:19], 11
	v_add_f32_dpp v35, v40, v40 row_ror:8 row_mask:0xf bank_mask:0xf bound_ctrl:1
	v_add_f32_dpp v34, v34, v34 row_ror:8 row_mask:0xf bank_mask:0xf bound_ctrl:1
	v_mul_f32_e32 v76, 0x3a800000, v45
	v_add_f32_dpp v35, v35, v35 row_ror:4 row_mask:0xf bank_mask:0xf bound_ctrl:1
	v_add_f32_dpp v34, v34, v34 row_ror:4 row_mask:0xf bank_mask:0xf bound_ctrl:1
	v_mul_f32_e32 v90, 0x3a800000, v38
	v_add_f32_dpp v35, v35, v35 row_ror:2 row_mask:0xf bank_mask:0xf bound_ctrl:1
	v_add_f32_dpp v34, v34, v34 row_ror:2 row_mask:0xf bank_mask:0xf bound_ctrl:1
	v_mov_b32_e32 v89, v37
	v_add_f32_dpp v35, v35, v35 row_ror:1 row_mask:0xf bank_mask:0xf bound_ctrl:1
	v_add_f32_dpp v34, v34, v34 row_ror:1 row_mask:0xf bank_mask:0xf bound_ctrl:1
	v_readlane_b32 s8, v35, 0
	v_readlane_b32 s11, v35, 16
	v_readlane_b32 s9, v35, 32
	v_readlane_b32 s13, v35, 48
	v_readlane_b32 s0, v34, 0
	v_readlane_b32 s3, v34, 16
	v_readlane_b32 s2, v34, 32
	v_readlane_b32 s10, v34, 48
	v_lshl_add_u64 v[34:35], v[50:51], 0, s[18:19]
	s_or_b32 s18, s1, 63
	s_ashr_i32 s19, s18, 31
	s_lshl_b64 s[18:19], s[18:19], 11
	v_lshl_add_u64 v[46:47], v[50:51], 0, s[18:19]
	v_mov_b32_e32 v57, v44
	v_mov_b32_e32 v61, v42
	v_mov_b32_e32 v65, v82
	v_mov_b32_e32 v82, v86
	v_mov_b32_e32 v86, v98
	v_mov_b32_e32 v88, v99
	v_mov_b32_e32 v98, s11
	v_mov_b32_e32 v99, s13
	v_pk_add_f32 v[98:99], s[8:9], v[98:99]
	s_nop 0
	v_add_f32_e32 v77, v98, v99
	v_fmamk_f32 v77, v77, 0x3a800000, v95
	v_mul_f32_e32 v91, 0x4f800000, v77
	v_cmp_gt_f32_e32 vcc, s14, v77
	v_mov_b32_e32 v98, s3
	v_mov_b32_e32 v99, s10
	v_cndmask_b32_e32 v77, v77, v91, vcc
	v_sqrt_f32_e32 v91, v77
	v_add_f32_e32 v98, s0, v98
	v_add_f32_e32 v99, s2, v99
	v_add_f32_e32 v98, v98, v99
	v_add_u32_e32 v92, -1, v91
	v_fma_f32 v94, -v92, v91, v77
	v_cmp_ge_f32_e64 s[8:9], 0, v94
	v_add_u32_e32 v94, 1, v91
	v_fmamk_f32 v98, v98, 0x3a800000, v95
	v_cndmask_b32_e64 v92, v91, v92, s[8:9]
	v_fma_f32 v91, -v94, v91, v77
	v_cmp_lt_f32_e64 s[8:9], 0, v91
	v_mul_f32_e32 v99, 0x4f800000, v98
	s_nop 0
	v_cndmask_b32_e64 v91, v92, v94, s[8:9]
	v_mul_f32_e32 v92, 0x37800000, v91
	v_cndmask_b32_e32 v91, v91, v92, vcc
	v_cmp_class_f32_e32 vcc, v77, v96
	s_nop 1
	v_cndmask_b32_e32 v77, v91, v77, vcc
	v_div_scale_f32 v91, s[8:9], v77, v77, 1.0
	v_rcp_f32_e32 v92, v91
	v_cmp_gt_f32_e64 s[8:9], s14, v98
	v_fma_f32 v94, -v91, v92, 1.0
	s_nop 0
	v_cndmask_b32_e64 v98, v98, v99, s[8:9]
	v_fmac_f32_e32 v92, v94, v92
	v_div_scale_f32 v94, vcc, 1.0, v77, 1.0
	v_sqrt_f32_e32 v99, v98
	v_mul_f32_e32 v97, v94, v92
	v_fma_f32 v100, -v91, v97, v94
	v_fmac_f32_e32 v97, v100, v92
	v_fma_f32 v91, -v91, v97, v94
	v_add_u32_e32 v94, -1, v99
	v_fma_f32 v100, -v94, v99, v98
	v_cmp_ge_f32_e64 s[10:11], 0, v100
	v_add_u32_e32 v100, 1, v99
	v_div_fmas_f32 v91, v91, v92, v97
	v_cndmask_b32_e64 v94, v99, v94, s[10:11]
	v_fma_f32 v99, -v100, v99, v98
	v_cmp_lt_f32_e64 s[10:11], 0, v99
	s_nop 1
	v_cndmask_b32_e64 v94, v94, v100, s[10:11]
	v_mul_f32_e32 v99, 0x37800000, v94
	v_cndmask_b32_e64 v94, v94, v99, s[8:9]
	v_cmp_class_f32_e64 s[8:9], v98, v96
	s_mov_b64 s[10:11], -1
	s_nop 0
	v_cndmask_b32_e64 v98, v94, v98, s[8:9]
	v_div_scale_f32 v99, s[0:1], v98, v98, 1.0
	v_rcp_f32_e32 v100, v99
	v_div_fixup_f32 v94, v91, v77, 1.0
	v_fma_f32 v77, -v99, v100, 1.0
	v_fmac_f32_e32 v100, v77, v100
	v_div_scale_f32 v77, vcc, 1.0, v98, 1.0
	v_mul_f32_e32 v91, v77, v100
	v_fma_f32 v92, -v99, v91, v77
	v_fmac_f32_e32 v91, v92, v100
	v_fma_f32 v77, -v99, v91, v77
	v_div_fmas_f32 v77, v77, v100, v91
	v_div_fixup_f32 v92, v77, v98, 1.0
	v_mov_b32_e32 v77, v94
	v_cmp_lt_i32_e32 vcc, 0, v1
	v_mov_b32_e32 v91, s22
	s_and_saveexec_b64 s[8:9], vcc
	s_cbranch_execz .Lhln15_m3
	v_cmp_eq_u32_e32 vcc, 1, v1
	s_mov_b64 s[10:11], 0
	s_and_saveexec_b64 s[26:27], vcc
	v_mov_b32_e32 v91, v92
	s_mov_b64 s[10:11], exec
	v_mov_b64_e32 v[76:77], v[90:91]
	s_or_b64 exec, exec, s[26:27]
	v_mov_b32_e32 v91, s12
	s_orn2_b64 s[10:11], s[10:11], exec

;     ...
;         for (int r = 0; r < NR; ++r) { s[r] = 0.f;
; #pragma unroll
;             for (int j = 0; j < 2; ++j) {
;                 v[r][2 * j][0] = __builtin_bit_cast(float, raw[r][j].x << 16); v[r][2 * j][1] = __builtin_bit_cast(float, raw[r][j].x & 0xffff0000u);
;                 v[r][2 * j][2] = __builtin_bit_cast(float, raw[r][j].y << 16); v[r][2 * j][3] = __builtin_bit_cast(float, raw[r][j].y & 0xffff0000u);
;                 v[r][2 * j + 1][0] = __builtin_bit_cast(float, raw[r][j].z << 16); v[r][2 * j + 1][1] = __builtin_bit_cast(float, raw[r][j].z & 0xffff0000u);
;                 v[r][2 * j + 1][2] = __builtin_bit_cast(float, raw[r][j].w << 16); v[r][2 * j + 1][3] = __builtin_bit_cast(float, raw[r][j].w & 0xffff0000u); } }
;         { const int nxt = pi + NP * pstep, pq = nxt < p1 ? nxt : pi;
; #pragma unroll
;           for (int r = 0; r < NR; ++r) { const bf16_t* pn = z + (size_t)rowr(pq, r) * DM;
; #pragma unroll
;               for (int j = 0; j < 2; ++j) raw[r][j] = *(const pg8::u32x4*)(pn + 8 * lane + 512 * j); } }
; #pragma unroll
;         for (int r = 0; r < NR; ++r)
; #pragma unroll
;             for (int j = 0; j < 4; ++j) s[r] += (v[r][j][0] + v[r][j][1]) + (v[r][j][2] + v[r][j][3]);
;         float mean[NR], q[NR], rstd[NR];
; #pragma unroll
;         for (int r = 0; r < NR; ++r) { mean[r] = wave_sum_dpp(s[r]) * (1.f / DM); q[r] = 0.f;
; #pragma unroll
;             for (int j = 0; j < 4; ++j) { v[r][j] = v[r][j] - mean[r]; q[r] += (v[r][j][0] * v[r][j][0] + v[r][j][1] * v[r][j][1]) + (v[r][j][2] * v[r][j][2] + v[r][j][3] * v[r][j][3]); } }
; #pragma unroll
;         for (int r = 0; r < NR; ++r) rstd[r] = 1.0f / sqrtf(wave_sum_dpp(q[r]) * (1.f / DM) + 1e-5f);
;         if (MODE == 1) {
; #pragma unroll
;             for (int r = 0; r < NR; ++r) if (lane == r) { stats[2 * row[r]] = mean[r]; stats[2 * row[r] + 1] = rstd[r]; } }
; #pragma unroll
;         for (int j = 0; j < 2; ++j) {
;             const int c = 8 * lane + 512 * j;
;             const f32x4 g0 = *(const f32x4*)(g + c), g1 = *(const f32x4*)(g + c + 4), b0 = *(const f32x4*)(b + c), b1 = *(const f32x4*)(b + c + 4);
; #pragma unroll
;             for (int r = 0; r < NR; ++r) {
;                 const f32x4 o0 = v[r][2 * j] * rstd[r] * g0 + b0, o1 = v[r][2 * j + 1] * rstd[r] * g1 + b1;
.Lhln15_t3:
	s_or_b64 exec, exec, s[8:9]
	s_add_i32 s0, s12, -1
	v_pk_mul_f32 v[74:75], v[74:75], v[94:95] op_sel_hi:[1,0]
	v_pk_mul_f32 v[72:73], v[72:73], v[94:95] op_sel_hi:[1,0]
	v_pk_mul_f32 v[76:77], v[80:81], v[94:95] op_sel_hi:[1,0]
	v_pk_mul_f32 v[78:79], v[78:79], v[94:95] op_sel_hi:[1,0]
	s_ashr_i32 s1, s0, 31
	v_pk_fma_f32 v[74:75], v[12:13], v[74:75], v[16:17]
	v_pk_fma_f32 v[72:73], v[10:11], v[72:73], v[14:15]
	v_pk_fma_f32 v[76:77], v[4:5], v[76:77], v[8:9]
	v_pk_fma_f32 v[78:79], v[2:3], v[78:79], v[6:7]
	s_lshl_b64 s[0:1], s[0:1], 11
	v_cvt_pk_bf16_f32 v72, v72, v73
	v_cvt_pk_bf16_f32 v73, v74, v75
	v_cvt_pk_bf16_f32 v74, v78, v79
	v_cvt_pk_bf16_f32 v75, v76, v77
	v_lshl_add_u64 v[76:77], v[52:53], 0, s[0:1]
	global_store_dwordx4 v[76:77], v[72:75], off
	v_pk_mul_f32 v[78:79], v[86:87], v[92:93] op_sel_hi:[1,0]
	s_ashr_i32 s13, s12, 31
	v_pk_mul_f32 v[72:73], v[84:85], v[92:93] op_sel_hi:[1,0]
	v_pk_mul_f32 v[74:75], v[82:83], v[92:93] op_sel_hi:[1,0]
	v_pk_fma_f32 v[76:77], v[12:13], v[72:73], v[16:17]
	v_pk_fma_f32 v[72:73], v[10:11], v[74:75], v[14:15]
	v_pk_mul_f32 v[74:75], v[88:89], v[92:93] op_sel_hi:[1,0]
	s_lshl_b64 s[2:3], s[12:13], 11
	v_pk_fma_f32 v[80:81], v[4:5], v[74:75], v[8:9]
	v_pk_fma_f32 v[74:75], v[2:3], v[78:79], v[6:7]
	v_cvt_pk_bf16_f32 v72, v72, v73
	v_cvt_pk_bf16_f32 v73, v76, v77
	v_cvt_pk_bf16_f32 v74, v74, v75
	v_cvt_pk_bf16_f32 v75, v80, v81
	v_lshl_add_u64 v[76:77], v[52:53], 0, s[2:3]
	v_pk_mul_f32 v[70:71], v[70:71], v[94:95] op_sel_hi:[1,0]
	v_pk_mul_f32 v[68:69], v[68:69], v[94:95] op_sel_hi:[1,0]
	v_pk_mul_f32 v[66:67], v[66:67], v[94:95] op_sel_hi:[1,0]
	v_pk_mul_f32 v[64:65], v[64:65], v[94:95] op_sel_hi:[1,0]
	global_store_dwordx4 v[76:77], v[72:75], off
	v_pk_fma_f32 v[70:71], v[28:29], v[70:71], v[32:33]
	v_pk_fma_f32 v[68:69], v[26:27], v[68:69], v[30:31]
	v_pk_fma_f32 v[72:73], v[20:21], v[66:67], v[24:25]
	v_pk_fma_f32 v[66:67], v[18:19], v[64:65], v[22:23]
	v_cvt_pk_bf16_f32 v64, v68, v69
	v_cvt_pk_bf16_f32 v65, v70, v71
	v_cvt_pk_bf16_f32 v66, v66, v67
	v_cvt_pk_bf16_f32 v67, v72, v73
	v_lshl_add_u64 v[68:69], v[54:55], 0, s[0:1]
	v_pk_mul_f32 v[62:63], v[62:63], v[92:93] op_sel_hi:[1,0]
	v_pk_mul_f32 v[58:59], v[58:59], v[92:93] op_sel_hi:[1,0]
	v_pk_mul_f32 v[60:61], v[60:61], v[92:93] op_sel_hi:[1,0]
	v_pk_mul_f32 v[56:57], v[56:57], v[92:93] op_sel_hi:[1,0]
	global_store_dwordx4 v[68:69], v[64:67], off
	v_pk_fma_f32 v[62:63], v[28:29], v[62:63], v[32:33]
	v_pk_fma_f32 v[58:59], v[26:27], v[58:59], v[30:31]
	v_pk_fma_f32 v[60:61], v[20:21], v[60:61], v[24:25]
	v_pk_fma_f32 v[64:65], v[18:19], v[56:57], v[22:23]
	v_cvt_pk_bf16_f32 v56, v58, v59
	v_cvt_pk_bf16_f32 v57, v62, v63
	v_cvt_pk_bf16_f32 v58, v64, v65
	v_cvt_pk_bf16_f32 v59, v60, v61
	v_lshl_add_u64 v[60:61], v[54:55], 0, s[2:3]
	s_andn2_b64 vcc, exec, s[20:21]
	s_addk_i32 s12, 0x200
	global_store_dwordx4 v[60:61], v[56:59], off
	s_cbranch_vccz .LBB0_1752
	s_waitcnt vmcnt(20)
	v_lshlrev_b32_e32 v58, 16, v216
	v_and_b32_e32 v59, 0xffff0000, v216
	v_lshlrev_b32_e32 v62, 16, v217
	v_and_b32_e32 v63, 0xffff0000, v217
	v_lshlrev_b32_e32 v47, 16, v209
	v_lshlrev_b32_e32 v46, 16, v208
	v_and_b32_e32 v39, 0xffff0000, v209
	v_and_b32_e32 v38, 0xffff0000, v208
	v_lshlrev_b32_e32 v68, 16, v212
	v_and_b32_e32 v69, 0xffff0000, v212
	v_lshlrev_b32_e32 v64, 16, v214
	v_and_b32_e32 v82, 0xffff0000, v214
	v_lshlrev_b32_e32 v56, 16, v218
	v_and_b32_e32 v44, 0xffff0000, v218
	v_lshlrev_b32_e32 v60, 16, v219
	v_and_b32_e32 v42, 0xffff0000, v219
	v_pk_add_f32 v[48:49], v[46:47], v[38:39]
	v_lshlrev_b32_e32 v70, 16, v213
	v_and_b32_e32 v71, 0xffff0000, v213
	v_add_f32_e32 v43, v48, v49
	v_lshlrev_b32_e32 v49, 16, v211
	v_lshlrev_b32_e32 v48, 16, v210
	v_and_b32_e32 v41, 0xffff0000, v211
	v_and_b32_e32 v40, 0xffff0000, v210
	v_pk_add_f32 v[72:73], v[48:49], v[40:41]
	v_lshlrev_b32_e32 v66, 16, v215
	v_pk_add_f32 v[72:73], v[72:73], v[72:73] op_sel_hi:[0,1]
	v_and_b32_e32 v84, 0xffff0000, v215
	v_add_f32_e32 v85, 0, v43
	v_add_f32_e32 v65, v68, v69
	v_add_f32_e32 v83, v70, v71
	v_mov_b32_e32 v67, v73
	v_pk_add_f32 v[74:75], v[64:65], v[82:83]
	v_pk_add_f32 v[72:73], v[66:67], v[84:85]
	v_lshlrev_b32_e32 v87, 16, v205
	v_pk_add_f32 v[72:73], v[74:75], v[72:73]
	v_lshlrev_b32_e32 v86, 16, v204
	v_and_b32_e32 v35, 0xffff0000, v205
	v_and_b32_e32 v34, 0xffff0000, v204
	v_add_f32_e32 v65, v72, v73
	v_pk_add_f32 v[72:73], v[86:87], v[34:35]
	v_lshlrev_b32_e32 v99, 16, v207
	v_lshlrev_b32_e32 v98, 16, v206
	v_and_b32_e32 v37, 0xffff0000, v207
	v_and_b32_e32 v36, 0xffff0000, v206
	v_add_f32_e32 v57, v58, v59
	v_add_f32_e32 v45, v62, v63
	v_add_f32_e32 v43, v72, v73
	v_pk_add_f32 v[72:73], v[98:99], v[36:37]
	v_pk_add_f32 v[74:75], v[56:57], v[44:45]
	v_add_f32_dpp v45, v65, v65 row_ror:8 row_mask:0xf bank_mask:0xf bound_ctrl:1
	v_pk_add_f32 v[72:73], v[72:73], v[72:73] op_sel_hi:[0,1]
	v_add_f32_e32 v43, 0, v43
	v_add_f32_dpp v45, v45, v45 row_ror:4 row_mask:0xf bank_mask:0xf bound_ctrl:1
	v_mov_b32_e32 v61, v73
	v_pk_add_f32 v[72:73], v[60:61], v[42:43]
	v_add_f32_dpp v45, v45, v45 row_ror:2 row_mask:0xf bank_mask:0xf bound_ctrl:1
	v_pk_add_f32 v[72:73], v[74:75], v[72:73]
	s_mov_b32 s1, s15
	v_add_f32_dpp v45, v45, v45 row_ror:1 row_mask:0xf bank_mask:0xf bound_ctrl:1
	v_add_f32_e32 v43, v72, v73
	v_readlane_b32 s0, v45, 16
	v_readlane_b32 s8, v45, 48
	v_readlane_b32 s2, v45, 0
	v_readlane_b32 s3, v45, 32
	v_mov_b32_e32 v72, s0
	v_mov_b32_e32 v73, s8
	v_pk_add_f32 v[72:73], s[2:3], v[72:73]
	s_lshl_b32 s15, s15, 6
	v_add_f32_e32 v45, v72, v73
	v_fmac_f32_e32 v39, 0xba800000, v45
	v_fmac_f32_e32 v47, 0xba800000, v45
	v_fmac_f32_e32 v38, 0xba800000, v45
; __device__ __forceinline__ float wave_sum_dpp(float x) { x = rowsum16(x); return (rl(x, 0) + rl(x, 16)) + (rl(x, 32) + rl(x, 48)); }
;     ...
;             for (int j = 0; j < 4; ++j) s[r] += (v[r][j][0] + v[r][j][1]) + (v[r][j][2] + v[r][j][3]);
;         float mean[NR], q[NR], rstd[NR];
; #pragma unroll
;         for (int r = 0; r < NR; ++r) { mean[r] = wave_sum_dpp(s[r]) * (1.f / DM); q[r] = 0.f;
; #pragma unroll
;             for (int j = 0; j < 4; ++j) { v[r][j] = v[r][j] - mean[r]; q[r] += (v[r][j][0] * v[r][j][0] + v[r][j][1] * v[r][j][1]) + (v[r][j][2] * v[r][j][2] + v[r][j][3] * v[r][j][3]); } }
	v_fmac_f32_e32 v46, 0xba800000, v45
	v_mov_b32_e32 v74, v47
	v_mov_b32_e32 v78, v47
	v_mov_b32_e32 v79, v39
	v_mov_b32_e32 v47, v38
	v_mov_b32_e32 v73, v38
	v_mov_b32_e32 v75, v39
	v_pk_mul_f32 v[78:79], v[78:79], v[78:79]
	v_pk_mul_f32 v[38:39], v[46:47], v[46:47]
	v_mov_b32_e32 v72, v46
	v_pk_mov_b32 v[46:47], v[38:39], v[78:79] op_sel:[1,0]
	v_mov_b32_e32 v39, v79
	v_fmac_f32_e32 v41, 0xba800000, v45
	v_fmac_f32_e32 v49, 0xba800000, v45
	v_fmac_f32_e32 v40, 0xba800000, v45
	v_pk_add_f32 v[38:39], v[46:47], v[38:39]
	v_fmac_f32_e32 v48, 0xba800000, v45
	v_mov_b32_e32 v80, v49
	v_mov_b32_e32 v46, v49
	v_mov_b32_e32 v47, v41
	v_mov_b32_e32 v49, v40
	v_pk_add_f32 v[38:39], v[38:39], v[38:39] op_sel_hi:[0,1]
	v_mov_b32_e32 v79, v40
	v_mov_b32_e32 v81, v41
	v_pk_mul_f32 v[46:47], v[46:47], v[46:47]
	v_pk_mul_f32 v[40:41], v[48:49], v[48:49]
	v_fmac_f32_e32 v68, 0xba800000, v45
	v_mov_b32_e32 v78, v48
	v_pk_mov_b32 v[48:49], v[40:41], v[46:47] op_sel:[1,0]
	v_mov_b32_e32 v41, v47
	v_fmac_f32_e32 v70, 0xba800000, v45
	v_fmac_f32_e32 v69, 0xba800000, v45
	v_mul_f32_e32 v38, v68, v68
	v_pk_add_f32 v[40:41], v[48:49], v[40:41]
	v_fmac_f32_e32 v71, 0xba800000, v45
	v_pk_fma_f32 v[46:47], v[68:69], v[68:69], v[38:39] op_sel_hi:[1,1,0]
	v_mul_f32_e32 v38, v70, v70
	v_pk_add_f32 v[40:41], v[40:41], v[40:41] op_sel_hi:[0,1]
	v_pk_fma_f32 v[48:49], v[70:71], v[70:71], v[38:39] op_sel_hi:[1,1,0]
	v_fmac_f32_e32 v84, 0xba800000, v45
	v_fmac_f32_e32 v66, 0xba800000, v45
	v_fmac_f32_e32 v82, 0xba800000, v45
	v_fmac_f32_e32 v64, 0xba800000, v45
	v_mul_f32_e32 v46, v64, v64
	v_mul_f32_e32 v48, v82, v82
	v_mul_f32_e32 v38, v66, v66
	v_mul_f32_e32 v40, v84, v84
	v_pk_add_f32 v[46:47], v[46:47], v[48:49]
	v_pk_add_f32 v[38:39], v[38:39], v[40:41]
	v_mov_b32_e32 v67, v84
	v_pk_add_f32 v[38:39], v[46:47], v[38:39]
	s_or_b32 s22, s15, 62
	v_add_f32_e32 v40, v38, v39
	v_add_f32_dpp v38, v43, v43 row_ror:8 row_mask:0xf bank_mask:0xf bound_ctrl:1
	s_add_i32 s15, s1, 8
	s_cmp_ge_i32 s1, s5
	v_add_f32_dpp v38, v38, v38 row_ror:4 row_mask:0xf bank_mask:0xf bound_ctrl:1
	s_cselect_b64 s[20:21], -1, 0
	s_cmp_lt_i32 s1, s5
	v_add_f32_dpp v38, v38, v38 row_ror:2 row_mask:0xf bank_mask:0xf bound_ctrl:1
	s_cselect_b32 s1, s15, s1
	s_lshl_b32 s1, s1, 6
	v_add_f32_dpp v38, v38, v38 row_ror:1 row_mask:0xf bank_mask:0xf bound_ctrl:1
	s_or_b32 s18, s1, 62
	v_readlane_b32 s0, v38, 16
	v_readlane_b32 s8, v38, 48
	v_readlane_b32 s2, v38, 0
	v_readlane_b32 s3, v38, 32
	v_mov_b32_e32 v38, s0
	v_mov_b32_e32 v39, s8
	v_pk_add_f32 v[38:39], s[2:3], v[38:39]
	s_ashr_i32 s19, s18, 31
	v_add_f32_e32 v38, v38, v39
	v_fmac_f32_e32 v35, 0xba800000, v38
	v_fmac_f32_e32 v34, 0xba800000, v38
	v_fmac_f32_e32 v87, 0xba800000, v38
	v_fmac_f32_e32 v86, 0xba800000, v38
	v_mov_b32_e32 v83, v34
	v_mov_b32_e32 v85, v35
	v_mul_f32_e32 v34, v34, v34
	v_mul_f32_e32 v35, v35, v35
	v_fmac_f32_e32 v34, v86, v86
	v_fmac_f32_e32 v35, v87, v87
	v_fmac_f32_e32 v37, 0xba800000, v38
	v_fmac_f32_e32 v36, 0xba800000, v38
	v_mov_b32_e32 v84, v87
	v_add_f32_e32 v34, v34, v35
	v_fmac_f32_e32 v99, 0xba800000, v38
	v_fmac_f32_e32 v98, 0xba800000, v38
	v_mov_b32_e32 v87, v36
	v_mul_f32_e32 v35, v36, v36
	v_mul_f32_e32 v36, v37, v37
	v_fmac_f32_e32 v35, v98, v98
	v_fmac_f32_e32 v36, v99, v99
	v_add_f32_e32 v35, v35, v36
	v_fmac_f32_e32 v63, 0xba800000, v38
	v_fmac_f32_e32 v59, 0xba800000, v38
	v_add_f32_e32 v34, v34, v35
	v_fmac_f32_e32 v62, 0xba800000, v38
	v_fmac_f32_e32 v58, 0xba800000, v38
	v_mul_f32_e32 v35, v59, v59
	v_mul_f32_e32 v36, v63, v63
	v_fmac_f32_e32 v35, v58, v58
	v_fmac_f32_e32 v36, v62, v62
	v_add_f32_e32 v35, v35, v36
	v_fmac_f32_e32 v42, 0xba800000, v38
	v_fmac_f32_e32 v44, 0xba800000, v38
	v_add_f32_e32 v34, v35, v34
	v_fmac_f32_e32 v60, 0xba800000, v38
	v_fmac_f32_e32 v56, 0xba800000, v38
	v_mul_f32_e32 v35, v44, v44
	v_mul_f32_e32 v36, v42, v42
	v_fmac_f32_e32 v35, v56, v56
	v_fmac_f32_e32 v36, v60, v60
	v_add_f32_e32 v35, v35, v36
	v_add_f32_e32 v34, v35, v34
; __device__ __forceinline__ float wave_sum_dpp(float x) { x = rowsum16(x); return (rl(x, 0) + rl(x, 16)) + (rl(x, 32) + rl(x, 48)); }
;     ...
;         for (int r = 0; r < NR; ++r) { mean[r] = wave_sum_dpp(s[r]) * (1.f / DM); q[r] = 0.f;
; #pragma unroll
;             for (int j = 0; j < 4; ++j) { v[r][j] = v[r][j] - mean[r]; q[r] += (v[r][j][0] * v[r][j][0] + v[r][j][1] * v[r][j][1]) + (v[r][j][2] * v[r][j][2] + v[r][j][3] * v[r][j][3]); } }
; #pragma unroll
;         for (int r = 0; r < NR; ++r) rstd[r] = 1.0f / sqrtf(wave_sum_dpp(q[r]) * (1.f / DM) + 1e-5f);
;         if (MODE == 1) {
; #pragma unroll
;             for (int r = 0; r < NR; ++r) if (lane == r) { stats[2 * row[r]] = mean[r]; stats[2 * row[r] + 1] = rstd[r]; } }
	s_lshl_b64 s[18:19], s[18:19], 11
	v_add_f32_dpp v35, v40, v40 row_ror:8 row_mask:0xf bank_mask:0xf bound_ctrl:1
	v_add_f32_dpp v34, v34, v34 row_ror:8 row_mask:0xf bank_mask:0xf bound_ctrl:1
	v_mul_f32_e32 v76, 0x3a800000, v45
	v_add_f32_dpp v35, v35, v35 row_ror:4 row_mask:0xf bank_mask:0xf bound_ctrl:1
	v_add_f32_dpp v34, v34, v34 row_ror:4 row_mask:0xf bank_mask:0xf bound_ctrl:1
	v_mul_f32_e32 v90, 0x3a800000, v38
	v_add_f32_dpp v35, v35, v35 row_ror:2 row_mask:0xf bank_mask:0xf bound_ctrl:1
	v_add_f32_dpp v34, v34, v34 row_ror:2 row_mask:0xf bank_mask:0xf bound_ctrl:1
	v_mov_b32_e32 v89, v37
	v_add_f32_dpp v35, v35, v35 row_ror:1 row_mask:0xf bank_mask:0xf bound_ctrl:1
	v_add_f32_dpp v34, v34, v34 row_ror:1 row_mask:0xf bank_mask:0xf bound_ctrl:1
	v_readlane_b32 s8, v35, 0
	v_readlane_b32 s11, v35, 16
	v_readlane_b32 s9, v35, 32
	v_readlane_b32 s13, v35, 48
	v_readlane_b32 s0, v34, 0
	v_readlane_b32 s3, v34, 16
	v_readlane_b32 s2, v34, 32
	v_readlane_b32 s10, v34, 48
	v_lshl_add_u64 v[34:35], v[50:51], 0, s[18:19]
	s_or_b32 s18, s1, 63
	s_ashr_i32 s19, s18, 31
	s_lshl_b64 s[18:19], s[18:19], 11
	v_lshl_add_u64 v[46:47], v[50:51], 0, s[18:19]
	v_mov_b32_e32 v57, v44
	v_mov_b32_e32 v61, v42
	v_mov_b32_e32 v65, v82
	v_mov_b32_e32 v82, v86
	v_mov_b32_e32 v86, v98
	v_mov_b32_e32 v88, v99
	v_mov_b32_e32 v98, s11
	v_mov_b32_e32 v99, s13
	v_pk_add_f32 v[98:99], s[8:9], v[98:99]
	s_nop 0
	v_add_f32_e32 v77, v98, v99
	v_fmamk_f32 v77, v77, 0x3a800000, v95
	v_mul_f32_e32 v91, 0x4f800000, v77
	v_cmp_gt_f32_e32 vcc, s14, v77
	v_mov_b32_e32 v98, s3
	v_mov_b32_e32 v99, s10
	v_cndmask_b32_e32 v77, v77, v91, vcc
	v_sqrt_f32_e32 v91, v77
	v_add_f32_e32 v98, s0, v98
	v_add_f32_e32 v99, s2, v99
	v_add_f32_e32 v98, v98, v99
	v_add_u32_e32 v92, -1, v91
	v_fma_f32 v94, -v92, v91, v77
	v_cmp_ge_f32_e64 s[8:9], 0, v94
	v_add_u32_e32 v94, 1, v91
	v_fmamk_f32 v98, v98, 0x3a800000, v95
	v_cndmask_b32_e64 v92, v91, v92, s[8:9]
	v_fma_f32 v91, -v94, v91, v77
	v_cmp_lt_f32_e64 s[8:9], 0, v91
	v_mul_f32_e32 v99, 0x4f800000, v98
	s_nop 0
	v_cndmask_b32_e64 v91, v92, v94, s[8:9]
	v_mul_f32_e32 v92, 0x37800000, v91
	v_cndmask_b32_e32 v91, v91, v92, vcc
	v_cmp_class_f32_e32 vcc, v77, v96
	s_nop 1
	v_cndmask_b32_e32 v77, v91, v77, vcc
	v_div_scale_f32 v91, s[8:9], v77, v77, 1.0
	v_rcp_f32_e32 v92, v91
	v_cmp_gt_f32_e64 s[8:9], s14, v98
	v_fma_f32 v94, -v91, v92, 1.0
	s_nop 0
	v_cndmask_b32_e64 v98, v98, v99, s[8:9]
	v_fmac_f32_e32 v92, v94, v92
	v_div_scale_f32 v94, vcc, 1.0, v77, 1.0
	v_sqrt_f32_e32 v99, v98
	v_mul_f32_e32 v97, v94, v92
	v_fma_f32 v100, -v91, v97, v94
	v_fmac_f32_e32 v97, v100, v92
	v_fma_f32 v91, -v91, v97, v94
	v_add_u32_e32 v94, -1, v99
	v_fma_f32 v100, -v94, v99, v98
	v_cmp_ge_f32_e64 s[10:11], 0, v100
	v_add_u32_e32 v100, 1, v99
	v_div_fmas_f32 v91, v91, v92, v97
	v_cndmask_b32_e64 v94, v99, v94, s[10:11]
	v_fma_f32 v99, -v100, v99, v98
	v_cmp_lt_f32_e64 s[10:11], 0, v99
	s_nop 1
	v_cndmask_b32_e64 v94, v94, v100, s[10:11]
	v_mul_f32_e32 v99, 0x37800000, v94
	v_cndmask_b32_e64 v94, v94, v99, s[8:9]
	v_cmp_class_f32_e64 s[8:9], v98, v96
	s_mov_b64 s[10:11], -1
	s_nop 0
	v_cndmask_b32_e64 v98, v94, v98, s[8:9]
	v_div_scale_f32 v99, s[0:1], v98, v98, 1.0
	v_rcp_f32_e32 v100, v99
	v_div_fixup_f32 v94, v91, v77, 1.0
	v_fma_f32 v77, -v99, v100, 1.0
	v_fmac_f32_e32 v100, v77, v100
	v_div_scale_f32 v77, vcc, 1.0, v98, 1.0
	v_mul_f32_e32 v91, v77, v100
	v_fma_f32 v92, -v99, v91, v77
	v_fmac_f32_e32 v91, v92, v100
	v_fma_f32 v77, -v99, v91, v77
	v_div_fmas_f32 v77, v77, v100, v91
	v_div_fixup_f32 v92, v77, v98, 1.0
	v_mov_b32_e32 v77, v94
	v_cmp_lt_i32_e32 vcc, 0, v1
	v_mov_b32_e32 v91, s22
	s_and_saveexec_b64 s[8:9], vcc
	s_cbranch_execz .Lhln15_m4
	v_cmp_eq_u32_e32 vcc, 1, v1
	s_mov_b64 s[10:11], 0
	s_and_saveexec_b64 s[26:27], vcc
	v_mov_b32_e32 v91, v92
	s_mov_b64 s[10:11], exec
	v_mov_b64_e32 v[76:77], v[90:91]
	s_or_b64 exec, exec, s[26:27]
	v_mov_b32_e32 v91, s12
	s_orn2_b64 s[10:11], s[10:11], exec

;     ...
;         for (int r = 0; r < NR; ++r) { s[r] = 0.f;
; #pragma unroll
;             for (int j = 0; j < 2; ++j) {
;                 v[r][2 * j][0] = __builtin_bit_cast(float, raw[r][j].x << 16); v[r][2 * j][1] = __builtin_bit_cast(float, raw[r][j].x & 0xffff0000u);
;                 v[r][2 * j][2] = __builtin_bit_cast(float, raw[r][j].y << 16); v[r][2 * j][3] = __builtin_bit_cast(float, raw[r][j].y & 0xffff0000u);
;                 v[r][2 * j + 1][0] = __builtin_bit_cast(float, raw[r][j].z << 16); v[r][2 * j + 1][1] = __builtin_bit_cast(float, raw[r][j].z & 0xffff0000u);
;                 v[r][2 * j + 1][2] = __builtin_bit_cast(float, raw[r][j].w << 16); v[r][2 * j + 1][3] = __builtin_bit_cast(float, raw[r][j].w & 0xffff0000u); } }
;         { const int nxt = pi + NP * pstep, pq = nxt < p1 ? nxt : pi;
; #pragma unroll
;           for (int r = 0; r < NR; ++r) { const bf16_t* pn = z + (size_t)rowr(pq, r) * DM;
; #pragma unroll
;               for (int j = 0; j < 2; ++j) raw[r][j] = *(const pg8::u32x4*)(pn + 8 * lane + 512 * j); } }
; #pragma unroll
;         for (int r = 0; r < NR; ++r)
; #pragma unroll
;             for (int j = 0; j < 4; ++j) s[r] += (v[r][j][0] + v[r][j][1]) + (v[r][j][2] + v[r][j][3]);
;         float mean[NR], q[NR], rstd[NR];
; #pragma unroll
;         for (int r = 0; r < NR; ++r) { mean[r] = wave_sum_dpp(s[r]) * (1.f / DM); q[r] = 0.f;
; #pragma unroll
;             for (int j = 0; j < 4; ++j) { v[r][j] = v[r][j] - mean[r]; q[r] += (v[r][j][0] * v[r][j][0] + v[r][j][1] * v[r][j][1]) + (v[r][j][2] * v[r][j][2] + v[r][j][3] * v[r][j][3]); } }
; #pragma unroll
;         for (int r = 0; r < NR; ++r) rstd[r] = 1.0f / sqrtf(wave_sum_dpp(q[r]) * (1.f / DM) + 1e-5f);
;         if (MODE == 1) {
; #pragma unroll
;             for (int r = 0; r < NR; ++r) if (lane == r) { stats[2 * row[r]] = mean[r]; stats[2 * row[r] + 1] = rstd[r]; } }
; #pragma unroll
;         for (int j = 0; j < 2; ++j) {
;             const int c = 8 * lane + 512 * j;
;             const f32x4 g0 = *(const f32x4*)(g + c), g1 = *(const f32x4*)(g + c + 4), b0 = *(const f32x4*)(b + c), b1 = *(const f32x4*)(b + c + 4);
; #pragma unroll
;             for (int r = 0; r < NR; ++r) {
;                 const f32x4 o0 = v[r][2 * j] * rstd[r] * g0 + b0, o1 = v[r][2 * j + 1] * rstd[r] * g1 + b1;
.Lhln15_t4:
	s_or_b64 exec, exec, s[8:9]
	s_add_i32 s0, s12, -1
	v_pk_mul_f32 v[74:75], v[74:75], v[94:95] op_sel_hi:[1,0]
	v_pk_mul_f32 v[72:73], v[72:73], v[94:95] op_sel_hi:[1,0]
	v_pk_mul_f32 v[76:77], v[80:81], v[94:95] op_sel_hi:[1,0]
	v_pk_mul_f32 v[78:79], v[78:79], v[94:95] op_sel_hi:[1,0]
	s_ashr_i32 s1, s0, 31
	v_pk_fma_f32 v[74:75], v[12:13], v[74:75], v[16:17]
	v_pk_fma_f32 v[72:73], v[10:11], v[72:73], v[14:15]
	v_pk_fma_f32 v[76:77], v[4:5], v[76:77], v[8:9]
	v_pk_fma_f32 v[78:79], v[2:3], v[78:79], v[6:7]
	s_lshl_b64 s[0:1], s[0:1], 11
	v_cvt_pk_bf16_f32 v72, v72, v73
	v_cvt_pk_bf16_f32 v73, v74, v75
	v_cvt_pk_bf16_f32 v74, v78, v79
	v_cvt_pk_bf16_f32 v75, v76, v77
	v_lshl_add_u64 v[76:77], v[52:53], 0, s[0:1]
	global_store_dwordx4 v[76:77], v[72:75], off
	v_pk_mul_f32 v[78:79], v[86:87], v[92:93] op_sel_hi:[1,0]
	s_ashr_i32 s13, s12, 31
	v_pk_mul_f32 v[72:73], v[84:85], v[92:93] op_sel_hi:[1,0]
	v_pk_mul_f32 v[74:75], v[82:83], v[92:93] op_sel_hi:[1,0]
	v_pk_fma_f32 v[76:77], v[12:13], v[72:73], v[16:17]
	v_pk_fma_f32 v[72:73], v[10:11], v[74:75], v[14:15]
	v_pk_mul_f32 v[74:75], v[88:89], v[92:93] op_sel_hi:[1,0]
	s_lshl_b64 s[2:3], s[12:13], 11
	v_pk_fma_f32 v[80:81], v[4:5], v[74:75], v[8:9]
	v_pk_fma_f32 v[74:75], v[2:3], v[78:79], v[6:7]
	v_cvt_pk_bf16_f32 v72, v72, v73
	v_cvt_pk_bf16_f32 v73, v76, v77
	v_cvt_pk_bf16_f32 v74, v74, v75
	v_cvt_pk_bf16_f32 v75, v80, v81
	v_lshl_add_u64 v[76:77], v[52:53], 0, s[2:3]
	v_pk_mul_f32 v[70:71], v[70:71], v[94:95] op_sel_hi:[1,0]
	v_pk_mul_f32 v[68:69], v[68:69], v[94:95] op_sel_hi:[1,0]
	v_pk_mul_f32 v[66:67], v[66:67], v[94:95] op_sel_hi:[1,0]
	v_pk_mul_f32 v[64:65], v[64:65], v[94:95] op_sel_hi:[1,0]
	global_store_dwordx4 v[76:77], v[72:75], off
	v_pk_fma_f32 v[70:71], v[28:29], v[70:71], v[32:33]
	v_pk_fma_f32 v[68:69], v[26:27], v[68:69], v[30:31]
	v_pk_fma_f32 v[72:73], v[20:21], v[66:67], v[24:25]
	v_pk_fma_f32 v[66:67], v[18:19], v[64:65], v[22:23]
	v_cvt_pk_bf16_f32 v64, v68, v69
	v_cvt_pk_bf16_f32 v65, v70, v71
	v_cvt_pk_bf16_f32 v66, v66, v67
	v_cvt_pk_bf16_f32 v67, v72, v73
	v_lshl_add_u64 v[68:69], v[54:55], 0, s[0:1]
	v_pk_mul_f32 v[62:63], v[62:63], v[92:93] op_sel_hi:[1,0]
	v_pk_mul_f32 v[58:59], v[58:59], v[92:93] op_sel_hi:[1,0]
	v_pk_mul_f32 v[60:61], v[60:61], v[92:93] op_sel_hi:[1,0]
	v_pk_mul_f32 v[56:57], v[56:57], v[92:93] op_sel_hi:[1,0]
	global_store_dwordx4 v[68:69], v[64:67], off
	v_pk_fma_f32 v[62:63], v[28:29], v[62:63], v[32:33]
	v_pk_fma_f32 v[58:59], v[26:27], v[58:59], v[30:31]
	v_pk_fma_f32 v[60:61], v[20:21], v[60:61], v[24:25]
	v_pk_fma_f32 v[64:65], v[18:19], v[56:57], v[22:23]
	v_cvt_pk_bf16_f32 v56, v58, v59
	v_cvt_pk_bf16_f32 v57, v62, v63
	v_cvt_pk_bf16_f32 v58, v64, v65
	v_cvt_pk_bf16_f32 v59, v60, v61
	v_lshl_add_u64 v[60:61], v[54:55], 0, s[2:3]
	s_andn2_b64 vcc, exec, s[20:21]
	s_addk_i32 s12, 0x200
	global_store_dwordx4 v[60:61], v[56:59], off
	s_cbranch_vccz .LBB0_1752
	s_waitcnt vmcnt(20)
	v_lshlrev_b32_e32 v58, 16, v232
	v_and_b32_e32 v59, 0xffff0000, v232
	v_lshlrev_b32_e32 v62, 16, v233
	v_and_b32_e32 v63, 0xffff0000, v233
	v_lshlrev_b32_e32 v47, 16, v225
	v_lshlrev_b32_e32 v46, 16, v224
	v_and_b32_e32 v39, 0xffff0000, v225
	v_and_b32_e32 v38, 0xffff0000, v224
	v_lshlrev_b32_e32 v68, 16, v228
	v_and_b32_e32 v69, 0xffff0000, v228
	v_lshlrev_b32_e32 v64, 16, v230
	v_and_b32_e32 v82, 0xffff0000, v230
	v_lshlrev_b32_e32 v56, 16, v234
	v_and_b32_e32 v44, 0xffff0000, v234
	v_lshlrev_b32_e32 v60, 16, v235
	v_and_b32_e32 v42, 0xffff0000, v235
	v_pk_add_f32 v[48:49], v[46:47], v[38:39]
	v_lshlrev_b32_e32 v70, 16, v229
	v_and_b32_e32 v71, 0xffff0000, v229
	v_add_f32_e32 v43, v48, v49
	v_lshlrev_b32_e32 v49, 16, v227
	v_lshlrev_b32_e32 v48, 16, v226
	v_and_b32_e32 v41, 0xffff0000, v227
	v_and_b32_e32 v40, 0xffff0000, v226
	v_pk_add_f32 v[72:73], v[48:49], v[40:41]
	v_lshlrev_b32_e32 v66, 16, v231
	v_pk_add_f32 v[72:73], v[72:73], v[72:73] op_sel_hi:[0,1]
	v_and_b32_e32 v84, 0xffff0000, v231
	v_add_f32_e32 v85, 0, v43
	v_add_f32_e32 v65, v68, v69
	v_add_f32_e32 v83, v70, v71
	v_mov_b32_e32 v67, v73
	v_pk_add_f32 v[74:75], v[64:65], v[82:83]
	v_pk_add_f32 v[72:73], v[66:67], v[84:85]
	v_lshlrev_b32_e32 v87, 16, v221
	v_pk_add_f32 v[72:73], v[74:75], v[72:73]
	v_lshlrev_b32_e32 v86, 16, v220
	v_and_b32_e32 v35, 0xffff0000, v221
	v_and_b32_e32 v34, 0xffff0000, v220
	v_add_f32_e32 v65, v72, v73
	v_pk_add_f32 v[72:73], v[86:87], v[34:35]
	v_lshlrev_b32_e32 v99, 16, v223
	v_lshlrev_b32_e32 v98, 16, v222
	v_and_b32_e32 v37, 0xffff0000, v223
	v_and_b32_e32 v36, 0xffff0000, v222
	v_add_f32_e32 v57, v58, v59
	v_add_f32_e32 v45, v62, v63
	v_add_f32_e32 v43, v72, v73
	v_pk_add_f32 v[72:73], v[98:99], v[36:37]
	v_pk_add_f32 v[74:75], v[56:57], v[44:45]
	v_add_f32_dpp v45, v65, v65 row_ror:8 row_mask:0xf bank_mask:0xf bound_ctrl:1
	v_pk_add_f32 v[72:73], v[72:73], v[72:73] op_sel_hi:[0,1]
	v_add_f32_e32 v43, 0, v43
	v_add_f32_dpp v45, v45, v45 row_ror:4 row_mask:0xf bank_mask:0xf bound_ctrl:1
	v_mov_b32_e32 v61, v73
	v_pk_add_f32 v[72:73], v[60:61], v[42:43]
	v_add_f32_dpp v45, v45, v45 row_ror:2 row_mask:0xf bank_mask:0xf bound_ctrl:1
	v_pk_add_f32 v[72:73], v[74:75], v[72:73]
	s_mov_b32 s1, s15
	v_add_f32_dpp v45, v45, v45 row_ror:1 row_mask:0xf bank_mask:0xf bound_ctrl:1
	v_add_f32_e32 v43, v72, v73
	v_readlane_b32 s0, v45, 16
	v_readlane_b32 s8, v45, 48
	v_readlane_b32 s2, v45, 0
	v_readlane_b32 s3, v45, 32
	v_mov_b32_e32 v72, s0
	v_mov_b32_e32 v73, s8
	v_pk_add_f32 v[72:73], s[2:3], v[72:73]
	s_lshl_b32 s15, s15, 6
	v_add_f32_e32 v45, v72, v73
	v_fmac_f32_e32 v39, 0xba800000, v45
	v_fmac_f32_e32 v47, 0xba800000, v45
	v_fmac_f32_e32 v38, 0xba800000, v45
; __device__ __forceinline__ float wave_sum_dpp(float x) { x = rowsum16(x); return (rl(x, 0) + rl(x, 16)) + (rl(x, 32) + rl(x, 48)); }
;     ...
;             for (int j = 0; j < 4; ++j) s[r] += (v[r][j][0] + v[r][j][1]) + (v[r][j][2] + v[r][j][3]);
;         float mean[NR], q[NR], rstd[NR];
; #pragma unroll
;         for (int r = 0; r < NR; ++r) { mean[r] = wave_sum_dpp(s[r]) * (1.f / DM); q[r] = 0.f;
; #pragma unroll
;             for (int j = 0; j < 4; ++j) { v[r][j] = v[r][j] - mean[r]; q[r] += (v[r][j][0] * v[r][j][0] + v[r][j][1] * v[r][j][1]) + (v[r][j][2] * v[r][j][2] + v[r][j][3] * v[r][j][3]); } }
	v_fmac_f32_e32 v46, 0xba800000, v45
	v_mov_b32_e32 v74, v47
	v_mov_b32_e32 v78, v47
	v_mov_b32_e32 v79, v39
	v_mov_b32_e32 v47, v38
	v_mov_b32_e32 v73, v38
	v_mov_b32_e32 v75, v39
	v_pk_mul_f32 v[78:79], v[78:79], v[78:79]
	v_pk_mul_f32 v[38:39], v[46:47], v[46:47]
	v_mov_b32_e32 v72, v46
	v_pk_mov_b32 v[46:47], v[38:39], v[78:79] op_sel:[1,0]
	v_mov_b32_e32 v39, v79
	v_fmac_f32_e32 v41, 0xba800000, v45
	v_fmac_f32_e32 v49, 0xba800000, v45
	v_fmac_f32_e32 v40, 0xba800000, v45
	v_pk_add_f32 v[38:39], v[46:47], v[38:39]
	v_fmac_f32_e32 v48, 0xba800000, v45
	v_mov_b32_e32 v80, v49
	v_mov_b32_e32 v46, v49
	v_mov_b32_e32 v47, v41
	v_mov_b32_e32 v49, v40
	v_pk_add_f32 v[38:39], v[38:39], v[38:39] op_sel_hi:[0,1]
	v_mov_b32_e32 v79, v40
	v_mov_b32_e32 v81, v41
	v_pk_mul_f32 v[46:47], v[46:47], v[46:47]
	v_pk_mul_f32 v[40:41], v[48:49], v[48:49]
	v_fmac_f32_e32 v68, 0xba800000, v45
	v_mov_b32_e32 v78, v48
	v_pk_mov_b32 v[48:49], v[40:41], v[46:47] op_sel:[1,0]
	v_mov_b32_e32 v41, v47
	v_fmac_f32_e32 v70, 0xba800000, v45
	v_fmac_f32_e32 v69, 0xba800000, v45
	v_mul_f32_e32 v38, v68, v68
	v_pk_add_f32 v[40:41], v[48:49], v[40:41]
	v_fmac_f32_e32 v71, 0xba800000, v45
	v_pk_fma_f32 v[46:47], v[68:69], v[68:69], v[38:39] op_sel_hi:[1,1,0]
	v_mul_f32_e32 v38, v70, v70
	v_pk_add_f32 v[40:41], v[40:41], v[40:41] op_sel_hi:[0,1]
	v_pk_fma_f32 v[48:49], v[70:71], v[70:71], v[38:39] op_sel_hi:[1,1,0]
	v_fmac_f32_e32 v84, 0xba800000, v45
	v_fmac_f32_e32 v66, 0xba800000, v45
	v_fmac_f32_e32 v82, 0xba800000, v45
	v_fmac_f32_e32 v64, 0xba800000, v45
	v_mul_f32_e32 v46, v64, v64
	v_mul_f32_e32 v48, v82, v82
	v_mul_f32_e32 v38, v66, v66
	v_mul_f32_e32 v40, v84, v84
	v_pk_add_f32 v[46:47], v[46:47], v[48:49]
	v_pk_add_f32 v[38:39], v[38:39], v[40:41]
	v_mov_b32_e32 v67, v84
	v_pk_add_f32 v[38:39], v[46:47], v[38:39]
	s_or_b32 s22, s15, 62
	v_add_f32_e32 v40, v38, v39
	v_add_f32_dpp v38, v43, v43 row_ror:8 row_mask:0xf bank_mask:0xf bound_ctrl:1
	s_add_i32 s15, s1, 8
	s_cmp_ge_i32 s1, s5
	v_add_f32_dpp v38, v38, v38 row_ror:4 row_mask:0xf bank_mask:0xf bound_ctrl:1
	s_cselect_b64 s[20:21], -1, 0
	s_cmp_lt_i32 s1, s5
	v_add_f32_dpp v38, v38, v38 row_ror:2 row_mask:0xf bank_mask:0xf bound_ctrl:1
	s_cselect_b32 s1, s15, s1
	s_lshl_b32 s1, s1, 6
	v_add_f32_dpp v38, v38, v38 row_ror:1 row_mask:0xf bank_mask:0xf bound_ctrl:1
	s_or_b32 s18, s1, 62
	v_readlane_b32 s0, v38, 16
	v_readlane_b32 s8, v38, 48
	v_readlane_b32 s2, v38, 0
	v_readlane_b32 s3, v38, 32
	v_mov_b32_e32 v38, s0
	v_mov_b32_e32 v39, s8
	v_pk_add_f32 v[38:39], s[2:3], v[38:39]
	s_ashr_i32 s19, s18, 31
	v_add_f32_e32 v38, v38, v39
	v_fmac_f32_e32 v35, 0xba800000, v38
	v_fmac_f32_e32 v34, 0xba800000, v38
	v_fmac_f32_e32 v87, 0xba800000, v38
	v_fmac_f32_e32 v86, 0xba800000, v38
	v_mov_b32_e32 v83, v34
	v_mov_b32_e32 v85, v35
	v_mul_f32_e32 v34, v34, v34
	v_mul_f32_e32 v35, v35, v35
	v_fmac_f32_e32 v34, v86, v86
	v_fmac_f32_e32 v35, v87, v87
	v_fmac_f32_e32 v37, 0xba800000, v38
	v_fmac_f32_e32 v36, 0xba800000, v38
	v_mov_b32_e32 v84, v87
	v_add_f32_e32 v34, v34, v35
	v_fmac_f32_e32 v99, 0xba800000, v38
	v_fmac_f32_e32 v98, 0xba800000, v38
	v_mov_b32_e32 v87, v36
	v_mul_f32_e32 v35, v36, v36
	v_mul_f32_e32 v36, v37, v37
	v_fmac_f32_e32 v35, v98, v98
	v_fmac_f32_e32 v36, v99, v99
	v_add_f32_e32 v35, v35, v36
	v_fmac_f32_e32 v63, 0xba800000, v38
	v_fmac_f32_e32 v59, 0xba800000, v38
	v_add_f32_e32 v34, v34, v35
	v_fmac_f32_e32 v62, 0xba800000, v38
	v_fmac_f32_e32 v58, 0xba800000, v38
	v_mul_f32_e32 v35, v59, v59
	v_mul_f32_e32 v36, v63, v63
	v_fmac_f32_e32 v35, v58, v58
	v_fmac_f32_e32 v36, v62, v62
	v_add_f32_e32 v35, v35, v36
	v_fmac_f32_e32 v42, 0xba800000, v38
	v_fmac_f32_e32 v44, 0xba800000, v38
	v_add_f32_e32 v34, v35, v34
	v_fmac_f32_e32 v60, 0xba800000, v38
	v_fmac_f32_e32 v56, 0xba800000, v38
	v_mul_f32_e32 v35, v44, v44
	v_mul_f32_e32 v36, v42, v42
	v_fmac_f32_e32 v35, v56, v56
	v_fmac_f32_e32 v36, v60, v60
	v_add_f32_e32 v35, v35, v36
	v_add_f32_e32 v34, v35, v34
; __device__ __forceinline__ float wave_sum_dpp(float x) { x = rowsum16(x); return (rl(x, 0) + rl(x, 16)) + (rl(x, 32) + rl(x, 48)); }
;     ...
;         for (int r = 0; r < NR; ++r) { mean[r] = wave_sum_dpp(s[r]) * (1.f / DM); q[r] = 0.f;
; #pragma unroll
;             for (int j = 0; j < 4; ++j) { v[r][j] = v[r][j] - mean[r]; q[r] += (v[r][j][0] * v[r][j][0] + v[r][j][1] * v[r][j][1]) + (v[r][j][2] * v[r][j][2] + v[r][j][3] * v[r][j][3]); } }
; #pragma unroll
;         for (int r = 0; r < NR; ++r) rstd[r] = 1.0f / sqrtf(wave_sum_dpp(q[r]) * (1.f / DM) + 1e-5f);
;         if (MODE == 1) {
; #pragma unroll
;             for (int r = 0; r < NR; ++r) if (lane == r) { stats[2 * row[r]] = mean[r]; stats[2 * row[r] + 1] = rstd[r]; } }
	s_lshl_b64 s[18:19], s[18:19], 11
	v_add_f32_dpp v35, v40, v40 row_ror:8 row_mask:0xf bank_mask:0xf bound_ctrl:1
	v_add_f32_dpp v34, v34, v34 row_ror:8 row_mask:0xf bank_mask:0xf bound_ctrl:1
	v_mul_f32_e32 v76, 0x3a800000, v45
	v_add_f32_dpp v35, v35, v35 row_ror:4 row_mask:0xf bank_mask:0xf bound_ctrl:1
	v_add_f32_dpp v34, v34, v34 row_ror:4 row_mask:0xf bank_mask:0xf bound_ctrl:1
	v_mul_f32_e32 v90, 0x3a800000, v38
	v_add_f32_dpp v35, v35, v35 row_ror:2 row_mask:0xf bank_mask:0xf bound_ctrl:1
	v_add_f32_dpp v34, v34, v34 row_ror:2 row_mask:0xf bank_mask:0xf bound_ctrl:1
	v_mov_b32_e32 v89, v37
	v_add_f32_dpp v35, v35, v35 row_ror:1 row_mask:0xf bank_mask:0xf bound_ctrl:1
	v_add_f32_dpp v34, v34, v34 row_ror:1 row_mask:0xf bank_mask:0xf bound_ctrl:1
	v_readlane_b32 s8, v35, 0
	v_readlane_b32 s11, v35, 16
	v_readlane_b32 s9, v35, 32
	v_readlane_b32 s13, v35, 48
	v_readlane_b32 s0, v34, 0
	v_readlane_b32 s3, v34, 16
	v_readlane_b32 s2, v34, 32
	v_readlane_b32 s10, v34, 48
	v_lshl_add_u64 v[34:35], v[50:51], 0, s[18:19]
	s_or_b32 s18, s1, 63
	s_ashr_i32 s19, s18, 31
	s_lshl_b64 s[18:19], s[18:19], 11
	v_lshl_add_u64 v[46:47], v[50:51], 0, s[18:19]
	v_mov_b32_e32 v57, v44
	v_mov_b32_e32 v61, v42
	v_mov_b32_e32 v65, v82
	v_mov_b32_e32 v82, v86
	v_mov_b32_e32 v86, v98
	v_mov_b32_e32 v88, v99
	v_mov_b32_e32 v98, s11
	v_mov_b32_e32 v99, s13
	v_pk_add_f32 v[98:99], s[8:9], v[98:99]
	s_nop 0
	v_add_f32_e32 v77, v98, v99
	v_fmamk_f32 v77, v77, 0x3a800000, v95
	v_mul_f32_e32 v91, 0x4f800000, v77
	v_cmp_gt_f32_e32 vcc, s14, v77
	v_mov_b32_e32 v98, s3
	v_mov_b32_e32 v99, s10
	v_cndmask_b32_e32 v77, v77, v91, vcc
	v_sqrt_f32_e32 v91, v77
	v_add_f32_e32 v98, s0, v98
	v_add_f32_e32 v99, s2, v99
	v_add_f32_e32 v98, v98, v99
	v_add_u32_e32 v92, -1, v91
	v_fma_f32 v94, -v92, v91, v77
	v_cmp_ge_f32_e64 s[8:9], 0, v94
	v_add_u32_e32 v94, 1, v91
	v_fmamk_f32 v98, v98, 0x3a800000, v95
	v_cndmask_b32_e64 v92, v91, v92, s[8:9]
	v_fma_f32 v91, -v94, v91, v77
	v_cmp_lt_f32_e64 s[8:9], 0, v91
	v_mul_f32_e32 v99, 0x4f800000, v98
	s_nop 0
	v_cndmask_b32_e64 v91, v92, v94, s[8:9]
	v_mul_f32_e32 v92, 0x37800000, v91
	v_cndmask_b32_e32 v91, v91, v92, vcc
	v_cmp_class_f32_e32 vcc, v77, v96
	s_nop 1
	v_cndmask_b32_e32 v77, v91, v77, vcc
	v_div_scale_f32 v91, s[8:9], v77, v77, 1.0
	v_rcp_f32_e32 v92, v91
	v_cmp_gt_f32_e64 s[8:9], s14, v98
	v_fma_f32 v94, -v91, v92, 1.0
	s_nop 0
	v_cndmask_b32_e64 v98, v98, v99, s[8:9]
	v_fmac_f32_e32 v92, v94, v92
	v_div_scale_f32 v94, vcc, 1.0, v77, 1.0
	v_sqrt_f32_e32 v99, v98
	v_mul_f32_e32 v97, v94, v92
	v_fma_f32 v100, -v91, v97, v94
	v_fmac_f32_e32 v97, v100, v92
	v_fma_f32 v91, -v91, v97, v94
	v_add_u32_e32 v94, -1, v99
	v_fma_f32 v100, -v94, v99, v98
	v_cmp_ge_f32_e64 s[10:11], 0, v100
	v_add_u32_e32 v100, 1, v99
	v_div_fmas_f32 v91, v91, v92, v97
	v_cndmask_b32_e64 v94, v99, v94, s[10:11]
	v_fma_f32 v99, -v100, v99, v98
	v_cmp_lt_f32_e64 s[10:11], 0, v99
	s_nop 1
	v_cndmask_b32_e64 v94, v94, v100, s[10:11]
	v_mul_f32_e32 v99, 0x37800000, v94
	v_cndmask_b32_e64 v94, v94, v99, s[8:9]
	v_cmp_class_f32_e64 s[8:9], v98, v96
	s_mov_b64 s[10:11], -1
	s_nop 0
	v_cndmask_b32_e64 v98, v94, v98, s[8:9]
	v_div_scale_f32 v99, s[0:1], v98, v98, 1.0
	v_rcp_f32_e32 v100, v99
	v_div_fixup_f32 v94, v91, v77, 1.0
	v_fma_f32 v77, -v99, v100, 1.0
	v_fmac_f32_e32 v100, v77, v100
	v_div_scale_f32 v77, vcc, 1.0, v98, 1.0
	v_mul_f32_e32 v91, v77, v100
	v_fma_f32 v92, -v99, v91, v77
	v_fmac_f32_e32 v91, v92, v100
	v_fma_f32 v77, -v99, v91, v77
	v_div_fmas_f32 v77, v77, v100, v91
	v_div_fixup_f32 v92, v77, v98, 1.0
	v_mov_b32_e32 v77, v94
	v_cmp_lt_i32_e32 vcc, 0, v1
	v_mov_b32_e32 v91, s22
	s_and_saveexec_b64 s[8:9], vcc
	s_cbranch_execz .Lhln15_m5
	v_cmp_eq_u32_e32 vcc, 1, v1
	s_mov_b64 s[10:11], 0
	s_and_saveexec_b64 s[26:27], vcc
	v_mov_b32_e32 v91, v92
	s_mov_b64 s[10:11], exec
	v_mov_b64_e32 v[76:77], v[90:91]
	s_or_b64 exec, exec, s[26:27]
	v_mov_b32_e32 v91, s12
	s_orn2_b64 s[10:11], s[10:11], exec

;     ...
;         for (int r = 0; r < NR; ++r) { s[r] = 0.f;
; #pragma unroll
;             for (int j = 0; j < 2; ++j) {
;                 v[r][2 * j][0] = __builtin_bit_cast(float, raw[r][j].x << 16); v[r][2 * j][1] = __builtin_bit_cast(float, raw[r][j].x & 0xffff0000u);
;                 v[r][2 * j][2] = __builtin_bit_cast(float, raw[r][j].y << 16); v[r][2 * j][3] = __builtin_bit_cast(float, raw[r][j].y & 0xffff0000u);
;                 v[r][2 * j + 1][0] = __builtin_bit_cast(float, raw[r][j].z << 16); v[r][2 * j + 1][1] = __builtin_bit_cast(float, raw[r][j].z & 0xffff0000u);
;                 v[r][2 * j + 1][2] = __builtin_bit_cast(float, raw[r][j].w << 16); v[r][2 * j + 1][3] = __builtin_bit_cast(float, raw[r][j].w & 0xffff0000u); } }
;         { const int nxt = pi + NP * pstep, pq = nxt < p1 ? nxt : pi;
; #pragma unroll
;           for (int r = 0; r < NR; ++r) { const bf16_t* pn = z + (size_t)rowr(pq, r) * DM;
; #pragma unroll
;               for (int j = 0; j < 2; ++j) raw[r][j] = *(const pg8::u32x4*)(pn + 8 * lane + 512 * j); } }
; #pragma unroll
;         for (int r = 0; r < NR; ++r)
; #pragma unroll
;             for (int j = 0; j < 4; ++j) s[r] += (v[r][j][0] + v[r][j][1]) + (v[r][j][2] + v[r][j][3]);
;         float mean[NR], q[NR], rstd[NR];
; #pragma unroll
;         for (int r = 0; r < NR; ++r) { mean[r] = wave_sum_dpp(s[r]) * (1.f / DM); q[r] = 0.f;
; #pragma unroll
;             for (int j = 0; j < 4; ++j) { v[r][j] = v[r][j] - mean[r]; q[r] += (v[r][j][0] * v[r][j][0] + v[r][j][1] * v[r][j][1]) + (v[r][j][2] * v[r][j][2] + v[r][j][3] * v[r][j][3]); } }
; #pragma unroll
;         for (int r = 0; r < NR; ++r) rstd[r] = 1.0f / sqrtf(wave_sum_dpp(q[r]) * (1.f / DM) + 1e-5f);
;         if (MODE == 1) {
; #pragma unroll
;             for (int r = 0; r < NR; ++r) if (lane == r) { stats[2 * row[r]] = mean[r]; stats[2 * row[r] + 1] = rstd[r]; } }
; #pragma unroll
;         for (int j = 0; j < 2; ++j) {
;             const int c = 8 * lane + 512 * j;
;             const f32x4 g0 = *(const f32x4*)(g + c), g1 = *(const f32x4*)(g + c + 4), b0 = *(const f32x4*)(b + c), b1 = *(const f32x4*)(b + c + 4);
; #pragma unroll
;             for (int r = 0; r < NR; ++r) {
;                 const f32x4 o0 = v[r][2 * j] * rstd[r] * g0 + b0, o1 = v[r][2 * j + 1] * rstd[r] * g1 + b1;
.Lhln15_t5:
	s_or_b64 exec, exec, s[8:9]
	s_add_i32 s0, s12, -1
	v_pk_mul_f32 v[74:75], v[74:75], v[94:95] op_sel_hi:[1,0]
	v_pk_mul_f32 v[72:73], v[72:73], v[94:95] op_sel_hi:[1,0]
	v_pk_mul_f32 v[76:77], v[80:81], v[94:95] op_sel_hi:[1,0]
	v_pk_mul_f32 v[78:79], v[78:79], v[94:95] op_sel_hi:[1,0]
	s_ashr_i32 s1, s0, 31
	v_pk_fma_f32 v[74:75], v[12:13], v[74:75], v[16:17]
	v_pk_fma_f32 v[72:73], v[10:11], v[72:73], v[14:15]
	v_pk_fma_f32 v[76:77], v[4:5], v[76:77], v[8:9]
	v_pk_fma_f32 v[78:79], v[2:3], v[78:79], v[6:7]
	s_lshl_b64 s[0:1], s[0:1], 11
	v_cvt_pk_bf16_f32 v72, v72, v73
	v_cvt_pk_bf16_f32 v73, v74, v75
	v_cvt_pk_bf16_f32 v74, v78, v79
	v_cvt_pk_bf16_f32 v75, v76, v77
	v_lshl_add_u64 v[76:77], v[52:53], 0, s[0:1]
	global_store_dwordx4 v[76:77], v[72:75], off
	v_pk_mul_f32 v[78:79], v[86:87], v[92:93] op_sel_hi:[1,0]
	s_ashr_i32 s13, s12, 31
	v_pk_mul_f32 v[72:73], v[84:85], v[92:93] op_sel_hi:[1,0]
	v_pk_mul_f32 v[74:75], v[82:83], v[92:93] op_sel_hi:[1,0]
	v_pk_fma_f32 v[76:77], v[12:13], v[72:73], v[16:17]
	v_pk_fma_f32 v[72:73], v[10:11], v[74:75], v[14:15]
	v_pk_mul_f32 v[74:75], v[88:89], v[92:93] op_sel_hi:[1,0]
	s_lshl_b64 s[2:3], s[12:13], 11
	v_pk_fma_f32 v[80:81], v[4:5], v[74:75], v[8:9]
	v_pk_fma_f32 v[74:75], v[2:3], v[78:79], v[6:7]
	v_cvt_pk_bf16_f32 v72, v72, v73
	v_cvt_pk_bf16_f32 v73, v76, v77
	v_cvt_pk_bf16_f32 v74, v74, v75
	v_cvt_pk_bf16_f32 v75, v80, v81
	v_lshl_add_u64 v[76:77], v[52:53], 0, s[2:3]
	v_pk_mul_f32 v[70:71], v[70:71], v[94:95] op_sel_hi:[1,0]
	v_pk_mul_f32 v[68:69], v[68:69], v[94:95] op_sel_hi:[1,0]
	v_pk_mul_f32 v[66:67], v[66:67], v[94:95] op_sel_hi:[1,0]
	v_pk_mul_f32 v[64:65], v[64:65], v[94:95] op_sel_hi:[1,0]
	global_store_dwordx4 v[76:77], v[72:75], off
	v_pk_fma_f32 v[70:71], v[28:29], v[70:71], v[32:33]
	v_pk_fma_f32 v[68:69], v[26:27], v[68:69], v[30:31]
	v_pk_fma_f32 v[72:73], v[20:21], v[66:67], v[24:25]
	v_pk_fma_f32 v[66:67], v[18:19], v[64:65], v[22:23]
	v_cvt_pk_bf16_f32 v64, v68, v69
	v_cvt_pk_bf16_f32 v65, v70, v71
	v_cvt_pk_bf16_f32 v66, v66, v67
	v_cvt_pk_bf16_f32 v67, v72, v73
	v_lshl_add_u64 v[68:69], v[54:55], 0, s[0:1]
	v_pk_mul_f32 v[62:63], v[62:63], v[92:93] op_sel_hi:[1,0]
	v_pk_mul_f32 v[58:59], v[58:59], v[92:93] op_sel_hi:[1,0]
	v_pk_mul_f32 v[60:61], v[60:61], v[92:93] op_sel_hi:[1,0]
	v_pk_mul_f32 v[56:57], v[56:57], v[92:93] op_sel_hi:[1,0]
	global_store_dwordx4 v[68:69], v[64:67], off
	v_pk_fma_f32 v[62:63], v[28:29], v[62:63], v[32:33]
	v_pk_fma_f32 v[58:59], v[26:27], v[58:59], v[30:31]
	v_pk_fma_f32 v[60:61], v[20:21], v[60:61], v[24:25]
	v_pk_fma_f32 v[64:65], v[18:19], v[56:57], v[22:23]
	v_cvt_pk_bf16_f32 v56, v58, v59
	v_cvt_pk_bf16_f32 v57, v62, v63
	v_cvt_pk_bf16_f32 v58, v64, v65
	v_cvt_pk_bf16_f32 v59, v60, v61
	v_lshl_add_u64 v[60:61], v[54:55], 0, s[2:3]
	s_andn2_b64 vcc, exec, s[20:21]
	s_addk_i32 s12, 0x200
	global_store_dwordx4 v[60:61], v[56:59], off
	s_cbranch_vccz .LBB0_1752
	s_waitcnt vmcnt(20)
	v_lshlrev_b32_e32 v58, 16, v248
	v_and_b32_e32 v59, 0xffff0000, v248
	v_lshlrev_b32_e32 v62, 16, v249
	v_and_b32_e32 v63, 0xffff0000, v249
	v_lshlrev_b32_e32 v47, 16, v241
	v_lshlrev_b32_e32 v46, 16, v240
	v_and_b32_e32 v39, 0xffff0000, v241
	v_and_b32_e32 v38, 0xffff0000, v240
	v_lshlrev_b32_e32 v68, 16, v244
	v_and_b32_e32 v69, 0xffff0000, v244
	v_lshlrev_b32_e32 v64, 16, v246
	v_and_b32_e32 v82, 0xffff0000, v246
	v_lshlrev_b32_e32 v56, 16, v250
	v_and_b32_e32 v44, 0xffff0000, v250
	v_lshlrev_b32_e32 v60, 16, v251
	v_and_b32_e32 v42, 0xffff0000, v251
	v_pk_add_f32 v[48:49], v[46:47], v[38:39]
	v_lshlrev_b32_e32 v70, 16, v245
	v_and_b32_e32 v71, 0xffff0000, v245
	v_add_f32_e32 v43, v48, v49
	v_lshlrev_b32_e32 v49, 16, v243
	v_lshlrev_b32_e32 v48, 16, v242
	v_and_b32_e32 v41, 0xffff0000, v243
	v_and_b32_e32 v40, 0xffff0000, v242
	v_pk_add_f32 v[72:73], v[48:49], v[40:41]
	v_lshlrev_b32_e32 v66, 16, v247
	v_pk_add_f32 v[72:73], v[72:73], v[72:73] op_sel_hi:[0,1]
	v_and_b32_e32 v84, 0xffff0000, v247
	v_add_f32_e32 v85, 0, v43
	v_add_f32_e32 v65, v68, v69
	v_add_f32_e32 v83, v70, v71
	v_mov_b32_e32 v67, v73
	v_pk_add_f32 v[74:75], v[64:65], v[82:83]
	v_pk_add_f32 v[72:73], v[66:67], v[84:85]
	v_lshlrev_b32_e32 v87, 16, v237
	v_pk_add_f32 v[72:73], v[74:75], v[72:73]
	v_lshlrev_b32_e32 v86, 16, v236
	v_and_b32_e32 v35, 0xffff0000, v237
	v_and_b32_e32 v34, 0xffff0000, v236
	v_add_f32_e32 v65, v72, v73
	v_pk_add_f32 v[72:73], v[86:87], v[34:35]
	v_lshlrev_b32_e32 v99, 16, v239
	v_lshlrev_b32_e32 v98, 16, v238
	v_and_b32_e32 v37, 0xffff0000, v239
	v_and_b32_e32 v36, 0xffff0000, v238
	v_add_f32_e32 v57, v58, v59
	v_add_f32_e32 v45, v62, v63
	v_add_f32_e32 v43, v72, v73
	v_pk_add_f32 v[72:73], v[98:99], v[36:37]
	v_pk_add_f32 v[74:75], v[56:57], v[44:45]
	v_add_f32_dpp v45, v65, v65 row_ror:8 row_mask:0xf bank_mask:0xf bound_ctrl:1
	v_pk_add_f32 v[72:73], v[72:73], v[72:73] op_sel_hi:[0,1]
	v_add_f32_e32 v43, 0, v43
	v_add_f32_dpp v45, v45, v45 row_ror:4 row_mask:0xf bank_mask:0xf bound_ctrl:1
	v_mov_b32_e32 v61, v73
	v_pk_add_f32 v[72:73], v[60:61], v[42:43]
	v_add_f32_dpp v45, v45, v45 row_ror:2 row_mask:0xf bank_mask:0xf bound_ctrl:1
	v_pk_add_f32 v[72:73], v[74:75], v[72:73]
	s_mov_b32 s1, s15
	v_add_f32_dpp v45, v45, v45 row_ror:1 row_mask:0xf bank_mask:0xf bound_ctrl:1
	v_add_f32_e32 v43, v72, v73
	v_readlane_b32 s0, v45, 16
	v_readlane_b32 s8, v45, 48
	v_readlane_b32 s2, v45, 0
	v_readlane_b32 s3, v45, 32
	v_mov_b32_e32 v72, s0
	v_mov_b32_e32 v73, s8
	v_pk_add_f32 v[72:73], s[2:3], v[72:73]
	s_lshl_b32 s15, s15, 6
	v_add_f32_e32 v45, v72, v73
	v_fmac_f32_e32 v39, 0xba800000, v45
	v_fmac_f32_e32 v47, 0xba800000, v45
	v_fmac_f32_e32 v38, 0xba800000, v45
; __device__ __forceinline__ float wave_sum_dpp(float x) { x = rowsum16(x); return (rl(x, 0) + rl(x, 16)) + (rl(x, 32) + rl(x, 48)); }
;     ...
;             for (int j = 0; j < 4; ++j) s[r] += (v[r][j][0] + v[r][j][1]) + (v[r][j][2] + v[r][j][3]);
;         float mean[NR], q[NR], rstd[NR];
; #pragma unroll
;         for (int r = 0; r < NR; ++r) { mean[r] = wave_sum_dpp(s[r]) * (1.f / DM); q[r] = 0.f;
; #pragma unroll
;             for (int j = 0; j < 4; ++j) { v[r][j] = v[r][j] - mean[r]; q[r] += (v[r][j][0] * v[r][j][0] + v[r][j][1] * v[r][j][1]) + (v[r][j][2] * v[r][j][2] + v[r][j][3] * v[r][j][3]); } }
	v_fmac_f32_e32 v46, 0xba800000, v45
	v_mov_b32_e32 v74, v47
	v_mov_b32_e32 v78, v47
	v_mov_b32_e32 v79, v39
	v_mov_b32_e32 v47, v38
	v_mov_b32_e32 v73, v38
	v_mov_b32_e32 v75, v39
	v_pk_mul_f32 v[78:79], v[78:79], v[78:79]
	v_pk_mul_f32 v[38:39], v[46:47], v[46:47]
	v_mov_b32_e32 v72, v46
	v_pk_mov_b32 v[46:47], v[38:39], v[78:79] op_sel:[1,0]
	v_mov_b32_e32 v39, v79
	v_fmac_f32_e32 v41, 0xba800000, v45
	v_fmac_f32_e32 v49, 0xba800000, v45
	v_fmac_f32_e32 v40, 0xba800000, v45
	v_pk_add_f32 v[38:39], v[46:47], v[38:39]
	v_fmac_f32_e32 v48, 0xba800000, v45
	v_mov_b32_e32 v80, v49
	v_mov_b32_e32 v46, v49
	v_mov_b32_e32 v47, v41
	v_mov_b32_e32 v49, v40
	v_pk_add_f32 v[38:39], v[38:39], v[38:39] op_sel_hi:[0,1]
	v_mov_b32_e32 v79, v40
	v_mov_b32_e32 v81, v41
	v_pk_mul_f32 v[46:47], v[46:47], v[46:47]
	v_pk_mul_f32 v[40:41], v[48:49], v[48:49]
	v_fmac_f32_e32 v68, 0xba800000, v45
	v_mov_b32_e32 v78, v48
	v_pk_mov_b32 v[48:49], v[40:41], v[46:47] op_sel:[1,0]
	v_mov_b32_e32 v41, v47
	v_fmac_f32_e32 v70, 0xba800000, v45
	v_fmac_f32_e32 v69, 0xba800000, v45
	v_mul_f32_e32 v38, v68, v68
	v_pk_add_f32 v[40:41], v[48:49], v[40:41]
	v_fmac_f32_e32 v71, 0xba800000, v45
	v_pk_fma_f32 v[46:47], v[68:69], v[68:69], v[38:39] op_sel_hi:[1,1,0]
	v_mul_f32_e32 v38, v70, v70
	v_pk_add_f32 v[40:41], v[40:41], v[40:41] op_sel_hi:[0,1]
	v_pk_fma_f32 v[48:49], v[70:71], v[70:71], v[38:39] op_sel_hi:[1,1,0]
	v_fmac_f32_e32 v84, 0xba800000, v45
	v_fmac_f32_e32 v66, 0xba800000, v45
	v_fmac_f32_e32 v82, 0xba800000, v45
	v_fmac_f32_e32 v64, 0xba800000, v45
	v_mul_f32_e32 v46, v64, v64
	v_mul_f32_e32 v48, v82, v82
	v_mul_f32_e32 v38, v66, v66
	v_mul_f32_e32 v40, v84, v84
	v_pk_add_f32 v[46:47], v[46:47], v[48:49]
	v_pk_add_f32 v[38:39], v[38:39], v[40:41]
	v_mov_b32_e32 v67, v84
	v_pk_add_f32 v[38:39], v[46:47], v[38:39]
	s_or_b32 s22, s15, 62
	v_add_f32_e32 v40, v38, v39
	v_add_f32_dpp v38, v43, v43 row_ror:8 row_mask:0xf bank_mask:0xf bound_ctrl:1
	s_add_i32 s15, s1, 8
	s_cmp_ge_i32 s1, s5
	v_add_f32_dpp v38, v38, v38 row_ror:4 row_mask:0xf bank_mask:0xf bound_ctrl:1
	s_cselect_b64 s[20:21], -1, 0
	s_cmp_lt_i32 s1, s5
	v_add_f32_dpp v38, v38, v38 row_ror:2 row_mask:0xf bank_mask:0xf bound_ctrl:1
	s_cselect_b32 s1, s15, s1
	s_lshl_b32 s1, s1, 6
	v_add_f32_dpp v38, v38, v38 row_ror:1 row_mask:0xf bank_mask:0xf bound_ctrl:1
	s_or_b32 s18, s1, 62
	v_readlane_b32 s0, v38, 16
	v_readlane_b32 s8, v38, 48
	v_readlane_b32 s2, v38, 0
	v_readlane_b32 s3, v38, 32
	v_mov_b32_e32 v38, s0
	v_mov_b32_e32 v39, s8
	v_pk_add_f32 v[38:39], s[2:3], v[38:39]
	s_ashr_i32 s19, s18, 31
	v_add_f32_e32 v38, v38, v39
	v_fmac_f32_e32 v35, 0xba800000, v38
	v_fmac_f32_e32 v34, 0xba800000, v38
	v_fmac_f32_e32 v87, 0xba800000, v38
	v_fmac_f32_e32 v86, 0xba800000, v38
	v_mov_b32_e32 v83, v34
	v_mov_b32_e32 v85, v35
	v_mul_f32_e32 v34, v34, v34
	v_mul_f32_e32 v35, v35, v35
	v_fmac_f32_e32 v34, v86, v86
	v_fmac_f32_e32 v35, v87, v87
	v_fmac_f32_e32 v37, 0xba800000, v38
	v_fmac_f32_e32 v36, 0xba800000, v38
	v_mov_b32_e32 v84, v87
	v_add_f32_e32 v34, v34, v35
	v_fmac_f32_e32 v99, 0xba800000, v38
	v_fmac_f32_e32 v98, 0xba800000, v38
	v_mov_b32_e32 v87, v36
	v_mul_f32_e32 v35, v36, v36
	v_mul_f32_e32 v36, v37, v37
	v_fmac_f32_e32 v35, v98, v98
	v_fmac_f32_e32 v36, v99, v99
	v_add_f32_e32 v35, v35, v36
	v_fmac_f32_e32 v63, 0xba800000, v38
	v_fmac_f32_e32 v59, 0xba800000, v38
	v_add_f32_e32 v34, v34, v35
	v_fmac_f32_e32 v62, 0xba800000, v38
	v_fmac_f32_e32 v58, 0xba800000, v38
	v_mul_f32_e32 v35, v59, v59
	v_mul_f32_e32 v36, v63, v63
	v_fmac_f32_e32 v35, v58, v58
	v_fmac_f32_e32 v36, v62, v62
	v_add_f32_e32 v35, v35, v36
	v_fmac_f32_e32 v42, 0xba800000, v38
	v_fmac_f32_e32 v44, 0xba800000, v38
	v_add_f32_e32 v34, v35, v34
	v_fmac_f32_e32 v60, 0xba800000, v38
	v_fmac_f32_e32 v56, 0xba800000, v38
	v_mul_f32_e32 v35, v44, v44
	v_mul_f32_e32 v36, v42, v42
	v_fmac_f32_e32 v35, v56, v56
	v_fmac_f32_e32 v36, v60, v60
	v_add_f32_e32 v35, v35, v36
	v_add_f32_e32 v34, v35, v34
; __device__ __forceinline__ float wave_sum_dpp(float x) { x = rowsum16(x); return (rl(x, 0) + rl(x, 16)) + (rl(x, 32) + rl(x, 48)); }
;     ...
;         for (int r = 0; r < NR; ++r) { mean[r] = wave_sum_dpp(s[r]) * (1.f / DM); q[r] = 0.f;
; #pragma unroll
;             for (int j = 0; j < 4; ++j) { v[r][j] = v[r][j] - mean[r]; q[r] += (v[r][j][0] * v[r][j][0] + v[r][j][1] * v[r][j][1]) + (v[r][j][2] * v[r][j][2] + v[r][j][3] * v[r][j][3]); } }
; #pragma unroll
;         for (int r = 0; r < NR; ++r) rstd[r] = 1.0f / sqrtf(wave_sum_dpp(q[r]) * (1.f / DM) + 1e-5f);
;         if (MODE == 1) {
; #pragma unroll
;             for (int r = 0; r < NR; ++r) if (lane == r) { stats[2 * row[r]] = mean[r]; stats[2 * row[r] + 1] = rstd[r]; } }
	s_lshl_b64 s[18:19], s[18:19], 11
	v_add_f32_dpp v35, v40, v40 row_ror:8 row_mask:0xf bank_mask:0xf bound_ctrl:1
	v_add_f32_dpp v34, v34, v34 row_ror:8 row_mask:0xf bank_mask:0xf bound_ctrl:1
	v_mul_f32_e32 v76, 0x3a800000, v45
	v_add_f32_dpp v35, v35, v35 row_ror:4 row_mask:0xf bank_mask:0xf bound_ctrl:1
	v_add_f32_dpp v34, v34, v34 row_ror:4 row_mask:0xf bank_mask:0xf bound_ctrl:1
	v_mul_f32_e32 v90, 0x3a800000, v38
	v_add_f32_dpp v35, v35, v35 row_ror:2 row_mask:0xf bank_mask:0xf bound_ctrl:1
	v_add_f32_dpp v34, v34, v34 row_ror:2 row_mask:0xf bank_mask:0xf bound_ctrl:1
	v_mov_b32_e32 v89, v37
	v_add_f32_dpp v35, v35, v35 row_ror:1 row_mask:0xf bank_mask:0xf bound_ctrl:1
	v_add_f32_dpp v34, v34, v34 row_ror:1 row_mask:0xf bank_mask:0xf bound_ctrl:1
	v_readlane_b32 s8, v35, 0
	v_readlane_b32 s11, v35, 16
	v_readlane_b32 s9, v35, 32
	v_readlane_b32 s13, v35, 48
	v_readlane_b32 s0, v34, 0
	v_readlane_b32 s3, v34, 16
	v_readlane_b32 s2, v34, 32
	v_readlane_b32 s10, v34, 48
	v_lshl_add_u64 v[34:35], v[50:51], 0, s[18:19]
	s_or_b32 s18, s1, 63
	s_ashr_i32 s19, s18, 31
	s_lshl_b64 s[18:19], s[18:19], 11
	v_lshl_add_u64 v[46:47], v[50:51], 0, s[18:19]
	v_mov_b32_e32 v57, v44
	v_mov_b32_e32 v61, v42
	v_mov_b32_e32 v65, v82
	v_mov_b32_e32 v82, v86
	v_mov_b32_e32 v86, v98
	v_mov_b32_e32 v88, v99
	v_mov_b32_e32 v98, s11
	v_mov_b32_e32 v99, s13
	v_pk_add_f32 v[98:99], s[8:9], v[98:99]
	s_nop 0
	v_add_f32_e32 v77, v98, v99
	v_fmamk_f32 v77, v77, 0x3a800000, v95
	v_mul_f32_e32 v91, 0x4f800000, v77
	v_cmp_gt_f32_e32 vcc, s14, v77
	v_mov_b32_e32 v98, s3
	v_mov_b32_e32 v99, s10
	v_cndmask_b32_e32 v77, v77, v91, vcc
	v_sqrt_f32_e32 v91, v77
	v_add_f32_e32 v98, s0, v98
	v_add_f32_e32 v99, s2, v99
	v_add_f32_e32 v98, v98, v99
	v_add_u32_e32 v92, -1, v91
	v_fma_f32 v94, -v92, v91, v77
	v_cmp_ge_f32_e64 s[8:9], 0, v94
	v_add_u32_e32 v94, 1, v91
	v_fmamk_f32 v98, v98, 0x3a800000, v95
	v_cndmask_b32_e64 v92, v91, v92, s[8:9]
	v_fma_f32 v91, -v94, v91, v77
	v_cmp_lt_f32_e64 s[8:9], 0, v91
	v_mul_f32_e32 v99, 0x4f800000, v98
	s_nop 0
	v_cndmask_b32_e64 v91, v92, v94, s[8:9]
	v_mul_f32_e32 v92, 0x37800000, v91
	v_cndmask_b32_e32 v91, v91, v92, vcc
	v_cmp_class_f32_e32 vcc, v77, v96
	s_nop 1
	v_cndmask_b32_e32 v77, v91, v77, vcc
	v_div_scale_f32 v91, s[8:9], v77, v77, 1.0
	v_rcp_f32_e32 v92, v91
	v_cmp_gt_f32_e64 s[8:9], s14, v98
	v_fma_f32 v94, -v91, v92, 1.0
	s_nop 0
	v_cndmask_b32_e64 v98, v98, v99, s[8:9]
	v_fmac_f32_e32 v92, v94, v92
	v_div_scale_f32 v94, vcc, 1.0, v77, 1.0
	v_sqrt_f32_e32 v99, v98
	v_mul_f32_e32 v97, v94, v92
	v_fma_f32 v100, -v91, v97, v94
	v_fmac_f32_e32 v97, v100, v92
	v_fma_f32 v91, -v91, v97, v94
	v_add_u32_e32 v94, -1, v99
	v_fma_f32 v100, -v94, v99, v98
	v_cmp_ge_f32_e64 s[10:11], 0, v100
	v_add_u32_e32 v100, 1, v99
	v_div_fmas_f32 v91, v91, v92, v97
	v_cndmask_b32_e64 v94, v99, v94, s[10:11]
	v_fma_f32 v99, -v100, v99, v98
	v_cmp_lt_f32_e64 s[10:11], 0, v99
	s_nop 1
	v_cndmask_b32_e64 v94, v94, v100, s[10:11]
	v_mul_f32_e32 v99, 0x37800000, v94
	v_cndmask_b32_e64 v94, v94, v99, s[8:9]
	v_cmp_class_f32_e64 s[8:9], v98, v96
	s_mov_b64 s[10:11], -1
	s_nop 0
	v_cndmask_b32_e64 v98, v94, v98, s[8:9]
	v_div_scale_f32 v99, s[0:1], v98, v98, 1.0
	v_rcp_f32_e32 v100, v99
	v_div_fixup_f32 v94, v91, v77, 1.0
	v_fma_f32 v77, -v99, v100, 1.0
	v_fmac_f32_e32 v100, v77, v100
	v_div_scale_f32 v77, vcc, 1.0, v98, 1.0
	v_mul_f32_e32 v91, v77, v100
	v_fma_f32 v92, -v99, v91, v77
	v_fmac_f32_e32 v91, v92, v100
	v_fma_f32 v77, -v99, v91, v77
	v_div_fmas_f32 v77, v77, v100, v91
	v_div_fixup_f32 v92, v77, v98, 1.0
	v_mov_b32_e32 v77, v94
	v_cmp_lt_i32_e32 vcc, 0, v1
	v_mov_b32_e32 v91, s22
	s_and_saveexec_b64 s[8:9], vcc
	s_cbranch_execz .Lhln15_m6
	v_cmp_eq_u32_e32 vcc, 1, v1
	s_mov_b64 s[10:11], 0
	s_and_saveexec_b64 s[26:27], vcc
	v_mov_b32_e32 v91, v92
	s_mov_b64 s[10:11], exec
	v_mov_b64_e32 v[76:77], v[90:91]
	s_or_b64 exec, exec, s[26:27]
	v_mov_b32_e32 v91, s12
	s_orn2_b64 s[10:11], s[10:11], exec

;     ...
;         for (int r = 0; r < NR; ++r) { s[r] = 0.f;
; #pragma unroll
;             for (int j = 0; j < 2; ++j) {
;                 v[r][2 * j][0] = __builtin_bit_cast(float, raw[r][j].x << 16); v[r][2 * j][1] = __builtin_bit_cast(float, raw[r][j].x & 0xffff0000u);
;                 v[r][2 * j][2] = __builtin_bit_cast(float, raw[r][j].y << 16); v[r][2 * j][3] = __builtin_bit_cast(float, raw[r][j].y & 0xffff0000u);
;                 v[r][2 * j + 1][0] = __builtin_bit_cast(float, raw[r][j].z << 16); v[r][2 * j + 1][1] = __builtin_bit_cast(float, raw[r][j].z & 0xffff0000u);
;                 v[r][2 * j + 1][2] = __builtin_bit_cast(float, raw[r][j].w << 16); v[r][2 * j + 1][3] = __builtin_bit_cast(float, raw[r][j].w & 0xffff0000u); } }
;         { const int nxt = pi + NP * pstep, pq = nxt < p1 ? nxt : pi;
; #pragma unroll
;           for (int r = 0; r < NR; ++r) { const bf16_t* pn = z + (size_t)rowr(pq, r) * DM;
; #pragma unroll
;               for (int j = 0; j < 2; ++j) raw[r][j] = *(const pg8::u32x4*)(pn + 8 * lane + 512 * j); } }
; #pragma unroll
;         for (int r = 0; r < NR; ++r)
; #pragma unroll
;             for (int j = 0; j < 4; ++j) s[r] += (v[r][j][0] + v[r][j][1]) + (v[r][j][2] + v[r][j][3]);
;         float mean[NR], q[NR], rstd[NR];
; #pragma unroll
;         for (int r = 0; r < NR; ++r) { mean[r] = wave_sum_dpp(s[r]) * (1.f / DM); q[r] = 0.f;
; #pragma unroll
;             for (int j = 0; j < 4; ++j) { v[r][j] = v[r][j] - mean[r]; q[r] += (v[r][j][0] * v[r][j][0] + v[r][j][1] * v[r][j][1]) + (v[r][j][2] * v[r][j][2] + v[r][j][3] * v[r][j][3]); } }
; #pragma unroll
;         for (int r = 0; r < NR; ++r) rstd[r] = 1.0f / sqrtf(wave_sum_dpp(q[r]) * (1.f / DM) + 1e-5f);
;         if (MODE == 1) {
; #pragma unroll
;             for (int r = 0; r < NR; ++r) if (lane == r) { stats[2 * row[r]] = mean[r]; stats[2 * row[r] + 1] = rstd[r]; } }
; #pragma unroll
;         for (int j = 0; j < 2; ++j) {
;             const int c = 8 * lane + 512 * j;
;             const f32x4 g0 = *(const f32x4*)(g + c), g1 = *(const f32x4*)(g + c + 4), b0 = *(const f32x4*)(b + c), b1 = *(const f32x4*)(b + c + 4);
; #pragma unroll
;             for (int r = 0; r < NR; ++r) {
;                 const f32x4 o0 = v[r][2 * j] * rstd[r] * g0 + b0, o1 = v[r][2 * j + 1] * rstd[r] * g1 + b1;
.Lhln15_t6:
	s_or_b64 exec, exec, s[8:9]
	s_add_i32 s0, s12, -1
	v_pk_mul_f32 v[74:75], v[74:75], v[94:95] op_sel_hi:[1,0]
	v_pk_mul_f32 v[72:73], v[72:73], v[94:95] op_sel_hi:[1,0]
	v_pk_mul_f32 v[76:77], v[80:81], v[94:95] op_sel_hi:[1,0]
	v_pk_mul_f32 v[78:79], v[78:79], v[94:95] op_sel_hi:[1,0]
	s_ashr_i32 s1, s0, 31
	v_pk_fma_f32 v[74:75], v[12:13], v[74:75], v[16:17]
	v_pk_fma_f32 v[72:73], v[10:11], v[72:73], v[14:15]
	v_pk_fma_f32 v[76:77], v[4:5], v[76:77], v[8:9]
	v_pk_fma_f32 v[78:79], v[2:3], v[78:79], v[6:7]
	s_lshl_b64 s[0:1], s[0:1], 11
	v_cvt_pk_bf16_f32 v72, v72, v73
	v_cvt_pk_bf16_f32 v73, v74, v75
	v_cvt_pk_bf16_f32 v74, v78, v79
	v_cvt_pk_bf16_f32 v75, v76, v77
	v_lshl_add_u64 v[76:77], v[52:53], 0, s[0:1]
	global_store_dwordx4 v[76:77], v[72:75], off
	v_pk_mul_f32 v[78:79], v[86:87], v[92:93] op_sel_hi:[1,0]
	s_ashr_i32 s13, s12, 31
	v_pk_mul_f32 v[72:73], v[84:85], v[92:93] op_sel_hi:[1,0]
	v_pk_mul_f32 v[74:75], v[82:83], v[92:93] op_sel_hi:[1,0]
	v_pk_fma_f32 v[76:77], v[12:13], v[72:73], v[16:17]
	v_pk_fma_f32 v[72:73], v[10:11], v[74:75], v[14:15]
	v_pk_mul_f32 v[74:75], v[88:89], v[92:93] op_sel_hi:[1,0]
	s_lshl_b64 s[2:3], s[12:13], 11
	v_pk_fma_f32 v[80:81], v[4:5], v[74:75], v[8:9]
	v_pk_fma_f32 v[74:75], v[2:3], v[78:79], v[6:7]
	v_cvt_pk_bf16_f32 v72, v72, v73
	v_cvt_pk_bf16_f32 v73, v76, v77
	v_cvt_pk_bf16_f32 v74, v74, v75
	v_cvt_pk_bf16_f32 v75, v80, v81
	v_lshl_add_u64 v[76:77], v[52:53], 0, s[2:3]
	v_pk_mul_f32 v[70:71], v[70:71], v[94:95] op_sel_hi:[1,0]
	v_pk_mul_f32 v[68:69], v[68:69], v[94:95] op_sel_hi:[1,0]
	v_pk_mul_f32 v[66:67], v[66:67], v[94:95] op_sel_hi:[1,0]
	v_pk_mul_f32 v[64:65], v[64:65], v[94:95] op_sel_hi:[1,0]
	global_store_dwordx4 v[76:77], v[72:75], off
	v_pk_fma_f32 v[70:71], v[28:29], v[70:71], v[32:33]
	v_pk_fma_f32 v[68:69], v[26:27], v[68:69], v[30:31]
	v_pk_fma_f32 v[72:73], v[20:21], v[66:67], v[24:25]
	v_pk_fma_f32 v[66:67], v[18:19], v[64:65], v[22:23]
	v_cvt_pk_bf16_f32 v64, v68, v69
	v_cvt_pk_bf16_f32 v65, v70, v71
	v_cvt_pk_bf16_f32 v66, v66, v67
	v_cvt_pk_bf16_f32 v67, v72, v73
	v_lshl_add_u64 v[68:69], v[54:55], 0, s[0:1]
	v_pk_mul_f32 v[62:63], v[62:63], v[92:93] op_sel_hi:[1,0]
	v_pk_mul_f32 v[58:59], v[58:59], v[92:93] op_sel_hi:[1,0]
	v_pk_mul_f32 v[60:61], v[60:61], v[92:93] op_sel_hi:[1,0]
	v_pk_mul_f32 v[56:57], v[56:57], v[92:93] op_sel_hi:[1,0]
	global_store_dwordx4 v[68:69], v[64:67], off
	v_pk_fma_f32 v[62:63], v[28:29], v[62:63], v[32:33]
	v_pk_fma_f32 v[58:59], v[26:27], v[58:59], v[30:31]
	v_pk_fma_f32 v[60:61], v[20:21], v[60:61], v[24:25]
	v_pk_fma_f32 v[64:65], v[18:19], v[56:57], v[22:23]
	v_cvt_pk_bf16_f32 v56, v58, v59
	v_cvt_pk_bf16_f32 v57, v62, v63
	v_cvt_pk_bf16_f32 v58, v64, v65
	v_cvt_pk_bf16_f32 v59, v60, v61
	v_lshl_add_u64 v[60:61], v[54:55], 0, s[2:3]
	s_andn2_b64 vcc, exec, s[20:21]
	s_addk_i32 s12, 0x200
	global_store_dwordx4 v[60:61], v[56:59], off
	s_cbranch_vccz .LBB0_1752
	s_waitcnt vmcnt(20)
	v_lshlrev_b32_e32 v58, 16, v168
	v_and_b32_e32 v59, 0xffff0000, v168
	v_lshlrev_b32_e32 v62, 16, v169
	v_and_b32_e32 v63, 0xffff0000, v169
	v_lshlrev_b32_e32 v47, 16, v161
	v_lshlrev_b32_e32 v46, 16, v160
	v_and_b32_e32 v39, 0xffff0000, v161
	v_and_b32_e32 v38, 0xffff0000, v160
	v_lshlrev_b32_e32 v68, 16, v164
	v_and_b32_e32 v69, 0xffff0000, v164
	v_lshlrev_b32_e32 v64, 16, v166
	v_and_b32_e32 v82, 0xffff0000, v166
	v_lshlrev_b32_e32 v56, 16, v170
	v_and_b32_e32 v44, 0xffff0000, v170
	v_lshlrev_b32_e32 v60, 16, v171
	v_and_b32_e32 v42, 0xffff0000, v171
	v_pk_add_f32 v[48:49], v[46:47], v[38:39]
	v_lshlrev_b32_e32 v70, 16, v165
	v_and_b32_e32 v71, 0xffff0000, v165
	v_add_f32_e32 v43, v48, v49
	v_lshlrev_b32_e32 v49, 16, v163
	v_lshlrev_b32_e32 v48, 16, v162
	v_and_b32_e32 v41, 0xffff0000, v163
	v_and_b32_e32 v40, 0xffff0000, v162
	v_pk_add_f32 v[72:73], v[48:49], v[40:41]
	v_lshlrev_b32_e32 v66, 16, v167
	v_pk_add_f32 v[72:73], v[72:73], v[72:73] op_sel_hi:[0,1]
	v_and_b32_e32 v84, 0xffff0000, v167
	v_add_f32_e32 v85, 0, v43
	v_add_f32_e32 v65, v68, v69
	v_add_f32_e32 v83, v70, v71
	v_mov_b32_e32 v67, v73
	v_pk_add_f32 v[74:75], v[64:65], v[82:83]
	v_pk_add_f32 v[72:73], v[66:67], v[84:85]
	v_lshlrev_b32_e32 v87, 16, v157
	v_pk_add_f32 v[72:73], v[74:75], v[72:73]
	v_lshlrev_b32_e32 v86, 16, v156
	v_and_b32_e32 v35, 0xffff0000, v157
	v_and_b32_e32 v34, 0xffff0000, v156
	v_add_f32_e32 v65, v72, v73
	v_pk_add_f32 v[72:73], v[86:87], v[34:35]
	v_lshlrev_b32_e32 v99, 16, v159
	v_lshlrev_b32_e32 v98, 16, v158
	v_and_b32_e32 v37, 0xffff0000, v159
	v_and_b32_e32 v36, 0xffff0000, v158
	v_add_f32_e32 v57, v58, v59
	v_add_f32_e32 v45, v62, v63
	v_add_f32_e32 v43, v72, v73
	v_pk_add_f32 v[72:73], v[98:99], v[36:37]
	v_pk_add_f32 v[74:75], v[56:57], v[44:45]
	v_add_f32_dpp v45, v65, v65 row_ror:8 row_mask:0xf bank_mask:0xf bound_ctrl:1
	v_pk_add_f32 v[72:73], v[72:73], v[72:73] op_sel_hi:[0,1]
	v_add_f32_e32 v43, 0, v43
	v_add_f32_dpp v45, v45, v45 row_ror:4 row_mask:0xf bank_mask:0xf bound_ctrl:1
	v_mov_b32_e32 v61, v73
	v_pk_add_f32 v[72:73], v[60:61], v[42:43]
	v_add_f32_dpp v45, v45, v45 row_ror:2 row_mask:0xf bank_mask:0xf bound_ctrl:1
	v_pk_add_f32 v[72:73], v[74:75], v[72:73]
	s_mov_b32 s1, s15
	v_add_f32_dpp v45, v45, v45 row_ror:1 row_mask:0xf bank_mask:0xf bound_ctrl:1
	v_add_f32_e32 v43, v72, v73
	v_readlane_b32 s0, v45, 16
	v_readlane_b32 s8, v45, 48
	v_readlane_b32 s2, v45, 0
	v_readlane_b32 s3, v45, 32
	v_mov_b32_e32 v72, s0
	v_mov_b32_e32 v73, s8
	v_pk_add_f32 v[72:73], s[2:3], v[72:73]
	s_lshl_b32 s15, s15, 6
	v_add_f32_e32 v45, v72, v73
	v_fmac_f32_e32 v39, 0xba800000, v45
	v_fmac_f32_e32 v47, 0xba800000, v45
	v_fmac_f32_e32 v38, 0xba800000, v45
; __device__ __forceinline__ float wave_sum_dpp(float x) { x = rowsum16(x); return (rl(x, 0) + rl(x, 16)) + (rl(x, 32) + rl(x, 48)); }
;     ...
;             for (int j = 0; j < 4; ++j) s[r] += (v[r][j][0] + v[r][j][1]) + (v[r][j][2] + v[r][j][3]);
;         float mean[NR], q[NR], rstd[NR];
; #pragma unroll
;         for (int r = 0; r < NR; ++r) { mean[r] = wave_sum_dpp(s[r]) * (1.f / DM); q[r] = 0.f;
; #pragma unroll
;             for (int j = 0; j < 4; ++j) { v[r][j] = v[r][j] - mean[r]; q[r] += (v[r][j][0] * v[r][j][0] + v[r][j][1] * v[r][j][1]) + (v[r][j][2] * v[r][j][2] + v[r][j][3] * v[r][j][3]); } }
	v_fmac_f32_e32 v46, 0xba800000, v45
	v_mov_b32_e32 v74, v47
	v_mov_b32_e32 v78, v47
	v_mov_b32_e32 v79, v39
	v_mov_b32_e32 v47, v38
	v_mov_b32_e32 v73, v38
	v_mov_b32_e32 v75, v39
	v_pk_mul_f32 v[78:79], v[78:79], v[78:79]
	v_pk_mul_f32 v[38:39], v[46:47], v[46:47]
	v_mov_b32_e32 v72, v46
	v_pk_mov_b32 v[46:47], v[38:39], v[78:79] op_sel:[1,0]
	v_mov_b32_e32 v39, v79
	v_fmac_f32_e32 v41, 0xba800000, v45
	v_fmac_f32_e32 v49, 0xba800000, v45
	v_fmac_f32_e32 v40, 0xba800000, v45
	v_pk_add_f32 v[38:39], v[46:47], v[38:39]
	v_fmac_f32_e32 v48, 0xba800000, v45
	v_mov_b32_e32 v80, v49
	v_mov_b32_e32 v46, v49
	v_mov_b32_e32 v47, v41
	v_mov_b32_e32 v49, v40
	v_pk_add_f32 v[38:39], v[38:39], v[38:39] op_sel_hi:[0,1]
	v_mov_b32_e32 v79, v40
	v_mov_b32_e32 v81, v41
	v_pk_mul_f32 v[46:47], v[46:47], v[46:47]
	v_pk_mul_f32 v[40:41], v[48:49], v[48:49]
	v_fmac_f32_e32 v68, 0xba800000, v45
	v_mov_b32_e32 v78, v48
	v_pk_mov_b32 v[48:49], v[40:41], v[46:47] op_sel:[1,0]
	v_mov_b32_e32 v41, v47
	v_fmac_f32_e32 v70, 0xba800000, v45
	v_fmac_f32_e32 v69, 0xba800000, v45
	v_mul_f32_e32 v38, v68, v68
	v_pk_add_f32 v[40:41], v[48:49], v[40:41]
	v_fmac_f32_e32 v71, 0xba800000, v45
	v_pk_fma_f32 v[46:47], v[68:69], v[68:69], v[38:39] op_sel_hi:[1,1,0]
	v_mul_f32_e32 v38, v70, v70
	v_pk_add_f32 v[40:41], v[40:41], v[40:41] op_sel_hi:[0,1]
	v_pk_fma_f32 v[48:49], v[70:71], v[70:71], v[38:39] op_sel_hi:[1,1,0]
	v_fmac_f32_e32 v84, 0xba800000, v45
	v_fmac_f32_e32 v66, 0xba800000, v45
	v_fmac_f32_e32 v82, 0xba800000, v45
	v_fmac_f32_e32 v64, 0xba800000, v45
	v_mul_f32_e32 v46, v64, v64
	v_mul_f32_e32 v48, v82, v82
	v_mul_f32_e32 v38, v66, v66
	v_mul_f32_e32 v40, v84, v84
	v_pk_add_f32 v[46:47], v[46:47], v[48:49]
	v_pk_add_f32 v[38:39], v[38:39], v[40:41]
	v_mov_b32_e32 v67, v84
	v_pk_add_f32 v[38:39], v[46:47], v[38:39]
	s_or_b32 s22, s15, 62
	v_add_f32_e32 v40, v38, v39
	v_add_f32_dpp v38, v43, v43 row_ror:8 row_mask:0xf bank_mask:0xf bound_ctrl:1
	s_add_i32 s15, s1, 8
	s_cmp_ge_i32 s1, s5
	v_add_f32_dpp v38, v38, v38 row_ror:4 row_mask:0xf bank_mask:0xf bound_ctrl:1
	s_cselect_b64 s[20:21], -1, 0
	s_cmp_lt_i32 s1, s5
	v_add_f32_dpp v38, v38, v38 row_ror:2 row_mask:0xf bank_mask:0xf bound_ctrl:1
	s_cselect_b32 s1, s15, s1
	s_lshl_b32 s1, s1, 6
	v_add_f32_dpp v38, v38, v38 row_ror:1 row_mask:0xf bank_mask:0xf bound_ctrl:1
	s_or_b32 s18, s1, 62
	v_readlane_b32 s0, v38, 16
	v_readlane_b32 s8, v38, 48
	v_readlane_b32 s2, v38, 0
	v_readlane_b32 s3, v38, 32
	v_mov_b32_e32 v38, s0
	v_mov_b32_e32 v39, s8
	v_pk_add_f32 v[38:39], s[2:3], v[38:39]
	s_ashr_i32 s19, s18, 31
	v_add_f32_e32 v38, v38, v39
	v_fmac_f32_e32 v35, 0xba800000, v38
	v_fmac_f32_e32 v34, 0xba800000, v38
	v_fmac_f32_e32 v87, 0xba800000, v38
	v_fmac_f32_e32 v86, 0xba800000, v38
	v_mov_b32_e32 v83, v34
	v_mov_b32_e32 v85, v35
	v_mul_f32_e32 v34, v34, v34
	v_mul_f32_e32 v35, v35, v35
	v_fmac_f32_e32 v34, v86, v86
	v_fmac_f32_e32 v35, v87, v87
	v_fmac_f32_e32 v37, 0xba800000, v38
	v_fmac_f32_e32 v36, 0xba800000, v38
	v_mov_b32_e32 v84, v87
	v_add_f32_e32 v34, v34, v35
	v_fmac_f32_e32 v99, 0xba800000, v38
	v_fmac_f32_e32 v98, 0xba800000, v38
	v_mov_b32_e32 v87, v36
	v_mul_f32_e32 v35, v36, v36
	v_mul_f32_e32 v36, v37, v37
	v_fmac_f32_e32 v35, v98, v98
	v_fmac_f32_e32 v36, v99, v99
	v_add_f32_e32 v35, v35, v36
	v_fmac_f32_e32 v63, 0xba800000, v38
	v_fmac_f32_e32 v59, 0xba800000, v38
	v_add_f32_e32 v34, v34, v35
	v_fmac_f32_e32 v62, 0xba800000, v38
	v_fmac_f32_e32 v58, 0xba800000, v38
	v_mul_f32_e32 v35, v59, v59
	v_mul_f32_e32 v36, v63, v63
	v_fmac_f32_e32 v35, v58, v58
	v_fmac_f32_e32 v36, v62, v62
	v_add_f32_e32 v35, v35, v36
	v_fmac_f32_e32 v42, 0xba800000, v38
	v_fmac_f32_e32 v44, 0xba800000, v38
	v_add_f32_e32 v34, v35, v34
	v_fmac_f32_e32 v60, 0xba800000, v38
	v_fmac_f32_e32 v56, 0xba800000, v38
	v_mul_f32_e32 v35, v44, v44
	v_mul_f32_e32 v36, v42, v42
	v_fmac_f32_e32 v35, v56, v56
	v_fmac_f32_e32 v36, v60, v60
	v_add_f32_e32 v35, v35, v36
	v_add_f32_e32 v34, v35, v34
; __device__ __forceinline__ float wave_sum_dpp(float x) { x = rowsum16(x); return (rl(x, 0) + rl(x, 16)) + (rl(x, 32) + rl(x, 48)); }
;     ...
;         for (int r = 0; r < NR; ++r) { mean[r] = wave_sum_dpp(s[r]) * (1.f / DM); q[r] = 0.f;
; #pragma unroll
;             for (int j = 0; j < 4; ++j) { v[r][j] = v[r][j] - mean[r]; q[r] += (v[r][j][0] * v[r][j][0] + v[r][j][1] * v[r][j][1]) + (v[r][j][2] * v[r][j][2] + v[r][j][3] * v[r][j][3]); } }
; #pragma unroll
;         for (int r = 0; r < NR; ++r) rstd[r] = 1.0f / sqrtf(wave_sum_dpp(q[r]) * (1.f / DM) + 1e-5f);
;         if (MODE == 1) {
; #pragma unroll
;             for (int r = 0; r < NR; ++r) if (lane == r) { stats[2 * row[r]] = mean[r]; stats[2 * row[r] + 1] = rstd[r]; } }
	s_lshl_b64 s[18:19], s[18:19], 11
	v_add_f32_dpp v35, v40, v40 row_ror:8 row_mask:0xf bank_mask:0xf bound_ctrl:1
	v_add_f32_dpp v34, v34, v34 row_ror:8 row_mask:0xf bank_mask:0xf bound_ctrl:1
	v_mul_f32_e32 v76, 0x3a800000, v45
	v_add_f32_dpp v35, v35, v35 row_ror:4 row_mask:0xf bank_mask:0xf bound_ctrl:1
	v_add_f32_dpp v34, v34, v34 row_ror:4 row_mask:0xf bank_mask:0xf bound_ctrl:1
	v_mul_f32_e32 v90, 0x3a800000, v38
	v_add_f32_dpp v35, v35, v35 row_ror:2 row_mask:0xf bank_mask:0xf bound_ctrl:1
	v_add_f32_dpp v34, v34, v34 row_ror:2 row_mask:0xf bank_mask:0xf bound_ctrl:1
	v_mov_b32_e32 v89, v37
	v_add_f32_dpp v35, v35, v35 row_ror:1 row_mask:0xf bank_mask:0xf bound_ctrl:1
	v_add_f32_dpp v34, v34, v34 row_ror:1 row_mask:0xf bank_mask:0xf bound_ctrl:1
	v_readlane_b32 s8, v35, 0
	v_readlane_b32 s11, v35, 16
	v_readlane_b32 s9, v35, 32
	v_readlane_b32 s13, v35, 48
	v_readlane_b32 s0, v34, 0
	v_readlane_b32 s3, v34, 16
	v_readlane_b32 s2, v34, 32
	v_readlane_b32 s10, v34, 48
	v_lshl_add_u64 v[34:35], v[50:51], 0, s[18:19]
	s_or_b32 s18, s1, 63
	s_ashr_i32 s19, s18, 31
	s_lshl_b64 s[18:19], s[18:19], 11
	v_lshl_add_u64 v[46:47], v[50:51], 0, s[18:19]
	v_mov_b32_e32 v57, v44
	v_mov_b32_e32 v61, v42
	v_mov_b32_e32 v65, v82
	v_mov_b32_e32 v82, v86
	v_mov_b32_e32 v86, v98
	v_mov_b32_e32 v88, v99
	v_mov_b32_e32 v98, s11
	v_mov_b32_e32 v99, s13
	v_pk_add_f32 v[98:99], s[8:9], v[98:99]
	s_nop 0
	v_add_f32_e32 v77, v98, v99
	v_fmamk_f32 v77, v77, 0x3a800000, v95
	v_mul_f32_e32 v91, 0x4f800000, v77
	v_cmp_gt_f32_e32 vcc, s14, v77
	v_mov_b32_e32 v98, s3
	v_mov_b32_e32 v99, s10
	v_cndmask_b32_e32 v77, v77, v91, vcc
	v_sqrt_f32_e32 v91, v77
	v_add_f32_e32 v98, s0, v98
	v_add_f32_e32 v99, s2, v99
	v_add_f32_e32 v98, v98, v99
	v_add_u32_e32 v92, -1, v91
	v_fma_f32 v94, -v92, v91, v77
	v_cmp_ge_f32_e64 s[8:9], 0, v94
	v_add_u32_e32 v94, 1, v91
	v_fmamk_f32 v98, v98, 0x3a800000, v95
	v_cndmask_b32_e64 v92, v91, v92, s[8:9]
	v_fma_f32 v91, -v94, v91, v77
	v_cmp_lt_f32_e64 s[8:9], 0, v91
	v_mul_f32_e32 v99, 0x4f800000, v98
	s_nop 0
	v_cndmask_b32_e64 v91, v92, v94, s[8:9]
	v_mul_f32_e32 v92, 0x37800000, v91
	v_cndmask_b32_e32 v91, v91, v92, vcc
	v_cmp_class_f32_e32 vcc, v77, v96
	s_nop 1
	v_cndmask_b32_e32 v77, v91, v77, vcc
	v_div_scale_f32 v91, s[8:9], v77, v77, 1.0
	v_rcp_f32_e32 v92, v91
	v_cmp_gt_f32_e64 s[8:9], s14, v98
	v_fma_f32 v94, -v91, v92, 1.0
	s_nop 0
	v_cndmask_b32_e64 v98, v98, v99, s[8:9]
	v_fmac_f32_e32 v92, v94, v92
	v_div_scale_f32 v94, vcc, 1.0, v77, 1.0
	v_sqrt_f32_e32 v99, v98
	v_mul_f32_e32 v97, v94, v92
	v_fma_f32 v100, -v91, v97, v94
	v_fmac_f32_e32 v97, v100, v92
	v_fma_f32 v91, -v91, v97, v94
	v_add_u32_e32 v94, -1, v99
	v_fma_f32 v100, -v94, v99, v98
	v_cmp_ge_f32_e64 s[10:11], 0, v100
	v_add_u32_e32 v100, 1, v99
	v_div_fmas_f32 v91, v91, v92, v97
	v_cndmask_b32_e64 v94, v99, v94, s[10:11]
	v_fma_f32 v99, -v100, v99, v98
	v_cmp_lt_f32_e64 s[10:11], 0, v99
	s_nop 1
	v_cndmask_b32_e64 v94, v94, v100, s[10:11]
	v_mul_f32_e32 v99, 0x37800000, v94
	v_cndmask_b32_e64 v94, v94, v99, s[8:9]
	v_cmp_class_f32_e64 s[8:9], v98, v96
	s_mov_b64 s[10:11], -1
	s_nop 0
	v_cndmask_b32_e64 v98, v94, v98, s[8:9]
	v_div_scale_f32 v99, s[0:1], v98, v98, 1.0
	v_rcp_f32_e32 v100, v99
	v_div_fixup_f32 v94, v91, v77, 1.0
	v_fma_f32 v77, -v99, v100, 1.0
	v_fmac_f32_e32 v100, v77, v100
	v_div_scale_f32 v77, vcc, 1.0, v98, 1.0
	v_mul_f32_e32 v91, v77, v100
	v_fma_f32 v92, -v99, v91, v77
	v_fmac_f32_e32 v91, v92, v100
	v_fma_f32 v77, -v99, v91, v77
	v_div_fmas_f32 v77, v77, v100, v91
	v_div_fixup_f32 v92, v77, v98, 1.0
	v_mov_b32_e32 v77, v94
	v_cmp_lt_i32_e32 vcc, 0, v1
	v_mov_b32_e32 v91, s22
	s_and_saveexec_b64 s[8:9], vcc
	s_cbranch_execz .Lhln15_m7
	v_cmp_eq_u32_e32 vcc, 1, v1
	s_mov_b64 s[10:11], 0
	s_and_saveexec_b64 s[26:27], vcc
	v_mov_b32_e32 v91, v92
	s_mov_b64 s[10:11], exec
	v_mov_b64_e32 v[76:77], v[90:91]
	s_or_b64 exec, exec, s[26:27]
	v_mov_b32_e32 v91, s12
	s_orn2_b64 s[10:11], s[10:11], exec

; __device__ __forceinline__ unsigned cvtpk(float lo, float hi) { f32x2_t v = {lo, hi}; bf16x2_t b = __builtin_convertvector(v, bf16x2_t); return __builtin_bit_cast(unsigned, b); }
;     ...
;         for (int j = 0; j < 2; ++j) {
;             const int c = 8 * lane + 512 * j;
;             const f32x4 g0 = *(const f32x4*)(g + c), g1 = *(const f32x4*)(g + c + 4), b0 = *(const f32x4*)(b + c), b1 = *(const f32x4*)(b + c + 4);
; #pragma unroll
;             for (int r = 0; r < NR; ++r) {
;                 const f32x4 o0 = v[r][2 * j] * rstd[r] * g0 + b0, o1 = v[r][2 * j + 1] * rstd[r] * g1 + b1;
;                 if (MODE == 1) { pg8::u32x4 w; w.x = cvtpk(o0[0], o0[1]); w.y = cvtpk(o0[2], o0[3]); w.z = cvtpk(o1[0], o1[1]); w.w = cvtpk(o1[2], o1[3]); *(pg8::u32x4*)(hb + (size_t)row[r] * DM + c) = w; }
;                 else { *(f32x4*)(outf + (size_t)row[r] * DM + c) = o0; *(f32x4*)(outf + (size_t)row[r] * DM + c + 4) = o1; }
;             }
.Lhln15_t7:
	s_or_b64 exec, exec, s[8:9]
	s_add_i32 s0, s12, -1
	v_pk_mul_f32 v[74:75], v[74:75], v[94:95] op_sel_hi:[1,0]
	v_pk_mul_f32 v[72:73], v[72:73], v[94:95] op_sel_hi:[1,0]
	v_pk_mul_f32 v[76:77], v[80:81], v[94:95] op_sel_hi:[1,0]
	v_pk_mul_f32 v[78:79], v[78:79], v[94:95] op_sel_hi:[1,0]
	s_ashr_i32 s1, s0, 31
	v_pk_fma_f32 v[74:75], v[12:13], v[74:75], v[16:17]
	v_pk_fma_f32 v[72:73], v[10:11], v[72:73], v[14:15]
	v_pk_fma_f32 v[76:77], v[4:5], v[76:77], v[8:9]
	v_pk_fma_f32 v[78:79], v[2:3], v[78:79], v[6:7]
	s_lshl_b64 s[0:1], s[0:1], 11
	v_cvt_pk_bf16_f32 v72, v72, v73
	v_cvt_pk_bf16_f32 v73, v74, v75
	v_cvt_pk_bf16_f32 v74, v78, v79
	v_cvt_pk_bf16_f32 v75, v76, v77
	v_lshl_add_u64 v[76:77], v[52:53], 0, s[0:1]
	global_store_dwordx4 v[76:77], v[72:75], off
	v_pk_mul_f32 v[78:79], v[86:87], v[92:93] op_sel_hi:[1,0]
	s_ashr_i32 s13, s12, 31
	v_pk_mul_f32 v[72:73], v[84:85], v[92:93] op_sel_hi:[1,0]
	v_pk_mul_f32 v[74:75], v[82:83], v[92:93] op_sel_hi:[1,0]
	v_pk_fma_f32 v[76:77], v[12:13], v[72:73], v[16:17]
	v_pk_fma_f32 v[72:73], v[10:11], v[74:75], v[14:15]
	v_pk_mul_f32 v[74:75], v[88:89], v[92:93] op_sel_hi:[1,0]
	s_lshl_b64 s[2:3], s[12:13], 11
	v_pk_fma_f32 v[80:81], v[4:5], v[74:75], v[8:9]
	v_pk_fma_f32 v[74:75], v[2:3], v[78:79], v[6:7]
	v_cvt_pk_bf16_f32 v72, v72, v73
	v_cvt_pk_bf16_f32 v73, v76, v77
	v_cvt_pk_bf16_f32 v74, v74, v75
	v_cvt_pk_bf16_f32 v75, v80, v81
	v_lshl_add_u64 v[76:77], v[52:53], 0, s[2:3]
	v_pk_mul_f32 v[70:71], v[70:71], v[94:95] op_sel_hi:[1,0]
	v_pk_mul_f32 v[68:69], v[68:69], v[94:95] op_sel_hi:[1,0]
	v_pk_mul_f32 v[66:67], v[66:67], v[94:95] op_sel_hi:[1,0]
	v_pk_mul_f32 v[64:65], v[64:65], v[94:95] op_sel_hi:[1,0]
	global_store_dwordx4 v[76:77], v[72:75], off
	v_pk_fma_f32 v[70:71], v[28:29], v[70:71], v[32:33]
	v_pk_fma_f32 v[68:69], v[26:27], v[68:69], v[30:31]
	v_pk_fma_f32 v[72:73], v[20:21], v[66:67], v[24:25]
	v_pk_fma_f32 v[66:67], v[18:19], v[64:65], v[22:23]
	v_cvt_pk_bf16_f32 v64, v68, v69
	v_cvt_pk_bf16_f32 v65, v70, v71
	v_cvt_pk_bf16_f32 v66, v66, v67
	v_cvt_pk_bf16_f32 v67, v72, v73
	v_lshl_add_u64 v[68:69], v[54:55], 0, s[0:1]
	v_pk_mul_f32 v[62:63], v[62:63], v[92:93] op_sel_hi:[1,0]
	v_pk_mul_f32 v[58:59], v[58:59], v[92:93] op_sel_hi:[1,0]
	v_pk_mul_f32 v[60:61], v[60:61], v[92:93] op_sel_hi:[1,0]
	v_pk_mul_f32 v[56:57], v[56:57], v[92:93] op_sel_hi:[1,0]
	global_store_dwordx4 v[68:69], v[64:67], off
	v_pk_fma_f32 v[62:63], v[28:29], v[62:63], v[32:33]
	v_pk_fma_f32 v[58:59], v[26:27], v[58:59], v[30:31]
	v_pk_fma_f32 v[60:61], v[20:21], v[60:61], v[24:25]
	v_pk_fma_f32 v[64:65], v[18:19], v[56:57], v[22:23]
	v_cvt_pk_bf16_f32 v56, v58, v59
	v_cvt_pk_bf16_f32 v57, v62, v63
	v_cvt_pk_bf16_f32 v58, v64, v65
	v_cvt_pk_bf16_f32 v59, v60, v61
	v_lshl_add_u64 v[60:61], v[54:55], 0, s[2:3]
	s_andn2_b64 vcc, exec, s[20:21]
	s_addk_i32 s12, 0x200
	global_store_dwordx4 v[60:61], v[56:59], off
	s_cbranch_vccz .LBB0_1752
	s_branch .LBB0_1752

; __global__ void __launch_bounds__(NWAVES * 64, 2) fwd_mega(Args args) {
	.amdhsa_kernel _Z8fwd_mega4Args
		.amdhsa_group_segment_fixed_size 0
		.amdhsa_private_segment_fixed_size 0
		.amdhsa_kernarg_size 616
		.amdhsa_user_sgpr_count 2
		.amdhsa_user_sgpr_dispatch_ptr 0
		.amdhsa_user_sgpr_queue_ptr 0
		.amdhsa_user_sgpr_kernarg_segment_ptr 1
		.amdhsa_user_sgpr_dispatch_id 0
		.amdhsa_user_sgpr_kernarg_preload_length 0
		.amdhsa_user_sgpr_kernarg_preload_offset 0
		.amdhsa_user_sgpr_private_segment_size 0
		.amdhsa_uses_dynamic_stack 0
		.amdhsa_enable_private_segment 0
		.amdhsa_system_sgpr_workgroup_id_x 1
		.amdhsa_system_sgpr_workgroup_id_y 0
		.amdhsa_system_sgpr_workgroup_id_z 0
		.amdhsa_system_sgpr_workgroup_info 0
		.amdhsa_system_vgpr_workitem_id 0
		.amdhsa_next_free_vgpr 256
		.amdhsa_next_free_sgpr 98
		.amdhsa_accum_offset 256
		.amdhsa_reserve_vcc 1
		.amdhsa_float_round_mode_32 0
		.amdhsa_float_round_mode_16_64 0
		.amdhsa_float_denorm_mode_32 3
		.amdhsa_float_denorm_mode_16_64 3
		.amdhsa_dx10_clamp 1
		.amdhsa_ieee_mode 1
		.amdhsa_fp16_overflow 0
		.amdhsa_tg_split 0
		.amdhsa_exception_fp_ieee_invalid_op 0
		.amdhsa_exception_fp_denorm_src 0
		.amdhsa_exception_fp_ieee_div_zero 0
		.amdhsa_exception_fp_ieee_overflow 0
		.amdhsa_exception_fp_ieee_underflow 0
		.amdhsa_exception_fp_ieee_inexact 0
		.amdhsa_exception_int_div_zero 0
	.end_amdhsa_kernel

; __global__ void __launch_bounds__(NWAVES * 64, 2) fwd_mega(Args args) {
amdhsa.kernels:
  - .agpr_count:     0
    .args:
      - .offset:         0
        .size:           360
        .value_kind:     by_value
      - .offset:         360
        .size:           4
        .value_kind:     hidden_block_count_x
      - .offset:         364
        .size:           4
        .value_kind:     hidden_block_count_y
      - .offset:         368
        .size:           4
        .value_kind:     hidden_block_count_z
      - .offset:         372
        .size:           2
        .value_kind:     hidden_group_size_x
      - .offset:         374
        .size:           2
        .value_kind:     hidden_group_size_y
      - .offset:         376
        .size:           2
        .value_kind:     hidden_group_size_z
      - .offset:         378
        .size:           2
        .value_kind:     hidden_remainder_x
      - .offset:         380
        .size:           2
        .value_kind:     hidden_remainder_y
      - .offset:         382
        .size:           2
        .value_kind:     hidden_remainder_z
      - .offset:         400
        .size:           8
        .value_kind:     hidden_global_offset_x
      - .offset:         408
        .size:           8
        .value_kind:     hidden_global_offset_y
      - .offset:         416
        .size:           8
        .value_kind:     hidden_global_offset_z
      - .offset:         424
        .size:           2
        .value_kind:     hidden_grid_dims
      - .offset:         480
        .size:           4
        .value_kind:     hidden_dynamic_lds_size
    .group_segment_fixed_size: 0
    .kernarg_segment_align: 8
    .kernarg_segment_size: 616
    .language:       OpenCL C
    .language_version:
      - 2
      - 0
    .max_flat_workgroup_size: 512
    .name:           _Z8fwd_mega4Args
    .private_segment_fixed_size: 0
    .sgpr_count:     104
    .sgpr_spill_count: 111
    .symbol:         _Z8fwd_mega4Args.kd
    .uniform_work_group_size: 1
    .uses_dynamic_stack: false
    .vgpr_count:     256
    .vgpr_spill_count: 0
    .wavefront_size: 64
